# K-loops: s_setprio 1 moved in front of the load-closing barrier and s_setprio 0 behind the MFMA-closing barrier (off the barrier hand-off path)
# speedup vs baseline: 1.0041x; 1.0041x over previous
; #define PG8_STAGE(bufoff, gbase, voff) do { _Pragma("unroll") for (int _i = 0; _i < 2; ++_i) \
;         __builtin_amdgcn_global_load_lds((const unsigned*)((const char*)(gbase) + (voff)[_i]), (PG8_LAS unsigned*)(lds + (bufoff) + ldsw + _i * 8192), 16, 0, 0); } while (0)
; #define PG8_LDA(dst, b, h) do { _Pragma("unroll") for (int m = 0; m < 4; ++m) _Pragma("unroll") for (int k = 0; k < 2; ++k) dst[m][k] = *(const PG8_LAS bf16x8*)(lds + PG8_SA(b, h) + aoff + m * 2048 + k * 1024); } while (0)
; #define PG8_LDB(dst, b, h) do { _Pragma("unroll") for (int n = 0; n < 2; ++n) _Pragma("unroll") for (int k = 0; k < 2; ++k) dst[n][k] = *(const PG8_LAS bf16x8*)(lds + PG8_SB(b, h) + boff + n * 2048 + k * 1024); } while (0)
; #define PG8_WAIT_V(n) asm volatile("s_waitcnt vmcnt(" #n ")" ::: "memory")
; #define PG8_WAIT_L(n) asm volatile("s_waitcnt lgkmcnt(" #n ")" ::: "memory")
; #define PG8_BAR __builtin_amdgcn_s_barrier()
; #define PG8_SCHED __builtin_amdgcn_sched_barrier(0)
; template <class Epi, class Sched, bool ALIGN_EPI = false, bool SP2 = false, bool I8 = false>
; __device__ __forceinline__ void gemm_phase(PG8_LAS unsigned char* lds, const Gemm g, const Sched& S, const Epi& E) {
;     ...
;         const bool has_next = S.next(ui + 1, nxt);
;         const char* nA = has_next ? (const char*)g.A + (size_t)nxt.pm * tstep : cA; const char* nB = has_next ? (const char*)g.Bt + (size_t)nxt.pn * tstep : cB;
;         for (int t = 0; t < nt; t += 2) {
;             const bool last = (t == nt - 2);
;             const char* a1 = cA + (size_t)(t + 1) * kstep;
;             const char* a2 = last ? nA : cA + (size_t)(t + 2) * kstep; const char* b2 = last ? nB : cB + (size_t)(t + 2) * kstep;
;             const char* a3 = a2 + kstep; const char* b3 = b2 + kstep;
;             if (last && has_next) S.a_ready(nxt);
;             if constexpr (SP2) {
;             PG8_LDB(B0, 0, 0); PG8_LDB(B1, 0, 1); PG8_SCHED; PG8_LDA(At, 0, 0); PG8_STAGE(PG8_SA(1, 1), a1 + hstep, voffA);
;             PG8_WAIT_V(8); PG8_WAIT_L(0); PG8_BAR; PG8_MMA(0, 0, At, B0); PG8_MMA(0, 1, At, B1); PG8_BAR; PG8_SCHED;
;             PG8_LDA(At, 0, 1); PG8_STAGE(PG8_SB(0, 0), b2, voffB); PG8_STAGE(PG8_SB(0, 1), b2 + hstep, voffB); PG8_STAGE(PG8_SA(0, 0), a2, voffA);
;             PG8_WAIT_V(8); PG8_WAIT_L(0); PG8_BAR; PG8_MMA(1, 0, At, B0); PG8_MMA(1, 1, At, B1); PG8_BAR; PG8_SCHED;
.LBB0_207:
	s_ashr_i32 s19, s18, 31
	s_lshl_b64 s[22:23], s[18:19], 20
	s_add_u32 s22, s28, s22
	s_addc_u32 s23, s34, s23
	s_and_b64 s[24:25], s[6:7], exec
	s_cselect_b32 s19, s23, s27
	s_cselect_b32 s64, s22, s26
	s_ashr_i32 s17, s16, 31
	s_lshl_b64 s[24:25], s[16:17], 20
	s_add_u32 s24, s35, s24
	s_addc_u32 s25, s42, s25
	s_and_b64 s[40:41], s[6:7], exec
	s_cselect_b32 s17, s25, s37
	s_cselect_b32 s65, s24, s36
	s_add_u32 s26, s26, 0x80080
	s_addc_u32 s27, s27, 0
	s_add_u32 s72, s36, 0x100
	s_addc_u32 s73, s37, 0
	s_mov_b32 s76, -2
	s_add_u32 s36, s26, 0xfff80080
	s_addc_u32 s37, s27, -1
	s_add_i32 s50, 0, 0x10000
	s_cmp_eq_u32 s76, 28
	s_cselect_b32 s41, s19, s37
	s_cselect_b32 s40, s64, s36
	s_cselect_b32 s37, s17, s73
	s_cselect_b32 s36, s65, s72
	s_add_i32 s56, 0, 0x14000
	v_add_u32_e32 v136, s50, v175
	v_add_u32_e32 v172, s56, v175
	ds_read_b128 v[116:119], v136
	ds_read_b128 v[124:127], v136 offset:1024
	ds_read_b128 v[132:135], v136 offset:2048
	ds_read_b128 v[136:139], v136 offset:3072
	ds_read_b128 v[160:163], v172
	ds_read_b128 v[164:167], v172 offset:1024
	ds_read_b128 v[168:171], v172 offset:2048
	ds_read_b128 v[178:181], v172 offset:3072
	s_add_i32 m0, s44, 0xc000
	ds_read_b128 v[182:185], v177
	ds_read_b128 v[186:189], v177 offset:1024
	ds_read_b128 v[204:207], v177 offset:2048
	ds_read_b128 v[208:211], v177 offset:3072
	ds_read_b128 v[212:215], v177 offset:4096
	ds_read_b128 v[216:219], v177 offset:5120
	ds_read_b128 v[220:223], v177 offset:6144
	ds_read_b128 v[224:227], v177 offset:7168
	global_load_lds_dwordx4 v156, s[26:27]
	s_add_i32 m0, s44, 0xe000
	s_nop 0
	global_load_lds_dwordx4 v158, s[26:27]
	s_waitcnt vmcnt(8)
	s_waitcnt lgkmcnt(0)
	s_setprio 1
	s_barrier
	s_waitcnt lgkmcnt(0)
	v_mfma_i32_16x16x64_i8 v[144:147], v[116:119], v[182:185], 0
	v_mfma_i32_16x16x64_i8 v[144:147], v[124:127], v[186:189], v[144:147]
	v_mfma_i32_16x16x64_i8 v[112:115], v[124:127], v[208:211], 0
	v_mfma_i32_16x16x64_i8 v[112:115], v[116:119], v[204:207], v[112:115]
	v_mfma_i32_16x16x64_i8 v[96:99], v[116:119], v[212:215], 0
	v_mfma_i32_16x16x64_i8 v[96:99], v[124:127], v[216:219], v[96:99]
	v_mfma_i32_16x16x64_i8 v[80:83], v[124:127], v[224:227], 0
	v_mfma_i32_16x16x64_i8 v[80:83], v[116:119], v[220:223], v[80:83]
	v_mfma_i32_16x16x64_i8 v[76:79], v[132:135], v[220:223], 0
	v_mfma_i32_16x16x64_i8 v[76:79], v[136:139], v[224:227], v[76:79]
	v_mfma_i32_16x16x64_i8 v[92:95], v[136:139], v[216:219], 0
	v_mfma_i32_16x16x64_i8 v[92:95], v[132:135], v[212:215], v[92:95]
	v_mfma_i32_16x16x64_i8 v[108:111], v[132:135], v[204:207], 0
	v_mfma_i32_16x16x64_i8 v[108:111], v[136:139], v[208:211], v[108:111]
	v_mfma_i32_16x16x64_i8 v[140:143], v[136:139], v[186:189], 0
	v_mfma_i32_16x16x64_i8 v[140:143], v[132:135], v[182:185], v[140:143]
	v_mfma_i32_16x16x64_i8 v[128:131], v[160:163], v[182:185], 0
	v_mfma_i32_16x16x64_i8 v[128:131], v[164:167], v[186:189], v[128:131]
	v_mfma_i32_16x16x64_i8 v[104:107], v[164:167], v[208:211], 0
	v_mfma_i32_16x16x64_i8 v[104:107], v[160:163], v[204:207], v[104:107]
	v_mfma_i32_16x16x64_i8 v[88:91], v[160:163], v[212:215], 0
	v_mfma_i32_16x16x64_i8 v[88:91], v[164:167], v[216:219], v[88:91]
	v_mfma_i32_16x16x64_i8 v[72:75], v[164:167], v[224:227], 0
	v_mfma_i32_16x16x64_i8 v[72:75], v[160:163], v[220:223], v[72:75]
	v_mfma_i32_16x16x64_i8 v[68:71], v[168:171], v[220:223], 0
	v_mfma_i32_16x16x64_i8 v[68:71], v[178:181], v[224:227], v[68:71]
	v_mfma_i32_16x16x64_i8 v[84:87], v[178:181], v[216:219], 0
	v_mfma_i32_16x16x64_i8 v[84:87], v[168:171], v[212:215], v[84:87]
	v_mfma_i32_16x16x64_i8 v[100:103], v[168:171], v[204:207], 0
	v_mfma_i32_16x16x64_i8 v[100:103], v[178:181], v[208:211], v[100:103]
	v_mfma_i32_16x16x64_i8 v[120:123], v[178:181], v[186:189], 0
	v_mfma_i32_16x16x64_i8 v[120:123], v[168:171], v[182:185], v[120:123]
	s_barrier
	s_setprio 0
	s_add_i32 s50, s50, s43
	v_lshl_add_u64 v[172:173], s[36:37], 0, v[2:3]
	s_mov_b32 m0, s50
	ds_read_b128 v[182:185], v177 offset:16384
	ds_read_b128 v[186:189], v177 offset:17408
	ds_read_b128 v[204:207], v177 offset:18432
	ds_read_b128 v[208:211], v177 offset:19456
	ds_read_b128 v[212:215], v177 offset:20480
	ds_read_b128 v[216:219], v177 offset:21504
	ds_read_b128 v[220:223], v177 offset:22528
	ds_read_b128 v[224:227], v177 offset:23552
	global_load_lds_dwordx4 v[172:173], off
	s_add_i32 m0, s50, 0x2000
	s_add_u32 s50, s36, 0x80000
	v_lshl_add_u64 v[190:191], s[36:37], 0, v[148:149]
	s_addc_u32 s51, s37, 0
	s_add_i32 s56, s56, s43
	global_load_lds_dwordx4 v[190:191], off
	s_mov_b32 m0, s56
	v_lshl_add_u64 v[240:241], s[40:41], 0, v[150:151]
	global_load_lds_dwordx4 v2, s[50:51]
	s_add_i32 m0, s56, 0x2000
	s_nop 0
	global_load_lds_dwordx4 v148, s[50:51]
	v_lshl_add_u64 v[228:229], s[40:41], 0, v[152:153]
	s_waitcnt vmcnt(6)
	s_waitcnt lgkmcnt(0)
	s_setprio 1
	s_barrier
; #define PG8_STAGE(bufoff, gbase, voff) do { _Pragma("unroll") for (int _i = 0; _i < 2; ++_i) \
;         __builtin_amdgcn_global_load_lds((const unsigned*)((const char*)(gbase) + (voff)[_i]), (PG8_LAS unsigned*)(lds + (bufoff) + ldsw + _i * 8192), 16, 0, 0); } while (0)
; #define PG8_LDA(dst, b, h) do { _Pragma("unroll") for (int m = 0; m < 4; ++m) _Pragma("unroll") for (int k = 0; k < 2; ++k) dst[m][k] = *(const PG8_LAS bf16x8*)(lds + PG8_SA(b, h) + aoff + m * 2048 + k * 1024); } while (0)
; #define PG8_LDB(dst, b, h) do { _Pragma("unroll") for (int n = 0; n < 2; ++n) _Pragma("unroll") for (int k = 0; k < 2; ++k) dst[n][k] = *(const PG8_LAS bf16x8*)(lds + PG8_SB(b, h) + boff + n * 2048 + k * 1024); } while (0)
; #define PG8_WAIT_V(n) asm volatile("s_waitcnt vmcnt(" #n ")" ::: "memory")
; #define PG8_WAIT_L(n) asm volatile("s_waitcnt lgkmcnt(" #n ")" ::: "memory")
; #define PG8_BAR __builtin_amdgcn_s_barrier()
; #define PG8_SCHED __builtin_amdgcn_sched_barrier(0)
; template <class Epi, class Sched, bool ALIGN_EPI = false, bool SP2 = false, bool I8 = false>
; __device__ __forceinline__ void gemm_phase(PG8_LAS unsigned char* lds, const Gemm g, const Sched& S, const Epi& E) {
;     ...
;             PG8_WAIT_V(8); PG8_WAIT_L(0); PG8_BAR; PG8_MMA(0, 0, At, B0); PG8_MMA(0, 1, At, B1); PG8_BAR; PG8_SCHED;
;             PG8_LDA(At, 0, 1); PG8_STAGE(PG8_SB(0, 0), b2, voffB); PG8_STAGE(PG8_SB(0, 1), b2 + hstep, voffB); PG8_STAGE(PG8_SA(0, 0), a2, voffA);
;             PG8_WAIT_V(8); PG8_WAIT_L(0); PG8_BAR; PG8_MMA(1, 0, At, B0); PG8_MMA(1, 1, At, B1); PG8_BAR; PG8_SCHED;
;             PG8_LDB(B0, 1, 0); PG8_LDB(B1, 1, 1); PG8_SCHED; PG8_LDA(At, 1, 0); PG8_STAGE(PG8_SA(0, 1), a2 + hstep, voffA);
;             PG8_WAIT_V(8); PG8_WAIT_L(0); PG8_BAR; PG8_MMA(0, 0, At, B0); PG8_MMA(0, 1, At, B1); PG8_BAR; PG8_SCHED;
;             PG8_LDA(At, 1, 1); PG8_STAGE(PG8_SB(1, 0), b3, voffB); PG8_STAGE(PG8_SB(1, 1), b3 + hstep, voffB); PG8_STAGE(PG8_SA(1, 0), a3, voffA);
;             PG8_WAIT_V(8); PG8_WAIT_L(0); PG8_BAR; PG8_MMA(1, 0, At, B0); PG8_MMA(1, 1, At, B1); PG8_BAR; PG8_SCHED;
	s_waitcnt lgkmcnt(0)
	v_mfma_i32_16x16x64_i8 v[64:67], v[116:119], v[182:185], 0
	v_mfma_i32_16x16x64_i8 v[64:67], v[124:127], v[186:189], v[64:67]
	v_mfma_i32_16x16x64_i8 v[48:51], v[124:127], v[208:211], 0
	v_mfma_i32_16x16x64_i8 v[48:51], v[116:119], v[204:207], v[48:51]
	v_mfma_i32_16x16x64_i8 v[32:35], v[116:119], v[212:215], 0
	v_mfma_i32_16x16x64_i8 v[32:35], v[124:127], v[216:219], v[32:35]
	v_mfma_i32_16x16x64_i8 v[16:19], v[124:127], v[224:227], 0
	v_mfma_i32_16x16x64_i8 v[16:19], v[116:119], v[220:223], v[16:19]
	v_mfma_i32_16x16x64_i8 v[12:15], v[132:135], v[220:223], 0
	v_mfma_i32_16x16x64_i8 v[12:15], v[136:139], v[224:227], v[12:15]
	v_mfma_i32_16x16x64_i8 v[28:31], v[136:139], v[216:219], 0
	v_mfma_i32_16x16x64_i8 v[28:31], v[132:135], v[212:215], v[28:31]
	v_mfma_i32_16x16x64_i8 v[44:47], v[132:135], v[204:207], 0
	v_mfma_i32_16x16x64_i8 v[44:47], v[136:139], v[208:211], v[44:47]
	v_mfma_i32_16x16x64_i8 v[60:63], v[136:139], v[186:189], 0
	v_mfma_i32_16x16x64_i8 v[60:63], v[132:135], v[182:185], v[60:63]
	v_mfma_i32_16x16x64_i8 v[56:59], v[160:163], v[182:185], 0
	v_mfma_i32_16x16x64_i8 v[56:59], v[164:167], v[186:189], v[56:59]
	v_mfma_i32_16x16x64_i8 v[40:43], v[164:167], v[208:211], 0
	v_mfma_i32_16x16x64_i8 v[40:43], v[160:163], v[204:207], v[40:43]
	v_mfma_i32_16x16x64_i8 v[24:27], v[160:163], v[212:215], 0
	v_mfma_i32_16x16x64_i8 v[24:27], v[164:167], v[216:219], v[24:27]
	v_mfma_i32_16x16x64_i8 v[8:11], v[164:167], v[224:227], 0
	v_mfma_i32_16x16x64_i8 v[8:11], v[160:163], v[220:223], v[8:11]
	v_mfma_i32_16x16x64_i8 v[4:7], v[168:171], v[220:223], 0
	v_mfma_i32_16x16x64_i8 v[4:7], v[178:181], v[224:227], v[4:7]
	v_mfma_i32_16x16x64_i8 v[20:23], v[178:181], v[216:219], 0
	v_mfma_i32_16x16x64_i8 v[20:23], v[168:171], v[212:215], v[20:23]
	v_mfma_i32_16x16x64_i8 v[36:39], v[168:171], v[204:207], 0
	v_mfma_i32_16x16x64_i8 v[36:39], v[178:181], v[208:211], v[36:39]
	v_mfma_i32_16x16x64_i8 v[52:55], v[178:181], v[186:189], 0
	v_mfma_i32_16x16x64_i8 v[52:55], v[168:171], v[182:185], v[52:55]
	s_barrier
	s_setprio 0
	s_mov_b32 m0, s44
	s_nop 0
	global_load_lds_dwordx4 v[228:229], off
	s_mov_b32 m0, s45
	s_nop 0
	global_load_lds_dwordx4 v[240:241], off
	s_add_i32 s50, 0, 0x18000
	s_add_i32 s51, 0, 0x1c000
	v_add_u32_e32 v136, s50, v175
	v_add_u32_e32 v178, s51, v175
	ds_read_b128 v[116:119], v136
	ds_read_b128 v[124:127], v136 offset:1024
	ds_read_b128 v[132:135], v136 offset:2048
	ds_read_b128 v[136:139], v136 offset:3072
	ds_read_b128 v[160:163], v178
	ds_read_b128 v[164:167], v178 offset:1024
	ds_read_b128 v[168:171], v178 offset:2048
	ds_read_b128 v[178:181], v178 offset:3072
	s_add_u32 s40, s40, 0x80000
	s_addc_u32 s41, s41, 0
	s_mov_b32 m0, s46
	ds_read_b128 v[182:185], v177 offset:32768
	ds_read_b128 v[186:189], v177 offset:33792
	ds_read_b128 v[204:207], v177 offset:34816
	ds_read_b128 v[208:211], v177 offset:35840
	ds_read_b128 v[212:215], v177 offset:36864
	ds_read_b128 v[216:219], v177 offset:37888
	ds_read_b128 v[220:223], v177 offset:38912
	ds_read_b128 v[224:227], v177 offset:39936
	global_load_lds_dwordx4 v152, s[40:41]
	s_mov_b32 m0, s47
	s_nop 0
	global_load_lds_dwordx4 v150, s[40:41]
	s_waitcnt vmcnt(8)
	s_waitcnt lgkmcnt(0)
	s_setprio 1
	s_barrier
	s_waitcnt lgkmcnt(0)
	v_mfma_i32_16x16x64_i8 v[144:147], v[116:119], v[182:185], v[144:147]
	v_mfma_i32_16x16x64_i8 v[144:147], v[124:127], v[186:189], v[144:147]
	v_mfma_i32_16x16x64_i8 v[112:115], v[124:127], v[208:211], v[112:115]
	v_mfma_i32_16x16x64_i8 v[112:115], v[116:119], v[204:207], v[112:115]
	v_mfma_i32_16x16x64_i8 v[96:99], v[116:119], v[212:215], v[96:99]
	v_mfma_i32_16x16x64_i8 v[96:99], v[124:127], v[216:219], v[96:99]
	v_mfma_i32_16x16x64_i8 v[80:83], v[124:127], v[224:227], v[80:83]
	v_mfma_i32_16x16x64_i8 v[80:83], v[116:119], v[220:223], v[80:83]
	v_mfma_i32_16x16x64_i8 v[76:79], v[132:135], v[220:223], v[76:79]
	v_mfma_i32_16x16x64_i8 v[76:79], v[136:139], v[224:227], v[76:79]
	v_mfma_i32_16x16x64_i8 v[92:95], v[136:139], v[216:219], v[92:95]
	v_mfma_i32_16x16x64_i8 v[92:95], v[132:135], v[212:215], v[92:95]
	v_mfma_i32_16x16x64_i8 v[108:111], v[132:135], v[204:207], v[108:111]
	v_mfma_i32_16x16x64_i8 v[108:111], v[136:139], v[208:211], v[108:111]
	v_mfma_i32_16x16x64_i8 v[140:143], v[136:139], v[186:189], v[140:143]
	v_mfma_i32_16x16x64_i8 v[140:143], v[132:135], v[182:185], v[140:143]
	v_mfma_i32_16x16x64_i8 v[128:131], v[160:163], v[182:185], v[128:131]
	v_mfma_i32_16x16x64_i8 v[128:131], v[164:167], v[186:189], v[128:131]
	v_mfma_i32_16x16x64_i8 v[104:107], v[164:167], v[208:211], v[104:107]
	v_mfma_i32_16x16x64_i8 v[104:107], v[160:163], v[204:207], v[104:107]
	v_mfma_i32_16x16x64_i8 v[88:91], v[160:163], v[212:215], v[88:91]
	v_mfma_i32_16x16x64_i8 v[88:91], v[164:167], v[216:219], v[88:91]
	v_mfma_i32_16x16x64_i8 v[72:75], v[164:167], v[224:227], v[72:75]
	v_mfma_i32_16x16x64_i8 v[72:75], v[160:163], v[220:223], v[72:75]
	v_mfma_i32_16x16x64_i8 v[68:71], v[168:171], v[220:223], v[68:71]
	v_mfma_i32_16x16x64_i8 v[68:71], v[178:181], v[224:227], v[68:71]
	v_mfma_i32_16x16x64_i8 v[84:87], v[178:181], v[216:219], v[84:87]
	v_mfma_i32_16x16x64_i8 v[84:87], v[168:171], v[212:215], v[84:87]
	v_mfma_i32_16x16x64_i8 v[100:103], v[168:171], v[204:207], v[100:103]
	v_mfma_i32_16x16x64_i8 v[100:103], v[178:181], v[208:211], v[100:103]
	v_mfma_i32_16x16x64_i8 v[120:123], v[178:181], v[186:189], v[120:123]
	v_mfma_i32_16x16x64_i8 v[120:123], v[168:171], v[182:185], v[120:123]
	s_barrier
	s_setprio 0
	s_add_i32 s40, s50, s43
	v_lshl_add_u64 v[172:173], v[172:173], 0, s[84:85]
	s_mov_b32 m0, s40
	ds_read_b128 v[182:185], v177 offset:49152
	ds_read_b128 v[186:189], v177 offset:50176
	ds_read_b128 v[204:207], v177 offset:51200
	ds_read_b128 v[208:211], v177 offset:52224
	ds_read_b128 v[212:215], v177 offset:53248
	ds_read_b128 v[216:219], v177 offset:54272
	ds_read_b128 v[220:223], v177 offset:55296
	ds_read_b128 v[224:227], v177 offset:56320
	global_load_lds_dwordx4 v[172:173], off
	s_add_i32 m0, s40, 0x2000
	s_add_u32 s36, s36, 0x80080
	v_lshl_add_u64 v[172:173], v[190:191], 0, s[84:85]
	s_addc_u32 s37, s37, 0
	s_add_i32 s40, s51, s43
	global_load_lds_dwordx4 v[172:173], off
	s_mov_b32 m0, s40
	s_nop 0
	global_load_lds_dwordx4 v2, s[36:37]
	s_add_i32 m0, s40, 0x2000
	s_nop 0
	global_load_lds_dwordx4 v148, s[36:37]
	s_cmp_eq_u32 s76, 28
	s_cbranch_scc0 .Ldefer_208_peel
	v_lshl_add_u64 v[172:173], v[228:229], 0, s[84:85]
	s_mov_b32 m0, s52
	s_nop 0
	global_load_lds_dwordx4 v[172:173], off
	v_lshl_add_u64 v[172:173], v[240:241], 0, s[84:85]
	s_mov_b32 m0, s53
	s_nop 0
	global_load_lds_dwordx4 v[172:173], off
; #define PG8_STAGE(bufoff, gbase, voff) do { _Pragma("unroll") for (int _i = 0; _i < 2; ++_i) \
;         __builtin_amdgcn_global_load_lds((const unsigned*)((const char*)(gbase) + (voff)[_i]), (PG8_LAS unsigned*)(lds + (bufoff) + ldsw + _i * 8192), 16, 0, 0); } while (0)
; #define PG8_LDA(dst, b, h) do { _Pragma("unroll") for (int m = 0; m < 4; ++m) _Pragma("unroll") for (int k = 0; k < 2; ++k) dst[m][k] = *(const PG8_LAS bf16x8*)(lds + PG8_SA(b, h) + aoff + m * 2048 + k * 1024); } while (0)
; #define PG8_LDB(dst, b, h) do { _Pragma("unroll") for (int n = 0; n < 2; ++n) _Pragma("unroll") for (int k = 0; k < 2; ++k) dst[n][k] = *(const PG8_LAS bf16x8*)(lds + PG8_SB(b, h) + boff + n * 2048 + k * 1024); } while (0)
; #define PG8_WAIT_V(n) asm volatile("s_waitcnt vmcnt(" #n ")" ::: "memory")
; #define PG8_WAIT_L(n) asm volatile("s_waitcnt lgkmcnt(" #n ")" ::: "memory")
; #define PG8_BAR __builtin_amdgcn_s_barrier()
; #define PG8_SCHED __builtin_amdgcn_sched_barrier(0)
; template <class Epi, class Sched, bool ALIGN_EPI = false, bool SP2 = false, bool I8 = false>
; __device__ __forceinline__ void gemm_phase(PG8_LAS unsigned char* lds, const Gemm g, const Sched& S, const Epi& E) {
;     ...
;         for (int t = 0; t < nt; t += 2) {
;             const bool last = (t == nt - 2);
;             const char* a1 = cA + (size_t)(t + 1) * kstep;
;             const char* a2 = last ? nA : cA + (size_t)(t + 2) * kstep; const char* b2 = last ? nB : cB + (size_t)(t + 2) * kstep;
;             const char* a3 = a2 + kstep; const char* b3 = b2 + kstep;
;             if (last && has_next) S.a_ready(nxt);
;             if constexpr (SP2) {
;             PG8_LDB(B0, 0, 0); PG8_LDB(B1, 0, 1); PG8_SCHED; PG8_LDA(At, 0, 0); PG8_STAGE(PG8_SA(1, 1), a1 + hstep, voffA);
;             PG8_WAIT_V(8); PG8_WAIT_L(0); PG8_BAR; PG8_MMA(0, 0, At, B0); PG8_MMA(0, 1, At, B1); PG8_BAR; PG8_SCHED;
;             PG8_LDA(At, 0, 1); PG8_STAGE(PG8_SB(0, 0), b2, voffB); PG8_STAGE(PG8_SB(0, 1), b2 + hstep, voffB); PG8_STAGE(PG8_SA(0, 0), a2, voffA);
;             PG8_WAIT_V(8); PG8_WAIT_L(0); PG8_BAR; PG8_MMA(1, 0, At, B0); PG8_MMA(1, 1, At, B1); PG8_BAR; PG8_SCHED;
.Ldefer_208_peel:
	s_waitcnt vmcnt(6)
	s_waitcnt lgkmcnt(0)
	s_setprio 1
	s_barrier
	s_waitcnt lgkmcnt(0)
	v_mfma_i32_16x16x64_i8 v[64:67], v[116:119], v[182:185], v[64:67]
	v_mfma_i32_16x16x64_i8 v[64:67], v[124:127], v[186:189], v[64:67]
	v_mfma_i32_16x16x64_i8 v[48:51], v[124:127], v[208:211], v[48:51]
	v_mfma_i32_16x16x64_i8 v[48:51], v[116:119], v[204:207], v[48:51]
	v_mfma_i32_16x16x64_i8 v[32:35], v[116:119], v[212:215], v[32:35]
	v_mfma_i32_16x16x64_i8 v[32:35], v[124:127], v[216:219], v[32:35]
	v_mfma_i32_16x16x64_i8 v[16:19], v[124:127], v[224:227], v[16:19]
	v_mfma_i32_16x16x64_i8 v[16:19], v[116:119], v[220:223], v[16:19]
	v_mfma_i32_16x16x64_i8 v[12:15], v[132:135], v[220:223], v[12:15]
	v_mfma_i32_16x16x64_i8 v[12:15], v[136:139], v[224:227], v[12:15]
	v_mfma_i32_16x16x64_i8 v[28:31], v[136:139], v[216:219], v[28:31]
	v_mfma_i32_16x16x64_i8 v[28:31], v[132:135], v[212:215], v[28:31]
	v_mfma_i32_16x16x64_i8 v[44:47], v[132:135], v[204:207], v[44:47]
	v_mfma_i32_16x16x64_i8 v[44:47], v[136:139], v[208:211], v[44:47]
	v_mfma_i32_16x16x64_i8 v[60:63], v[136:139], v[186:189], v[60:63]
	v_mfma_i32_16x16x64_i8 v[60:63], v[132:135], v[182:185], v[60:63]
	v_mfma_i32_16x16x64_i8 v[56:59], v[160:163], v[182:185], v[56:59]
	v_mfma_i32_16x16x64_i8 v[56:59], v[164:167], v[186:189], v[56:59]
	v_mfma_i32_16x16x64_i8 v[40:43], v[164:167], v[208:211], v[40:43]
	v_mfma_i32_16x16x64_i8 v[40:43], v[160:163], v[204:207], v[40:43]
	v_mfma_i32_16x16x64_i8 v[24:27], v[160:163], v[212:215], v[24:27]
	v_mfma_i32_16x16x64_i8 v[24:27], v[164:167], v[216:219], v[24:27]
	v_mfma_i32_16x16x64_i8 v[8:11], v[164:167], v[224:227], v[8:11]
	v_mfma_i32_16x16x64_i8 v[8:11], v[160:163], v[220:223], v[8:11]
	v_mfma_i32_16x16x64_i8 v[4:7], v[168:171], v[220:223], v[4:7]
	v_mfma_i32_16x16x64_i8 v[4:7], v[178:181], v[224:227], v[4:7]
	v_mfma_i32_16x16x64_i8 v[20:23], v[178:181], v[216:219], v[20:23]
	v_mfma_i32_16x16x64_i8 v[20:23], v[168:171], v[212:215], v[20:23]
	v_mfma_i32_16x16x64_i8 v[36:39], v[168:171], v[204:207], v[36:39]
	v_mfma_i32_16x16x64_i8 v[36:39], v[178:181], v[208:211], v[36:39]
	v_mfma_i32_16x16x64_i8 v[52:55], v[178:181], v[186:189], v[52:55]
	v_mfma_i32_16x16x64_i8 v[52:55], v[168:171], v[182:185], v[52:55]
	s_barrier
	s_setprio 0
	s_add_i32 s76, s76, 2
	s_add_u32 s26, s26, 0x100
	s_addc_u32 s27, s27, 0
	s_add_u32 s72, s72, 0x100
	s_addc_u32 s73, s73, 0
	s_cmp_gt_u32 s76, 29
	s_cbranch_scc1 .Lkloop_exit_0
.LBB0_208:
	s_add_u32 s36, s26, 0xfff80080
	s_addc_u32 s37, s27, -1
	s_add_i32 s50, 0, 0x10000
	s_cmp_eq_u32 s76, 28
	s_cselect_b32 s41, s19, s37
	s_cselect_b32 s40, s64, s36
	s_cselect_b32 s37, s17, s73
	s_cselect_b32 s36, s65, s72
	s_add_i32 s56, 0, 0x14000
	v_add_u32_e32 v136, s50, v175
	v_add_u32_e32 v172, s56, v175
	ds_read_b128 v[116:119], v136
	ds_read_b128 v[124:127], v136 offset:1024
	ds_read_b128 v[132:135], v136 offset:2048
	ds_read_b128 v[136:139], v136 offset:3072
	ds_read_b128 v[160:163], v172
	ds_read_b128 v[164:167], v172 offset:1024
	ds_read_b128 v[168:171], v172 offset:2048
	ds_read_b128 v[178:181], v172 offset:3072
	v_lshl_add_u64 v[172:173], v[228:229], 0, s[84:85]
	s_mov_b32 m0, s52
	s_nop 0
	global_load_lds_dwordx4 v[172:173], off
	v_lshl_add_u64 v[172:173], v[240:241], 0, s[84:85]
	s_mov_b32 m0, s53
	s_nop 0
	global_load_lds_dwordx4 v[172:173], off
	s_add_i32 m0, s44, 0xc000
	ds_read_b128 v[182:185], v177
	ds_read_b128 v[186:189], v177 offset:1024
	ds_read_b128 v[204:207], v177 offset:2048
	ds_read_b128 v[208:211], v177 offset:3072
	ds_read_b128 v[212:215], v177 offset:4096
	ds_read_b128 v[216:219], v177 offset:5120
	ds_read_b128 v[220:223], v177 offset:6144
	ds_read_b128 v[224:227], v177 offset:7168
	global_load_lds_dwordx4 v156, s[26:27]
	s_add_i32 m0, s44, 0xe000
	s_nop 0
	global_load_lds_dwordx4 v158, s[26:27]
	s_waitcnt vmcnt(8)
	s_waitcnt lgkmcnt(0)
	s_setprio 1
	s_barrier
	s_waitcnt lgkmcnt(0)
	v_mfma_i32_16x16x64_i8 v[144:147], v[116:119], v[182:185], v[144:147]
	v_mfma_i32_16x16x64_i8 v[144:147], v[124:127], v[186:189], v[144:147]
	v_mfma_i32_16x16x64_i8 v[112:115], v[124:127], v[208:211], v[112:115]
	v_mfma_i32_16x16x64_i8 v[112:115], v[116:119], v[204:207], v[112:115]
	v_mfma_i32_16x16x64_i8 v[96:99], v[116:119], v[212:215], v[96:99]
	v_mfma_i32_16x16x64_i8 v[96:99], v[124:127], v[216:219], v[96:99]
	v_mfma_i32_16x16x64_i8 v[80:83], v[124:127], v[224:227], v[80:83]
	v_mfma_i32_16x16x64_i8 v[80:83], v[116:119], v[220:223], v[80:83]
	v_mfma_i32_16x16x64_i8 v[76:79], v[132:135], v[220:223], v[76:79]
	v_mfma_i32_16x16x64_i8 v[76:79], v[136:139], v[224:227], v[76:79]
	v_mfma_i32_16x16x64_i8 v[92:95], v[136:139], v[216:219], v[92:95]
	v_mfma_i32_16x16x64_i8 v[92:95], v[132:135], v[212:215], v[92:95]
	v_mfma_i32_16x16x64_i8 v[108:111], v[132:135], v[204:207], v[108:111]
	v_mfma_i32_16x16x64_i8 v[108:111], v[136:139], v[208:211], v[108:111]
	v_mfma_i32_16x16x64_i8 v[140:143], v[136:139], v[186:189], v[140:143]
	v_mfma_i32_16x16x64_i8 v[140:143], v[132:135], v[182:185], v[140:143]
	v_mfma_i32_16x16x64_i8 v[128:131], v[160:163], v[182:185], v[128:131]
	v_mfma_i32_16x16x64_i8 v[128:131], v[164:167], v[186:189], v[128:131]
	v_mfma_i32_16x16x64_i8 v[104:107], v[164:167], v[208:211], v[104:107]
	v_mfma_i32_16x16x64_i8 v[104:107], v[160:163], v[204:207], v[104:107]
	v_mfma_i32_16x16x64_i8 v[88:91], v[160:163], v[212:215], v[88:91]
	v_mfma_i32_16x16x64_i8 v[88:91], v[164:167], v[216:219], v[88:91]
	v_mfma_i32_16x16x64_i8 v[72:75], v[164:167], v[224:227], v[72:75]
	v_mfma_i32_16x16x64_i8 v[72:75], v[160:163], v[220:223], v[72:75]
	v_mfma_i32_16x16x64_i8 v[68:71], v[168:171], v[220:223], v[68:71]
	v_mfma_i32_16x16x64_i8 v[68:71], v[178:181], v[224:227], v[68:71]
	v_mfma_i32_16x16x64_i8 v[84:87], v[178:181], v[216:219], v[84:87]
	v_mfma_i32_16x16x64_i8 v[84:87], v[168:171], v[212:215], v[84:87]
	v_mfma_i32_16x16x64_i8 v[100:103], v[168:171], v[204:207], v[100:103]
	v_mfma_i32_16x16x64_i8 v[100:103], v[178:181], v[208:211], v[100:103]
	v_mfma_i32_16x16x64_i8 v[120:123], v[178:181], v[186:189], v[120:123]
	v_mfma_i32_16x16x64_i8 v[120:123], v[168:171], v[182:185], v[120:123]
	s_barrier
; #define PG8_STAGE(bufoff, gbase, voff) do { _Pragma("unroll") for (int _i = 0; _i < 2; ++_i) \
;         __builtin_amdgcn_global_load_lds((const unsigned*)((const char*)(gbase) + (voff)[_i]), (PG8_LAS unsigned*)(lds + (bufoff) + ldsw + _i * 8192), 16, 0, 0); } while (0)
; #define PG8_LDA(dst, b, h) do { _Pragma("unroll") for (int m = 0; m < 4; ++m) _Pragma("unroll") for (int k = 0; k < 2; ++k) dst[m][k] = *(const PG8_LAS bf16x8*)(lds + PG8_SA(b, h) + aoff + m * 2048 + k * 1024); } while (0)
; #define PG8_LDB(dst, b, h) do { _Pragma("unroll") for (int n = 0; n < 2; ++n) _Pragma("unroll") for (int k = 0; k < 2; ++k) dst[n][k] = *(const PG8_LAS bf16x8*)(lds + PG8_SB(b, h) + boff + n * 2048 + k * 1024); } while (0)
; #define PG8_WAIT_V(n) asm volatile("s_waitcnt vmcnt(" #n ")" ::: "memory")
; #define PG8_WAIT_L(n) asm volatile("s_waitcnt lgkmcnt(" #n ")" ::: "memory")
; #define PG8_BAR __builtin_amdgcn_s_barrier()
; #define PG8_SCHED __builtin_amdgcn_sched_barrier(0)
; template <class Epi, class Sched, bool ALIGN_EPI = false, bool SP2 = false, bool I8 = false>
; __device__ __forceinline__ void gemm_phase(PG8_LAS unsigned char* lds, const Gemm g, const Sched& S, const Epi& E) {
;     ...
;             PG8_LDA(At, 0, 1); PG8_STAGE(PG8_SB(0, 0), b2, voffB); PG8_STAGE(PG8_SB(0, 1), b2 + hstep, voffB); PG8_STAGE(PG8_SA(0, 0), a2, voffA);
;             PG8_WAIT_V(8); PG8_WAIT_L(0); PG8_BAR; PG8_MMA(1, 0, At, B0); PG8_MMA(1, 1, At, B1); PG8_BAR; PG8_SCHED;
;             PG8_LDB(B0, 1, 0); PG8_LDB(B1, 1, 1); PG8_SCHED; PG8_LDA(At, 1, 0); PG8_STAGE(PG8_SA(0, 1), a2 + hstep, voffA);
;             PG8_WAIT_V(8); PG8_WAIT_L(0); PG8_BAR; PG8_MMA(0, 0, At, B0); PG8_MMA(0, 1, At, B1); PG8_BAR; PG8_SCHED;
	s_setprio 0
	s_add_i32 s50, s50, s43
	v_lshl_add_u64 v[172:173], s[36:37], 0, v[2:3]
	s_mov_b32 m0, s50
	ds_read_b128 v[182:185], v177 offset:16384
	ds_read_b128 v[186:189], v177 offset:17408
	ds_read_b128 v[204:207], v177 offset:18432
	ds_read_b128 v[208:211], v177 offset:19456
	ds_read_b128 v[212:215], v177 offset:20480
	ds_read_b128 v[216:219], v177 offset:21504
	ds_read_b128 v[220:223], v177 offset:22528
	ds_read_b128 v[224:227], v177 offset:23552
	global_load_lds_dwordx4 v[172:173], off
	s_add_i32 m0, s50, 0x2000
	s_add_u32 s50, s36, 0x80000
	v_lshl_add_u64 v[190:191], s[36:37], 0, v[148:149]
	s_addc_u32 s51, s37, 0
	s_add_i32 s56, s56, s43
	global_load_lds_dwordx4 v[190:191], off
	s_mov_b32 m0, s56
	v_lshl_add_u64 v[240:241], s[40:41], 0, v[150:151]
	global_load_lds_dwordx4 v2, s[50:51]
	s_add_i32 m0, s56, 0x2000
	s_nop 0
	global_load_lds_dwordx4 v148, s[50:51]
	v_lshl_add_u64 v[228:229], s[40:41], 0, v[152:153]
	s_waitcnt vmcnt(6)
	s_waitcnt lgkmcnt(0)
	s_setprio 1
	s_barrier
	s_waitcnt lgkmcnt(0)
	v_mfma_i32_16x16x64_i8 v[64:67], v[116:119], v[182:185], v[64:67]
	v_mfma_i32_16x16x64_i8 v[64:67], v[124:127], v[186:189], v[64:67]
	v_mfma_i32_16x16x64_i8 v[48:51], v[124:127], v[208:211], v[48:51]
	v_mfma_i32_16x16x64_i8 v[48:51], v[116:119], v[204:207], v[48:51]
	v_mfma_i32_16x16x64_i8 v[32:35], v[116:119], v[212:215], v[32:35]
	v_mfma_i32_16x16x64_i8 v[32:35], v[124:127], v[216:219], v[32:35]
	v_mfma_i32_16x16x64_i8 v[16:19], v[124:127], v[224:227], v[16:19]
	v_mfma_i32_16x16x64_i8 v[16:19], v[116:119], v[220:223], v[16:19]
	v_mfma_i32_16x16x64_i8 v[12:15], v[132:135], v[220:223], v[12:15]
	v_mfma_i32_16x16x64_i8 v[12:15], v[136:139], v[224:227], v[12:15]
	v_mfma_i32_16x16x64_i8 v[28:31], v[136:139], v[216:219], v[28:31]
	v_mfma_i32_16x16x64_i8 v[28:31], v[132:135], v[212:215], v[28:31]
	v_mfma_i32_16x16x64_i8 v[44:47], v[132:135], v[204:207], v[44:47]
	v_mfma_i32_16x16x64_i8 v[44:47], v[136:139], v[208:211], v[44:47]
	v_mfma_i32_16x16x64_i8 v[60:63], v[136:139], v[186:189], v[60:63]
	v_mfma_i32_16x16x64_i8 v[60:63], v[132:135], v[182:185], v[60:63]
	v_mfma_i32_16x16x64_i8 v[56:59], v[160:163], v[182:185], v[56:59]
	v_mfma_i32_16x16x64_i8 v[56:59], v[164:167], v[186:189], v[56:59]
	v_mfma_i32_16x16x64_i8 v[40:43], v[164:167], v[208:211], v[40:43]
	v_mfma_i32_16x16x64_i8 v[40:43], v[160:163], v[204:207], v[40:43]
	v_mfma_i32_16x16x64_i8 v[24:27], v[160:163], v[212:215], v[24:27]
	v_mfma_i32_16x16x64_i8 v[24:27], v[164:167], v[216:219], v[24:27]
	v_mfma_i32_16x16x64_i8 v[8:11], v[164:167], v[224:227], v[8:11]
	v_mfma_i32_16x16x64_i8 v[8:11], v[160:163], v[220:223], v[8:11]
	v_mfma_i32_16x16x64_i8 v[4:7], v[168:171], v[220:223], v[4:7]
	v_mfma_i32_16x16x64_i8 v[4:7], v[178:181], v[224:227], v[4:7]
	v_mfma_i32_16x16x64_i8 v[20:23], v[178:181], v[216:219], v[20:23]
	v_mfma_i32_16x16x64_i8 v[20:23], v[168:171], v[212:215], v[20:23]
	v_mfma_i32_16x16x64_i8 v[36:39], v[168:171], v[204:207], v[36:39]
	v_mfma_i32_16x16x64_i8 v[36:39], v[178:181], v[208:211], v[36:39]
	v_mfma_i32_16x16x64_i8 v[52:55], v[178:181], v[186:189], v[52:55]
	v_mfma_i32_16x16x64_i8 v[52:55], v[168:171], v[182:185], v[52:55]
	s_barrier
	s_setprio 0
	s_mov_b32 m0, s44
	s_nop 0
	global_load_lds_dwordx4 v[228:229], off
	s_mov_b32 m0, s45
	s_nop 0
	global_load_lds_dwordx4 v[240:241], off
	s_add_i32 s50, 0, 0x18000
	s_add_i32 s51, 0, 0x1c000
	v_add_u32_e32 v136, s50, v175
	v_add_u32_e32 v178, s51, v175
	ds_read_b128 v[116:119], v136
	ds_read_b128 v[124:127], v136 offset:1024
	ds_read_b128 v[132:135], v136 offset:2048
	ds_read_b128 v[136:139], v136 offset:3072
	ds_read_b128 v[160:163], v178
	ds_read_b128 v[164:167], v178 offset:1024
	ds_read_b128 v[168:171], v178 offset:2048
	ds_read_b128 v[178:181], v178 offset:3072
	s_add_u32 s40, s40, 0x80000
	s_addc_u32 s41, s41, 0
	s_mov_b32 m0, s46
	ds_read_b128 v[182:185], v177 offset:32768
	ds_read_b128 v[186:189], v177 offset:33792
	ds_read_b128 v[204:207], v177 offset:34816
	ds_read_b128 v[208:211], v177 offset:35840
	ds_read_b128 v[212:215], v177 offset:36864
	ds_read_b128 v[216:219], v177 offset:37888
	ds_read_b128 v[220:223], v177 offset:38912
	ds_read_b128 v[224:227], v177 offset:39936
	global_load_lds_dwordx4 v152, s[40:41]
	s_mov_b32 m0, s47
	s_nop 0
	global_load_lds_dwordx4 v150, s[40:41]
	s_waitcnt vmcnt(8)
	s_waitcnt lgkmcnt(0)
	s_setprio 1
	s_barrier
; #define PG8_STAGE(bufoff, gbase, voff) do { _Pragma("unroll") for (int _i = 0; _i < 2; ++_i) \
;         __builtin_amdgcn_global_load_lds((const unsigned*)((const char*)(gbase) + (voff)[_i]), (PG8_LAS unsigned*)(lds + (bufoff) + ldsw + _i * 8192), 16, 0, 0); } while (0)
; #define PG8_LDA(dst, b, h) do { _Pragma("unroll") for (int m = 0; m < 4; ++m) _Pragma("unroll") for (int k = 0; k < 2; ++k) dst[m][k] = *(const PG8_LAS bf16x8*)(lds + PG8_SA(b, h) + aoff + m * 2048 + k * 1024); } while (0)
; #define PG8_LDB(dst, b, h) do { _Pragma("unroll") for (int n = 0; n < 2; ++n) _Pragma("unroll") for (int k = 0; k < 2; ++k) dst[n][k] = *(const PG8_LAS bf16x8*)(lds + PG8_SB(b, h) + boff + n * 2048 + k * 1024); } while (0)
; #define PG8_WAIT_V(n) asm volatile("s_waitcnt vmcnt(" #n ")" ::: "memory")
; #define PG8_WAIT_L(n) asm volatile("s_waitcnt lgkmcnt(" #n ")" ::: "memory")
; #define PG8_BAR __builtin_amdgcn_s_barrier()
; #define PG8_SCHED __builtin_amdgcn_sched_barrier(0)
; template <class Epi, class Sched, bool ALIGN_EPI = false, bool SP2 = false, bool I8 = false>
; __device__ __forceinline__ void gemm_phase(PG8_LAS unsigned char* lds, const Gemm g, const Sched& S, const Epi& E) {
;     ...
;             PG8_LDB(B0, 0, 0); PG8_LDB(B1, 0, 1); PG8_SCHED; PG8_LDA(At, 0, 0); PG8_STAGE(PG8_SA(1, 1), a1 + hstep, voffA);
;             PG8_WAIT_V(8); PG8_WAIT_L(0); PG8_BAR; PG8_MMA(0, 0, At, B0); PG8_MMA(0, 1, At, B1); PG8_BAR; PG8_SCHED;
;             PG8_LDA(At, 0, 1); PG8_STAGE(PG8_SB(0, 0), b2, voffB); PG8_STAGE(PG8_SB(0, 1), b2 + hstep, voffB); PG8_STAGE(PG8_SA(0, 0), a2, voffA);
;             PG8_WAIT_V(8); PG8_WAIT_L(0); PG8_BAR; PG8_MMA(1, 0, At, B0); PG8_MMA(1, 1, At, B1); PG8_BAR; PG8_SCHED;
;             PG8_LDB(B0, 1, 0); PG8_LDB(B1, 1, 1); PG8_SCHED; PG8_LDA(At, 1, 0); PG8_STAGE(PG8_SA(0, 1), a2 + hstep, voffA);
;             PG8_WAIT_V(8); PG8_WAIT_L(0); PG8_BAR; PG8_MMA(0, 0, At, B0); PG8_MMA(0, 1, At, B1); PG8_BAR; PG8_SCHED;
;             PG8_LDA(At, 1, 1); PG8_STAGE(PG8_SB(1, 0), b3, voffB); PG8_STAGE(PG8_SB(1, 1), b3 + hstep, voffB); PG8_STAGE(PG8_SA(1, 0), a3, voffA);
;             PG8_WAIT_V(8); PG8_WAIT_L(0); PG8_BAR; PG8_MMA(1, 0, At, B0); PG8_MMA(1, 1, At, B1); PG8_BAR; PG8_SCHED;
	s_waitcnt lgkmcnt(0)
	v_mfma_i32_16x16x64_i8 v[144:147], v[116:119], v[182:185], v[144:147]
	v_mfma_i32_16x16x64_i8 v[144:147], v[124:127], v[186:189], v[144:147]
	v_mfma_i32_16x16x64_i8 v[112:115], v[124:127], v[208:211], v[112:115]
	v_mfma_i32_16x16x64_i8 v[112:115], v[116:119], v[204:207], v[112:115]
	v_mfma_i32_16x16x64_i8 v[96:99], v[116:119], v[212:215], v[96:99]
	v_mfma_i32_16x16x64_i8 v[96:99], v[124:127], v[216:219], v[96:99]
	v_mfma_i32_16x16x64_i8 v[80:83], v[124:127], v[224:227], v[80:83]
	v_mfma_i32_16x16x64_i8 v[80:83], v[116:119], v[220:223], v[80:83]
	v_mfma_i32_16x16x64_i8 v[76:79], v[132:135], v[220:223], v[76:79]
	v_mfma_i32_16x16x64_i8 v[76:79], v[136:139], v[224:227], v[76:79]
	v_mfma_i32_16x16x64_i8 v[92:95], v[136:139], v[216:219], v[92:95]
	v_mfma_i32_16x16x64_i8 v[92:95], v[132:135], v[212:215], v[92:95]
	v_mfma_i32_16x16x64_i8 v[108:111], v[132:135], v[204:207], v[108:111]
	v_mfma_i32_16x16x64_i8 v[108:111], v[136:139], v[208:211], v[108:111]
	v_mfma_i32_16x16x64_i8 v[140:143], v[136:139], v[186:189], v[140:143]
	v_mfma_i32_16x16x64_i8 v[140:143], v[132:135], v[182:185], v[140:143]
	v_mfma_i32_16x16x64_i8 v[128:131], v[160:163], v[182:185], v[128:131]
	v_mfma_i32_16x16x64_i8 v[128:131], v[164:167], v[186:189], v[128:131]
	v_mfma_i32_16x16x64_i8 v[104:107], v[164:167], v[208:211], v[104:107]
	v_mfma_i32_16x16x64_i8 v[104:107], v[160:163], v[204:207], v[104:107]
	v_mfma_i32_16x16x64_i8 v[88:91], v[160:163], v[212:215], v[88:91]
	v_mfma_i32_16x16x64_i8 v[88:91], v[164:167], v[216:219], v[88:91]
	v_mfma_i32_16x16x64_i8 v[72:75], v[164:167], v[224:227], v[72:75]
	v_mfma_i32_16x16x64_i8 v[72:75], v[160:163], v[220:223], v[72:75]
	v_mfma_i32_16x16x64_i8 v[68:71], v[168:171], v[220:223], v[68:71]
	v_mfma_i32_16x16x64_i8 v[68:71], v[178:181], v[224:227], v[68:71]
	v_mfma_i32_16x16x64_i8 v[84:87], v[178:181], v[216:219], v[84:87]
	v_mfma_i32_16x16x64_i8 v[84:87], v[168:171], v[212:215], v[84:87]
	v_mfma_i32_16x16x64_i8 v[100:103], v[168:171], v[204:207], v[100:103]
	v_mfma_i32_16x16x64_i8 v[100:103], v[178:181], v[208:211], v[100:103]
	v_mfma_i32_16x16x64_i8 v[120:123], v[178:181], v[186:189], v[120:123]
	v_mfma_i32_16x16x64_i8 v[120:123], v[168:171], v[182:185], v[120:123]
	s_barrier
	s_setprio 0
	s_add_i32 s40, s50, s43
	v_lshl_add_u64 v[172:173], v[172:173], 0, s[84:85]
	s_mov_b32 m0, s40
	ds_read_b128 v[182:185], v177 offset:49152
	ds_read_b128 v[186:189], v177 offset:50176
	ds_read_b128 v[204:207], v177 offset:51200
	ds_read_b128 v[208:211], v177 offset:52224
	ds_read_b128 v[212:215], v177 offset:53248
	ds_read_b128 v[216:219], v177 offset:54272
	ds_read_b128 v[220:223], v177 offset:55296
	ds_read_b128 v[224:227], v177 offset:56320
	global_load_lds_dwordx4 v[172:173], off
	s_add_i32 m0, s40, 0x2000
	s_add_u32 s36, s36, 0x80080
	v_lshl_add_u64 v[172:173], v[190:191], 0, s[84:85]
	s_addc_u32 s37, s37, 0
	s_add_i32 s40, s51, s43
	global_load_lds_dwordx4 v[172:173], off
	s_mov_b32 m0, s40
	s_nop 0
	global_load_lds_dwordx4 v2, s[36:37]
	s_add_i32 m0, s40, 0x2000
	s_nop 0
	global_load_lds_dwordx4 v148, s[36:37]
	s_cmp_eq_u32 s76, 28
	s_cbranch_scc0 .Ldefer_208_body
	v_lshl_add_u64 v[172:173], v[228:229], 0, s[84:85]
	s_mov_b32 m0, s52
	s_nop 0
	global_load_lds_dwordx4 v[172:173], off
	v_lshl_add_u64 v[172:173], v[240:241], 0, s[84:85]
	s_mov_b32 m0, s53
	s_nop 0
	global_load_lds_dwordx4 v[172:173], off
.Ldefer_208_body:
	s_waitcnt vmcnt(6)
	s_waitcnt lgkmcnt(0)
	s_setprio 1
	s_barrier
	s_waitcnt lgkmcnt(0)
	v_mfma_i32_16x16x64_i8 v[64:67], v[116:119], v[182:185], v[64:67]
	v_mfma_i32_16x16x64_i8 v[64:67], v[124:127], v[186:189], v[64:67]
	v_mfma_i32_16x16x64_i8 v[48:51], v[124:127], v[208:211], v[48:51]
	v_mfma_i32_16x16x64_i8 v[48:51], v[116:119], v[204:207], v[48:51]
	v_mfma_i32_16x16x64_i8 v[32:35], v[116:119], v[212:215], v[32:35]
	v_mfma_i32_16x16x64_i8 v[32:35], v[124:127], v[216:219], v[32:35]
	v_mfma_i32_16x16x64_i8 v[16:19], v[124:127], v[224:227], v[16:19]
	v_mfma_i32_16x16x64_i8 v[16:19], v[116:119], v[220:223], v[16:19]
	v_mfma_i32_16x16x64_i8 v[12:15], v[132:135], v[220:223], v[12:15]
	v_mfma_i32_16x16x64_i8 v[12:15], v[136:139], v[224:227], v[12:15]
	v_mfma_i32_16x16x64_i8 v[28:31], v[136:139], v[216:219], v[28:31]
	v_mfma_i32_16x16x64_i8 v[28:31], v[132:135], v[212:215], v[28:31]
	v_mfma_i32_16x16x64_i8 v[44:47], v[132:135], v[204:207], v[44:47]
	v_mfma_i32_16x16x64_i8 v[44:47], v[136:139], v[208:211], v[44:47]
	v_mfma_i32_16x16x64_i8 v[60:63], v[136:139], v[186:189], v[60:63]
	v_mfma_i32_16x16x64_i8 v[60:63], v[132:135], v[182:185], v[60:63]
	v_mfma_i32_16x16x64_i8 v[56:59], v[160:163], v[182:185], v[56:59]
	v_mfma_i32_16x16x64_i8 v[56:59], v[164:167], v[186:189], v[56:59]
	v_mfma_i32_16x16x64_i8 v[40:43], v[164:167], v[208:211], v[40:43]
	v_mfma_i32_16x16x64_i8 v[40:43], v[160:163], v[204:207], v[40:43]
	v_mfma_i32_16x16x64_i8 v[24:27], v[160:163], v[212:215], v[24:27]
	v_mfma_i32_16x16x64_i8 v[24:27], v[164:167], v[216:219], v[24:27]
	v_mfma_i32_16x16x64_i8 v[8:11], v[164:167], v[224:227], v[8:11]
	v_mfma_i32_16x16x64_i8 v[8:11], v[160:163], v[220:223], v[8:11]
	v_mfma_i32_16x16x64_i8 v[4:7], v[168:171], v[220:223], v[4:7]
	v_mfma_i32_16x16x64_i8 v[4:7], v[178:181], v[224:227], v[4:7]
	v_mfma_i32_16x16x64_i8 v[20:23], v[178:181], v[216:219], v[20:23]
	v_mfma_i32_16x16x64_i8 v[20:23], v[168:171], v[212:215], v[20:23]
	v_mfma_i32_16x16x64_i8 v[36:39], v[168:171], v[204:207], v[36:39]
	v_mfma_i32_16x16x64_i8 v[36:39], v[178:181], v[208:211], v[36:39]
	v_mfma_i32_16x16x64_i8 v[52:55], v[178:181], v[186:189], v[52:55]
	v_mfma_i32_16x16x64_i8 v[52:55], v[168:171], v[182:185], v[52:55]
	s_barrier
	s_setprio 0
	s_add_i32 s76, s76, 2
	s_add_u32 s26, s26, 0x100
	s_addc_u32 s27, s27, 0
	s_add_u32 s72, s72, 0x100
	s_addc_u32 s73, s73, 0
	s_cmp_gt_u32 s76, 29
	s_cbranch_scc0 .LBB0_208

; #define PG8_STAGE(bufoff, gbase, voff) do { _Pragma("unroll") for (int _i = 0; _i < 2; ++_i) \
;         __builtin_amdgcn_global_load_lds((const unsigned*)((const char*)(gbase) + (voff)[_i]), (PG8_LAS unsigned*)(lds + (bufoff) + ldsw + _i * 8192), 16, 0, 0); } while (0)
; #define PG8_LDA(dst, b, h) do { _Pragma("unroll") for (int m = 0; m < 4; ++m) _Pragma("unroll") for (int k = 0; k < 2; ++k) dst[m][k] = *(const PG8_LAS bf16x8*)(lds + PG8_SA(b, h) + aoff + m * 2048 + k * 1024); } while (0)
; #define PG8_LDB(dst, b, h) do { _Pragma("unroll") for (int n = 0; n < 2; ++n) _Pragma("unroll") for (int k = 0; k < 2; ++k) dst[n][k] = *(const PG8_LAS bf16x8*)(lds + PG8_SB(b, h) + boff + n * 2048 + k * 1024); } while (0)
; #define PG8_WAIT_V(n) asm volatile("s_waitcnt vmcnt(" #n ")" ::: "memory")
; #define PG8_WAIT_L(n) asm volatile("s_waitcnt lgkmcnt(" #n ")" ::: "memory")
; #define PG8_BAR __builtin_amdgcn_s_barrier()
; #define PG8_SCHED __builtin_amdgcn_sched_barrier(0)
; template <class Epi, class Sched, bool ALIGN_EPI = false, bool SP2 = false, bool I8 = false>
; __device__ __forceinline__ void gemm_phase(PG8_LAS unsigned char* lds, const Gemm g, const Sched& S, const Epi& E) {
;     ...
;         const bool has_next = S.next(ui + 1, nxt);
;         const char* nA = has_next ? (const char*)g.A + (size_t)nxt.pm * tstep : cA; const char* nB = has_next ? (const char*)g.Bt + (size_t)nxt.pn * tstep : cB;
;         for (int t = 0; t < nt; t += 2) {
;             const bool last = (t == nt - 2);
;             const char* a1 = cA + (size_t)(t + 1) * kstep;
;             const char* a2 = last ? nA : cA + (size_t)(t + 2) * kstep; const char* b2 = last ? nB : cB + (size_t)(t + 2) * kstep;
;             const char* a3 = a2 + kstep; const char* b3 = b2 + kstep;
;             if (last && has_next) S.a_ready(nxt);
;             if constexpr (SP2) {
;             PG8_LDB(B0, 0, 0); PG8_LDB(B1, 0, 1); PG8_SCHED; PG8_LDA(At, 0, 0); PG8_STAGE(PG8_SA(1, 1), a1 + hstep, voffA);
;             PG8_WAIT_V(8); PG8_WAIT_L(0); PG8_BAR; PG8_MMA(0, 0, At, B0); PG8_MMA(0, 1, At, B1); PG8_BAR; PG8_SCHED;
;             PG8_LDA(At, 0, 1); PG8_STAGE(PG8_SB(0, 0), b2, voffB); PG8_STAGE(PG8_SB(0, 1), b2 + hstep, voffB); PG8_STAGE(PG8_SA(0, 0), a2, voffA);
;             PG8_WAIT_V(8); PG8_WAIT_L(0); PG8_BAR; PG8_MMA(1, 0, At, B0); PG8_MMA(1, 1, At, B1); PG8_BAR; PG8_SCHED;
.LBB0_229:
	s_ashr_i32 s37, s36, 31
	s_lshl_b64 s[34:35], s[36:37], 21
	s_add_u32 s40, s42, s34
	s_addc_u32 s41, s43, s35
	s_and_b64 s[34:35], s[8:9], exec
	s_cselect_b32 s11, s41, s13
	s_cselect_b32 s34, s40, s12
	s_ashr_i32 s27, s26, 31
	s_lshl_b64 s[50:51], s[26:27], 21
	s_add_u32 s54, s44, s50
	s_addc_u32 s55, s45, s51
	s_and_b64 s[50:51], s[8:9], exec
	s_cselect_b32 s27, s55, s73
	s_cselect_b32 s35, s54, s72
	s_add_u32 s12, s12, 0x100080
	s_addc_u32 s13, s13, 0
	s_add_u32 s37, s72, 0x100
	s_addc_u32 s61, s73, 0
	s_mov_b32 s97, -2
	s_add_u32 s50, s12, 0xfff00080
	s_addc_u32 s51, s13, -1
	s_add_i32 s56, 0, 0x10000
	s_cmp_eq_u32 s97, 60
	s_cselect_b32 s77, s11, s51
	s_cselect_b32 s76, s34, s50
	s_cselect_b32 s73, s27, s61
	s_cselect_b32 s72, s35, s37
	s_add_i32 s57, 0, 0x14000
	v_add_u32_e32 v156, s56, v171
	v_add_u32_e32 v168, s57, v171
	s_waitcnt vmcnt(0)
	ds_read_b128 v[112:115], v156
	ds_read_b128 v[120:123], v156 offset:1024
	ds_read_b128 v[152:155], v156 offset:2048
	ds_read_b128 v[156:159], v156 offset:3072
	ds_read_b128 v[160:163], v168
	ds_read_b128 v[164:167], v168 offset:1024
	s_waitcnt lgkmcnt(0)
	ds_read_b128 v[176:179], v168 offset:2048
	ds_read_b128 v[180:183], v168 offset:3072
	s_add_i32 m0, s47, 0xc000
	ds_read_b128 v[184:187], v173
	ds_read_b128 v[188:191], v173 offset:1024
	ds_read_b128 v[204:207], v173 offset:2048
	ds_read_b128 v[208:211], v173 offset:3072
	ds_read_b128 v[212:215], v173 offset:4096
	ds_read_b128 v[216:219], v173 offset:5120
	ds_read_b128 v[220:223], v173 offset:6144
	ds_read_b128 v[224:227], v173 offset:7168
	global_load_lds_dwordx4 v148, s[12:13]
	s_add_i32 m0, s47, 0xe000
	s_nop 0
	global_load_lds_dwordx4 v150, s[12:13]
	s_waitcnt vmcnt(8)
	s_waitcnt lgkmcnt(0)
	s_setprio 1
	s_barrier
	s_waitcnt lgkmcnt(0)
	v_mfma_f32_16x16x32_bf16 v[136:139], v[112:115], v[184:187], 0
	v_mfma_f32_16x16x32_bf16 v[136:139], v[120:123], v[188:191], v[136:139]
	v_mfma_f32_16x16x32_bf16 v[116:119], v[120:123], v[208:211], 0
	v_mfma_f32_16x16x32_bf16 v[116:119], v[112:115], v[204:207], v[116:119]
	v_mfma_f32_16x16x32_bf16 v[96:99], v[112:115], v[212:215], 0
	v_mfma_f32_16x16x32_bf16 v[96:99], v[120:123], v[216:219], v[96:99]
	v_mfma_f32_16x16x32_bf16 v[80:83], v[120:123], v[224:227], 0
	v_mfma_f32_16x16x32_bf16 v[80:83], v[112:115], v[220:223], v[80:83]
	v_mfma_f32_16x16x32_bf16 v[76:79], v[152:155], v[220:223], 0
	v_mfma_f32_16x16x32_bf16 v[76:79], v[156:159], v[224:227], v[76:79]
	v_mfma_f32_16x16x32_bf16 v[92:95], v[156:159], v[216:219], 0
	v_mfma_f32_16x16x32_bf16 v[92:95], v[152:155], v[212:215], v[92:95]
	v_mfma_f32_16x16x32_bf16 v[108:111], v[152:155], v[204:207], 0
	v_mfma_f32_16x16x32_bf16 v[108:111], v[156:159], v[208:211], v[108:111]
	v_mfma_f32_16x16x32_bf16 v[132:135], v[156:159], v[188:191], 0
	v_mfma_f32_16x16x32_bf16 v[132:135], v[152:155], v[184:187], v[132:135]
	v_mfma_f32_16x16x32_bf16 v[128:131], v[160:163], v[184:187], 0
	v_mfma_f32_16x16x32_bf16 v[128:131], v[164:167], v[188:191], v[128:131]
	v_mfma_f32_16x16x32_bf16 v[104:107], v[164:167], v[208:211], 0
	v_mfma_f32_16x16x32_bf16 v[104:107], v[160:163], v[204:207], v[104:107]
	v_mfma_f32_16x16x32_bf16 v[88:91], v[160:163], v[212:215], 0
	v_mfma_f32_16x16x32_bf16 v[88:91], v[164:167], v[216:219], v[88:91]
	v_mfma_f32_16x16x32_bf16 v[72:75], v[164:167], v[224:227], 0
	v_mfma_f32_16x16x32_bf16 v[72:75], v[160:163], v[220:223], v[72:75]
	v_mfma_f32_16x16x32_bf16 v[68:71], v[176:179], v[220:223], 0
	v_mfma_f32_16x16x32_bf16 v[68:71], v[180:183], v[224:227], v[68:71]
	v_mfma_f32_16x16x32_bf16 v[84:87], v[180:183], v[216:219], 0
	v_mfma_f32_16x16x32_bf16 v[84:87], v[176:179], v[212:215], v[84:87]
	v_mfma_f32_16x16x32_bf16 v[100:103], v[176:179], v[204:207], 0
	v_mfma_f32_16x16x32_bf16 v[100:103], v[180:183], v[208:211], v[100:103]
	v_mfma_f32_16x16x32_bf16 v[124:127], v[180:183], v[188:191], 0
	v_mfma_f32_16x16x32_bf16 v[124:127], v[176:179], v[184:187], v[124:127]
	s_barrier
	s_setprio 0
	s_add_i32 s50, s56, s46
	v_lshl_add_u64 v[168:169], s[72:73], 0, v[2:3]
	s_mov_b32 m0, s50
	ds_read_b128 v[184:187], v173 offset:16384
	ds_read_b128 v[188:191], v173 offset:17408
	ds_read_b128 v[204:207], v173 offset:18432
	ds_read_b128 v[208:211], v173 offset:19456
	ds_read_b128 v[212:215], v173 offset:20480
	ds_read_b128 v[216:219], v173 offset:21504
	ds_read_b128 v[220:223], v173 offset:22528
	ds_read_b128 v[224:227], v173 offset:23552
	global_load_lds_dwordx4 v[168:169], off
	s_add_i32 m0, s50, 0x2000
	s_add_u32 s50, s72, 0x100000
	v_lshl_add_u64 v[228:229], s[72:73], 0, v[144:145]
	s_addc_u32 s51, s73, 0
	s_add_i32 s56, s57, s46
	global_load_lds_dwordx4 v[228:229], off
	s_mov_b32 m0, s56
	v_lshl_add_u64 v[242:243], s[76:77], 0, v[142:143]
	global_load_lds_dwordx4 v2, s[50:51]
	s_add_i32 m0, s56, 0x2000
	s_nop 0
	global_load_lds_dwordx4 v144, s[50:51]
	v_lshl_add_u64 v[240:241], s[76:77], 0, v[140:141]
	s_waitcnt vmcnt(6)
	s_waitcnt lgkmcnt(0)
	s_setprio 1
	s_barrier
; #define PG8_STAGE(bufoff, gbase, voff) do { _Pragma("unroll") for (int _i = 0; _i < 2; ++_i) \
;         __builtin_amdgcn_global_load_lds((const unsigned*)((const char*)(gbase) + (voff)[_i]), (PG8_LAS unsigned*)(lds + (bufoff) + ldsw + _i * 8192), 16, 0, 0); } while (0)
; #define PG8_LDA(dst, b, h) do { _Pragma("unroll") for (int m = 0; m < 4; ++m) _Pragma("unroll") for (int k = 0; k < 2; ++k) dst[m][k] = *(const PG8_LAS bf16x8*)(lds + PG8_SA(b, h) + aoff + m * 2048 + k * 1024); } while (0)
; #define PG8_LDB(dst, b, h) do { _Pragma("unroll") for (int n = 0; n < 2; ++n) _Pragma("unroll") for (int k = 0; k < 2; ++k) dst[n][k] = *(const PG8_LAS bf16x8*)(lds + PG8_SB(b, h) + boff + n * 2048 + k * 1024); } while (0)
; #define PG8_WAIT_V(n) asm volatile("s_waitcnt vmcnt(" #n ")" ::: "memory")
; #define PG8_WAIT_L(n) asm volatile("s_waitcnt lgkmcnt(" #n ")" ::: "memory")
; #define PG8_BAR __builtin_amdgcn_s_barrier()
; #define PG8_SCHED __builtin_amdgcn_sched_barrier(0)
; template <class Epi, class Sched, bool ALIGN_EPI = false, bool SP2 = false, bool I8 = false>
; __device__ __forceinline__ void gemm_phase(PG8_LAS unsigned char* lds, const Gemm g, const Sched& S, const Epi& E) {
;     ...
;             PG8_WAIT_V(8); PG8_WAIT_L(0); PG8_BAR; PG8_MMA(0, 0, At, B0); PG8_MMA(0, 1, At, B1); PG8_BAR; PG8_SCHED;
;             PG8_LDA(At, 0, 1); PG8_STAGE(PG8_SB(0, 0), b2, voffB); PG8_STAGE(PG8_SB(0, 1), b2 + hstep, voffB); PG8_STAGE(PG8_SA(0, 0), a2, voffA);
;             PG8_WAIT_V(8); PG8_WAIT_L(0); PG8_BAR; PG8_MMA(1, 0, At, B0); PG8_MMA(1, 1, At, B1); PG8_BAR; PG8_SCHED;
;             PG8_LDB(B0, 1, 0); PG8_LDB(B1, 1, 1); PG8_SCHED; PG8_LDA(At, 1, 0); PG8_STAGE(PG8_SA(0, 1), a2 + hstep, voffA);
;             PG8_WAIT_V(8); PG8_WAIT_L(0); PG8_BAR; PG8_MMA(0, 0, At, B0); PG8_MMA(0, 1, At, B1); PG8_BAR; PG8_SCHED;
;             PG8_LDA(At, 1, 1); PG8_STAGE(PG8_SB(1, 0), b3, voffB); PG8_STAGE(PG8_SB(1, 1), b3 + hstep, voffB); PG8_STAGE(PG8_SA(1, 0), a3, voffA);
;             PG8_WAIT_V(8); PG8_WAIT_L(0); PG8_BAR; PG8_MMA(1, 0, At, B0); PG8_MMA(1, 1, At, B1); PG8_BAR; PG8_SCHED;
	s_waitcnt lgkmcnt(0)
	v_mfma_f32_16x16x32_bf16 v[64:67], v[112:115], v[184:187], 0
	v_mfma_f32_16x16x32_bf16 v[64:67], v[120:123], v[188:191], v[64:67]
	v_mfma_f32_16x16x32_bf16 v[48:51], v[120:123], v[208:211], 0
	v_mfma_f32_16x16x32_bf16 v[48:51], v[112:115], v[204:207], v[48:51]
	v_mfma_f32_16x16x32_bf16 v[32:35], v[112:115], v[212:215], 0
	v_mfma_f32_16x16x32_bf16 v[32:35], v[120:123], v[216:219], v[32:35]
	v_mfma_f32_16x16x32_bf16 v[16:19], v[120:123], v[224:227], 0
	v_mfma_f32_16x16x32_bf16 v[16:19], v[112:115], v[220:223], v[16:19]
	v_mfma_f32_16x16x32_bf16 v[12:15], v[152:155], v[220:223], 0
	v_mfma_f32_16x16x32_bf16 v[12:15], v[156:159], v[224:227], v[12:15]
	v_mfma_f32_16x16x32_bf16 v[28:31], v[156:159], v[216:219], 0
	v_mfma_f32_16x16x32_bf16 v[28:31], v[152:155], v[212:215], v[28:31]
	v_mfma_f32_16x16x32_bf16 v[44:47], v[152:155], v[204:207], 0
	v_mfma_f32_16x16x32_bf16 v[44:47], v[156:159], v[208:211], v[44:47]
	v_mfma_f32_16x16x32_bf16 v[60:63], v[156:159], v[188:191], 0
	v_mfma_f32_16x16x32_bf16 v[60:63], v[152:155], v[184:187], v[60:63]
	v_mfma_f32_16x16x32_bf16 v[56:59], v[160:163], v[184:187], 0
	v_mfma_f32_16x16x32_bf16 v[56:59], v[164:167], v[188:191], v[56:59]
	v_mfma_f32_16x16x32_bf16 v[40:43], v[164:167], v[208:211], 0
	v_mfma_f32_16x16x32_bf16 v[40:43], v[160:163], v[204:207], v[40:43]
	v_mfma_f32_16x16x32_bf16 v[24:27], v[160:163], v[212:215], 0
	v_mfma_f32_16x16x32_bf16 v[24:27], v[164:167], v[216:219], v[24:27]
	v_mfma_f32_16x16x32_bf16 v[8:11], v[164:167], v[224:227], 0
	v_mfma_f32_16x16x32_bf16 v[8:11], v[160:163], v[220:223], v[8:11]
	v_mfma_f32_16x16x32_bf16 v[4:7], v[176:179], v[220:223], 0
	v_mfma_f32_16x16x32_bf16 v[4:7], v[180:183], v[224:227], v[4:7]
	v_mfma_f32_16x16x32_bf16 v[20:23], v[180:183], v[216:219], 0
	v_mfma_f32_16x16x32_bf16 v[20:23], v[176:179], v[212:215], v[20:23]
	v_mfma_f32_16x16x32_bf16 v[36:39], v[176:179], v[204:207], 0
	v_mfma_f32_16x16x32_bf16 v[36:39], v[180:183], v[208:211], v[36:39]
	v_mfma_f32_16x16x32_bf16 v[52:55], v[180:183], v[188:191], 0
	v_mfma_f32_16x16x32_bf16 v[52:55], v[176:179], v[184:187], v[52:55]
	s_barrier
	s_setprio 0
	s_mov_b32 m0, s47
	s_nop 0
	global_load_lds_dwordx4 v[240:241], off
	s_mov_b32 m0, s52
	s_nop 0
	global_load_lds_dwordx4 v[242:243], off
	s_add_i32 s56, 0, 0x18000
	s_add_i32 s57, 0, 0x1c000
	v_add_u32_e32 v156, s56, v171
	v_add_u32_e32 v175, s57, v171
	ds_read_b128 v[112:115], v156
	ds_read_b128 v[120:123], v156 offset:1024
	ds_read_b128 v[152:155], v156 offset:2048
	ds_read_b128 v[156:159], v156 offset:3072
	ds_read_b128 v[160:163], v175
	ds_read_b128 v[164:167], v175 offset:1024
	ds_read_b128 v[176:179], v175 offset:2048
	ds_read_b128 v[180:183], v175 offset:3072
	s_add_u32 s50, s76, 0x100000
	s_addc_u32 s51, s77, 0
	s_mov_b32 m0, s53
	ds_read_b128 v[184:187], v173 offset:32768
	ds_read_b128 v[188:191], v173 offset:33792
	ds_read_b128 v[204:207], v173 offset:34816
	ds_read_b128 v[208:211], v173 offset:35840
	ds_read_b128 v[212:215], v173 offset:36864
	ds_read_b128 v[216:219], v173 offset:37888
	ds_read_b128 v[220:223], v173 offset:38912
	ds_read_b128 v[224:227], v173 offset:39936
	global_load_lds_dwordx4 v140, s[50:51]
	s_mov_b32 m0, s64
	s_nop 0
	global_load_lds_dwordx4 v142, s[50:51]
	s_waitcnt vmcnt(8)
	s_waitcnt lgkmcnt(0)
	s_setprio 1
	s_barrier
	s_waitcnt lgkmcnt(0)
	v_mfma_f32_16x16x32_bf16 v[136:139], v[112:115], v[184:187], v[136:139]
	v_mfma_f32_16x16x32_bf16 v[136:139], v[120:123], v[188:191], v[136:139]
	v_mfma_f32_16x16x32_bf16 v[116:119], v[120:123], v[208:211], v[116:119]
	v_mfma_f32_16x16x32_bf16 v[116:119], v[112:115], v[204:207], v[116:119]
	v_mfma_f32_16x16x32_bf16 v[96:99], v[112:115], v[212:215], v[96:99]
	v_mfma_f32_16x16x32_bf16 v[96:99], v[120:123], v[216:219], v[96:99]
	v_mfma_f32_16x16x32_bf16 v[80:83], v[120:123], v[224:227], v[80:83]
	v_mfma_f32_16x16x32_bf16 v[80:83], v[112:115], v[220:223], v[80:83]
	v_mfma_f32_16x16x32_bf16 v[76:79], v[152:155], v[220:223], v[76:79]
	v_mfma_f32_16x16x32_bf16 v[76:79], v[156:159], v[224:227], v[76:79]
	v_mfma_f32_16x16x32_bf16 v[92:95], v[156:159], v[216:219], v[92:95]
	v_mfma_f32_16x16x32_bf16 v[92:95], v[152:155], v[212:215], v[92:95]
	v_mfma_f32_16x16x32_bf16 v[108:111], v[152:155], v[204:207], v[108:111]
	v_mfma_f32_16x16x32_bf16 v[108:111], v[156:159], v[208:211], v[108:111]
	v_mfma_f32_16x16x32_bf16 v[132:135], v[156:159], v[188:191], v[132:135]
	v_mfma_f32_16x16x32_bf16 v[132:135], v[152:155], v[184:187], v[132:135]
	v_mfma_f32_16x16x32_bf16 v[128:131], v[160:163], v[184:187], v[128:131]
	v_mfma_f32_16x16x32_bf16 v[128:131], v[164:167], v[188:191], v[128:131]
	v_mfma_f32_16x16x32_bf16 v[104:107], v[164:167], v[208:211], v[104:107]
	v_mfma_f32_16x16x32_bf16 v[104:107], v[160:163], v[204:207], v[104:107]
	v_mfma_f32_16x16x32_bf16 v[88:91], v[160:163], v[212:215], v[88:91]
	v_mfma_f32_16x16x32_bf16 v[88:91], v[164:167], v[216:219], v[88:91]
	v_mfma_f32_16x16x32_bf16 v[72:75], v[164:167], v[224:227], v[72:75]
	v_mfma_f32_16x16x32_bf16 v[72:75], v[160:163], v[220:223], v[72:75]
	v_mfma_f32_16x16x32_bf16 v[68:71], v[176:179], v[220:223], v[68:71]
	v_mfma_f32_16x16x32_bf16 v[68:71], v[180:183], v[224:227], v[68:71]
	v_mfma_f32_16x16x32_bf16 v[84:87], v[180:183], v[216:219], v[84:87]
	v_mfma_f32_16x16x32_bf16 v[84:87], v[176:179], v[212:215], v[84:87]
	v_mfma_f32_16x16x32_bf16 v[100:103], v[176:179], v[204:207], v[100:103]
	v_mfma_f32_16x16x32_bf16 v[100:103], v[180:183], v[208:211], v[100:103]
	v_mfma_f32_16x16x32_bf16 v[124:127], v[180:183], v[188:191], v[124:127]
	v_mfma_f32_16x16x32_bf16 v[124:127], v[176:179], v[184:187], v[124:127]
	s_barrier
	s_setprio 0
	s_add_i32 s50, s56, s46
	v_lshl_add_u64 v[168:169], v[168:169], 0, s[84:85]
	s_mov_b32 m0, s50
	ds_read_b128 v[184:187], v173 offset:49152
	ds_read_b128 v[188:191], v173 offset:50176
	ds_read_b128 v[204:207], v173 offset:51200
	ds_read_b128 v[208:211], v173 offset:52224
	ds_read_b128 v[212:215], v173 offset:53248
	ds_read_b128 v[216:219], v173 offset:54272
	ds_read_b128 v[220:223], v173 offset:55296
	ds_read_b128 v[224:227], v173 offset:56320
	global_load_lds_dwordx4 v[168:169], off
	s_add_i32 m0, s50, 0x2000
	s_add_u32 s50, s72, 0x100080
	v_lshl_add_u64 v[168:169], v[228:229], 0, s[84:85]
	s_addc_u32 s51, s73, 0
	s_add_i32 s56, s57, s46
	global_load_lds_dwordx4 v[168:169], off
	s_mov_b32 m0, s56
	s_nop 0
	global_load_lds_dwordx4 v2, s[50:51]
	s_add_i32 m0, s56, 0x2000
	s_nop 0
	global_load_lds_dwordx4 v144, s[50:51]
	s_cmp_eq_u32 s97, 60
	s_cbranch_scc0 .Ldefer_230_peel
	v_lshl_add_u64 v[168:169], v[240:241], 0, s[84:85]
	s_mov_b32 m0, s28
	s_nop 0
	global_load_lds_dwordx4 v[168:169], off
	v_lshl_add_u64 v[168:169], v[242:243], 0, s[84:85]
	s_mov_b32 m0, s65
	s_nop 0
	global_load_lds_dwordx4 v[168:169], off
; #define PG8_STAGE(bufoff, gbase, voff) do { _Pragma("unroll") for (int _i = 0; _i < 2; ++_i) \
;         __builtin_amdgcn_global_load_lds((const unsigned*)((const char*)(gbase) + (voff)[_i]), (PG8_LAS unsigned*)(lds + (bufoff) + ldsw + _i * 8192), 16, 0, 0); } while (0)
; #define PG8_LDA(dst, b, h) do { _Pragma("unroll") for (int m = 0; m < 4; ++m) _Pragma("unroll") for (int k = 0; k < 2; ++k) dst[m][k] = *(const PG8_LAS bf16x8*)(lds + PG8_SA(b, h) + aoff + m * 2048 + k * 1024); } while (0)
; #define PG8_LDB(dst, b, h) do { _Pragma("unroll") for (int n = 0; n < 2; ++n) _Pragma("unroll") for (int k = 0; k < 2; ++k) dst[n][k] = *(const PG8_LAS bf16x8*)(lds + PG8_SB(b, h) + boff + n * 2048 + k * 1024); } while (0)
; #define PG8_WAIT_V(n) asm volatile("s_waitcnt vmcnt(" #n ")" ::: "memory")
; #define PG8_WAIT_L(n) asm volatile("s_waitcnt lgkmcnt(" #n ")" ::: "memory")
; #define PG8_BAR __builtin_amdgcn_s_barrier()
; #define PG8_SCHED __builtin_amdgcn_sched_barrier(0)
; template <class Epi, class Sched, bool ALIGN_EPI = false, bool SP2 = false, bool I8 = false>
; __device__ __forceinline__ void gemm_phase(PG8_LAS unsigned char* lds, const Gemm g, const Sched& S, const Epi& E) {
;     ...
;         for (int t = 0; t < nt; t += 2) {
;             const bool last = (t == nt - 2);
;             const char* a1 = cA + (size_t)(t + 1) * kstep;
;             const char* a2 = last ? nA : cA + (size_t)(t + 2) * kstep; const char* b2 = last ? nB : cB + (size_t)(t + 2) * kstep;
;             const char* a3 = a2 + kstep; const char* b3 = b2 + kstep;
;             if (last && has_next) S.a_ready(nxt);
;             if constexpr (SP2) {
;             PG8_LDB(B0, 0, 0); PG8_LDB(B1, 0, 1); PG8_SCHED; PG8_LDA(At, 0, 0); PG8_STAGE(PG8_SA(1, 1), a1 + hstep, voffA);
;             PG8_WAIT_V(8); PG8_WAIT_L(0); PG8_BAR; PG8_MMA(0, 0, At, B0); PG8_MMA(0, 1, At, B1); PG8_BAR; PG8_SCHED;
;             PG8_LDA(At, 0, 1); PG8_STAGE(PG8_SB(0, 0), b2, voffB); PG8_STAGE(PG8_SB(0, 1), b2 + hstep, voffB); PG8_STAGE(PG8_SA(0, 0), a2, voffA);
;             PG8_WAIT_V(8); PG8_WAIT_L(0); PG8_BAR; PG8_MMA(1, 0, At, B0); PG8_MMA(1, 1, At, B1); PG8_BAR; PG8_SCHED;
.Ldefer_230_peel:
	s_waitcnt vmcnt(6)
	s_waitcnt lgkmcnt(0)
	s_setprio 1
	s_barrier
	s_waitcnt lgkmcnt(0)
	v_mfma_f32_16x16x32_bf16 v[64:67], v[112:115], v[184:187], v[64:67]
	v_mfma_f32_16x16x32_bf16 v[64:67], v[120:123], v[188:191], v[64:67]
	v_mfma_f32_16x16x32_bf16 v[48:51], v[120:123], v[208:211], v[48:51]
	v_mfma_f32_16x16x32_bf16 v[48:51], v[112:115], v[204:207], v[48:51]
	v_mfma_f32_16x16x32_bf16 v[32:35], v[112:115], v[212:215], v[32:35]
	v_mfma_f32_16x16x32_bf16 v[32:35], v[120:123], v[216:219], v[32:35]
	v_mfma_f32_16x16x32_bf16 v[16:19], v[120:123], v[224:227], v[16:19]
	v_mfma_f32_16x16x32_bf16 v[16:19], v[112:115], v[220:223], v[16:19]
	v_mfma_f32_16x16x32_bf16 v[12:15], v[152:155], v[220:223], v[12:15]
	v_mfma_f32_16x16x32_bf16 v[12:15], v[156:159], v[224:227], v[12:15]
	v_mfma_f32_16x16x32_bf16 v[28:31], v[156:159], v[216:219], v[28:31]
	v_mfma_f32_16x16x32_bf16 v[28:31], v[152:155], v[212:215], v[28:31]
	v_mfma_f32_16x16x32_bf16 v[44:47], v[152:155], v[204:207], v[44:47]
	v_mfma_f32_16x16x32_bf16 v[44:47], v[156:159], v[208:211], v[44:47]
	v_mfma_f32_16x16x32_bf16 v[60:63], v[156:159], v[188:191], v[60:63]
	v_mfma_f32_16x16x32_bf16 v[60:63], v[152:155], v[184:187], v[60:63]
	v_mfma_f32_16x16x32_bf16 v[56:59], v[160:163], v[184:187], v[56:59]
	v_mfma_f32_16x16x32_bf16 v[56:59], v[164:167], v[188:191], v[56:59]
	v_mfma_f32_16x16x32_bf16 v[40:43], v[164:167], v[208:211], v[40:43]
	v_mfma_f32_16x16x32_bf16 v[40:43], v[160:163], v[204:207], v[40:43]
	v_mfma_f32_16x16x32_bf16 v[24:27], v[160:163], v[212:215], v[24:27]
	v_mfma_f32_16x16x32_bf16 v[24:27], v[164:167], v[216:219], v[24:27]
	v_mfma_f32_16x16x32_bf16 v[8:11], v[164:167], v[224:227], v[8:11]
	v_mfma_f32_16x16x32_bf16 v[8:11], v[160:163], v[220:223], v[8:11]
	v_mfma_f32_16x16x32_bf16 v[4:7], v[176:179], v[220:223], v[4:7]
	v_mfma_f32_16x16x32_bf16 v[4:7], v[180:183], v[224:227], v[4:7]
	v_mfma_f32_16x16x32_bf16 v[20:23], v[180:183], v[216:219], v[20:23]
	v_mfma_f32_16x16x32_bf16 v[20:23], v[176:179], v[212:215], v[20:23]
	v_mfma_f32_16x16x32_bf16 v[36:39], v[176:179], v[204:207], v[36:39]
	v_mfma_f32_16x16x32_bf16 v[36:39], v[180:183], v[208:211], v[36:39]
	v_mfma_f32_16x16x32_bf16 v[52:55], v[180:183], v[188:191], v[52:55]
	v_mfma_f32_16x16x32_bf16 v[52:55], v[176:179], v[184:187], v[52:55]
	s_barrier
	s_setprio 0
	s_add_i32 s97, s97, 2
	s_add_u32 s12, s12, 0x100
	s_addc_u32 s13, s13, 0
	s_add_u32 s37, s37, 0x100
	s_addc_u32 s61, s61, 0
	s_cmp_gt_u32 s97, 61
	s_cbranch_scc1 .Lkloop_exit_1
.LBB0_230:
	s_add_u32 s50, s12, 0xfff00080
	s_addc_u32 s51, s13, -1
	s_add_i32 s56, 0, 0x10000
	s_cmp_eq_u32 s97, 60
	s_cselect_b32 s77, s11, s51
	s_cselect_b32 s76, s34, s50
	s_cselect_b32 s73, s27, s61
	s_cselect_b32 s72, s35, s37
	s_add_i32 s57, 0, 0x14000
	v_add_u32_e32 v156, s56, v171
	v_add_u32_e32 v168, s57, v171
	ds_read_b128 v[112:115], v156
	ds_read_b128 v[120:123], v156 offset:1024
	ds_read_b128 v[152:155], v156 offset:2048
	ds_read_b128 v[156:159], v156 offset:3072
	ds_read_b128 v[160:163], v168
	ds_read_b128 v[164:167], v168 offset:1024
	ds_read_b128 v[176:179], v168 offset:2048
	ds_read_b128 v[180:183], v168 offset:3072
	v_lshl_add_u64 v[168:169], v[240:241], 0, s[84:85]
	s_mov_b32 m0, s28
	s_nop 0
	global_load_lds_dwordx4 v[168:169], off
	v_lshl_add_u64 v[168:169], v[242:243], 0, s[84:85]
	s_mov_b32 m0, s65
	s_nop 0
	global_load_lds_dwordx4 v[168:169], off
	s_add_i32 m0, s47, 0xc000
	ds_read_b128 v[184:187], v173
	ds_read_b128 v[188:191], v173 offset:1024
	ds_read_b128 v[204:207], v173 offset:2048
	ds_read_b128 v[208:211], v173 offset:3072
	ds_read_b128 v[212:215], v173 offset:4096
	ds_read_b128 v[216:219], v173 offset:5120
	ds_read_b128 v[220:223], v173 offset:6144
	ds_read_b128 v[224:227], v173 offset:7168
	global_load_lds_dwordx4 v148, s[12:13]
	s_add_i32 m0, s47, 0xe000
	s_nop 0
	global_load_lds_dwordx4 v150, s[12:13]
	s_waitcnt vmcnt(8)
	s_waitcnt lgkmcnt(0)
	s_setprio 1
	s_barrier
	s_waitcnt lgkmcnt(0)
	v_mfma_f32_16x16x32_bf16 v[136:139], v[112:115], v[184:187], v[136:139]
	v_mfma_f32_16x16x32_bf16 v[136:139], v[120:123], v[188:191], v[136:139]
	v_mfma_f32_16x16x32_bf16 v[116:119], v[120:123], v[208:211], v[116:119]
	v_mfma_f32_16x16x32_bf16 v[116:119], v[112:115], v[204:207], v[116:119]
	v_mfma_f32_16x16x32_bf16 v[96:99], v[112:115], v[212:215], v[96:99]
	v_mfma_f32_16x16x32_bf16 v[96:99], v[120:123], v[216:219], v[96:99]
	v_mfma_f32_16x16x32_bf16 v[80:83], v[120:123], v[224:227], v[80:83]
	v_mfma_f32_16x16x32_bf16 v[80:83], v[112:115], v[220:223], v[80:83]
	v_mfma_f32_16x16x32_bf16 v[76:79], v[152:155], v[220:223], v[76:79]
	v_mfma_f32_16x16x32_bf16 v[76:79], v[156:159], v[224:227], v[76:79]
	v_mfma_f32_16x16x32_bf16 v[92:95], v[156:159], v[216:219], v[92:95]
	v_mfma_f32_16x16x32_bf16 v[92:95], v[152:155], v[212:215], v[92:95]
	v_mfma_f32_16x16x32_bf16 v[108:111], v[152:155], v[204:207], v[108:111]
	v_mfma_f32_16x16x32_bf16 v[108:111], v[156:159], v[208:211], v[108:111]
	v_mfma_f32_16x16x32_bf16 v[132:135], v[156:159], v[188:191], v[132:135]
	v_mfma_f32_16x16x32_bf16 v[132:135], v[152:155], v[184:187], v[132:135]
	v_mfma_f32_16x16x32_bf16 v[128:131], v[160:163], v[184:187], v[128:131]
	v_mfma_f32_16x16x32_bf16 v[128:131], v[164:167], v[188:191], v[128:131]
	v_mfma_f32_16x16x32_bf16 v[104:107], v[164:167], v[208:211], v[104:107]
	v_mfma_f32_16x16x32_bf16 v[104:107], v[160:163], v[204:207], v[104:107]
	v_mfma_f32_16x16x32_bf16 v[88:91], v[160:163], v[212:215], v[88:91]
	v_mfma_f32_16x16x32_bf16 v[88:91], v[164:167], v[216:219], v[88:91]
	v_mfma_f32_16x16x32_bf16 v[72:75], v[164:167], v[224:227], v[72:75]
	v_mfma_f32_16x16x32_bf16 v[72:75], v[160:163], v[220:223], v[72:75]
	v_mfma_f32_16x16x32_bf16 v[68:71], v[176:179], v[220:223], v[68:71]
	v_mfma_f32_16x16x32_bf16 v[68:71], v[180:183], v[224:227], v[68:71]
	v_mfma_f32_16x16x32_bf16 v[84:87], v[180:183], v[216:219], v[84:87]
	v_mfma_f32_16x16x32_bf16 v[84:87], v[176:179], v[212:215], v[84:87]
	v_mfma_f32_16x16x32_bf16 v[100:103], v[176:179], v[204:207], v[100:103]
	v_mfma_f32_16x16x32_bf16 v[100:103], v[180:183], v[208:211], v[100:103]
	v_mfma_f32_16x16x32_bf16 v[124:127], v[180:183], v[188:191], v[124:127]
	v_mfma_f32_16x16x32_bf16 v[124:127], v[176:179], v[184:187], v[124:127]
	s_barrier
; #define PG8_STAGE(bufoff, gbase, voff) do { _Pragma("unroll") for (int _i = 0; _i < 2; ++_i) \
;         __builtin_amdgcn_global_load_lds((const unsigned*)((const char*)(gbase) + (voff)[_i]), (PG8_LAS unsigned*)(lds + (bufoff) + ldsw + _i * 8192), 16, 0, 0); } while (0)
; #define PG8_LDA(dst, b, h) do { _Pragma("unroll") for (int m = 0; m < 4; ++m) _Pragma("unroll") for (int k = 0; k < 2; ++k) dst[m][k] = *(const PG8_LAS bf16x8*)(lds + PG8_SA(b, h) + aoff + m * 2048 + k * 1024); } while (0)
; #define PG8_LDB(dst, b, h) do { _Pragma("unroll") for (int n = 0; n < 2; ++n) _Pragma("unroll") for (int k = 0; k < 2; ++k) dst[n][k] = *(const PG8_LAS bf16x8*)(lds + PG8_SB(b, h) + boff + n * 2048 + k * 1024); } while (0)
; #define PG8_WAIT_V(n) asm volatile("s_waitcnt vmcnt(" #n ")" ::: "memory")
; #define PG8_WAIT_L(n) asm volatile("s_waitcnt lgkmcnt(" #n ")" ::: "memory")
; #define PG8_BAR __builtin_amdgcn_s_barrier()
; #define PG8_SCHED __builtin_amdgcn_sched_barrier(0)
; template <class Epi, class Sched, bool ALIGN_EPI = false, bool SP2 = false, bool I8 = false>
; __device__ __forceinline__ void gemm_phase(PG8_LAS unsigned char* lds, const Gemm g, const Sched& S, const Epi& E) {
;     ...
;             PG8_LDA(At, 0, 1); PG8_STAGE(PG8_SB(0, 0), b2, voffB); PG8_STAGE(PG8_SB(0, 1), b2 + hstep, voffB); PG8_STAGE(PG8_SA(0, 0), a2, voffA);
;             PG8_WAIT_V(8); PG8_WAIT_L(0); PG8_BAR; PG8_MMA(1, 0, At, B0); PG8_MMA(1, 1, At, B1); PG8_BAR; PG8_SCHED;
;             PG8_LDB(B0, 1, 0); PG8_LDB(B1, 1, 1); PG8_SCHED; PG8_LDA(At, 1, 0); PG8_STAGE(PG8_SA(0, 1), a2 + hstep, voffA);
;             PG8_WAIT_V(8); PG8_WAIT_L(0); PG8_BAR; PG8_MMA(0, 0, At, B0); PG8_MMA(0, 1, At, B1); PG8_BAR; PG8_SCHED;
	s_setprio 0
	s_add_i32 s50, s56, s46
	v_lshl_add_u64 v[168:169], s[72:73], 0, v[2:3]
	s_mov_b32 m0, s50
	ds_read_b128 v[184:187], v173 offset:16384
	ds_read_b128 v[188:191], v173 offset:17408
	ds_read_b128 v[204:207], v173 offset:18432
	ds_read_b128 v[208:211], v173 offset:19456
	ds_read_b128 v[212:215], v173 offset:20480
	ds_read_b128 v[216:219], v173 offset:21504
	ds_read_b128 v[220:223], v173 offset:22528
	ds_read_b128 v[224:227], v173 offset:23552
	global_load_lds_dwordx4 v[168:169], off
	s_add_i32 m0, s50, 0x2000
	s_add_u32 s50, s72, 0x100000
	v_lshl_add_u64 v[228:229], s[72:73], 0, v[144:145]
	s_addc_u32 s51, s73, 0
	s_add_i32 s56, s57, s46
	global_load_lds_dwordx4 v[228:229], off
	s_mov_b32 m0, s56
	v_lshl_add_u64 v[242:243], s[76:77], 0, v[142:143]
	global_load_lds_dwordx4 v2, s[50:51]
	s_add_i32 m0, s56, 0x2000
	s_nop 0
	global_load_lds_dwordx4 v144, s[50:51]
	v_lshl_add_u64 v[240:241], s[76:77], 0, v[140:141]
	s_waitcnt vmcnt(6)
	s_waitcnt lgkmcnt(0)
	s_setprio 1
	s_barrier
	s_waitcnt lgkmcnt(0)
	v_mfma_f32_16x16x32_bf16 v[64:67], v[112:115], v[184:187], v[64:67]
	v_mfma_f32_16x16x32_bf16 v[64:67], v[120:123], v[188:191], v[64:67]
	v_mfma_f32_16x16x32_bf16 v[48:51], v[120:123], v[208:211], v[48:51]
	v_mfma_f32_16x16x32_bf16 v[48:51], v[112:115], v[204:207], v[48:51]
	v_mfma_f32_16x16x32_bf16 v[32:35], v[112:115], v[212:215], v[32:35]
	v_mfma_f32_16x16x32_bf16 v[32:35], v[120:123], v[216:219], v[32:35]
	v_mfma_f32_16x16x32_bf16 v[16:19], v[120:123], v[224:227], v[16:19]
	v_mfma_f32_16x16x32_bf16 v[16:19], v[112:115], v[220:223], v[16:19]
	v_mfma_f32_16x16x32_bf16 v[12:15], v[152:155], v[220:223], v[12:15]
	v_mfma_f32_16x16x32_bf16 v[12:15], v[156:159], v[224:227], v[12:15]
	v_mfma_f32_16x16x32_bf16 v[28:31], v[156:159], v[216:219], v[28:31]
	v_mfma_f32_16x16x32_bf16 v[28:31], v[152:155], v[212:215], v[28:31]
	v_mfma_f32_16x16x32_bf16 v[44:47], v[152:155], v[204:207], v[44:47]
	v_mfma_f32_16x16x32_bf16 v[44:47], v[156:159], v[208:211], v[44:47]
	v_mfma_f32_16x16x32_bf16 v[60:63], v[156:159], v[188:191], v[60:63]
	v_mfma_f32_16x16x32_bf16 v[60:63], v[152:155], v[184:187], v[60:63]
	v_mfma_f32_16x16x32_bf16 v[56:59], v[160:163], v[184:187], v[56:59]
	v_mfma_f32_16x16x32_bf16 v[56:59], v[164:167], v[188:191], v[56:59]
	v_mfma_f32_16x16x32_bf16 v[40:43], v[164:167], v[208:211], v[40:43]
	v_mfma_f32_16x16x32_bf16 v[40:43], v[160:163], v[204:207], v[40:43]
	v_mfma_f32_16x16x32_bf16 v[24:27], v[160:163], v[212:215], v[24:27]
	v_mfma_f32_16x16x32_bf16 v[24:27], v[164:167], v[216:219], v[24:27]
	v_mfma_f32_16x16x32_bf16 v[8:11], v[164:167], v[224:227], v[8:11]
	v_mfma_f32_16x16x32_bf16 v[8:11], v[160:163], v[220:223], v[8:11]
	v_mfma_f32_16x16x32_bf16 v[4:7], v[176:179], v[220:223], v[4:7]
	v_mfma_f32_16x16x32_bf16 v[4:7], v[180:183], v[224:227], v[4:7]
	v_mfma_f32_16x16x32_bf16 v[20:23], v[180:183], v[216:219], v[20:23]
	v_mfma_f32_16x16x32_bf16 v[20:23], v[176:179], v[212:215], v[20:23]
	v_mfma_f32_16x16x32_bf16 v[36:39], v[176:179], v[204:207], v[36:39]
	v_mfma_f32_16x16x32_bf16 v[36:39], v[180:183], v[208:211], v[36:39]
	v_mfma_f32_16x16x32_bf16 v[52:55], v[180:183], v[188:191], v[52:55]
	v_mfma_f32_16x16x32_bf16 v[52:55], v[176:179], v[184:187], v[52:55]
	s_barrier
	s_setprio 0
	s_mov_b32 m0, s47
	s_nop 0
	global_load_lds_dwordx4 v[240:241], off
	s_mov_b32 m0, s52
	s_nop 0
	global_load_lds_dwordx4 v[242:243], off
	s_add_i32 s56, 0, 0x18000
	s_add_i32 s57, 0, 0x1c000
	v_add_u32_e32 v156, s56, v171
	v_add_u32_e32 v175, s57, v171
	ds_read_b128 v[112:115], v156
	ds_read_b128 v[120:123], v156 offset:1024
	ds_read_b128 v[152:155], v156 offset:2048
	ds_read_b128 v[156:159], v156 offset:3072
	ds_read_b128 v[160:163], v175
	ds_read_b128 v[164:167], v175 offset:1024
	ds_read_b128 v[176:179], v175 offset:2048
	ds_read_b128 v[180:183], v175 offset:3072
	s_add_u32 s50, s76, 0x100000
	s_addc_u32 s51, s77, 0
	s_mov_b32 m0, s53
	ds_read_b128 v[184:187], v173 offset:32768
	ds_read_b128 v[188:191], v173 offset:33792
	ds_read_b128 v[204:207], v173 offset:34816
	ds_read_b128 v[208:211], v173 offset:35840
	ds_read_b128 v[212:215], v173 offset:36864
	ds_read_b128 v[216:219], v173 offset:37888
	ds_read_b128 v[220:223], v173 offset:38912
	ds_read_b128 v[224:227], v173 offset:39936
	global_load_lds_dwordx4 v140, s[50:51]
	s_mov_b32 m0, s64
	s_nop 0
	global_load_lds_dwordx4 v142, s[50:51]
	s_waitcnt vmcnt(8)
	s_waitcnt lgkmcnt(0)
	s_setprio 1
	s_barrier
; #define PG8_STAGE(bufoff, gbase, voff) do { _Pragma("unroll") for (int _i = 0; _i < 2; ++_i) \
;         __builtin_amdgcn_global_load_lds((const unsigned*)((const char*)(gbase) + (voff)[_i]), (PG8_LAS unsigned*)(lds + (bufoff) + ldsw + _i * 8192), 16, 0, 0); } while (0)
; #define PG8_LDA(dst, b, h) do { _Pragma("unroll") for (int m = 0; m < 4; ++m) _Pragma("unroll") for (int k = 0; k < 2; ++k) dst[m][k] = *(const PG8_LAS bf16x8*)(lds + PG8_SA(b, h) + aoff + m * 2048 + k * 1024); } while (0)
; #define PG8_LDB(dst, b, h) do { _Pragma("unroll") for (int n = 0; n < 2; ++n) _Pragma("unroll") for (int k = 0; k < 2; ++k) dst[n][k] = *(const PG8_LAS bf16x8*)(lds + PG8_SB(b, h) + boff + n * 2048 + k * 1024); } while (0)
; #define PG8_WAIT_V(n) asm volatile("s_waitcnt vmcnt(" #n ")" ::: "memory")
; #define PG8_WAIT_L(n) asm volatile("s_waitcnt lgkmcnt(" #n ")" ::: "memory")
; #define PG8_BAR __builtin_amdgcn_s_barrier()
; #define PG8_SCHED __builtin_amdgcn_sched_barrier(0)
; template <class Epi, class Sched, bool ALIGN_EPI = false, bool SP2 = false, bool I8 = false>
; __device__ __forceinline__ void gemm_phase(PG8_LAS unsigned char* lds, const Gemm g, const Sched& S, const Epi& E) {
;     ...
;             PG8_LDB(B0, 0, 0); PG8_LDB(B1, 0, 1); PG8_SCHED; PG8_LDA(At, 0, 0); PG8_STAGE(PG8_SA(1, 1), a1 + hstep, voffA);
;             PG8_WAIT_V(8); PG8_WAIT_L(0); PG8_BAR; PG8_MMA(0, 0, At, B0); PG8_MMA(0, 1, At, B1); PG8_BAR; PG8_SCHED;
;             PG8_LDA(At, 0, 1); PG8_STAGE(PG8_SB(0, 0), b2, voffB); PG8_STAGE(PG8_SB(0, 1), b2 + hstep, voffB); PG8_STAGE(PG8_SA(0, 0), a2, voffA);
;             PG8_WAIT_V(8); PG8_WAIT_L(0); PG8_BAR; PG8_MMA(1, 0, At, B0); PG8_MMA(1, 1, At, B1); PG8_BAR; PG8_SCHED;
;             PG8_LDB(B0, 1, 0); PG8_LDB(B1, 1, 1); PG8_SCHED; PG8_LDA(At, 1, 0); PG8_STAGE(PG8_SA(0, 1), a2 + hstep, voffA);
;             PG8_WAIT_V(8); PG8_WAIT_L(0); PG8_BAR; PG8_MMA(0, 0, At, B0); PG8_MMA(0, 1, At, B1); PG8_BAR; PG8_SCHED;
;             PG8_LDA(At, 1, 1); PG8_STAGE(PG8_SB(1, 0), b3, voffB); PG8_STAGE(PG8_SB(1, 1), b3 + hstep, voffB); PG8_STAGE(PG8_SA(1, 0), a3, voffA);
;             PG8_WAIT_V(8); PG8_WAIT_L(0); PG8_BAR; PG8_MMA(1, 0, At, B0); PG8_MMA(1, 1, At, B1); PG8_BAR; PG8_SCHED;
	s_waitcnt lgkmcnt(0)
	v_mfma_f32_16x16x32_bf16 v[136:139], v[112:115], v[184:187], v[136:139]
	v_mfma_f32_16x16x32_bf16 v[136:139], v[120:123], v[188:191], v[136:139]
	v_mfma_f32_16x16x32_bf16 v[116:119], v[120:123], v[208:211], v[116:119]
	v_mfma_f32_16x16x32_bf16 v[116:119], v[112:115], v[204:207], v[116:119]
	v_mfma_f32_16x16x32_bf16 v[96:99], v[112:115], v[212:215], v[96:99]
	v_mfma_f32_16x16x32_bf16 v[96:99], v[120:123], v[216:219], v[96:99]
	v_mfma_f32_16x16x32_bf16 v[80:83], v[120:123], v[224:227], v[80:83]
	v_mfma_f32_16x16x32_bf16 v[80:83], v[112:115], v[220:223], v[80:83]
	v_mfma_f32_16x16x32_bf16 v[76:79], v[152:155], v[220:223], v[76:79]
	v_mfma_f32_16x16x32_bf16 v[76:79], v[156:159], v[224:227], v[76:79]
	v_mfma_f32_16x16x32_bf16 v[92:95], v[156:159], v[216:219], v[92:95]
	v_mfma_f32_16x16x32_bf16 v[92:95], v[152:155], v[212:215], v[92:95]
	v_mfma_f32_16x16x32_bf16 v[108:111], v[152:155], v[204:207], v[108:111]
	v_mfma_f32_16x16x32_bf16 v[108:111], v[156:159], v[208:211], v[108:111]
	v_mfma_f32_16x16x32_bf16 v[132:135], v[156:159], v[188:191], v[132:135]
	v_mfma_f32_16x16x32_bf16 v[132:135], v[152:155], v[184:187], v[132:135]
	v_mfma_f32_16x16x32_bf16 v[128:131], v[160:163], v[184:187], v[128:131]
	v_mfma_f32_16x16x32_bf16 v[128:131], v[164:167], v[188:191], v[128:131]
	v_mfma_f32_16x16x32_bf16 v[104:107], v[164:167], v[208:211], v[104:107]
	v_mfma_f32_16x16x32_bf16 v[104:107], v[160:163], v[204:207], v[104:107]
	v_mfma_f32_16x16x32_bf16 v[88:91], v[160:163], v[212:215], v[88:91]
	v_mfma_f32_16x16x32_bf16 v[88:91], v[164:167], v[216:219], v[88:91]
	v_mfma_f32_16x16x32_bf16 v[72:75], v[164:167], v[224:227], v[72:75]
	v_mfma_f32_16x16x32_bf16 v[72:75], v[160:163], v[220:223], v[72:75]
	v_mfma_f32_16x16x32_bf16 v[68:71], v[176:179], v[220:223], v[68:71]
	v_mfma_f32_16x16x32_bf16 v[68:71], v[180:183], v[224:227], v[68:71]
	v_mfma_f32_16x16x32_bf16 v[84:87], v[180:183], v[216:219], v[84:87]
	v_mfma_f32_16x16x32_bf16 v[84:87], v[176:179], v[212:215], v[84:87]
	v_mfma_f32_16x16x32_bf16 v[100:103], v[176:179], v[204:207], v[100:103]
	v_mfma_f32_16x16x32_bf16 v[100:103], v[180:183], v[208:211], v[100:103]
	v_mfma_f32_16x16x32_bf16 v[124:127], v[180:183], v[188:191], v[124:127]
	v_mfma_f32_16x16x32_bf16 v[124:127], v[176:179], v[184:187], v[124:127]
	s_barrier
	s_setprio 0
	s_add_i32 s50, s56, s46
	v_lshl_add_u64 v[168:169], v[168:169], 0, s[84:85]
	s_mov_b32 m0, s50
	ds_read_b128 v[184:187], v173 offset:49152
	ds_read_b128 v[188:191], v173 offset:50176
	ds_read_b128 v[204:207], v173 offset:51200
	ds_read_b128 v[208:211], v173 offset:52224
	ds_read_b128 v[212:215], v173 offset:53248
	ds_read_b128 v[216:219], v173 offset:54272
	ds_read_b128 v[220:223], v173 offset:55296
	ds_read_b128 v[224:227], v173 offset:56320
	global_load_lds_dwordx4 v[168:169], off
	s_add_i32 m0, s50, 0x2000
	s_add_u32 s50, s72, 0x100080
	v_lshl_add_u64 v[168:169], v[228:229], 0, s[84:85]
	s_addc_u32 s51, s73, 0
	s_add_i32 s56, s57, s46
	global_load_lds_dwordx4 v[168:169], off
	s_mov_b32 m0, s56
	s_nop 0
	global_load_lds_dwordx4 v2, s[50:51]
	s_add_i32 m0, s56, 0x2000
	s_nop 0
	global_load_lds_dwordx4 v144, s[50:51]
	s_cmp_eq_u32 s97, 60
	s_cbranch_scc0 .Ldefer_230_body
	v_lshl_add_u64 v[168:169], v[240:241], 0, s[84:85]
	s_mov_b32 m0, s28
	s_nop 0
	global_load_lds_dwordx4 v[168:169], off
	v_lshl_add_u64 v[168:169], v[242:243], 0, s[84:85]
	s_mov_b32 m0, s65
	s_nop 0
	global_load_lds_dwordx4 v[168:169], off
.Ldefer_230_body:
	s_waitcnt vmcnt(6)
	s_waitcnt lgkmcnt(0)
	s_setprio 1
	s_barrier
	s_waitcnt lgkmcnt(0)
	v_mfma_f32_16x16x32_bf16 v[64:67], v[112:115], v[184:187], v[64:67]
	v_mfma_f32_16x16x32_bf16 v[64:67], v[120:123], v[188:191], v[64:67]
	v_mfma_f32_16x16x32_bf16 v[48:51], v[120:123], v[208:211], v[48:51]
	v_mfma_f32_16x16x32_bf16 v[48:51], v[112:115], v[204:207], v[48:51]
	v_mfma_f32_16x16x32_bf16 v[32:35], v[112:115], v[212:215], v[32:35]
	v_mfma_f32_16x16x32_bf16 v[32:35], v[120:123], v[216:219], v[32:35]
	v_mfma_f32_16x16x32_bf16 v[16:19], v[120:123], v[224:227], v[16:19]
	v_mfma_f32_16x16x32_bf16 v[16:19], v[112:115], v[220:223], v[16:19]
	v_mfma_f32_16x16x32_bf16 v[12:15], v[152:155], v[220:223], v[12:15]
	v_mfma_f32_16x16x32_bf16 v[12:15], v[156:159], v[224:227], v[12:15]
	v_mfma_f32_16x16x32_bf16 v[28:31], v[156:159], v[216:219], v[28:31]
	v_mfma_f32_16x16x32_bf16 v[28:31], v[152:155], v[212:215], v[28:31]
	v_mfma_f32_16x16x32_bf16 v[44:47], v[152:155], v[204:207], v[44:47]
	v_mfma_f32_16x16x32_bf16 v[44:47], v[156:159], v[208:211], v[44:47]
	v_mfma_f32_16x16x32_bf16 v[60:63], v[156:159], v[188:191], v[60:63]
	v_mfma_f32_16x16x32_bf16 v[60:63], v[152:155], v[184:187], v[60:63]
	v_mfma_f32_16x16x32_bf16 v[56:59], v[160:163], v[184:187], v[56:59]
	v_mfma_f32_16x16x32_bf16 v[56:59], v[164:167], v[188:191], v[56:59]
	v_mfma_f32_16x16x32_bf16 v[40:43], v[164:167], v[208:211], v[40:43]
	v_mfma_f32_16x16x32_bf16 v[40:43], v[160:163], v[204:207], v[40:43]
	v_mfma_f32_16x16x32_bf16 v[24:27], v[160:163], v[212:215], v[24:27]
	v_mfma_f32_16x16x32_bf16 v[24:27], v[164:167], v[216:219], v[24:27]
	v_mfma_f32_16x16x32_bf16 v[8:11], v[164:167], v[224:227], v[8:11]
	v_mfma_f32_16x16x32_bf16 v[8:11], v[160:163], v[220:223], v[8:11]
	v_mfma_f32_16x16x32_bf16 v[4:7], v[176:179], v[220:223], v[4:7]
	v_mfma_f32_16x16x32_bf16 v[4:7], v[180:183], v[224:227], v[4:7]
	v_mfma_f32_16x16x32_bf16 v[20:23], v[180:183], v[216:219], v[20:23]
	v_mfma_f32_16x16x32_bf16 v[20:23], v[176:179], v[212:215], v[20:23]
	v_mfma_f32_16x16x32_bf16 v[36:39], v[176:179], v[204:207], v[36:39]
	v_mfma_f32_16x16x32_bf16 v[36:39], v[180:183], v[208:211], v[36:39]
	v_mfma_f32_16x16x32_bf16 v[52:55], v[180:183], v[188:191], v[52:55]
	v_mfma_f32_16x16x32_bf16 v[52:55], v[176:179], v[184:187], v[52:55]
	s_barrier
	s_setprio 0
	s_add_i32 s97, s97, 2
	s_add_u32 s12, s12, 0x100
	s_addc_u32 s13, s13, 0
	s_add_u32 s37, s37, 0x100
	s_addc_u32 s61, s61, 0
	s_cmp_gt_u32 s97, 61
	s_cbranch_scc0 .LBB0_230

; #define PG8_STAGE(bufoff, gbase, voff) do { _Pragma("unroll") for (int _i = 0; _i < 2; ++_i) \
;         __builtin_amdgcn_global_load_lds((const unsigned*)((const char*)(gbase) + (voff)[_i]), (PG8_LAS unsigned*)(lds + (bufoff) + ldsw + _i * 8192), 16, 0, 0); } while (0)
; #define PG8_LDA(dst, b, h) do { _Pragma("unroll") for (int m = 0; m < 4; ++m) _Pragma("unroll") for (int k = 0; k < 2; ++k) dst[m][k] = *(const PG8_LAS bf16x8*)(lds + PG8_SA(b, h) + aoff + m * 2048 + k * 1024); } while (0)
; #define PG8_LDB(dst, b, h) do { _Pragma("unroll") for (int n = 0; n < 2; ++n) _Pragma("unroll") for (int k = 0; k < 2; ++k) dst[n][k] = *(const PG8_LAS bf16x8*)(lds + PG8_SB(b, h) + boff + n * 2048 + k * 1024); } while (0)
; #define PG8_WAIT_V(n) asm volatile("s_waitcnt vmcnt(" #n ")" ::: "memory")
; #define PG8_WAIT_L(n) asm volatile("s_waitcnt lgkmcnt(" #n ")" ::: "memory")
; #define PG8_BAR __builtin_amdgcn_s_barrier()
; #define PG8_SCHED __builtin_amdgcn_sched_barrier(0)
; template <class Epi, class Sched, bool ALIGN_EPI = false, bool SP2 = false, bool I8 = false>
; __device__ __forceinline__ void gemm_phase(PG8_LAS unsigned char* lds, const Gemm g, const Sched& S, const Epi& E) {
;     ...
;         const bool has_next = S.next(ui + 1, nxt);
;         const char* nA = has_next ? (const char*)g.A + (size_t)nxt.pm * tstep : cA; const char* nB = has_next ? (const char*)g.Bt + (size_t)nxt.pn * tstep : cB;
;         for (int t = 0; t < nt; t += 2) {
;             const bool last = (t == nt - 2);
;             const char* a1 = cA + (size_t)(t + 1) * kstep;
;             const char* a2 = last ? nA : cA + (size_t)(t + 2) * kstep; const char* b2 = last ? nB : cB + (size_t)(t + 2) * kstep;
;             const char* a3 = a2 + kstep; const char* b3 = b2 + kstep;
;             if (last && has_next) S.a_ready(nxt);
;             if constexpr (SP2) {
;             PG8_LDB(B0, 0, 0); PG8_LDB(B1, 0, 1); PG8_SCHED; PG8_LDA(At, 0, 0); PG8_STAGE(PG8_SA(1, 1), a1 + hstep, voffA);
;             PG8_WAIT_V(8); PG8_WAIT_L(0); PG8_BAR; PG8_MMA(0, 0, At, B0); PG8_MMA(0, 1, At, B1); PG8_BAR; PG8_SCHED;
;             PG8_LDA(At, 0, 1); PG8_STAGE(PG8_SB(0, 0), b2, voffB); PG8_STAGE(PG8_SB(0, 1), b2 + hstep, voffB); PG8_STAGE(PG8_SA(0, 0), a2, voffA);
;             PG8_WAIT_V(8); PG8_WAIT_L(0); PG8_BAR; PG8_MMA(1, 0, At, B0); PG8_MMA(1, 1, At, B1); PG8_BAR; PG8_SCHED;
.LBB0_1455:
	s_ashr_i32 s17, s16, 31
	s_lshl_b64 s[20:21], s[16:17], 21
	s_add_u32 s20, s28, s20
	s_addc_u32 s21, s34, s21
	s_and_b64 s[22:23], s[8:9], exec
	s_cselect_b32 s17, s21, s25
	s_cselect_b32 s51, s20, s24
	s_ashr_i32 s19, s18, 31
	s_lshl_b64 s[22:23], s[18:19], 21
	s_add_u32 s22, s35, s22
	s_addc_u32 s23, s39, s23
	s_and_b64 s[36:37], s[8:9], exec
	s_cselect_b32 s19, s23, s27
	s_cselect_b32 s52, s22, s26
	s_add_u32 s24, s24, 0x100080
	s_addc_u32 s25, s25, 0
	s_add_u32 s53, s26, 0x100
	s_addc_u32 s54, s27, 0
	s_mov_b32 s55, -2
	s_waitcnt vmcnt(0)
	s_add_u32 s26, s24, 0xfff00080
	s_addc_u32 s27, s25, -1
	s_add_i32 s56, 0, 0x10000
	s_cmp_eq_u32 s55, 60
	s_cselect_b32 s37, s17, s27
	s_cselect_b32 s36, s51, s26
	s_cselect_b32 s27, s19, s54
	s_cselect_b32 s26, s52, s53
	s_add_i32 s58, 0, 0x14000
	v_add_u32_e32 v144, s56, v240
	v_add_u32_e32 v160, s58, v240
	ds_read_b128 v[124:127], v144
	ds_read_b128 v[128:131], v144 offset:1024
	ds_read_b128 v[132:135], v144 offset:2048
	ds_read_b128 v[144:147], v144 offset:3072
	ds_read_b128 v[148:151], v160
	ds_read_b128 v[152:155], v160 offset:1024
	ds_read_b128 v[156:159], v160 offset:2048
	ds_read_b128 v[160:163], v160 offset:3072
	s_add_i32 m0, s41, 0xc000
	ds_read_b128 v[164:167], v242
	ds_read_b128 v[168:171], v242 offset:1024
	ds_read_b128 v[172:175], v242 offset:2048
	ds_read_b128 v[176:179], v242 offset:3072
	ds_read_b128 v[180:183], v242 offset:4096
	ds_read_b128 v[184:187], v242 offset:5120
	ds_read_b128 v[188:191], v242 offset:6144
	ds_read_b128 v[214:217], v242 offset:7168
	global_load_lds_dwordx4 v210, s[24:25]
	s_add_i32 m0, s41, 0xe000
	s_nop 0
	global_load_lds_dwordx4 v212, s[24:25]
	s_waitcnt vmcnt(8)
	s_waitcnt lgkmcnt(0)
	s_setprio 1
	s_barrier
	s_waitcnt lgkmcnt(0)
	v_mfma_f32_16x16x32_bf16 v[140:143], v[124:127], v[164:167], 0
	v_mfma_f32_16x16x32_bf16 v[140:143], v[128:131], v[168:171], v[140:143]
	v_mfma_f32_16x16x32_bf16 v[112:115], v[128:131], v[176:179], 0
	v_mfma_f32_16x16x32_bf16 v[112:115], v[124:127], v[172:175], v[112:115]
	v_mfma_f32_16x16x32_bf16 v[96:99], v[124:127], v[180:183], 0
	v_mfma_f32_16x16x32_bf16 v[96:99], v[128:131], v[184:187], v[96:99]
	v_mfma_f32_16x16x32_bf16 v[80:83], v[128:131], v[214:217], 0
	v_mfma_f32_16x16x32_bf16 v[80:83], v[124:127], v[188:191], v[80:83]
	v_mfma_f32_16x16x32_bf16 v[76:79], v[132:135], v[188:191], 0
	v_mfma_f32_16x16x32_bf16 v[76:79], v[144:147], v[214:217], v[76:79]
	v_mfma_f32_16x16x32_bf16 v[92:95], v[144:147], v[184:187], 0
	v_mfma_f32_16x16x32_bf16 v[92:95], v[132:135], v[180:183], v[92:95]
	v_mfma_f32_16x16x32_bf16 v[108:111], v[132:135], v[172:175], 0
	v_mfma_f32_16x16x32_bf16 v[108:111], v[144:147], v[176:179], v[108:111]
	v_mfma_f32_16x16x32_bf16 v[136:139], v[144:147], v[168:171], 0
	v_mfma_f32_16x16x32_bf16 v[136:139], v[132:135], v[164:167], v[136:139]
	v_mfma_f32_16x16x32_bf16 v[120:123], v[148:151], v[164:167], 0
	v_mfma_f32_16x16x32_bf16 v[120:123], v[152:155], v[168:171], v[120:123]
	v_mfma_f32_16x16x32_bf16 v[104:107], v[152:155], v[176:179], 0
	v_mfma_f32_16x16x32_bf16 v[104:107], v[148:151], v[172:175], v[104:107]
	v_mfma_f32_16x16x32_bf16 v[88:91], v[148:151], v[180:183], 0
	v_mfma_f32_16x16x32_bf16 v[88:91], v[152:155], v[184:187], v[88:91]
	v_mfma_f32_16x16x32_bf16 v[72:75], v[152:155], v[214:217], 0
	v_mfma_f32_16x16x32_bf16 v[72:75], v[148:151], v[188:191], v[72:75]
	v_mfma_f32_16x16x32_bf16 v[68:71], v[156:159], v[188:191], 0
	v_mfma_f32_16x16x32_bf16 v[68:71], v[160:163], v[214:217], v[68:71]
	v_mfma_f32_16x16x32_bf16 v[84:87], v[160:163], v[184:187], 0
	v_mfma_f32_16x16x32_bf16 v[84:87], v[156:159], v[180:183], v[84:87]
	v_mfma_f32_16x16x32_bf16 v[100:103], v[156:159], v[172:175], 0
	v_mfma_f32_16x16x32_bf16 v[100:103], v[160:163], v[176:179], v[100:103]
	v_mfma_f32_16x16x32_bf16 v[116:119], v[160:163], v[168:171], 0
	v_mfma_f32_16x16x32_bf16 v[116:119], v[156:159], v[164:167], v[116:119]
	s_barrier
	s_setprio 0
	s_add_i32 s56, s56, s40
	v_lshl_add_u64 v[218:219], s[26:27], 0, v[2:3]
	s_mov_b32 m0, s56
	ds_read_b128 v[164:167], v242 offset:16384
	ds_read_b128 v[168:171], v242 offset:17408
	ds_read_b128 v[172:175], v242 offset:18432
	ds_read_b128 v[176:179], v242 offset:19456
	ds_read_b128 v[180:183], v242 offset:20480
	ds_read_b128 v[184:187], v242 offset:21504
	ds_read_b128 v[188:191], v242 offset:22528
	ds_read_b128 v[214:217], v242 offset:23552
	global_load_lds_dwordx4 v[218:219], off
	s_add_i32 m0, s56, 0x2000
	s_add_u32 s56, s26, 0x100000
	v_lshl_add_u64 v[220:221], s[26:27], 0, v[204:205]
	s_addc_u32 s57, s27, 0
	s_add_i32 s58, s58, s40
	global_load_lds_dwordx4 v[220:221], off
	s_mov_b32 m0, s58
	v_lshl_add_u64 v[224:225], s[36:37], 0, v[206:207]
	global_load_lds_dwordx4 v2, s[56:57]
	s_add_i32 m0, s58, 0x2000
	s_nop 0
	global_load_lds_dwordx4 v204, s[56:57]
	v_lshl_add_u64 v[222:223], s[36:37], 0, v[208:209]
	s_waitcnt vmcnt(6)
	s_waitcnt lgkmcnt(0)
	s_setprio 1
	s_barrier
; #define PG8_STAGE(bufoff, gbase, voff) do { _Pragma("unroll") for (int _i = 0; _i < 2; ++_i) \
;         __builtin_amdgcn_global_load_lds((const unsigned*)((const char*)(gbase) + (voff)[_i]), (PG8_LAS unsigned*)(lds + (bufoff) + ldsw + _i * 8192), 16, 0, 0); } while (0)
; #define PG8_LDA(dst, b, h) do { _Pragma("unroll") for (int m = 0; m < 4; ++m) _Pragma("unroll") for (int k = 0; k < 2; ++k) dst[m][k] = *(const PG8_LAS bf16x8*)(lds + PG8_SA(b, h) + aoff + m * 2048 + k * 1024); } while (0)
; #define PG8_LDB(dst, b, h) do { _Pragma("unroll") for (int n = 0; n < 2; ++n) _Pragma("unroll") for (int k = 0; k < 2; ++k) dst[n][k] = *(const PG8_LAS bf16x8*)(lds + PG8_SB(b, h) + boff + n * 2048 + k * 1024); } while (0)
; #define PG8_WAIT_V(n) asm volatile("s_waitcnt vmcnt(" #n ")" ::: "memory")
; #define PG8_WAIT_L(n) asm volatile("s_waitcnt lgkmcnt(" #n ")" ::: "memory")
; #define PG8_BAR __builtin_amdgcn_s_barrier()
; #define PG8_SCHED __builtin_amdgcn_sched_barrier(0)
; template <class Epi, class Sched, bool ALIGN_EPI = false, bool SP2 = false, bool I8 = false>
; __device__ __forceinline__ void gemm_phase(PG8_LAS unsigned char* lds, const Gemm g, const Sched& S, const Epi& E) {
;     ...
;             if constexpr (SP2) {
;             PG8_LDB(B0, 0, 0); PG8_LDB(B1, 0, 1); PG8_SCHED; PG8_LDA(At, 0, 0); PG8_STAGE(PG8_SA(1, 1), a1 + hstep, voffA);
;             PG8_WAIT_V(8); PG8_WAIT_L(0); PG8_BAR; PG8_MMA(0, 0, At, B0); PG8_MMA(0, 1, At, B1); PG8_BAR; PG8_SCHED;
;             PG8_LDA(At, 0, 1); PG8_STAGE(PG8_SB(0, 0), b2, voffB); PG8_STAGE(PG8_SB(0, 1), b2 + hstep, voffB); PG8_STAGE(PG8_SA(0, 0), a2, voffA);
;             PG8_WAIT_V(8); PG8_WAIT_L(0); PG8_BAR; PG8_MMA(1, 0, At, B0); PG8_MMA(1, 1, At, B1); PG8_BAR; PG8_SCHED;
;             PG8_LDB(B0, 1, 0); PG8_LDB(B1, 1, 1); PG8_SCHED; PG8_LDA(At, 1, 0); PG8_STAGE(PG8_SA(0, 1), a2 + hstep, voffA);
;             PG8_WAIT_V(8); PG8_WAIT_L(0); PG8_BAR; PG8_MMA(0, 0, At, B0); PG8_MMA(0, 1, At, B1); PG8_BAR; PG8_SCHED;
;             PG8_LDA(At, 1, 1); PG8_STAGE(PG8_SB(1, 0), b3, voffB); PG8_STAGE(PG8_SB(1, 1), b3 + hstep, voffB); PG8_STAGE(PG8_SA(1, 0), a3, voffA);
;             PG8_WAIT_V(8); PG8_WAIT_L(0); PG8_BAR; PG8_MMA(1, 0, At, B0); PG8_MMA(1, 1, At, B1); PG8_BAR; PG8_SCHED;
	s_waitcnt lgkmcnt(0)
	v_mfma_f32_16x16x32_bf16 v[64:67], v[124:127], v[164:167], 0
	v_mfma_f32_16x16x32_bf16 v[64:67], v[128:131], v[168:171], v[64:67]
	v_mfma_f32_16x16x32_bf16 v[48:51], v[128:131], v[176:179], 0
	v_mfma_f32_16x16x32_bf16 v[48:51], v[124:127], v[172:175], v[48:51]
	v_mfma_f32_16x16x32_bf16 v[32:35], v[124:127], v[180:183], 0
	v_mfma_f32_16x16x32_bf16 v[32:35], v[128:131], v[184:187], v[32:35]
	v_mfma_f32_16x16x32_bf16 v[16:19], v[128:131], v[214:217], 0
	v_mfma_f32_16x16x32_bf16 v[16:19], v[124:127], v[188:191], v[16:19]
	v_mfma_f32_16x16x32_bf16 v[12:15], v[132:135], v[188:191], 0
	v_mfma_f32_16x16x32_bf16 v[12:15], v[144:147], v[214:217], v[12:15]
	v_mfma_f32_16x16x32_bf16 v[28:31], v[144:147], v[184:187], 0
	v_mfma_f32_16x16x32_bf16 v[28:31], v[132:135], v[180:183], v[28:31]
	v_mfma_f32_16x16x32_bf16 v[44:47], v[132:135], v[172:175], 0
	v_mfma_f32_16x16x32_bf16 v[44:47], v[144:147], v[176:179], v[44:47]
	v_mfma_f32_16x16x32_bf16 v[60:63], v[144:147], v[168:171], 0
	v_mfma_f32_16x16x32_bf16 v[60:63], v[132:135], v[164:167], v[60:63]
	v_mfma_f32_16x16x32_bf16 v[56:59], v[148:151], v[164:167], 0
	v_mfma_f32_16x16x32_bf16 v[56:59], v[152:155], v[168:171], v[56:59]
	v_mfma_f32_16x16x32_bf16 v[40:43], v[152:155], v[176:179], 0
	v_mfma_f32_16x16x32_bf16 v[40:43], v[148:151], v[172:175], v[40:43]
	v_mfma_f32_16x16x32_bf16 v[24:27], v[148:151], v[180:183], 0
	v_mfma_f32_16x16x32_bf16 v[24:27], v[152:155], v[184:187], v[24:27]
	v_mfma_f32_16x16x32_bf16 v[8:11], v[152:155], v[214:217], 0
	v_mfma_f32_16x16x32_bf16 v[8:11], v[148:151], v[188:191], v[8:11]
	v_mfma_f32_16x16x32_bf16 v[4:7], v[156:159], v[188:191], 0
	v_mfma_f32_16x16x32_bf16 v[4:7], v[160:163], v[214:217], v[4:7]
	v_mfma_f32_16x16x32_bf16 v[20:23], v[160:163], v[184:187], 0
	v_mfma_f32_16x16x32_bf16 v[20:23], v[156:159], v[180:183], v[20:23]
	v_mfma_f32_16x16x32_bf16 v[36:39], v[156:159], v[172:175], 0
	v_mfma_f32_16x16x32_bf16 v[36:39], v[160:163], v[176:179], v[36:39]
	v_mfma_f32_16x16x32_bf16 v[52:55], v[160:163], v[168:171], 0
	v_mfma_f32_16x16x32_bf16 v[52:55], v[156:159], v[164:167], v[52:55]
	s_barrier
	s_setprio 0
	s_mov_b32 m0, s41
	s_nop 0
	global_load_lds_dwordx4 v[222:223], off
	s_mov_b32 m0, s42
	s_nop 0
	global_load_lds_dwordx4 v[224:225], off
	s_add_i32 s56, 0, 0x18000
	s_add_i32 s57, 0, 0x1c000
	v_add_u32_e32 v144, s56, v240
	v_add_u32_e32 v160, s57, v240
	ds_read_b128 v[124:127], v144
	ds_read_b128 v[128:131], v144 offset:1024
	ds_read_b128 v[132:135], v144 offset:2048
	ds_read_b128 v[144:147], v144 offset:3072
	ds_read_b128 v[148:151], v160
	ds_read_b128 v[152:155], v160 offset:1024
	ds_read_b128 v[156:159], v160 offset:2048
	ds_read_b128 v[160:163], v160 offset:3072
	s_add_u32 s36, s36, 0x100000
	s_addc_u32 s37, s37, 0
	s_mov_b32 m0, s43
	ds_read_b128 v[164:167], v242 offset:32768
	ds_read_b128 v[168:171], v242 offset:33792
	ds_read_b128 v[172:175], v242 offset:34816
	ds_read_b128 v[176:179], v242 offset:35840
	ds_read_b128 v[180:183], v242 offset:36864
	ds_read_b128 v[184:187], v242 offset:37888
	ds_read_b128 v[188:191], v242 offset:38912
	ds_read_b128 v[214:217], v242 offset:39936
	global_load_lds_dwordx4 v208, s[36:37]
	s_mov_b32 m0, s44
	s_nop 0
	global_load_lds_dwordx4 v206, s[36:37]
	s_waitcnt vmcnt(8)
	s_waitcnt lgkmcnt(0)
	s_setprio 1
	s_barrier
	s_waitcnt lgkmcnt(0)
	v_mfma_f32_16x16x32_bf16 v[140:143], v[124:127], v[164:167], v[140:143]
	v_mfma_f32_16x16x32_bf16 v[140:143], v[128:131], v[168:171], v[140:143]
	v_mfma_f32_16x16x32_bf16 v[112:115], v[128:131], v[176:179], v[112:115]
	v_mfma_f32_16x16x32_bf16 v[112:115], v[124:127], v[172:175], v[112:115]
	v_mfma_f32_16x16x32_bf16 v[96:99], v[124:127], v[180:183], v[96:99]
	v_mfma_f32_16x16x32_bf16 v[96:99], v[128:131], v[184:187], v[96:99]
	v_mfma_f32_16x16x32_bf16 v[80:83], v[128:131], v[214:217], v[80:83]
	v_mfma_f32_16x16x32_bf16 v[80:83], v[124:127], v[188:191], v[80:83]
	v_mfma_f32_16x16x32_bf16 v[76:79], v[132:135], v[188:191], v[76:79]
	v_mfma_f32_16x16x32_bf16 v[76:79], v[144:147], v[214:217], v[76:79]
	v_mfma_f32_16x16x32_bf16 v[92:95], v[144:147], v[184:187], v[92:95]
	v_mfma_f32_16x16x32_bf16 v[92:95], v[132:135], v[180:183], v[92:95]
	v_mfma_f32_16x16x32_bf16 v[108:111], v[132:135], v[172:175], v[108:111]
	v_mfma_f32_16x16x32_bf16 v[108:111], v[144:147], v[176:179], v[108:111]
	v_mfma_f32_16x16x32_bf16 v[136:139], v[144:147], v[168:171], v[136:139]
	v_mfma_f32_16x16x32_bf16 v[136:139], v[132:135], v[164:167], v[136:139]
	v_mfma_f32_16x16x32_bf16 v[120:123], v[148:151], v[164:167], v[120:123]
	v_mfma_f32_16x16x32_bf16 v[120:123], v[152:155], v[168:171], v[120:123]
	v_mfma_f32_16x16x32_bf16 v[104:107], v[152:155], v[176:179], v[104:107]
	v_mfma_f32_16x16x32_bf16 v[104:107], v[148:151], v[172:175], v[104:107]
	v_mfma_f32_16x16x32_bf16 v[88:91], v[148:151], v[180:183], v[88:91]
	v_mfma_f32_16x16x32_bf16 v[88:91], v[152:155], v[184:187], v[88:91]
	v_mfma_f32_16x16x32_bf16 v[72:75], v[152:155], v[214:217], v[72:75]
	v_mfma_f32_16x16x32_bf16 v[72:75], v[148:151], v[188:191], v[72:75]
	v_mfma_f32_16x16x32_bf16 v[68:71], v[156:159], v[188:191], v[68:71]
	v_mfma_f32_16x16x32_bf16 v[68:71], v[160:163], v[214:217], v[68:71]
	v_mfma_f32_16x16x32_bf16 v[84:87], v[160:163], v[184:187], v[84:87]
	v_mfma_f32_16x16x32_bf16 v[84:87], v[156:159], v[180:183], v[84:87]
	v_mfma_f32_16x16x32_bf16 v[100:103], v[156:159], v[172:175], v[100:103]
	v_mfma_f32_16x16x32_bf16 v[100:103], v[160:163], v[176:179], v[100:103]
	v_mfma_f32_16x16x32_bf16 v[116:119], v[160:163], v[168:171], v[116:119]
	v_mfma_f32_16x16x32_bf16 v[116:119], v[156:159], v[164:167], v[116:119]
	s_barrier
	s_setprio 0
	s_add_i32 s36, s56, s40
	v_lshl_add_u64 v[218:219], v[218:219], 0, s[84:85]
	s_mov_b32 m0, s36
	ds_read_b128 v[164:167], v242 offset:49152
	ds_read_b128 v[168:171], v242 offset:50176
	ds_read_b128 v[172:175], v242 offset:51200
	ds_read_b128 v[176:179], v242 offset:52224
	ds_read_b128 v[180:183], v242 offset:53248
	ds_read_b128 v[184:187], v242 offset:54272
	ds_read_b128 v[188:191], v242 offset:55296
	ds_read_b128 v[214:217], v242 offset:56320
	global_load_lds_dwordx4 v[218:219], off
	s_add_i32 m0, s36, 0x2000
	s_add_u32 s26, s26, 0x100080
	v_lshl_add_u64 v[218:219], v[220:221], 0, s[84:85]
	s_addc_u32 s27, s27, 0
	s_add_i32 s36, s57, s40
	global_load_lds_dwordx4 v[218:219], off
	s_mov_b32 m0, s36
	s_nop 0
	global_load_lds_dwordx4 v2, s[26:27]
	s_add_i32 m0, s36, 0x2000
	s_nop 0
	global_load_lds_dwordx4 v204, s[26:27]
	s_cmp_eq_u32 s55, 60
	s_cbranch_scc0 .Ldefer_1456_peel
	v_lshl_add_u64 v[218:219], v[222:223], 0, s[84:85]
	s_mov_b32 m0, s45
	s_nop 0
	global_load_lds_dwordx4 v[218:219], off
	v_lshl_add_u64 v[218:219], v[224:225], 0, s[84:85]
	s_mov_b32 m0, s46
	s_nop 0
	global_load_lds_dwordx4 v[218:219], off
; #define PG8_STAGE(bufoff, gbase, voff) do { _Pragma("unroll") for (int _i = 0; _i < 2; ++_i) \
;         __builtin_amdgcn_global_load_lds((const unsigned*)((const char*)(gbase) + (voff)[_i]), (PG8_LAS unsigned*)(lds + (bufoff) + ldsw + _i * 8192), 16, 0, 0); } while (0)
; #define PG8_LDA(dst, b, h) do { _Pragma("unroll") for (int m = 0; m < 4; ++m) _Pragma("unroll") for (int k = 0; k < 2; ++k) dst[m][k] = *(const PG8_LAS bf16x8*)(lds + PG8_SA(b, h) + aoff + m * 2048 + k * 1024); } while (0)
; #define PG8_WAIT_V(n) asm volatile("s_waitcnt vmcnt(" #n ")" ::: "memory")
; #define PG8_WAIT_L(n) asm volatile("s_waitcnt lgkmcnt(" #n ")" ::: "memory")
; #define PG8_BAR __builtin_amdgcn_s_barrier()
; template <class Epi, class Sched, bool ALIGN_EPI = false, bool SP2 = false, bool I8 = false>
; __device__ __forceinline__ void gemm_phase(PG8_LAS unsigned char* lds, const Gemm g, const Sched& S, const Epi& E) {
;     ...
;         for (int t = 0; t < nt; t += 2) {
;             const bool last = (t == nt - 2);
;             const char* a1 = cA + (size_t)(t + 1) * kstep;
;             const char* a2 = last ? nA : cA + (size_t)(t + 2) * kstep; const char* b2 = last ? nB : cB + (size_t)(t + 2) * kstep;
;             const char* a3 = a2 + kstep; const char* b3 = b2 + kstep;
;             if (last && has_next) S.a_ready(nxt);
;             if constexpr (SP2) {
;             PG8_LDB(B0, 0, 0); PG8_LDB(B1, 0, 1); PG8_SCHED; PG8_LDA(At, 0, 0); PG8_STAGE(PG8_SA(1, 1), a1 + hstep, voffA);
;             PG8_WAIT_V(8); PG8_WAIT_L(0); PG8_BAR; PG8_MMA(0, 0, At, B0); PG8_MMA(0, 1, At, B1); PG8_BAR; PG8_SCHED;
;             PG8_LDA(At, 0, 1); PG8_STAGE(PG8_SB(0, 0), b2, voffB); PG8_STAGE(PG8_SB(0, 1), b2 + hstep, voffB); PG8_STAGE(PG8_SA(0, 0), a2, voffA);
;             PG8_WAIT_V(8); PG8_WAIT_L(0); PG8_BAR; PG8_MMA(1, 0, At, B0); PG8_MMA(1, 1, At, B1); PG8_BAR; PG8_SCHED;
;             PG8_LDB(B0, 1, 0); PG8_LDB(B1, 1, 1); PG8_SCHED; PG8_LDA(At, 1, 0); PG8_STAGE(PG8_SA(0, 1), a2 + hstep, voffA);
;             PG8_WAIT_V(8); PG8_WAIT_L(0); PG8_BAR; PG8_MMA(0, 0, At, B0); PG8_MMA(0, 1, At, B1); PG8_BAR; PG8_SCHED;
;             PG8_LDA(At, 1, 1); PG8_STAGE(PG8_SB(1, 0), b3, voffB); PG8_STAGE(PG8_SB(1, 1), b3 + hstep, voffB); PG8_STAGE(PG8_SA(1, 0), a3, voffA);
;             PG8_WAIT_V(8); PG8_WAIT_L(0); PG8_BAR; PG8_MMA(1, 0, At, B0); PG8_MMA(1, 1, At, B1); PG8_BAR; PG8_SCHED;
.Ldefer_1456_peel:
	s_waitcnt vmcnt(6)
	s_waitcnt lgkmcnt(0)
	s_setprio 1
	s_barrier
	s_waitcnt lgkmcnt(0)
	v_mfma_f32_16x16x32_bf16 v[64:67], v[124:127], v[164:167], v[64:67]
	v_mfma_f32_16x16x32_bf16 v[64:67], v[128:131], v[168:171], v[64:67]
	v_mfma_f32_16x16x32_bf16 v[48:51], v[128:131], v[176:179], v[48:51]
	v_mfma_f32_16x16x32_bf16 v[48:51], v[124:127], v[172:175], v[48:51]
	v_mfma_f32_16x16x32_bf16 v[32:35], v[124:127], v[180:183], v[32:35]
	v_mfma_f32_16x16x32_bf16 v[32:35], v[128:131], v[184:187], v[32:35]
	v_mfma_f32_16x16x32_bf16 v[16:19], v[128:131], v[214:217], v[16:19]
	v_mfma_f32_16x16x32_bf16 v[16:19], v[124:127], v[188:191], v[16:19]
	v_mfma_f32_16x16x32_bf16 v[12:15], v[132:135], v[188:191], v[12:15]
	v_mfma_f32_16x16x32_bf16 v[12:15], v[144:147], v[214:217], v[12:15]
	v_mfma_f32_16x16x32_bf16 v[28:31], v[144:147], v[184:187], v[28:31]
	v_mfma_f32_16x16x32_bf16 v[28:31], v[132:135], v[180:183], v[28:31]
	v_mfma_f32_16x16x32_bf16 v[44:47], v[132:135], v[172:175], v[44:47]
	v_mfma_f32_16x16x32_bf16 v[44:47], v[144:147], v[176:179], v[44:47]
	v_mfma_f32_16x16x32_bf16 v[60:63], v[144:147], v[168:171], v[60:63]
	v_mfma_f32_16x16x32_bf16 v[60:63], v[132:135], v[164:167], v[60:63]
	v_mfma_f32_16x16x32_bf16 v[56:59], v[148:151], v[164:167], v[56:59]
	v_mfma_f32_16x16x32_bf16 v[56:59], v[152:155], v[168:171], v[56:59]
	v_mfma_f32_16x16x32_bf16 v[40:43], v[152:155], v[176:179], v[40:43]
	v_mfma_f32_16x16x32_bf16 v[40:43], v[148:151], v[172:175], v[40:43]
	v_mfma_f32_16x16x32_bf16 v[24:27], v[148:151], v[180:183], v[24:27]
	v_mfma_f32_16x16x32_bf16 v[24:27], v[152:155], v[184:187], v[24:27]
	v_mfma_f32_16x16x32_bf16 v[8:11], v[152:155], v[214:217], v[8:11]
	v_mfma_f32_16x16x32_bf16 v[8:11], v[148:151], v[188:191], v[8:11]
	v_mfma_f32_16x16x32_bf16 v[4:7], v[156:159], v[188:191], v[4:7]
	v_mfma_f32_16x16x32_bf16 v[4:7], v[160:163], v[214:217], v[4:7]
	v_mfma_f32_16x16x32_bf16 v[20:23], v[160:163], v[184:187], v[20:23]
	v_mfma_f32_16x16x32_bf16 v[20:23], v[156:159], v[180:183], v[20:23]
	v_mfma_f32_16x16x32_bf16 v[36:39], v[156:159], v[172:175], v[36:39]
	v_mfma_f32_16x16x32_bf16 v[36:39], v[160:163], v[176:179], v[36:39]
	v_mfma_f32_16x16x32_bf16 v[52:55], v[160:163], v[168:171], v[52:55]
	v_mfma_f32_16x16x32_bf16 v[52:55], v[156:159], v[164:167], v[52:55]
	s_barrier
	s_setprio 0
	s_add_i32 s55, s55, 2
	s_add_u32 s24, s24, 0x100
	s_addc_u32 s25, s25, 0
	s_add_u32 s53, s53, 0x100
	s_addc_u32 s54, s54, 0
	s_cmp_gt_u32 s55, 61
	s_cbranch_scc1 .Lkloop_exit_2
.LBB0_1456:
	s_add_u32 s26, s24, 0xfff00080
	s_addc_u32 s27, s25, -1
	s_add_i32 s56, 0, 0x10000
	s_cmp_eq_u32 s55, 60
	s_cselect_b32 s37, s17, s27
	s_cselect_b32 s36, s51, s26
	s_cselect_b32 s27, s19, s54
	s_cselect_b32 s26, s52, s53
	s_add_i32 s58, 0, 0x14000
	v_add_u32_e32 v144, s56, v240
	v_add_u32_e32 v160, s58, v240
	ds_read_b128 v[124:127], v144
	ds_read_b128 v[128:131], v144 offset:1024
	ds_read_b128 v[132:135], v144 offset:2048
	ds_read_b128 v[144:147], v144 offset:3072
	ds_read_b128 v[148:151], v160
	ds_read_b128 v[152:155], v160 offset:1024
	ds_read_b128 v[156:159], v160 offset:2048
	ds_read_b128 v[160:163], v160 offset:3072
	v_lshl_add_u64 v[218:219], v[222:223], 0, s[84:85]
	s_mov_b32 m0, s45
	s_nop 0
	global_load_lds_dwordx4 v[218:219], off
	v_lshl_add_u64 v[218:219], v[224:225], 0, s[84:85]
	s_mov_b32 m0, s46
	s_nop 0
	global_load_lds_dwordx4 v[218:219], off
	s_add_i32 m0, s41, 0xc000
	ds_read_b128 v[164:167], v242
	ds_read_b128 v[168:171], v242 offset:1024
	ds_read_b128 v[172:175], v242 offset:2048
	ds_read_b128 v[176:179], v242 offset:3072
	ds_read_b128 v[180:183], v242 offset:4096
	ds_read_b128 v[184:187], v242 offset:5120
	ds_read_b128 v[188:191], v242 offset:6144
	ds_read_b128 v[214:217], v242 offset:7168
	global_load_lds_dwordx4 v210, s[24:25]
	s_add_i32 m0, s41, 0xe000
	s_nop 0
	global_load_lds_dwordx4 v212, s[24:25]
	s_waitcnt vmcnt(8)
	s_waitcnt lgkmcnt(0)
	s_setprio 1
	s_barrier
	s_waitcnt lgkmcnt(0)
	v_mfma_f32_16x16x32_bf16 v[140:143], v[124:127], v[164:167], v[140:143]
	v_mfma_f32_16x16x32_bf16 v[140:143], v[128:131], v[168:171], v[140:143]
	v_mfma_f32_16x16x32_bf16 v[112:115], v[128:131], v[176:179], v[112:115]
	v_mfma_f32_16x16x32_bf16 v[112:115], v[124:127], v[172:175], v[112:115]
	v_mfma_f32_16x16x32_bf16 v[96:99], v[124:127], v[180:183], v[96:99]
	v_mfma_f32_16x16x32_bf16 v[96:99], v[128:131], v[184:187], v[96:99]
	v_mfma_f32_16x16x32_bf16 v[80:83], v[128:131], v[214:217], v[80:83]
	v_mfma_f32_16x16x32_bf16 v[80:83], v[124:127], v[188:191], v[80:83]
	v_mfma_f32_16x16x32_bf16 v[76:79], v[132:135], v[188:191], v[76:79]
	v_mfma_f32_16x16x32_bf16 v[76:79], v[144:147], v[214:217], v[76:79]
	v_mfma_f32_16x16x32_bf16 v[92:95], v[144:147], v[184:187], v[92:95]
	v_mfma_f32_16x16x32_bf16 v[92:95], v[132:135], v[180:183], v[92:95]
	v_mfma_f32_16x16x32_bf16 v[108:111], v[132:135], v[172:175], v[108:111]
	v_mfma_f32_16x16x32_bf16 v[108:111], v[144:147], v[176:179], v[108:111]
	v_mfma_f32_16x16x32_bf16 v[136:139], v[144:147], v[168:171], v[136:139]
	v_mfma_f32_16x16x32_bf16 v[136:139], v[132:135], v[164:167], v[136:139]
	v_mfma_f32_16x16x32_bf16 v[120:123], v[148:151], v[164:167], v[120:123]
	v_mfma_f32_16x16x32_bf16 v[120:123], v[152:155], v[168:171], v[120:123]
	v_mfma_f32_16x16x32_bf16 v[104:107], v[152:155], v[176:179], v[104:107]
	v_mfma_f32_16x16x32_bf16 v[104:107], v[148:151], v[172:175], v[104:107]
	v_mfma_f32_16x16x32_bf16 v[88:91], v[148:151], v[180:183], v[88:91]
	v_mfma_f32_16x16x32_bf16 v[88:91], v[152:155], v[184:187], v[88:91]
	v_mfma_f32_16x16x32_bf16 v[72:75], v[152:155], v[214:217], v[72:75]
	v_mfma_f32_16x16x32_bf16 v[72:75], v[148:151], v[188:191], v[72:75]
	v_mfma_f32_16x16x32_bf16 v[68:71], v[156:159], v[188:191], v[68:71]
	v_mfma_f32_16x16x32_bf16 v[68:71], v[160:163], v[214:217], v[68:71]
	v_mfma_f32_16x16x32_bf16 v[84:87], v[160:163], v[184:187], v[84:87]
	v_mfma_f32_16x16x32_bf16 v[84:87], v[156:159], v[180:183], v[84:87]
	v_mfma_f32_16x16x32_bf16 v[100:103], v[156:159], v[172:175], v[100:103]
	v_mfma_f32_16x16x32_bf16 v[100:103], v[160:163], v[176:179], v[100:103]
	v_mfma_f32_16x16x32_bf16 v[116:119], v[160:163], v[168:171], v[116:119]
	v_mfma_f32_16x16x32_bf16 v[116:119], v[156:159], v[164:167], v[116:119]
	s_barrier
; #define PG8_STAGE(bufoff, gbase, voff) do { _Pragma("unroll") for (int _i = 0; _i < 2; ++_i) \
;         __builtin_amdgcn_global_load_lds((const unsigned*)((const char*)(gbase) + (voff)[_i]), (PG8_LAS unsigned*)(lds + (bufoff) + ldsw + _i * 8192), 16, 0, 0); } while (0)
; #define PG8_LDA(dst, b, h) do { _Pragma("unroll") for (int m = 0; m < 4; ++m) _Pragma("unroll") for (int k = 0; k < 2; ++k) dst[m][k] = *(const PG8_LAS bf16x8*)(lds + PG8_SA(b, h) + aoff + m * 2048 + k * 1024); } while (0)
; #define PG8_LDB(dst, b, h) do { _Pragma("unroll") for (int n = 0; n < 2; ++n) _Pragma("unroll") for (int k = 0; k < 2; ++k) dst[n][k] = *(const PG8_LAS bf16x8*)(lds + PG8_SB(b, h) + boff + n * 2048 + k * 1024); } while (0)
; #define PG8_WAIT_V(n) asm volatile("s_waitcnt vmcnt(" #n ")" ::: "memory")
; #define PG8_WAIT_L(n) asm volatile("s_waitcnt lgkmcnt(" #n ")" ::: "memory")
; #define PG8_BAR __builtin_amdgcn_s_barrier()
; #define PG8_SCHED __builtin_amdgcn_sched_barrier(0)
; template <class Epi, class Sched, bool ALIGN_EPI = false, bool SP2 = false, bool I8 = false>
; __device__ __forceinline__ void gemm_phase(PG8_LAS unsigned char* lds, const Gemm g, const Sched& S, const Epi& E) {
;     ...
;             if constexpr (SP2) {
;             PG8_LDB(B0, 0, 0); PG8_LDB(B1, 0, 1); PG8_SCHED; PG8_LDA(At, 0, 0); PG8_STAGE(PG8_SA(1, 1), a1 + hstep, voffA);
;             PG8_WAIT_V(8); PG8_WAIT_L(0); PG8_BAR; PG8_MMA(0, 0, At, B0); PG8_MMA(0, 1, At, B1); PG8_BAR; PG8_SCHED;
;             PG8_LDA(At, 0, 1); PG8_STAGE(PG8_SB(0, 0), b2, voffB); PG8_STAGE(PG8_SB(0, 1), b2 + hstep, voffB); PG8_STAGE(PG8_SA(0, 0), a2, voffA);
;             PG8_WAIT_V(8); PG8_WAIT_L(0); PG8_BAR; PG8_MMA(1, 0, At, B0); PG8_MMA(1, 1, At, B1); PG8_BAR; PG8_SCHED;
;             PG8_LDB(B0, 1, 0); PG8_LDB(B1, 1, 1); PG8_SCHED; PG8_LDA(At, 1, 0); PG8_STAGE(PG8_SA(0, 1), a2 + hstep, voffA);
;             PG8_WAIT_V(8); PG8_WAIT_L(0); PG8_BAR; PG8_MMA(0, 0, At, B0); PG8_MMA(0, 1, At, B1); PG8_BAR; PG8_SCHED;
;             PG8_LDA(At, 1, 1); PG8_STAGE(PG8_SB(1, 0), b3, voffB); PG8_STAGE(PG8_SB(1, 1), b3 + hstep, voffB); PG8_STAGE(PG8_SA(1, 0), a3, voffA);
;             PG8_WAIT_V(8); PG8_WAIT_L(0); PG8_BAR; PG8_MMA(1, 0, At, B0); PG8_MMA(1, 1, At, B1); PG8_BAR; PG8_SCHED;
	s_setprio 0
	s_add_i32 s56, s56, s40
	v_lshl_add_u64 v[218:219], s[26:27], 0, v[2:3]
	s_mov_b32 m0, s56
	ds_read_b128 v[164:167], v242 offset:16384
	ds_read_b128 v[168:171], v242 offset:17408
	ds_read_b128 v[172:175], v242 offset:18432
	ds_read_b128 v[176:179], v242 offset:19456
	ds_read_b128 v[180:183], v242 offset:20480
	ds_read_b128 v[184:187], v242 offset:21504
	ds_read_b128 v[188:191], v242 offset:22528
	ds_read_b128 v[214:217], v242 offset:23552
	global_load_lds_dwordx4 v[218:219], off
	s_add_i32 m0, s56, 0x2000
	s_add_u32 s56, s26, 0x100000
	v_lshl_add_u64 v[220:221], s[26:27], 0, v[204:205]
	s_addc_u32 s57, s27, 0
	s_add_i32 s58, s58, s40
	global_load_lds_dwordx4 v[220:221], off
	s_mov_b32 m0, s58
	v_lshl_add_u64 v[224:225], s[36:37], 0, v[206:207]
	global_load_lds_dwordx4 v2, s[56:57]
	s_add_i32 m0, s58, 0x2000
	s_nop 0
	global_load_lds_dwordx4 v204, s[56:57]
	v_lshl_add_u64 v[222:223], s[36:37], 0, v[208:209]
	s_waitcnt vmcnt(6)
	s_waitcnt lgkmcnt(0)
	s_setprio 1
	s_barrier
	s_waitcnt lgkmcnt(0)
	v_mfma_f32_16x16x32_bf16 v[64:67], v[124:127], v[164:167], v[64:67]
	v_mfma_f32_16x16x32_bf16 v[64:67], v[128:131], v[168:171], v[64:67]
	v_mfma_f32_16x16x32_bf16 v[48:51], v[128:131], v[176:179], v[48:51]
	v_mfma_f32_16x16x32_bf16 v[48:51], v[124:127], v[172:175], v[48:51]
	v_mfma_f32_16x16x32_bf16 v[32:35], v[124:127], v[180:183], v[32:35]
	v_mfma_f32_16x16x32_bf16 v[32:35], v[128:131], v[184:187], v[32:35]
	v_mfma_f32_16x16x32_bf16 v[16:19], v[128:131], v[214:217], v[16:19]
	v_mfma_f32_16x16x32_bf16 v[16:19], v[124:127], v[188:191], v[16:19]
	v_mfma_f32_16x16x32_bf16 v[12:15], v[132:135], v[188:191], v[12:15]
	v_mfma_f32_16x16x32_bf16 v[12:15], v[144:147], v[214:217], v[12:15]
	v_mfma_f32_16x16x32_bf16 v[28:31], v[144:147], v[184:187], v[28:31]
	v_mfma_f32_16x16x32_bf16 v[28:31], v[132:135], v[180:183], v[28:31]
	v_mfma_f32_16x16x32_bf16 v[44:47], v[132:135], v[172:175], v[44:47]
	v_mfma_f32_16x16x32_bf16 v[44:47], v[144:147], v[176:179], v[44:47]
	v_mfma_f32_16x16x32_bf16 v[60:63], v[144:147], v[168:171], v[60:63]
	v_mfma_f32_16x16x32_bf16 v[60:63], v[132:135], v[164:167], v[60:63]
	v_mfma_f32_16x16x32_bf16 v[56:59], v[148:151], v[164:167], v[56:59]
	v_mfma_f32_16x16x32_bf16 v[56:59], v[152:155], v[168:171], v[56:59]
	v_mfma_f32_16x16x32_bf16 v[40:43], v[152:155], v[176:179], v[40:43]
	v_mfma_f32_16x16x32_bf16 v[40:43], v[148:151], v[172:175], v[40:43]
	v_mfma_f32_16x16x32_bf16 v[24:27], v[148:151], v[180:183], v[24:27]
	v_mfma_f32_16x16x32_bf16 v[24:27], v[152:155], v[184:187], v[24:27]
	v_mfma_f32_16x16x32_bf16 v[8:11], v[152:155], v[214:217], v[8:11]
	v_mfma_f32_16x16x32_bf16 v[8:11], v[148:151], v[188:191], v[8:11]
	v_mfma_f32_16x16x32_bf16 v[4:7], v[156:159], v[188:191], v[4:7]
	v_mfma_f32_16x16x32_bf16 v[4:7], v[160:163], v[214:217], v[4:7]
	v_mfma_f32_16x16x32_bf16 v[20:23], v[160:163], v[184:187], v[20:23]
	v_mfma_f32_16x16x32_bf16 v[20:23], v[156:159], v[180:183], v[20:23]
	v_mfma_f32_16x16x32_bf16 v[36:39], v[156:159], v[172:175], v[36:39]
	v_mfma_f32_16x16x32_bf16 v[36:39], v[160:163], v[176:179], v[36:39]
	v_mfma_f32_16x16x32_bf16 v[52:55], v[160:163], v[168:171], v[52:55]
	v_mfma_f32_16x16x32_bf16 v[52:55], v[156:159], v[164:167], v[52:55]
	s_barrier
	s_setprio 0
	s_mov_b32 m0, s41
	s_nop 0
	global_load_lds_dwordx4 v[222:223], off
	s_mov_b32 m0, s42
	s_nop 0
	global_load_lds_dwordx4 v[224:225], off
	s_add_i32 s56, 0, 0x18000
	s_add_i32 s57, 0, 0x1c000
	v_add_u32_e32 v144, s56, v240
	v_add_u32_e32 v160, s57, v240
	ds_read_b128 v[124:127], v144
	ds_read_b128 v[128:131], v144 offset:1024
	ds_read_b128 v[132:135], v144 offset:2048
	ds_read_b128 v[144:147], v144 offset:3072
	ds_read_b128 v[148:151], v160
	ds_read_b128 v[152:155], v160 offset:1024
	ds_read_b128 v[156:159], v160 offset:2048
	ds_read_b128 v[160:163], v160 offset:3072
	s_add_u32 s36, s36, 0x100000
	s_addc_u32 s37, s37, 0
	s_mov_b32 m0, s43
	ds_read_b128 v[164:167], v242 offset:32768
	ds_read_b128 v[168:171], v242 offset:33792
	ds_read_b128 v[172:175], v242 offset:34816
	ds_read_b128 v[176:179], v242 offset:35840
	ds_read_b128 v[180:183], v242 offset:36864
	ds_read_b128 v[184:187], v242 offset:37888
	ds_read_b128 v[188:191], v242 offset:38912
	ds_read_b128 v[214:217], v242 offset:39936
	global_load_lds_dwordx4 v208, s[36:37]
	s_mov_b32 m0, s44
	s_nop 0
	global_load_lds_dwordx4 v206, s[36:37]
	s_waitcnt vmcnt(8)
	s_waitcnt lgkmcnt(0)
	s_setprio 1
	s_barrier
; #define PG8_STAGE(bufoff, gbase, voff) do { _Pragma("unroll") for (int _i = 0; _i < 2; ++_i) \
;         __builtin_amdgcn_global_load_lds((const unsigned*)((const char*)(gbase) + (voff)[_i]), (PG8_LAS unsigned*)(lds + (bufoff) + ldsw + _i * 8192), 16, 0, 0); } while (0)
; #define PG8_LDA(dst, b, h) do { _Pragma("unroll") for (int m = 0; m < 4; ++m) _Pragma("unroll") for (int k = 0; k < 2; ++k) dst[m][k] = *(const PG8_LAS bf16x8*)(lds + PG8_SA(b, h) + aoff + m * 2048 + k * 1024); } while (0)
; #define PG8_WAIT_V(n) asm volatile("s_waitcnt vmcnt(" #n ")" ::: "memory")
; #define PG8_WAIT_L(n) asm volatile("s_waitcnt lgkmcnt(" #n ")" ::: "memory")
; #define PG8_BAR __builtin_amdgcn_s_barrier()
; template <class Epi, class Sched, bool ALIGN_EPI = false, bool SP2 = false, bool I8 = false>
; __device__ __forceinline__ void gemm_phase(PG8_LAS unsigned char* lds, const Gemm g, const Sched& S, const Epi& E) {
;     ...
;         for (int t = 0; t < nt; t += 2) {
;             const bool last = (t == nt - 2);
;             const char* a1 = cA + (size_t)(t + 1) * kstep;
;             const char* a2 = last ? nA : cA + (size_t)(t + 2) * kstep; const char* b2 = last ? nB : cB + (size_t)(t + 2) * kstep;
;             const char* a3 = a2 + kstep; const char* b3 = b2 + kstep;
;             if (last && has_next) S.a_ready(nxt);
;             if constexpr (SP2) {
;             PG8_LDB(B0, 0, 0); PG8_LDB(B1, 0, 1); PG8_SCHED; PG8_LDA(At, 0, 0); PG8_STAGE(PG8_SA(1, 1), a1 + hstep, voffA);
;             PG8_WAIT_V(8); PG8_WAIT_L(0); PG8_BAR; PG8_MMA(0, 0, At, B0); PG8_MMA(0, 1, At, B1); PG8_BAR; PG8_SCHED;
;             PG8_LDA(At, 0, 1); PG8_STAGE(PG8_SB(0, 0), b2, voffB); PG8_STAGE(PG8_SB(0, 1), b2 + hstep, voffB); PG8_STAGE(PG8_SA(0, 0), a2, voffA);
;             PG8_WAIT_V(8); PG8_WAIT_L(0); PG8_BAR; PG8_MMA(1, 0, At, B0); PG8_MMA(1, 1, At, B1); PG8_BAR; PG8_SCHED;
;             PG8_LDB(B0, 1, 0); PG8_LDB(B1, 1, 1); PG8_SCHED; PG8_LDA(At, 1, 0); PG8_STAGE(PG8_SA(0, 1), a2 + hstep, voffA);
;             PG8_WAIT_V(8); PG8_WAIT_L(0); PG8_BAR; PG8_MMA(0, 0, At, B0); PG8_MMA(0, 1, At, B1); PG8_BAR; PG8_SCHED;
;             PG8_LDA(At, 1, 1); PG8_STAGE(PG8_SB(1, 0), b3, voffB); PG8_STAGE(PG8_SB(1, 1), b3 + hstep, voffB); PG8_STAGE(PG8_SA(1, 0), a3, voffA);
;             PG8_WAIT_V(8); PG8_WAIT_L(0); PG8_BAR; PG8_MMA(1, 0, At, B0); PG8_MMA(1, 1, At, B1); PG8_BAR; PG8_SCHED;
	s_waitcnt lgkmcnt(0)
	v_mfma_f32_16x16x32_bf16 v[140:143], v[124:127], v[164:167], v[140:143]
	v_mfma_f32_16x16x32_bf16 v[140:143], v[128:131], v[168:171], v[140:143]
	v_mfma_f32_16x16x32_bf16 v[112:115], v[128:131], v[176:179], v[112:115]
	v_mfma_f32_16x16x32_bf16 v[112:115], v[124:127], v[172:175], v[112:115]
	v_mfma_f32_16x16x32_bf16 v[96:99], v[124:127], v[180:183], v[96:99]
	v_mfma_f32_16x16x32_bf16 v[96:99], v[128:131], v[184:187], v[96:99]
	v_mfma_f32_16x16x32_bf16 v[80:83], v[128:131], v[214:217], v[80:83]
	v_mfma_f32_16x16x32_bf16 v[80:83], v[124:127], v[188:191], v[80:83]
	v_mfma_f32_16x16x32_bf16 v[76:79], v[132:135], v[188:191], v[76:79]
	v_mfma_f32_16x16x32_bf16 v[76:79], v[144:147], v[214:217], v[76:79]
	v_mfma_f32_16x16x32_bf16 v[92:95], v[144:147], v[184:187], v[92:95]
	v_mfma_f32_16x16x32_bf16 v[92:95], v[132:135], v[180:183], v[92:95]
	v_mfma_f32_16x16x32_bf16 v[108:111], v[132:135], v[172:175], v[108:111]
	v_mfma_f32_16x16x32_bf16 v[108:111], v[144:147], v[176:179], v[108:111]
	v_mfma_f32_16x16x32_bf16 v[136:139], v[144:147], v[168:171], v[136:139]
	v_mfma_f32_16x16x32_bf16 v[136:139], v[132:135], v[164:167], v[136:139]
	v_mfma_f32_16x16x32_bf16 v[120:123], v[148:151], v[164:167], v[120:123]
	v_mfma_f32_16x16x32_bf16 v[120:123], v[152:155], v[168:171], v[120:123]
	v_mfma_f32_16x16x32_bf16 v[104:107], v[152:155], v[176:179], v[104:107]
	v_mfma_f32_16x16x32_bf16 v[104:107], v[148:151], v[172:175], v[104:107]
	v_mfma_f32_16x16x32_bf16 v[88:91], v[148:151], v[180:183], v[88:91]
	v_mfma_f32_16x16x32_bf16 v[88:91], v[152:155], v[184:187], v[88:91]
	v_mfma_f32_16x16x32_bf16 v[72:75], v[152:155], v[214:217], v[72:75]
	v_mfma_f32_16x16x32_bf16 v[72:75], v[148:151], v[188:191], v[72:75]
	v_mfma_f32_16x16x32_bf16 v[68:71], v[156:159], v[188:191], v[68:71]
	v_mfma_f32_16x16x32_bf16 v[68:71], v[160:163], v[214:217], v[68:71]
	v_mfma_f32_16x16x32_bf16 v[84:87], v[160:163], v[184:187], v[84:87]
	v_mfma_f32_16x16x32_bf16 v[84:87], v[156:159], v[180:183], v[84:87]
	v_mfma_f32_16x16x32_bf16 v[100:103], v[156:159], v[172:175], v[100:103]
	v_mfma_f32_16x16x32_bf16 v[100:103], v[160:163], v[176:179], v[100:103]
	v_mfma_f32_16x16x32_bf16 v[116:119], v[160:163], v[168:171], v[116:119]
	v_mfma_f32_16x16x32_bf16 v[116:119], v[156:159], v[164:167], v[116:119]
	s_barrier
	s_setprio 0
	s_add_i32 s36, s56, s40
	v_lshl_add_u64 v[218:219], v[218:219], 0, s[84:85]
	s_mov_b32 m0, s36
	ds_read_b128 v[164:167], v242 offset:49152
	ds_read_b128 v[168:171], v242 offset:50176
	ds_read_b128 v[172:175], v242 offset:51200
	ds_read_b128 v[176:179], v242 offset:52224
	ds_read_b128 v[180:183], v242 offset:53248
	ds_read_b128 v[184:187], v242 offset:54272
	ds_read_b128 v[188:191], v242 offset:55296
	ds_read_b128 v[214:217], v242 offset:56320
	global_load_lds_dwordx4 v[218:219], off
	s_add_i32 m0, s36, 0x2000
	s_add_u32 s26, s26, 0x100080
	v_lshl_add_u64 v[218:219], v[220:221], 0, s[84:85]
	s_addc_u32 s27, s27, 0
	s_add_i32 s36, s57, s40
	global_load_lds_dwordx4 v[218:219], off
	s_mov_b32 m0, s36
	s_nop 0
	global_load_lds_dwordx4 v2, s[26:27]
	s_add_i32 m0, s36, 0x2000
	s_nop 0
	global_load_lds_dwordx4 v204, s[26:27]
	s_cmp_eq_u32 s55, 60
	s_cbranch_scc0 .Ldefer_1456_body
	v_lshl_add_u64 v[218:219], v[222:223], 0, s[84:85]
	s_mov_b32 m0, s45
	s_nop 0
	global_load_lds_dwordx4 v[218:219], off
	v_lshl_add_u64 v[218:219], v[224:225], 0, s[84:85]
	s_mov_b32 m0, s46
	s_nop 0
	global_load_lds_dwordx4 v[218:219], off
.Ldefer_1456_body:
	s_waitcnt vmcnt(6)
	s_waitcnt lgkmcnt(0)
	s_setprio 1
	s_barrier
	s_waitcnt lgkmcnt(0)
	v_mfma_f32_16x16x32_bf16 v[64:67], v[124:127], v[164:167], v[64:67]
	v_mfma_f32_16x16x32_bf16 v[64:67], v[128:131], v[168:171], v[64:67]
	v_mfma_f32_16x16x32_bf16 v[48:51], v[128:131], v[176:179], v[48:51]
	v_mfma_f32_16x16x32_bf16 v[48:51], v[124:127], v[172:175], v[48:51]
	v_mfma_f32_16x16x32_bf16 v[32:35], v[124:127], v[180:183], v[32:35]
	v_mfma_f32_16x16x32_bf16 v[32:35], v[128:131], v[184:187], v[32:35]
	v_mfma_f32_16x16x32_bf16 v[16:19], v[128:131], v[214:217], v[16:19]
	v_mfma_f32_16x16x32_bf16 v[16:19], v[124:127], v[188:191], v[16:19]
	v_mfma_f32_16x16x32_bf16 v[12:15], v[132:135], v[188:191], v[12:15]
	v_mfma_f32_16x16x32_bf16 v[12:15], v[144:147], v[214:217], v[12:15]
	v_mfma_f32_16x16x32_bf16 v[28:31], v[144:147], v[184:187], v[28:31]
	v_mfma_f32_16x16x32_bf16 v[28:31], v[132:135], v[180:183], v[28:31]
	v_mfma_f32_16x16x32_bf16 v[44:47], v[132:135], v[172:175], v[44:47]
	v_mfma_f32_16x16x32_bf16 v[44:47], v[144:147], v[176:179], v[44:47]
	v_mfma_f32_16x16x32_bf16 v[60:63], v[144:147], v[168:171], v[60:63]
	v_mfma_f32_16x16x32_bf16 v[60:63], v[132:135], v[164:167], v[60:63]
	v_mfma_f32_16x16x32_bf16 v[56:59], v[148:151], v[164:167], v[56:59]
	v_mfma_f32_16x16x32_bf16 v[56:59], v[152:155], v[168:171], v[56:59]
	v_mfma_f32_16x16x32_bf16 v[40:43], v[152:155], v[176:179], v[40:43]
	v_mfma_f32_16x16x32_bf16 v[40:43], v[148:151], v[172:175], v[40:43]
	v_mfma_f32_16x16x32_bf16 v[24:27], v[148:151], v[180:183], v[24:27]
	v_mfma_f32_16x16x32_bf16 v[24:27], v[152:155], v[184:187], v[24:27]
	v_mfma_f32_16x16x32_bf16 v[8:11], v[152:155], v[214:217], v[8:11]
	v_mfma_f32_16x16x32_bf16 v[8:11], v[148:151], v[188:191], v[8:11]
	v_mfma_f32_16x16x32_bf16 v[4:7], v[156:159], v[188:191], v[4:7]
	v_mfma_f32_16x16x32_bf16 v[4:7], v[160:163], v[214:217], v[4:7]
	v_mfma_f32_16x16x32_bf16 v[20:23], v[160:163], v[184:187], v[20:23]
	v_mfma_f32_16x16x32_bf16 v[20:23], v[156:159], v[180:183], v[20:23]
	v_mfma_f32_16x16x32_bf16 v[36:39], v[156:159], v[172:175], v[36:39]
	v_mfma_f32_16x16x32_bf16 v[36:39], v[160:163], v[176:179], v[36:39]
	v_mfma_f32_16x16x32_bf16 v[52:55], v[160:163], v[168:171], v[52:55]
	v_mfma_f32_16x16x32_bf16 v[52:55], v[156:159], v[164:167], v[52:55]
	s_barrier
	s_setprio 0
	s_add_i32 s55, s55, 2
	s_add_u32 s24, s24, 0x100
	s_addc_u32 s25, s25, 0
	s_add_u32 s53, s53, 0x100
	s_addc_u32 s54, s54, 0
	s_cmp_gt_u32 s55, 61
	s_cbranch_scc0 .LBB0_1456

; #define PG8_STAGE(bufoff, gbase, voff) do { _Pragma("unroll") for (int _i = 0; _i < 2; ++_i) \
;         __builtin_amdgcn_global_load_lds((const unsigned*)((const char*)(gbase) + (voff)[_i]), (PG8_LAS unsigned*)(lds + (bufoff) + ldsw + _i * 8192), 16, 0, 0); } while (0)
; #define PG8_LDA(dst, b, h) do { _Pragma("unroll") for (int m = 0; m < 4; ++m) _Pragma("unroll") for (int k = 0; k < 2; ++k) dst[m][k] = *(const PG8_LAS bf16x8*)(lds + PG8_SA(b, h) + aoff + m * 2048 + k * 1024); } while (0)
; #define PG8_LDB(dst, b, h) do { _Pragma("unroll") for (int n = 0; n < 2; ++n) _Pragma("unroll") for (int k = 0; k < 2; ++k) dst[n][k] = *(const PG8_LAS bf16x8*)(lds + PG8_SB(b, h) + boff + n * 2048 + k * 1024); } while (0)
; #define PG8_WAIT_V(n) asm volatile("s_waitcnt vmcnt(" #n ")" ::: "memory")
; #define PG8_WAIT_L(n) asm volatile("s_waitcnt lgkmcnt(" #n ")" ::: "memory")
; #define PG8_BAR __builtin_amdgcn_s_barrier()
; #define PG8_SCHED __builtin_amdgcn_sched_barrier(0)
; template <class Epi, class Sched, bool ALIGN_EPI = false, bool SP2 = false, bool I8 = false>
; __device__ __forceinline__ void gemm_phase(PG8_LAS unsigned char* lds, const Gemm g, const Sched& S, const Epi& E) {
;     ...
;         const bool has_next = S.next(ui + 1, nxt);
;         const char* nA = has_next ? (const char*)g.A + (size_t)nxt.pm * tstep : cA; const char* nB = has_next ? (const char*)g.Bt + (size_t)nxt.pn * tstep : cB;
;         for (int t = 0; t < nt; t += 2) {
;             const bool last = (t == nt - 2);
;             const char* a1 = cA + (size_t)(t + 1) * kstep;
;             const char* a2 = last ? nA : cA + (size_t)(t + 2) * kstep; const char* b2 = last ? nB : cB + (size_t)(t + 2) * kstep;
;             const char* a3 = a2 + kstep; const char* b3 = b2 + kstep;
;             if (last && has_next) S.a_ready(nxt);
;             if constexpr (SP2) {
;             PG8_LDB(B0, 0, 0); PG8_LDB(B1, 0, 1); PG8_SCHED; PG8_LDA(At, 0, 0); PG8_STAGE(PG8_SA(1, 1), a1 + hstep, voffA);
;             PG8_WAIT_V(8); PG8_WAIT_L(0); PG8_BAR; PG8_MMA(0, 0, At, B0); PG8_MMA(0, 1, At, B1); PG8_BAR; PG8_SCHED;
;             PG8_LDA(At, 0, 1); PG8_STAGE(PG8_SB(0, 0), b2, voffB); PG8_STAGE(PG8_SB(0, 1), b2 + hstep, voffB); PG8_STAGE(PG8_SA(0, 0), a2, voffA);
.LBB0_1590:
	s_ashr_i32 s25, s24, 31
	s_lshl_b64 s[26:27], s[24:25], 20
	s_add_u32 s26, s28, s26
	s_addc_u32 s27, s42, s27
	s_and_b64 s[36:37], s[10:11], exec
	s_cselect_b32 s25, s27, s41
	s_cselect_b32 s57, s26, s40
	s_ashr_i32 s23, s22, 31
	s_lshl_b64 s[36:37], s[22:23], 20
	s_add_u32 s36, s43, s36
	s_addc_u32 s37, s46, s37
	s_and_b64 s[48:49], s[10:11], exec
	s_cselect_b32 s23, s37, s45
	s_cselect_b32 s58, s36, s44
	s_add_u32 s40, s40, 0x80080
	s_addc_u32 s41, s41, 0
	s_add_u32 s59, s44, 0x100
	s_addc_u32 s60, s45, 0
	s_mov_b32 s61, -2
	s_add_u32 s44, s40, 0xfff80080
	s_addc_u32 s45, s41, -1
	s_add_i32 s64, 0, 0x10000
	s_cmp_eq_u32 s61, 28
	s_cselect_b32 s49, s25, s45
	s_cselect_b32 s48, s57, s44
	s_cselect_b32 s45, s23, s60
	s_cselect_b32 s44, s58, s59
	s_add_i32 s67, 0, 0x14000
	v_add_u32_e32 v144, s64, v167
	v_add_u32_e32 v158, s67, v167
	ds_read_b128 v[36:39], v144
	ds_read_b128 v[44:47], v144 offset:1024
	ds_read_b128 v[140:143], v144 offset:2048
	ds_read_b128 v[144:147], v144 offset:3072
	ds_read_b128 v[160:163], v158
	ds_read_b128 v[172:175], v158 offset:1024
	ds_read_b128 v[176:179], v158 offset:2048
	ds_read_b128 v[180:183], v158 offset:3072
	s_add_i32 m0, s50, 0xc000
	ds_read_b128 v[184:187], v171
	ds_read_b128 v[188:191], v171 offset:1024
	ds_read_b128 v[204:207], v171 offset:2048
	ds_read_b128 v[208:211], v171 offset:3072
	ds_read_b128 v[212:215], v171 offset:4096
	ds_read_b128 v[216:219], v171 offset:5120
	ds_read_b128 v[220:223], v171 offset:6144
	ds_read_b128 v[224:227], v171 offset:7168
	global_load_lds_dwordx4 v154, s[40:41]
	s_add_i32 m0, s50, 0xe000
	s_nop 0
	global_load_lds_dwordx4 v156, s[40:41]
	s_waitcnt vmcnt(8)
	s_waitcnt lgkmcnt(0)
	s_setprio 1
	s_barrier
	s_waitcnt lgkmcnt(0)
	v_mfma_i32_16x16x64_i8 v[136:139], v[36:39], v[184:187], 0
	v_mfma_i32_16x16x64_i8 v[136:139], v[44:47], v[188:191], v[136:139]
	v_mfma_i32_16x16x64_i8 v[120:123], v[44:47], v[208:211], 0
	v_mfma_i32_16x16x64_i8 v[120:123], v[36:39], v[204:207], v[120:123]
	v_mfma_i32_16x16x64_i8 v[104:107], v[36:39], v[212:215], 0
	v_mfma_i32_16x16x64_i8 v[104:107], v[44:47], v[216:219], v[104:107]
	v_mfma_i32_16x16x64_i8 v[88:91], v[44:47], v[224:227], 0
	v_mfma_i32_16x16x64_i8 v[88:91], v[36:39], v[220:223], v[88:91]
	v_mfma_i32_16x16x64_i8 v[80:83], v[140:143], v[220:223], 0
	v_mfma_i32_16x16x64_i8 v[80:83], v[144:147], v[224:227], v[80:83]
	v_mfma_i32_16x16x64_i8 v[96:99], v[144:147], v[216:219], 0
	v_mfma_i32_16x16x64_i8 v[96:99], v[140:143], v[212:215], v[96:99]
	v_mfma_i32_16x16x64_i8 v[112:115], v[140:143], v[204:207], 0
	v_mfma_i32_16x16x64_i8 v[112:115], v[144:147], v[208:211], v[112:115]
	v_mfma_i32_16x16x64_i8 v[128:131], v[144:147], v[188:191], 0
	v_mfma_i32_16x16x64_i8 v[128:131], v[140:143], v[184:187], v[128:131]
	v_mfma_i32_16x16x64_i8 v[132:135], v[160:163], v[184:187], 0
	v_mfma_i32_16x16x64_i8 v[132:135], v[172:175], v[188:191], v[132:135]
	v_mfma_i32_16x16x64_i8 v[116:119], v[172:175], v[208:211], 0
	v_mfma_i32_16x16x64_i8 v[116:119], v[160:163], v[204:207], v[116:119]
	v_mfma_i32_16x16x64_i8 v[100:103], v[160:163], v[212:215], 0
	v_mfma_i32_16x16x64_i8 v[100:103], v[172:175], v[216:219], v[100:103]
	v_mfma_i32_16x16x64_i8 v[84:87], v[172:175], v[224:227], 0
	v_mfma_i32_16x16x64_i8 v[84:87], v[160:163], v[220:223], v[84:87]
	v_mfma_i32_16x16x64_i8 v[76:79], v[176:179], v[220:223], 0
	v_mfma_i32_16x16x64_i8 v[76:79], v[180:183], v[224:227], v[76:79]
	v_mfma_i32_16x16x64_i8 v[92:95], v[180:183], v[216:219], 0
	v_mfma_i32_16x16x64_i8 v[92:95], v[176:179], v[212:215], v[92:95]
	v_mfma_i32_16x16x64_i8 v[108:111], v[176:179], v[204:207], 0
	v_mfma_i32_16x16x64_i8 v[108:111], v[180:183], v[208:211], v[108:111]
	v_mfma_i32_16x16x64_i8 v[124:127], v[180:183], v[188:191], 0
	v_mfma_i32_16x16x64_i8 v[124:127], v[176:179], v[184:187], v[124:127]
	s_barrier
	s_setprio 0
	s_add_i32 s64, s64, s47
	v_lshl_add_u64 v[164:165], s[44:45], 0, v[2:3]
	s_mov_b32 m0, s64
	ds_read_b128 v[184:187], v171 offset:16384
	ds_read_b128 v[188:191], v171 offset:17408
	ds_read_b128 v[204:207], v171 offset:18432
	ds_read_b128 v[208:211], v171 offset:19456
	ds_read_b128 v[212:215], v171 offset:20480
	ds_read_b128 v[216:219], v171 offset:21504
	ds_read_b128 v[220:223], v171 offset:22528
	ds_read_b128 v[224:227], v171 offset:23552
	global_load_lds_dwordx4 v[164:165], off
	s_add_i32 m0, s64, 0x2000
	s_add_u32 s64, s44, 0x80000
	v_lshl_add_u64 v[228:229], s[44:45], 0, v[148:149]
	s_addc_u32 s65, s45, 0
	s_add_i32 s67, s67, s47
	global_load_lds_dwordx4 v[228:229], off
	s_mov_b32 m0, s67
	v_lshl_add_u64 v[242:243], s[48:49], 0, v[150:151]
	global_load_lds_dwordx4 v2, s[64:65]
	s_add_i32 m0, s67, 0x2000
	s_nop 0
	global_load_lds_dwordx4 v148, s[64:65]
	v_lshl_add_u64 v[240:241], s[48:49], 0, v[152:153]
	s_waitcnt vmcnt(6)
	s_waitcnt lgkmcnt(0)
	s_setprio 1
	s_barrier
; #define PG8_STAGE(bufoff, gbase, voff) do { _Pragma("unroll") for (int _i = 0; _i < 2; ++_i) \
;         __builtin_amdgcn_global_load_lds((const unsigned*)((const char*)(gbase) + (voff)[_i]), (PG8_LAS unsigned*)(lds + (bufoff) + ldsw + _i * 8192), 16, 0, 0); } while (0)
; #define PG8_LDA(dst, b, h) do { _Pragma("unroll") for (int m = 0; m < 4; ++m) _Pragma("unroll") for (int k = 0; k < 2; ++k) dst[m][k] = *(const PG8_LAS bf16x8*)(lds + PG8_SA(b, h) + aoff + m * 2048 + k * 1024); } while (0)
; #define PG8_LDB(dst, b, h) do { _Pragma("unroll") for (int n = 0; n < 2; ++n) _Pragma("unroll") for (int k = 0; k < 2; ++k) dst[n][k] = *(const PG8_LAS bf16x8*)(lds + PG8_SB(b, h) + boff + n * 2048 + k * 1024); } while (0)
; #define PG8_WAIT_V(n) asm volatile("s_waitcnt vmcnt(" #n ")" ::: "memory")
; #define PG8_WAIT_L(n) asm volatile("s_waitcnt lgkmcnt(" #n ")" ::: "memory")
; #define PG8_BAR __builtin_amdgcn_s_barrier()
; #define PG8_SCHED __builtin_amdgcn_sched_barrier(0)
; template <class Epi, class Sched, bool ALIGN_EPI = false, bool SP2 = false, bool I8 = false>
; __device__ __forceinline__ void gemm_phase(PG8_LAS unsigned char* lds, const Gemm g, const Sched& S, const Epi& E) {
;     ...
;             if constexpr (SP2) {
;             PG8_LDB(B0, 0, 0); PG8_LDB(B1, 0, 1); PG8_SCHED; PG8_LDA(At, 0, 0); PG8_STAGE(PG8_SA(1, 1), a1 + hstep, voffA);
;             PG8_WAIT_V(8); PG8_WAIT_L(0); PG8_BAR; PG8_MMA(0, 0, At, B0); PG8_MMA(0, 1, At, B1); PG8_BAR; PG8_SCHED;
;             PG8_LDA(At, 0, 1); PG8_STAGE(PG8_SB(0, 0), b2, voffB); PG8_STAGE(PG8_SB(0, 1), b2 + hstep, voffB); PG8_STAGE(PG8_SA(0, 0), a2, voffA);
;             PG8_WAIT_V(8); PG8_WAIT_L(0); PG8_BAR; PG8_MMA(1, 0, At, B0); PG8_MMA(1, 1, At, B1); PG8_BAR; PG8_SCHED;
;             PG8_LDB(B0, 1, 0); PG8_LDB(B1, 1, 1); PG8_SCHED; PG8_LDA(At, 1, 0); PG8_STAGE(PG8_SA(0, 1), a2 + hstep, voffA);
;             PG8_WAIT_V(8); PG8_WAIT_L(0); PG8_BAR; PG8_MMA(0, 0, At, B0); PG8_MMA(0, 1, At, B1); PG8_BAR; PG8_SCHED;
;             PG8_LDA(At, 1, 1); PG8_STAGE(PG8_SB(1, 0), b3, voffB); PG8_STAGE(PG8_SB(1, 1), b3 + hstep, voffB); PG8_STAGE(PG8_SA(1, 0), a3, voffA);
;             PG8_WAIT_V(8); PG8_WAIT_L(0); PG8_BAR; PG8_MMA(1, 0, At, B0); PG8_MMA(1, 1, At, B1); PG8_BAR; PG8_SCHED;
	s_waitcnt lgkmcnt(0)
	v_mfma_i32_16x16x64_i8 v[72:75], v[36:39], v[184:187], 0
	v_mfma_i32_16x16x64_i8 v[72:75], v[44:47], v[188:191], v[72:75]
	v_mfma_i32_16x16x64_i8 v[56:59], v[44:47], v[208:211], 0
	v_mfma_i32_16x16x64_i8 v[56:59], v[36:39], v[204:207], v[56:59]
	v_mfma_i32_16x16x64_i8 v[32:35], v[36:39], v[212:215], 0
	v_mfma_i32_16x16x64_i8 v[32:35], v[44:47], v[216:219], v[32:35]
	v_mfma_i32_16x16x64_i8 v[16:19], v[44:47], v[224:227], 0
	v_mfma_i32_16x16x64_i8 v[16:19], v[36:39], v[220:223], v[16:19]
	v_mfma_i32_16x16x64_i8 v[8:11], v[140:143], v[220:223], 0
	v_mfma_i32_16x16x64_i8 v[8:11], v[144:147], v[224:227], v[8:11]
	v_mfma_i32_16x16x64_i8 v[24:27], v[144:147], v[216:219], 0
	v_mfma_i32_16x16x64_i8 v[24:27], v[140:143], v[212:215], v[24:27]
	v_mfma_i32_16x16x64_i8 v[48:51], v[140:143], v[204:207], 0
	v_mfma_i32_16x16x64_i8 v[48:51], v[144:147], v[208:211], v[48:51]
	v_mfma_i32_16x16x64_i8 v[64:67], v[144:147], v[188:191], 0
	v_mfma_i32_16x16x64_i8 v[64:67], v[140:143], v[184:187], v[64:67]
	v_mfma_i32_16x16x64_i8 v[36:39], v[160:163], v[184:187], 0
	v_mfma_i32_16x16x64_i8 v[36:39], v[172:175], v[188:191], v[36:39]
	v_mfma_i32_16x16x64_i8 v[52:55], v[172:175], v[208:211], 0
	v_mfma_i32_16x16x64_i8 v[52:55], v[160:163], v[204:207], v[52:55]
	v_mfma_i32_16x16x64_i8 v[28:31], v[160:163], v[212:215], 0
	v_mfma_i32_16x16x64_i8 v[28:31], v[172:175], v[216:219], v[28:31]
	v_mfma_i32_16x16x64_i8 v[12:15], v[172:175], v[224:227], 0
	v_mfma_i32_16x16x64_i8 v[12:15], v[160:163], v[220:223], v[12:15]
	v_mfma_i32_16x16x64_i8 v[4:7], v[176:179], v[220:223], 0
	v_mfma_i32_16x16x64_i8 v[4:7], v[180:183], v[224:227], v[4:7]
	v_mfma_i32_16x16x64_i8 v[20:23], v[180:183], v[216:219], 0
	v_mfma_i32_16x16x64_i8 v[20:23], v[176:179], v[212:215], v[20:23]
	v_mfma_i32_16x16x64_i8 v[40:43], v[176:179], v[204:207], 0
	v_mfma_i32_16x16x64_i8 v[40:43], v[180:183], v[208:211], v[40:43]
	v_mfma_i32_16x16x64_i8 v[44:47], v[180:183], v[188:191], 0
	v_mfma_i32_16x16x64_i8 v[44:47], v[176:179], v[184:187], v[44:47]
	s_barrier
	s_setprio 0
	s_mov_b32 m0, s50
	s_nop 0
	global_load_lds_dwordx4 v[240:241], off
	s_mov_b32 m0, s51
	s_nop 0
	global_load_lds_dwordx4 v[242:243], off
	s_add_i32 s64, 0, 0x18000
	s_add_i32 s65, 0, 0x1c000
	v_add_u32_e32 v144, s64, v167
	v_add_u32_e32 v158, s65, v167
	ds_read_b128 v[60:63], v144
	ds_read_b128 v[68:71], v144 offset:1024
	ds_read_b128 v[140:143], v144 offset:2048
	ds_read_b128 v[144:147], v144 offset:3072
	ds_read_b128 v[160:163], v158
	ds_read_b128 v[172:175], v158 offset:1024
	ds_read_b128 v[176:179], v158 offset:2048
	ds_read_b128 v[180:183], v158 offset:3072
	s_add_u32 s48, s48, 0x80000
	s_addc_u32 s49, s49, 0
	s_mov_b32 m0, s52
	ds_read_b128 v[184:187], v171 offset:32768
	ds_read_b128 v[188:191], v171 offset:33792
	ds_read_b128 v[204:207], v171 offset:34816
	ds_read_b128 v[208:211], v171 offset:35840
	ds_read_b128 v[212:215], v171 offset:36864
	ds_read_b128 v[216:219], v171 offset:37888
	ds_read_b128 v[220:223], v171 offset:38912
	ds_read_b128 v[224:227], v171 offset:39936
	global_load_lds_dwordx4 v152, s[48:49]
	s_mov_b32 m0, s53
	s_nop 0
	global_load_lds_dwordx4 v150, s[48:49]
	s_waitcnt vmcnt(8)
	s_waitcnt lgkmcnt(0)
	s_setprio 1
	s_barrier
	s_waitcnt lgkmcnt(0)
	v_mfma_i32_16x16x64_i8 v[136:139], v[60:63], v[184:187], v[136:139]
	v_mfma_i32_16x16x64_i8 v[136:139], v[68:71], v[188:191], v[136:139]
	v_mfma_i32_16x16x64_i8 v[120:123], v[68:71], v[208:211], v[120:123]
	v_mfma_i32_16x16x64_i8 v[120:123], v[60:63], v[204:207], v[120:123]
	v_mfma_i32_16x16x64_i8 v[104:107], v[60:63], v[212:215], v[104:107]
	v_mfma_i32_16x16x64_i8 v[104:107], v[68:71], v[216:219], v[104:107]
	v_mfma_i32_16x16x64_i8 v[88:91], v[68:71], v[224:227], v[88:91]
	v_mfma_i32_16x16x64_i8 v[88:91], v[60:63], v[220:223], v[88:91]
	v_mfma_i32_16x16x64_i8 v[80:83], v[140:143], v[220:223], v[80:83]
	v_mfma_i32_16x16x64_i8 v[80:83], v[144:147], v[224:227], v[80:83]
	v_mfma_i32_16x16x64_i8 v[96:99], v[144:147], v[216:219], v[96:99]
	v_mfma_i32_16x16x64_i8 v[96:99], v[140:143], v[212:215], v[96:99]
	v_mfma_i32_16x16x64_i8 v[112:115], v[140:143], v[204:207], v[112:115]
	v_mfma_i32_16x16x64_i8 v[112:115], v[144:147], v[208:211], v[112:115]
	v_mfma_i32_16x16x64_i8 v[128:131], v[144:147], v[188:191], v[128:131]
	v_mfma_i32_16x16x64_i8 v[128:131], v[140:143], v[184:187], v[128:131]
	v_mfma_i32_16x16x64_i8 v[132:135], v[160:163], v[184:187], v[132:135]
	v_mfma_i32_16x16x64_i8 v[132:135], v[172:175], v[188:191], v[132:135]
	v_mfma_i32_16x16x64_i8 v[116:119], v[172:175], v[208:211], v[116:119]
	v_mfma_i32_16x16x64_i8 v[116:119], v[160:163], v[204:207], v[116:119]
	v_mfma_i32_16x16x64_i8 v[100:103], v[160:163], v[212:215], v[100:103]
	v_mfma_i32_16x16x64_i8 v[100:103], v[172:175], v[216:219], v[100:103]
	v_mfma_i32_16x16x64_i8 v[84:87], v[172:175], v[224:227], v[84:87]
	v_mfma_i32_16x16x64_i8 v[84:87], v[160:163], v[220:223], v[84:87]
	v_mfma_i32_16x16x64_i8 v[76:79], v[176:179], v[220:223], v[76:79]
	v_mfma_i32_16x16x64_i8 v[76:79], v[180:183], v[224:227], v[76:79]
	v_mfma_i32_16x16x64_i8 v[92:95], v[180:183], v[216:219], v[92:95]
	v_mfma_i32_16x16x64_i8 v[92:95], v[176:179], v[212:215], v[92:95]
	v_mfma_i32_16x16x64_i8 v[108:111], v[176:179], v[204:207], v[108:111]
	v_mfma_i32_16x16x64_i8 v[108:111], v[180:183], v[208:211], v[108:111]
	v_mfma_i32_16x16x64_i8 v[124:127], v[180:183], v[188:191], v[124:127]
	v_mfma_i32_16x16x64_i8 v[124:127], v[176:179], v[184:187], v[124:127]
	s_barrier
	s_setprio 0
	s_add_i32 s48, s64, s47
	v_lshl_add_u64 v[164:165], v[164:165], 0, s[84:85]
	s_mov_b32 m0, s48
	ds_read_b128 v[184:187], v171 offset:49152
	ds_read_b128 v[188:191], v171 offset:50176
	ds_read_b128 v[204:207], v171 offset:51200
	ds_read_b128 v[208:211], v171 offset:52224
	ds_read_b128 v[212:215], v171 offset:53248
	ds_read_b128 v[216:219], v171 offset:54272
	ds_read_b128 v[220:223], v171 offset:55296
	ds_read_b128 v[224:227], v171 offset:56320
	global_load_lds_dwordx4 v[164:165], off
	s_add_i32 m0, s48, 0x2000
	s_add_u32 s44, s44, 0x80080
	v_lshl_add_u64 v[164:165], v[228:229], 0, s[84:85]
	s_addc_u32 s45, s45, 0
	s_add_i32 s48, s65, s47
	global_load_lds_dwordx4 v[164:165], off
	s_mov_b32 m0, s48
	s_nop 0
	global_load_lds_dwordx4 v2, s[44:45]
	s_add_i32 m0, s48, 0x2000
	s_nop 0
	global_load_lds_dwordx4 v148, s[44:45]
	s_cmp_eq_u32 s61, 28
	s_cbranch_scc0 .Ldefer_1591_peel
	v_lshl_add_u64 v[164:165], v[240:241], 0, s[84:85]
	s_mov_b32 m0, s54
	s_nop 0
	global_load_lds_dwordx4 v[164:165], off
	v_lshl_add_u64 v[164:165], v[242:243], 0, s[84:85]
	s_mov_b32 m0, s55
	s_nop 0
	global_load_lds_dwordx4 v[164:165], off
; #define PG8_STAGE(bufoff, gbase, voff) do { _Pragma("unroll") for (int _i = 0; _i < 2; ++_i) \
;         __builtin_amdgcn_global_load_lds((const unsigned*)((const char*)(gbase) + (voff)[_i]), (PG8_LAS unsigned*)(lds + (bufoff) + ldsw + _i * 8192), 16, 0, 0); } while (0)
; #define PG8_LDA(dst, b, h) do { _Pragma("unroll") for (int m = 0; m < 4; ++m) _Pragma("unroll") for (int k = 0; k < 2; ++k) dst[m][k] = *(const PG8_LAS bf16x8*)(lds + PG8_SA(b, h) + aoff + m * 2048 + k * 1024); } while (0)
; #define PG8_WAIT_V(n) asm volatile("s_waitcnt vmcnt(" #n ")" ::: "memory")
; #define PG8_WAIT_L(n) asm volatile("s_waitcnt lgkmcnt(" #n ")" ::: "memory")
; #define PG8_BAR __builtin_amdgcn_s_barrier()
; template <class Epi, class Sched, bool ALIGN_EPI = false, bool SP2 = false, bool I8 = false>
; __device__ __forceinline__ void gemm_phase(PG8_LAS unsigned char* lds, const Gemm g, const Sched& S, const Epi& E) {
;     ...
;         for (int t = 0; t < nt; t += 2) {
;             const bool last = (t == nt - 2);
;             const char* a1 = cA + (size_t)(t + 1) * kstep;
;             const char* a2 = last ? nA : cA + (size_t)(t + 2) * kstep; const char* b2 = last ? nB : cB + (size_t)(t + 2) * kstep;
;             const char* a3 = a2 + kstep; const char* b3 = b2 + kstep;
;             if (last && has_next) S.a_ready(nxt);
;             if constexpr (SP2) {
;             PG8_LDB(B0, 0, 0); PG8_LDB(B1, 0, 1); PG8_SCHED; PG8_LDA(At, 0, 0); PG8_STAGE(PG8_SA(1, 1), a1 + hstep, voffA);
;             PG8_WAIT_V(8); PG8_WAIT_L(0); PG8_BAR; PG8_MMA(0, 0, At, B0); PG8_MMA(0, 1, At, B1); PG8_BAR; PG8_SCHED;
;             PG8_LDA(At, 0, 1); PG8_STAGE(PG8_SB(0, 0), b2, voffB); PG8_STAGE(PG8_SB(0, 1), b2 + hstep, voffB); PG8_STAGE(PG8_SA(0, 0), a2, voffA);
;             PG8_WAIT_V(8); PG8_WAIT_L(0); PG8_BAR; PG8_MMA(1, 0, At, B0); PG8_MMA(1, 1, At, B1); PG8_BAR; PG8_SCHED;
;             PG8_LDB(B0, 1, 0); PG8_LDB(B1, 1, 1); PG8_SCHED; PG8_LDA(At, 1, 0); PG8_STAGE(PG8_SA(0, 1), a2 + hstep, voffA);
;             PG8_WAIT_V(8); PG8_WAIT_L(0); PG8_BAR; PG8_MMA(0, 0, At, B0); PG8_MMA(0, 1, At, B1); PG8_BAR; PG8_SCHED;
;             PG8_LDA(At, 1, 1); PG8_STAGE(PG8_SB(1, 0), b3, voffB); PG8_STAGE(PG8_SB(1, 1), b3 + hstep, voffB); PG8_STAGE(PG8_SA(1, 0), a3, voffA);
;             PG8_WAIT_V(8); PG8_WAIT_L(0); PG8_BAR; PG8_MMA(1, 0, At, B0); PG8_MMA(1, 1, At, B1); PG8_BAR; PG8_SCHED;
.Ldefer_1591_peel:
	s_waitcnt vmcnt(6)
	s_waitcnt lgkmcnt(0)
	s_setprio 1
	s_barrier
	s_waitcnt lgkmcnt(0)
	v_mfma_i32_16x16x64_i8 v[72:75], v[60:63], v[184:187], v[72:75]
	v_mfma_i32_16x16x64_i8 v[72:75], v[68:71], v[188:191], v[72:75]
	v_mfma_i32_16x16x64_i8 v[56:59], v[68:71], v[208:211], v[56:59]
	v_mfma_i32_16x16x64_i8 v[56:59], v[60:63], v[204:207], v[56:59]
	v_mfma_i32_16x16x64_i8 v[32:35], v[60:63], v[212:215], v[32:35]
	v_mfma_i32_16x16x64_i8 v[32:35], v[68:71], v[216:219], v[32:35]
	v_mfma_i32_16x16x64_i8 v[16:19], v[68:71], v[224:227], v[16:19]
	v_mfma_i32_16x16x64_i8 v[16:19], v[60:63], v[220:223], v[16:19]
	v_mfma_i32_16x16x64_i8 v[8:11], v[140:143], v[220:223], v[8:11]
	v_mfma_i32_16x16x64_i8 v[8:11], v[144:147], v[224:227], v[8:11]
	v_mfma_i32_16x16x64_i8 v[24:27], v[144:147], v[216:219], v[24:27]
	v_mfma_i32_16x16x64_i8 v[24:27], v[140:143], v[212:215], v[24:27]
	v_mfma_i32_16x16x64_i8 v[48:51], v[140:143], v[204:207], v[48:51]
	v_mfma_i32_16x16x64_i8 v[48:51], v[144:147], v[208:211], v[48:51]
	v_mfma_i32_16x16x64_i8 v[64:67], v[144:147], v[188:191], v[64:67]
	v_mfma_i32_16x16x64_i8 v[64:67], v[140:143], v[184:187], v[64:67]
	v_mfma_i32_16x16x64_i8 v[36:39], v[160:163], v[184:187], v[36:39]
	v_mfma_i32_16x16x64_i8 v[68:71], v[172:175], v[188:191], v[36:39]
	v_mfma_i32_16x16x64_i8 v[36:39], v[172:175], v[208:211], v[52:55]
	v_mfma_i32_16x16x64_i8 v[52:55], v[160:163], v[204:207], v[36:39]
	v_mfma_i32_16x16x64_i8 v[28:31], v[160:163], v[212:215], v[28:31]
	v_mfma_i32_16x16x64_i8 v[28:31], v[172:175], v[216:219], v[28:31]
	v_mfma_i32_16x16x64_i8 v[12:15], v[172:175], v[224:227], v[12:15]
	v_mfma_i32_16x16x64_i8 v[12:15], v[160:163], v[220:223], v[12:15]
	v_mfma_i32_16x16x64_i8 v[4:7], v[176:179], v[220:223], v[4:7]
	v_mfma_i32_16x16x64_i8 v[4:7], v[180:183], v[224:227], v[4:7]
	v_mfma_i32_16x16x64_i8 v[20:23], v[180:183], v[216:219], v[20:23]
	v_mfma_i32_16x16x64_i8 v[20:23], v[176:179], v[212:215], v[20:23]
	v_mfma_i32_16x16x64_i8 v[36:39], v[176:179], v[204:207], v[40:43]
	v_mfma_i32_16x16x64_i8 v[40:43], v[180:183], v[208:211], v[36:39]
	v_mfma_i32_16x16x64_i8 v[36:39], v[180:183], v[188:191], v[44:47]
	v_mfma_i32_16x16x64_i8 v[60:63], v[176:179], v[184:187], v[36:39]
	s_barrier
	s_setprio 0
	s_add_i32 s61, s61, 2
	s_add_u32 s40, s40, 0x100
	s_addc_u32 s41, s41, 0
	s_add_u32 s59, s59, 0x100
	s_addc_u32 s60, s60, 0
	s_cmp_gt_u32 s61, 29
	s_cbranch_scc1 .Lkloop_exit_3
.LBB0_1591:
	s_add_u32 s44, s40, 0xfff80080
	s_addc_u32 s45, s41, -1
	s_add_i32 s64, 0, 0x10000
	s_cmp_eq_u32 s61, 28
	s_cselect_b32 s49, s25, s45
	s_cselect_b32 s48, s57, s44
	s_cselect_b32 s45, s23, s60
	s_cselect_b32 s44, s58, s59
	s_add_i32 s67, 0, 0x14000
	v_add_u32_e32 v144, s64, v167
	v_add_u32_e32 v158, s67, v167
	ds_read_b128 v[36:39], v144
	ds_read_b128 v[44:47], v144 offset:1024
	ds_read_b128 v[140:143], v144 offset:2048
	ds_read_b128 v[144:147], v144 offset:3072
	ds_read_b128 v[160:163], v158
	ds_read_b128 v[172:175], v158 offset:1024
	ds_read_b128 v[176:179], v158 offset:2048
	ds_read_b128 v[180:183], v158 offset:3072
	v_lshl_add_u64 v[164:165], v[240:241], 0, s[84:85]
	s_mov_b32 m0, s54
	s_nop 0
	global_load_lds_dwordx4 v[164:165], off
	v_lshl_add_u64 v[164:165], v[242:243], 0, s[84:85]
	s_mov_b32 m0, s55
	s_nop 0
	global_load_lds_dwordx4 v[164:165], off
	s_add_i32 m0, s50, 0xc000
	ds_read_b128 v[184:187], v171
	ds_read_b128 v[188:191], v171 offset:1024
	ds_read_b128 v[204:207], v171 offset:2048
	ds_read_b128 v[208:211], v171 offset:3072
	ds_read_b128 v[212:215], v171 offset:4096
	ds_read_b128 v[216:219], v171 offset:5120
	ds_read_b128 v[220:223], v171 offset:6144
	ds_read_b128 v[224:227], v171 offset:7168
	global_load_lds_dwordx4 v154, s[40:41]
	s_add_i32 m0, s50, 0xe000
	s_nop 0
	global_load_lds_dwordx4 v156, s[40:41]
	s_waitcnt vmcnt(8)
	s_waitcnt lgkmcnt(0)
	s_setprio 1
	s_barrier
	s_waitcnt lgkmcnt(0)
	v_mfma_i32_16x16x64_i8 v[136:139], v[36:39], v[184:187], v[136:139]
	v_mfma_i32_16x16x64_i8 v[136:139], v[44:47], v[188:191], v[136:139]
	v_mfma_i32_16x16x64_i8 v[120:123], v[44:47], v[208:211], v[120:123]
	v_mfma_i32_16x16x64_i8 v[120:123], v[36:39], v[204:207], v[120:123]
	v_mfma_i32_16x16x64_i8 v[104:107], v[36:39], v[212:215], v[104:107]
	v_mfma_i32_16x16x64_i8 v[104:107], v[44:47], v[216:219], v[104:107]
	v_mfma_i32_16x16x64_i8 v[88:91], v[44:47], v[224:227], v[88:91]
	v_mfma_i32_16x16x64_i8 v[88:91], v[36:39], v[220:223], v[88:91]
	v_mfma_i32_16x16x64_i8 v[80:83], v[140:143], v[220:223], v[80:83]
	v_mfma_i32_16x16x64_i8 v[80:83], v[144:147], v[224:227], v[80:83]
	v_mfma_i32_16x16x64_i8 v[96:99], v[144:147], v[216:219], v[96:99]
	v_mfma_i32_16x16x64_i8 v[96:99], v[140:143], v[212:215], v[96:99]
	v_mfma_i32_16x16x64_i8 v[112:115], v[140:143], v[204:207], v[112:115]
	v_mfma_i32_16x16x64_i8 v[112:115], v[144:147], v[208:211], v[112:115]
	v_mfma_i32_16x16x64_i8 v[128:131], v[144:147], v[188:191], v[128:131]
	v_mfma_i32_16x16x64_i8 v[128:131], v[140:143], v[184:187], v[128:131]
	v_mfma_i32_16x16x64_i8 v[132:135], v[160:163], v[184:187], v[132:135]
	v_mfma_i32_16x16x64_i8 v[132:135], v[172:175], v[188:191], v[132:135]
	v_mfma_i32_16x16x64_i8 v[116:119], v[172:175], v[208:211], v[116:119]
	v_mfma_i32_16x16x64_i8 v[116:119], v[160:163], v[204:207], v[116:119]
	v_mfma_i32_16x16x64_i8 v[100:103], v[160:163], v[212:215], v[100:103]
	v_mfma_i32_16x16x64_i8 v[100:103], v[172:175], v[216:219], v[100:103]
	v_mfma_i32_16x16x64_i8 v[84:87], v[172:175], v[224:227], v[84:87]
	v_mfma_i32_16x16x64_i8 v[84:87], v[160:163], v[220:223], v[84:87]
	v_mfma_i32_16x16x64_i8 v[76:79], v[176:179], v[220:223], v[76:79]
	v_mfma_i32_16x16x64_i8 v[76:79], v[180:183], v[224:227], v[76:79]
	v_mfma_i32_16x16x64_i8 v[92:95], v[180:183], v[216:219], v[92:95]
	v_mfma_i32_16x16x64_i8 v[92:95], v[176:179], v[212:215], v[92:95]
	v_mfma_i32_16x16x64_i8 v[108:111], v[176:179], v[204:207], v[108:111]
	v_mfma_i32_16x16x64_i8 v[108:111], v[180:183], v[208:211], v[108:111]
	v_mfma_i32_16x16x64_i8 v[124:127], v[180:183], v[188:191], v[124:127]
	v_mfma_i32_16x16x64_i8 v[124:127], v[176:179], v[184:187], v[124:127]
	s_barrier
; #define PG8_STAGE(bufoff, gbase, voff) do { _Pragma("unroll") for (int _i = 0; _i < 2; ++_i) \
;         __builtin_amdgcn_global_load_lds((const unsigned*)((const char*)(gbase) + (voff)[_i]), (PG8_LAS unsigned*)(lds + (bufoff) + ldsw + _i * 8192), 16, 0, 0); } while (0)
; #define PG8_LDA(dst, b, h) do { _Pragma("unroll") for (int m = 0; m < 4; ++m) _Pragma("unroll") for (int k = 0; k < 2; ++k) dst[m][k] = *(const PG8_LAS bf16x8*)(lds + PG8_SA(b, h) + aoff + m * 2048 + k * 1024); } while (0)
; #define PG8_LDB(dst, b, h) do { _Pragma("unroll") for (int n = 0; n < 2; ++n) _Pragma("unroll") for (int k = 0; k < 2; ++k) dst[n][k] = *(const PG8_LAS bf16x8*)(lds + PG8_SB(b, h) + boff + n * 2048 + k * 1024); } while (0)
; #define PG8_WAIT_V(n) asm volatile("s_waitcnt vmcnt(" #n ")" ::: "memory")
; #define PG8_WAIT_L(n) asm volatile("s_waitcnt lgkmcnt(" #n ")" ::: "memory")
; #define PG8_BAR __builtin_amdgcn_s_barrier()
; #define PG8_SCHED __builtin_amdgcn_sched_barrier(0)
; template <class Epi, class Sched, bool ALIGN_EPI = false, bool SP2 = false, bool I8 = false>
; __device__ __forceinline__ void gemm_phase(PG8_LAS unsigned char* lds, const Gemm g, const Sched& S, const Epi& E) {
;     ...
;             if constexpr (SP2) {
;             PG8_LDB(B0, 0, 0); PG8_LDB(B1, 0, 1); PG8_SCHED; PG8_LDA(At, 0, 0); PG8_STAGE(PG8_SA(1, 1), a1 + hstep, voffA);
;             PG8_WAIT_V(8); PG8_WAIT_L(0); PG8_BAR; PG8_MMA(0, 0, At, B0); PG8_MMA(0, 1, At, B1); PG8_BAR; PG8_SCHED;
;             PG8_LDA(At, 0, 1); PG8_STAGE(PG8_SB(0, 0), b2, voffB); PG8_STAGE(PG8_SB(0, 1), b2 + hstep, voffB); PG8_STAGE(PG8_SA(0, 0), a2, voffA);
;             PG8_WAIT_V(8); PG8_WAIT_L(0); PG8_BAR; PG8_MMA(1, 0, At, B0); PG8_MMA(1, 1, At, B1); PG8_BAR; PG8_SCHED;
;             PG8_LDB(B0, 1, 0); PG8_LDB(B1, 1, 1); PG8_SCHED; PG8_LDA(At, 1, 0); PG8_STAGE(PG8_SA(0, 1), a2 + hstep, voffA);
;             PG8_WAIT_V(8); PG8_WAIT_L(0); PG8_BAR; PG8_MMA(0, 0, At, B0); PG8_MMA(0, 1, At, B1); PG8_BAR; PG8_SCHED;
;             PG8_LDA(At, 1, 1); PG8_STAGE(PG8_SB(1, 0), b3, voffB); PG8_STAGE(PG8_SB(1, 1), b3 + hstep, voffB); PG8_STAGE(PG8_SA(1, 0), a3, voffA);
;             PG8_WAIT_V(8); PG8_WAIT_L(0); PG8_BAR; PG8_MMA(1, 0, At, B0); PG8_MMA(1, 1, At, B1); PG8_BAR; PG8_SCHED;
	s_setprio 0
	s_add_i32 s64, s64, s47
	v_lshl_add_u64 v[164:165], s[44:45], 0, v[2:3]
	s_mov_b32 m0, s64
	ds_read_b128 v[184:187], v171 offset:16384
	ds_read_b128 v[188:191], v171 offset:17408
	ds_read_b128 v[204:207], v171 offset:18432
	ds_read_b128 v[208:211], v171 offset:19456
	ds_read_b128 v[212:215], v171 offset:20480
	ds_read_b128 v[216:219], v171 offset:21504
	ds_read_b128 v[220:223], v171 offset:22528
	ds_read_b128 v[224:227], v171 offset:23552
	global_load_lds_dwordx4 v[164:165], off
	s_add_i32 m0, s64, 0x2000
	s_add_u32 s64, s44, 0x80000
	v_lshl_add_u64 v[228:229], s[44:45], 0, v[148:149]
	s_addc_u32 s65, s45, 0
	s_add_i32 s67, s67, s47
	global_load_lds_dwordx4 v[228:229], off
	s_mov_b32 m0, s67
	v_lshl_add_u64 v[242:243], s[48:49], 0, v[150:151]
	global_load_lds_dwordx4 v2, s[64:65]
	s_add_i32 m0, s67, 0x2000
	s_nop 0
	global_load_lds_dwordx4 v148, s[64:65]
	v_lshl_add_u64 v[240:241], s[48:49], 0, v[152:153]
	s_waitcnt vmcnt(6)
	s_waitcnt lgkmcnt(0)
	s_setprio 1
	s_barrier
	s_waitcnt lgkmcnt(0)
	v_mfma_i32_16x16x64_i8 v[72:75], v[36:39], v[184:187], v[72:75]
	v_mfma_i32_16x16x64_i8 v[72:75], v[44:47], v[188:191], v[72:75]
	v_mfma_i32_16x16x64_i8 v[56:59], v[44:47], v[208:211], v[56:59]
	v_mfma_i32_16x16x64_i8 v[56:59], v[36:39], v[204:207], v[56:59]
	v_mfma_i32_16x16x64_i8 v[32:35], v[36:39], v[212:215], v[32:35]
	v_mfma_i32_16x16x64_i8 v[32:35], v[44:47], v[216:219], v[32:35]
	v_mfma_i32_16x16x64_i8 v[16:19], v[44:47], v[224:227], v[16:19]
	v_mfma_i32_16x16x64_i8 v[16:19], v[36:39], v[220:223], v[16:19]
	v_mfma_i32_16x16x64_i8 v[8:11], v[140:143], v[220:223], v[8:11]
	v_mfma_i32_16x16x64_i8 v[8:11], v[144:147], v[224:227], v[8:11]
	v_mfma_i32_16x16x64_i8 v[24:27], v[144:147], v[216:219], v[24:27]
	v_mfma_i32_16x16x64_i8 v[24:27], v[140:143], v[212:215], v[24:27]
	v_mfma_i32_16x16x64_i8 v[48:51], v[140:143], v[204:207], v[48:51]
	v_mfma_i32_16x16x64_i8 v[48:51], v[144:147], v[208:211], v[48:51]
	v_mfma_i32_16x16x64_i8 v[64:67], v[144:147], v[188:191], v[64:67]
	v_mfma_i32_16x16x64_i8 v[64:67], v[140:143], v[184:187], v[64:67]
	v_mfma_i32_16x16x64_i8 v[36:39], v[160:163], v[184:187], v[68:71]
	v_mfma_i32_16x16x64_i8 v[36:39], v[172:175], v[188:191], v[36:39]
	v_mfma_i32_16x16x64_i8 v[52:55], v[172:175], v[208:211], v[52:55]
	v_mfma_i32_16x16x64_i8 v[52:55], v[160:163], v[204:207], v[52:55]
	v_mfma_i32_16x16x64_i8 v[28:31], v[160:163], v[212:215], v[28:31]
	v_mfma_i32_16x16x64_i8 v[28:31], v[172:175], v[216:219], v[28:31]
	v_mfma_i32_16x16x64_i8 v[12:15], v[172:175], v[224:227], v[12:15]
	v_mfma_i32_16x16x64_i8 v[12:15], v[160:163], v[220:223], v[12:15]
	v_mfma_i32_16x16x64_i8 v[4:7], v[176:179], v[220:223], v[4:7]
	v_mfma_i32_16x16x64_i8 v[4:7], v[180:183], v[224:227], v[4:7]
	v_mfma_i32_16x16x64_i8 v[20:23], v[180:183], v[216:219], v[20:23]
	v_mfma_i32_16x16x64_i8 v[20:23], v[176:179], v[212:215], v[20:23]
	v_mfma_i32_16x16x64_i8 v[40:43], v[176:179], v[204:207], v[40:43]
	v_mfma_i32_16x16x64_i8 v[40:43], v[180:183], v[208:211], v[40:43]
	v_mfma_i32_16x16x64_i8 v[44:47], v[180:183], v[188:191], v[60:63]
	v_mfma_i32_16x16x64_i8 v[44:47], v[176:179], v[184:187], v[44:47]
	s_barrier
	s_setprio 0
	s_mov_b32 m0, s50
	s_nop 0
	global_load_lds_dwordx4 v[240:241], off
	s_mov_b32 m0, s51
	s_nop 0
	global_load_lds_dwordx4 v[242:243], off
	s_add_i32 s64, 0, 0x18000
	s_add_i32 s65, 0, 0x1c000
	v_add_u32_e32 v144, s64, v167
	v_add_u32_e32 v158, s65, v167
	ds_read_b128 v[60:63], v144
	ds_read_b128 v[68:71], v144 offset:1024
	ds_read_b128 v[140:143], v144 offset:2048
	ds_read_b128 v[144:147], v144 offset:3072
	ds_read_b128 v[160:163], v158
	ds_read_b128 v[172:175], v158 offset:1024
	ds_read_b128 v[176:179], v158 offset:2048
	ds_read_b128 v[180:183], v158 offset:3072
	s_add_u32 s48, s48, 0x80000
	s_addc_u32 s49, s49, 0
	s_mov_b32 m0, s52
	ds_read_b128 v[184:187], v171 offset:32768
	ds_read_b128 v[188:191], v171 offset:33792
	ds_read_b128 v[204:207], v171 offset:34816
	ds_read_b128 v[208:211], v171 offset:35840
	ds_read_b128 v[212:215], v171 offset:36864
	ds_read_b128 v[216:219], v171 offset:37888
	ds_read_b128 v[220:223], v171 offset:38912
	ds_read_b128 v[224:227], v171 offset:39936
	global_load_lds_dwordx4 v152, s[48:49]
	s_mov_b32 m0, s53
	s_nop 0
	global_load_lds_dwordx4 v150, s[48:49]
	s_waitcnt vmcnt(8)
	s_waitcnt lgkmcnt(0)
	s_setprio 1
	s_barrier
; #define PG8_STAGE(bufoff, gbase, voff) do { _Pragma("unroll") for (int _i = 0; _i < 2; ++_i) \
;         __builtin_amdgcn_global_load_lds((const unsigned*)((const char*)(gbase) + (voff)[_i]), (PG8_LAS unsigned*)(lds + (bufoff) + ldsw + _i * 8192), 16, 0, 0); } while (0)
; #define PG8_LDA(dst, b, h) do { _Pragma("unroll") for (int m = 0; m < 4; ++m) _Pragma("unroll") for (int k = 0; k < 2; ++k) dst[m][k] = *(const PG8_LAS bf16x8*)(lds + PG8_SA(b, h) + aoff + m * 2048 + k * 1024); } while (0)
; #define PG8_WAIT_V(n) asm volatile("s_waitcnt vmcnt(" #n ")" ::: "memory")
; #define PG8_WAIT_L(n) asm volatile("s_waitcnt lgkmcnt(" #n ")" ::: "memory")
; #define PG8_BAR __builtin_amdgcn_s_barrier()
; template <class Epi, class Sched, bool ALIGN_EPI = false, bool SP2 = false, bool I8 = false>
; __device__ __forceinline__ void gemm_phase(PG8_LAS unsigned char* lds, const Gemm g, const Sched& S, const Epi& E) {
;     ...
;         for (int t = 0; t < nt; t += 2) {
;             const bool last = (t == nt - 2);
;             const char* a1 = cA + (size_t)(t + 1) * kstep;
;             const char* a2 = last ? nA : cA + (size_t)(t + 2) * kstep; const char* b2 = last ? nB : cB + (size_t)(t + 2) * kstep;
;             const char* a3 = a2 + kstep; const char* b3 = b2 + kstep;
;             if (last && has_next) S.a_ready(nxt);
;             if constexpr (SP2) {
;             PG8_LDB(B0, 0, 0); PG8_LDB(B1, 0, 1); PG8_SCHED; PG8_LDA(At, 0, 0); PG8_STAGE(PG8_SA(1, 1), a1 + hstep, voffA);
;             PG8_WAIT_V(8); PG8_WAIT_L(0); PG8_BAR; PG8_MMA(0, 0, At, B0); PG8_MMA(0, 1, At, B1); PG8_BAR; PG8_SCHED;
;             PG8_LDA(At, 0, 1); PG8_STAGE(PG8_SB(0, 0), b2, voffB); PG8_STAGE(PG8_SB(0, 1), b2 + hstep, voffB); PG8_STAGE(PG8_SA(0, 0), a2, voffA);
;             PG8_WAIT_V(8); PG8_WAIT_L(0); PG8_BAR; PG8_MMA(1, 0, At, B0); PG8_MMA(1, 1, At, B1); PG8_BAR; PG8_SCHED;
;             PG8_LDB(B0, 1, 0); PG8_LDB(B1, 1, 1); PG8_SCHED; PG8_LDA(At, 1, 0); PG8_STAGE(PG8_SA(0, 1), a2 + hstep, voffA);
;             PG8_WAIT_V(8); PG8_WAIT_L(0); PG8_BAR; PG8_MMA(0, 0, At, B0); PG8_MMA(0, 1, At, B1); PG8_BAR; PG8_SCHED;
;             PG8_LDA(At, 1, 1); PG8_STAGE(PG8_SB(1, 0), b3, voffB); PG8_STAGE(PG8_SB(1, 1), b3 + hstep, voffB); PG8_STAGE(PG8_SA(1, 0), a3, voffA);
;             PG8_WAIT_V(8); PG8_WAIT_L(0); PG8_BAR; PG8_MMA(1, 0, At, B0); PG8_MMA(1, 1, At, B1); PG8_BAR; PG8_SCHED;
	s_waitcnt lgkmcnt(0)
	v_mfma_i32_16x16x64_i8 v[136:139], v[60:63], v[184:187], v[136:139]
	v_mfma_i32_16x16x64_i8 v[136:139], v[68:71], v[188:191], v[136:139]
	v_mfma_i32_16x16x64_i8 v[120:123], v[68:71], v[208:211], v[120:123]
	v_mfma_i32_16x16x64_i8 v[120:123], v[60:63], v[204:207], v[120:123]
	v_mfma_i32_16x16x64_i8 v[104:107], v[60:63], v[212:215], v[104:107]
	v_mfma_i32_16x16x64_i8 v[104:107], v[68:71], v[216:219], v[104:107]
	v_mfma_i32_16x16x64_i8 v[88:91], v[68:71], v[224:227], v[88:91]
	v_mfma_i32_16x16x64_i8 v[88:91], v[60:63], v[220:223], v[88:91]
	v_mfma_i32_16x16x64_i8 v[80:83], v[140:143], v[220:223], v[80:83]
	v_mfma_i32_16x16x64_i8 v[80:83], v[144:147], v[224:227], v[80:83]
	v_mfma_i32_16x16x64_i8 v[96:99], v[144:147], v[216:219], v[96:99]
	v_mfma_i32_16x16x64_i8 v[96:99], v[140:143], v[212:215], v[96:99]
	v_mfma_i32_16x16x64_i8 v[112:115], v[140:143], v[204:207], v[112:115]
	v_mfma_i32_16x16x64_i8 v[112:115], v[144:147], v[208:211], v[112:115]
	v_mfma_i32_16x16x64_i8 v[128:131], v[144:147], v[188:191], v[128:131]
	v_mfma_i32_16x16x64_i8 v[128:131], v[140:143], v[184:187], v[128:131]
	v_mfma_i32_16x16x64_i8 v[132:135], v[160:163], v[184:187], v[132:135]
	v_mfma_i32_16x16x64_i8 v[132:135], v[172:175], v[188:191], v[132:135]
	v_mfma_i32_16x16x64_i8 v[116:119], v[172:175], v[208:211], v[116:119]
	v_mfma_i32_16x16x64_i8 v[116:119], v[160:163], v[204:207], v[116:119]
	v_mfma_i32_16x16x64_i8 v[100:103], v[160:163], v[212:215], v[100:103]
	v_mfma_i32_16x16x64_i8 v[100:103], v[172:175], v[216:219], v[100:103]
	v_mfma_i32_16x16x64_i8 v[84:87], v[172:175], v[224:227], v[84:87]
	v_mfma_i32_16x16x64_i8 v[84:87], v[160:163], v[220:223], v[84:87]
	v_mfma_i32_16x16x64_i8 v[76:79], v[176:179], v[220:223], v[76:79]
	v_mfma_i32_16x16x64_i8 v[76:79], v[180:183], v[224:227], v[76:79]
	v_mfma_i32_16x16x64_i8 v[92:95], v[180:183], v[216:219], v[92:95]
	v_mfma_i32_16x16x64_i8 v[92:95], v[176:179], v[212:215], v[92:95]
	v_mfma_i32_16x16x64_i8 v[108:111], v[176:179], v[204:207], v[108:111]
	v_mfma_i32_16x16x64_i8 v[108:111], v[180:183], v[208:211], v[108:111]
	v_mfma_i32_16x16x64_i8 v[124:127], v[180:183], v[188:191], v[124:127]
	v_mfma_i32_16x16x64_i8 v[124:127], v[176:179], v[184:187], v[124:127]
	s_barrier
	s_setprio 0
	s_add_i32 s48, s64, s47
	v_lshl_add_u64 v[164:165], v[164:165], 0, s[84:85]
	s_mov_b32 m0, s48
	ds_read_b128 v[184:187], v171 offset:49152
	ds_read_b128 v[188:191], v171 offset:50176
	ds_read_b128 v[204:207], v171 offset:51200
	ds_read_b128 v[208:211], v171 offset:52224
	ds_read_b128 v[212:215], v171 offset:53248
	ds_read_b128 v[216:219], v171 offset:54272
	ds_read_b128 v[220:223], v171 offset:55296
	ds_read_b128 v[224:227], v171 offset:56320
	global_load_lds_dwordx4 v[164:165], off
	s_add_i32 m0, s48, 0x2000
	s_add_u32 s44, s44, 0x80080
	v_lshl_add_u64 v[164:165], v[228:229], 0, s[84:85]
	s_addc_u32 s45, s45, 0
	s_add_i32 s48, s65, s47
	global_load_lds_dwordx4 v[164:165], off
	s_mov_b32 m0, s48
	s_nop 0
	global_load_lds_dwordx4 v2, s[44:45]
	s_add_i32 m0, s48, 0x2000
	s_nop 0
	global_load_lds_dwordx4 v148, s[44:45]
	s_cmp_eq_u32 s61, 28
	s_cbranch_scc0 .Ldefer_1591_body
	v_lshl_add_u64 v[164:165], v[240:241], 0, s[84:85]
	s_mov_b32 m0, s54
	s_nop 0
	global_load_lds_dwordx4 v[164:165], off
	v_lshl_add_u64 v[164:165], v[242:243], 0, s[84:85]
	s_mov_b32 m0, s55
	s_nop 0
	global_load_lds_dwordx4 v[164:165], off
.Ldefer_1591_body:
	s_waitcnt vmcnt(6)
	s_waitcnt lgkmcnt(0)
	s_setprio 1
	s_barrier
	s_waitcnt lgkmcnt(0)
	v_mfma_i32_16x16x64_i8 v[72:75], v[60:63], v[184:187], v[72:75]
	v_mfma_i32_16x16x64_i8 v[72:75], v[68:71], v[188:191], v[72:75]
	v_mfma_i32_16x16x64_i8 v[56:59], v[68:71], v[208:211], v[56:59]
	v_mfma_i32_16x16x64_i8 v[56:59], v[60:63], v[204:207], v[56:59]
	v_mfma_i32_16x16x64_i8 v[32:35], v[60:63], v[212:215], v[32:35]
	v_mfma_i32_16x16x64_i8 v[32:35], v[68:71], v[216:219], v[32:35]
	v_mfma_i32_16x16x64_i8 v[16:19], v[68:71], v[224:227], v[16:19]
	v_mfma_i32_16x16x64_i8 v[16:19], v[60:63], v[220:223], v[16:19]
	v_mfma_i32_16x16x64_i8 v[8:11], v[140:143], v[220:223], v[8:11]
	v_mfma_i32_16x16x64_i8 v[8:11], v[144:147], v[224:227], v[8:11]
	v_mfma_i32_16x16x64_i8 v[24:27], v[144:147], v[216:219], v[24:27]
	v_mfma_i32_16x16x64_i8 v[24:27], v[140:143], v[212:215], v[24:27]
	v_mfma_i32_16x16x64_i8 v[48:51], v[140:143], v[204:207], v[48:51]
	v_mfma_i32_16x16x64_i8 v[48:51], v[144:147], v[208:211], v[48:51]
	v_mfma_i32_16x16x64_i8 v[64:67], v[144:147], v[188:191], v[64:67]
	v_mfma_i32_16x16x64_i8 v[64:67], v[140:143], v[184:187], v[64:67]
	v_mfma_i32_16x16x64_i8 v[36:39], v[160:163], v[184:187], v[36:39]
	v_mfma_i32_16x16x64_i8 v[68:71], v[172:175], v[188:191], v[36:39]
	v_mfma_i32_16x16x64_i8 v[36:39], v[172:175], v[208:211], v[52:55]
	v_mfma_i32_16x16x64_i8 v[52:55], v[160:163], v[204:207], v[36:39]
	v_mfma_i32_16x16x64_i8 v[28:31], v[160:163], v[212:215], v[28:31]
	v_mfma_i32_16x16x64_i8 v[28:31], v[172:175], v[216:219], v[28:31]
	v_mfma_i32_16x16x64_i8 v[12:15], v[172:175], v[224:227], v[12:15]
	v_mfma_i32_16x16x64_i8 v[12:15], v[160:163], v[220:223], v[12:15]
	v_mfma_i32_16x16x64_i8 v[4:7], v[176:179], v[220:223], v[4:7]
	v_mfma_i32_16x16x64_i8 v[4:7], v[180:183], v[224:227], v[4:7]
	v_mfma_i32_16x16x64_i8 v[20:23], v[180:183], v[216:219], v[20:23]
	v_mfma_i32_16x16x64_i8 v[20:23], v[176:179], v[212:215], v[20:23]
	v_mfma_i32_16x16x64_i8 v[36:39], v[176:179], v[204:207], v[40:43]
	v_mfma_i32_16x16x64_i8 v[40:43], v[180:183], v[208:211], v[36:39]
	v_mfma_i32_16x16x64_i8 v[36:39], v[180:183], v[188:191], v[44:47]
	v_mfma_i32_16x16x64_i8 v[60:63], v[176:179], v[184:187], v[36:39]
	s_barrier
	s_setprio 0
	s_add_i32 s61, s61, 2
	s_add_u32 s40, s40, 0x100
	s_addc_u32 s41, s41, 0
	s_add_u32 s59, s59, 0x100
	s_addc_u32 s60, s60, 0
	s_cmp_gt_u32 s61, 29
	s_cbranch_scc0 .LBB0_1591

; #define PG8_STAGE(bufoff, gbase, voff) do { _Pragma("unroll") for (int _i = 0; _i < 2; ++_i) \
;         __builtin_amdgcn_global_load_lds((const unsigned*)((const char*)(gbase) + (voff)[_i]), (PG8_LAS unsigned*)(lds + (bufoff) + ldsw + _i * 8192), 16, 0, 0); } while (0)
; #define PG8_LDA(dst, b, h) do { _Pragma("unroll") for (int m = 0; m < 4; ++m) _Pragma("unroll") for (int k = 0; k < 2; ++k) dst[m][k] = *(const PG8_LAS bf16x8*)(lds + PG8_SA(b, h) + aoff + m * 2048 + k * 1024); } while (0)
; #define PG8_LDB(dst, b, h) do { _Pragma("unroll") for (int n = 0; n < 2; ++n) _Pragma("unroll") for (int k = 0; k < 2; ++k) dst[n][k] = *(const PG8_LAS bf16x8*)(lds + PG8_SB(b, h) + boff + n * 2048 + k * 1024); } while (0)
; #define PG8_WAIT_V(n) asm volatile("s_waitcnt vmcnt(" #n ")" ::: "memory")
; #define PG8_WAIT_L(n) asm volatile("s_waitcnt lgkmcnt(" #n ")" ::: "memory")
; #define PG8_BAR __builtin_amdgcn_s_barrier()
; #define PG8_SCHED __builtin_amdgcn_sched_barrier(0)
; template <class Epi, class Sched, bool ALIGN_EPI = false, bool SP2 = false, bool I8 = false>
; __device__ __forceinline__ void gemm_phase(PG8_LAS unsigned char* lds, const Gemm g, const Sched& S, const Epi& E) {
;     ...
;         const bool has_next = S.next(ui + 1, nxt);
;         const char* nA = has_next ? (const char*)g.A + (size_t)nxt.pm * tstep : cA; const char* nB = has_next ? (const char*)g.Bt + (size_t)nxt.pn * tstep : cB;
;         for (int t = 0; t < nt; t += 2) {
;             const bool last = (t == nt - 2);
;             const char* a1 = cA + (size_t)(t + 1) * kstep;
;             const char* a2 = last ? nA : cA + (size_t)(t + 2) * kstep; const char* b2 = last ? nB : cB + (size_t)(t + 2) * kstep;
;             const char* a3 = a2 + kstep; const char* b3 = b2 + kstep;
;             if (last && has_next) S.a_ready(nxt);
;             if constexpr (SP2) {
;             PG8_LDB(B0, 0, 0); PG8_LDB(B1, 0, 1); PG8_SCHED; PG8_LDA(At, 0, 0); PG8_STAGE(PG8_SA(1, 1), a1 + hstep, voffA);
;             PG8_WAIT_V(8); PG8_WAIT_L(0); PG8_BAR; PG8_MMA(0, 0, At, B0); PG8_MMA(0, 1, At, B1); PG8_BAR; PG8_SCHED;
;     ...
; #pragma unroll
;         for (int a = 0; a < 2; ++a)
; #pragma unroll
;             for (int b = 0; b < 2; ++b)
; #pragma unroll
;                 for (int m = 0; m < 4; ++m)
; #pragma unroll
;                     for (int n = 0; n < 2; ++n) acc[a][b][m][n] = (acc_t){0, 0, 0, 0};
.LBB0_1621:
	v_mov_b32_e32 v127, 0
	s_andn2_b64 vcc, exec, s[26:27]
	v_mov_b32_e32 v126, v127
	v_mov_b32_e32 v125, v127
	v_mov_b32_e32 v124, v127
	v_mov_b32_e32 v131, v127
	v_mov_b32_e32 v130, v127
	v_mov_b32_e32 v129, v127
	v_mov_b32_e32 v128, v127
	v_mov_b32_e32 v115, v127
	v_mov_b32_e32 v114, v127
	v_mov_b32_e32 v113, v127
	v_mov_b32_e32 v112, v127
	v_mov_b32_e32 v111, v127
	v_mov_b32_e32 v110, v127
	v_mov_b32_e32 v109, v127
	v_mov_b32_e32 v108, v127
	v_mov_b32_e32 v99, v127
	v_mov_b32_e32 v98, v127
	v_mov_b32_e32 v97, v127
	v_mov_b32_e32 v96, v127
	v_mov_b32_e32 v95, v127
	v_mov_b32_e32 v94, v127
	v_mov_b32_e32 v93, v127
	v_mov_b32_e32 v92, v127
	v_mov_b32_e32 v83, v127
	v_mov_b32_e32 v82, v127
	v_mov_b32_e32 v81, v127
	v_mov_b32_e32 v80, v127
	v_mov_b32_e32 v79, v127
	v_mov_b32_e32 v78, v127
	v_mov_b32_e32 v77, v127
	v_mov_b32_e32 v76, v127
	v_mov_b32_e32 v123, v127
	v_mov_b32_e32 v122, v127
	v_mov_b32_e32 v121, v127
	v_mov_b32_e32 v120, v127
	v_mov_b32_e32 v119, v127
	v_mov_b32_e32 v118, v127
	v_mov_b32_e32 v117, v127
	v_mov_b32_e32 v116, v127
	v_mov_b32_e32 v107, v127
	v_mov_b32_e32 v106, v127
	v_mov_b32_e32 v105, v127
	v_mov_b32_e32 v104, v127
	v_mov_b32_e32 v103, v127
	v_mov_b32_e32 v102, v127
	v_mov_b32_e32 v101, v127
	v_mov_b32_e32 v100, v127
	v_mov_b32_e32 v91, v127
	v_mov_b32_e32 v90, v127
	v_mov_b32_e32 v89, v127
	v_mov_b32_e32 v88, v127
	v_mov_b32_e32 v87, v127
	v_mov_b32_e32 v86, v127
	v_mov_b32_e32 v85, v127
	v_mov_b32_e32 v84, v127
	v_mov_b32_e32 v75, v127
	v_mov_b32_e32 v74, v127
	v_mov_b32_e32 v73, v127
	v_mov_b32_e32 v72, v127
	v_mov_b32_e32 v71, v127
	v_mov_b32_e32 v70, v127
	v_mov_b32_e32 v69, v127
	v_mov_b32_e32 v68, v127
	v_mov_b32_e32 v67, v127
	v_mov_b32_e32 v66, v127
	v_mov_b32_e32 v65, v127
	v_mov_b32_e32 v64, v127
	v_mov_b32_e32 v63, v127
	v_mov_b32_e32 v62, v127
	v_mov_b32_e32 v61, v127
	v_mov_b32_e32 v60, v127
	v_mov_b32_e32 v51, v127
	v_mov_b32_e32 v50, v127
	v_mov_b32_e32 v49, v127
	v_mov_b32_e32 v48, v127
	v_mov_b32_e32 v47, v127
	v_mov_b32_e32 v46, v127
	v_mov_b32_e32 v45, v127
	v_mov_b32_e32 v44, v127
	v_mov_b32_e32 v35, v127
	v_mov_b32_e32 v34, v127
	v_mov_b32_e32 v33, v127
	v_mov_b32_e32 v32, v127
	v_mov_b32_e32 v31, v127
	v_mov_b32_e32 v30, v127
	v_mov_b32_e32 v29, v127
	v_mov_b32_e32 v28, v127
	v_mov_b32_e32 v19, v127
	v_mov_b32_e32 v18, v127
	v_mov_b32_e32 v17, v127
	v_mov_b32_e32 v16, v127
	v_mov_b32_e32 v15, v127
	v_mov_b32_e32 v14, v127
	v_mov_b32_e32 v13, v127
	v_mov_b32_e32 v12, v127
	v_mov_b32_e32 v59, v127
	v_mov_b32_e32 v58, v127
	v_mov_b32_e32 v57, v127
	v_mov_b32_e32 v56, v127
	v_mov_b32_e32 v55, v127
	v_mov_b32_e32 v54, v127
	v_mov_b32_e32 v53, v127
	v_mov_b32_e32 v52, v127
	v_mov_b32_e32 v43, v127
	v_mov_b32_e32 v42, v127
	v_mov_b32_e32 v41, v127
	v_mov_b32_e32 v40, v127
	v_mov_b32_e32 v39, v127
	v_mov_b32_e32 v38, v127
	v_mov_b32_e32 v37, v127
	v_mov_b32_e32 v36, v127
	v_mov_b32_e32 v27, v127
	v_mov_b32_e32 v26, v127
	v_mov_b32_e32 v25, v127
	v_mov_b32_e32 v24, v127
	v_mov_b32_e32 v23, v127
	v_mov_b32_e32 v22, v127
	v_mov_b32_e32 v21, v127
	v_mov_b32_e32 v20, v127
	v_mov_b32_e32 v11, v127
	v_mov_b32_e32 v10, v127
	v_mov_b32_e32 v9, v127
	v_mov_b32_e32 v8, v127
	v_mov_b32_e32 v7, v127
	v_mov_b32_e32 v6, v127
	v_mov_b32_e32 v5, v127
	v_mov_b32_e32 v4, v127
	s_cbranch_vccnz .LBB0_1625
	s_add_u32 s44, s44, 0x80
	s_addc_u32 s45, s45, 0
	s_add_u32 s65, s48, 0x100
	s_addc_u32 s67, s49, 0
	s_mov_b32 s48, 0
	s_add_i32 s72, s48, 2
	s_add_u32 s73, s44, 0x80
	s_addc_u32 s49, s45, 0
	s_add_i32 s86, 0, 0x10000
	s_cmp_eq_u32 s57, s48
	s_cselect_b32 s49, s13, s49
	s_cselect_b32 s48, s12, s73
	s_cselect_b32 s77, s41, s67
	s_cselect_b32 s76, s40, s65
	s_add_i32 s73, 0, 0x14000
	v_add_u32_e32 v158, s86, v143
	v_add_u32_e32 v174, s73, v143
	ds_read_b128 v[146:149], v158
	ds_read_b128 v[150:153], v158 offset:1024
	ds_read_b128 v[154:157], v158 offset:2048
	ds_read_b128 v[158:161], v158 offset:3072
	ds_read_b128 v[162:165], v174
	ds_read_b128 v[166:169], v174 offset:1024
	ds_read_b128 v[170:173], v174 offset:2048
	ds_read_b128 v[174:177], v174 offset:3072
	v_lshl_add_u64 v[190:191], s[44:45], 0, v[138:139]
	s_add_i32 m0, s47, 0xc000
	ds_read_b128 v[178:181], v145
	ds_read_b128 v[182:185], v145 offset:1024
	ds_read_b128 v[186:189], v145 offset:2048
	ds_read_b128 v[204:207], v145 offset:3072
	ds_read_b128 v[208:211], v145 offset:4096
	ds_read_b128 v[212:215], v145 offset:5120
	ds_read_b128 v[216:219], v145 offset:6144
	ds_read_b128 v[220:223], v145 offset:7168
	global_load_lds_dwordx4 v[190:191], off
	v_lshl_add_u64 v[190:191], s[44:45], 0, v[140:141]
	s_add_i32 m0, s47, 0xe000
	s_nop 0
	global_load_lds_dwordx4 v[190:191], off
	s_waitcnt vmcnt(8)
	s_waitcnt lgkmcnt(0)
	s_setprio 1
	s_barrier
; #define PG8_STAGE(bufoff, gbase, voff) do { _Pragma("unroll") for (int _i = 0; _i < 2; ++_i) \
;         __builtin_amdgcn_global_load_lds((const unsigned*)((const char*)(gbase) + (voff)[_i]), (PG8_LAS unsigned*)(lds + (bufoff) + ldsw + _i * 8192), 16, 0, 0); } while (0)
; #define PG8_LDA(dst, b, h) do { _Pragma("unroll") for (int m = 0; m < 4; ++m) _Pragma("unroll") for (int k = 0; k < 2; ++k) dst[m][k] = *(const PG8_LAS bf16x8*)(lds + PG8_SA(b, h) + aoff + m * 2048 + k * 1024); } while (0)
; #define PG8_LDB(dst, b, h) do { _Pragma("unroll") for (int n = 0; n < 2; ++n) _Pragma("unroll") for (int k = 0; k < 2; ++k) dst[n][k] = *(const PG8_LAS bf16x8*)(lds + PG8_SB(b, h) + boff + n * 2048 + k * 1024); } while (0)
; #define PG8_WAIT_V(n) asm volatile("s_waitcnt vmcnt(" #n ")" ::: "memory")
; #define PG8_WAIT_L(n) asm volatile("s_waitcnt lgkmcnt(" #n ")" ::: "memory")
; #define PG8_BAR __builtin_amdgcn_s_barrier()
; #define PG8_SCHED __builtin_amdgcn_sched_barrier(0)
; template <class Epi, class Sched, bool ALIGN_EPI = false, bool SP2 = false, bool I8 = false>
; __device__ __forceinline__ void gemm_phase(PG8_LAS unsigned char* lds, const Gemm g, const Sched& S, const Epi& E) {
;     ...
;             if constexpr (SP2) {
;             PG8_LDB(B0, 0, 0); PG8_LDB(B1, 0, 1); PG8_SCHED; PG8_LDA(At, 0, 0); PG8_STAGE(PG8_SA(1, 1), a1 + hstep, voffA);
;             PG8_WAIT_V(8); PG8_WAIT_L(0); PG8_BAR; PG8_MMA(0, 0, At, B0); PG8_MMA(0, 1, At, B1); PG8_BAR; PG8_SCHED;
;             PG8_LDA(At, 0, 1); PG8_STAGE(PG8_SB(0, 0), b2, voffB); PG8_STAGE(PG8_SB(0, 1), b2 + hstep, voffB); PG8_STAGE(PG8_SA(0, 0), a2, voffA);
;             PG8_WAIT_V(8); PG8_WAIT_L(0); PG8_BAR; PG8_MMA(1, 0, At, B0); PG8_MMA(1, 1, At, B1); PG8_BAR; PG8_SCHED;
;             PG8_LDB(B0, 1, 0); PG8_LDB(B1, 1, 1); PG8_SCHED; PG8_LDA(At, 1, 0); PG8_STAGE(PG8_SA(0, 1), a2 + hstep, voffA);
;             PG8_WAIT_V(8); PG8_WAIT_L(0); PG8_BAR; PG8_MMA(0, 0, At, B0); PG8_MMA(0, 1, At, B1); PG8_BAR; PG8_SCHED;
;             PG8_LDA(At, 1, 1); PG8_STAGE(PG8_SB(1, 0), b3, voffB); PG8_STAGE(PG8_SB(1, 1), b3 + hstep, voffB); PG8_STAGE(PG8_SA(1, 0), a3, voffA);
;             PG8_WAIT_V(8); PG8_WAIT_L(0); PG8_BAR; PG8_MMA(1, 0, At, B0); PG8_MMA(1, 1, At, B1); PG8_BAR; PG8_SCHED;
	s_waitcnt lgkmcnt(0)
	v_mfma_f32_16x16x32_bf16 v[124:127], v[146:149], v[178:181], 0
	v_mfma_f32_16x16x32_bf16 v[124:127], v[150:153], v[182:185], v[124:127]
	v_mfma_f32_16x16x32_bf16 v[112:115], v[150:153], v[204:207], 0
	v_mfma_f32_16x16x32_bf16 v[112:115], v[146:149], v[186:189], v[112:115]
	v_mfma_f32_16x16x32_bf16 v[96:99], v[146:149], v[208:211], 0
	v_mfma_f32_16x16x32_bf16 v[96:99], v[150:153], v[212:215], v[96:99]
	v_mfma_f32_16x16x32_bf16 v[80:83], v[150:153], v[220:223], 0
	v_mfma_f32_16x16x32_bf16 v[80:83], v[146:149], v[216:219], v[80:83]
	v_mfma_f32_16x16x32_bf16 v[76:79], v[154:157], v[216:219], 0
	v_mfma_f32_16x16x32_bf16 v[76:79], v[158:161], v[220:223], v[76:79]
	v_mfma_f32_16x16x32_bf16 v[92:95], v[158:161], v[212:215], 0
	v_mfma_f32_16x16x32_bf16 v[92:95], v[154:157], v[208:211], v[92:95]
	v_mfma_f32_16x16x32_bf16 v[108:111], v[154:157], v[186:189], 0
	v_mfma_f32_16x16x32_bf16 v[108:111], v[158:161], v[204:207], v[108:111]
	v_mfma_f32_16x16x32_bf16 v[128:131], v[158:161], v[182:185], 0
	v_mfma_f32_16x16x32_bf16 v[128:131], v[154:157], v[178:181], v[128:131]
	v_mfma_f32_16x16x32_bf16 v[120:123], v[162:165], v[178:181], 0
	v_mfma_f32_16x16x32_bf16 v[120:123], v[166:169], v[182:185], v[120:123]
	v_mfma_f32_16x16x32_bf16 v[104:107], v[166:169], v[204:207], 0
	v_mfma_f32_16x16x32_bf16 v[104:107], v[162:165], v[186:189], v[104:107]
	v_mfma_f32_16x16x32_bf16 v[88:91], v[162:165], v[208:211], 0
	v_mfma_f32_16x16x32_bf16 v[88:91], v[166:169], v[212:215], v[88:91]
	v_mfma_f32_16x16x32_bf16 v[72:75], v[166:169], v[220:223], 0
	v_mfma_f32_16x16x32_bf16 v[72:75], v[162:165], v[216:219], v[72:75]
	v_mfma_f32_16x16x32_bf16 v[68:71], v[170:173], v[216:219], 0
	v_mfma_f32_16x16x32_bf16 v[68:71], v[174:177], v[220:223], v[68:71]
	v_mfma_f32_16x16x32_bf16 v[84:87], v[174:177], v[212:215], 0
	v_mfma_f32_16x16x32_bf16 v[84:87], v[170:173], v[208:211], v[84:87]
	v_mfma_f32_16x16x32_bf16 v[100:103], v[170:173], v[186:189], 0
	v_mfma_f32_16x16x32_bf16 v[100:103], v[174:177], v[204:207], v[100:103]
	v_mfma_f32_16x16x32_bf16 v[116:119], v[174:177], v[182:185], 0
	v_mfma_f32_16x16x32_bf16 v[116:119], v[170:173], v[178:181], v[116:119]
	s_barrier
	s_setprio 0
	s_add_i32 s86, s86, s28
	v_lshl_add_u64 v[190:191], s[76:77], 0, v[2:3]
	s_mov_b32 m0, s86
	ds_read_b128 v[178:181], v145 offset:16384
	ds_read_b128 v[182:185], v145 offset:17408
	ds_read_b128 v[186:189], v145 offset:18432
	ds_read_b128 v[204:207], v145 offset:19456
	ds_read_b128 v[208:211], v145 offset:20480
	ds_read_b128 v[212:215], v145 offset:21504
	ds_read_b128 v[216:219], v145 offset:22528
	ds_read_b128 v[220:223], v145 offset:23552
	global_load_lds_dwordx4 v[190:191], off
	s_add_i32 m0, s86, 0x2000
	v_lshl_add_u64 v[224:225], s[76:77], 0, v[136:137]
	s_add_u32 s76, s76, s18
	s_addc_u32 s77, s77, s19
	s_add_i32 s73, s73, s28
	global_load_lds_dwordx4 v[224:225], off
	v_lshl_add_u64 v[226:227], s[76:77], 0, v[2:3]
	s_mov_b32 m0, s73
	v_lshl_add_u64 v[228:229], s[76:77], 0, v[136:137]
	global_load_lds_dwordx4 v[226:227], off
	s_add_i32 m0, s73, 0x2000
	v_lshl_add_u64 v[240:241], s[48:49], 0, v[132:133]
	global_load_lds_dwordx4 v[228:229], off
	v_lshl_add_u64 v[242:243], s[48:49], 0, v[134:135]
	s_waitcnt vmcnt(6)
	s_waitcnt lgkmcnt(0)
	s_setprio 1
	s_barrier
	s_waitcnt lgkmcnt(0)
	v_mfma_f32_16x16x32_bf16 v[64:67], v[146:149], v[178:181], 0
	v_mfma_f32_16x16x32_bf16 v[64:67], v[150:153], v[182:185], v[64:67]
	v_mfma_f32_16x16x32_bf16 v[48:51], v[150:153], v[204:207], 0
	v_mfma_f32_16x16x32_bf16 v[48:51], v[146:149], v[186:189], v[48:51]
	v_mfma_f32_16x16x32_bf16 v[32:35], v[146:149], v[208:211], 0
	v_mfma_f32_16x16x32_bf16 v[32:35], v[150:153], v[212:215], v[32:35]
	v_mfma_f32_16x16x32_bf16 v[16:19], v[150:153], v[220:223], 0
	v_mfma_f32_16x16x32_bf16 v[16:19], v[146:149], v[216:219], v[16:19]
	v_mfma_f32_16x16x32_bf16 v[12:15], v[154:157], v[216:219], 0
	v_mfma_f32_16x16x32_bf16 v[12:15], v[158:161], v[220:223], v[12:15]
	v_mfma_f32_16x16x32_bf16 v[28:31], v[158:161], v[212:215], 0
	v_mfma_f32_16x16x32_bf16 v[28:31], v[154:157], v[208:211], v[28:31]
	v_mfma_f32_16x16x32_bf16 v[44:47], v[154:157], v[186:189], 0
	v_mfma_f32_16x16x32_bf16 v[44:47], v[158:161], v[204:207], v[44:47]
	v_mfma_f32_16x16x32_bf16 v[60:63], v[158:161], v[182:185], 0
	v_mfma_f32_16x16x32_bf16 v[60:63], v[154:157], v[178:181], v[60:63]
	v_mfma_f32_16x16x32_bf16 v[56:59], v[162:165], v[178:181], 0
	v_mfma_f32_16x16x32_bf16 v[56:59], v[166:169], v[182:185], v[56:59]
	v_mfma_f32_16x16x32_bf16 v[40:43], v[166:169], v[204:207], 0
	v_mfma_f32_16x16x32_bf16 v[40:43], v[162:165], v[186:189], v[40:43]
	v_mfma_f32_16x16x32_bf16 v[24:27], v[162:165], v[208:211], 0
	v_mfma_f32_16x16x32_bf16 v[24:27], v[166:169], v[212:215], v[24:27]
	v_mfma_f32_16x16x32_bf16 v[8:11], v[166:169], v[220:223], 0
	v_mfma_f32_16x16x32_bf16 v[8:11], v[162:165], v[216:219], v[8:11]
	v_mfma_f32_16x16x32_bf16 v[4:7], v[170:173], v[216:219], 0
	v_mfma_f32_16x16x32_bf16 v[4:7], v[174:177], v[220:223], v[4:7]
	v_mfma_f32_16x16x32_bf16 v[20:23], v[174:177], v[212:215], 0
	v_mfma_f32_16x16x32_bf16 v[20:23], v[170:173], v[208:211], v[20:23]
	v_mfma_f32_16x16x32_bf16 v[36:39], v[170:173], v[186:189], 0
	v_mfma_f32_16x16x32_bf16 v[36:39], v[174:177], v[204:207], v[36:39]
	v_mfma_f32_16x16x32_bf16 v[52:55], v[174:177], v[182:185], 0
	v_mfma_f32_16x16x32_bf16 v[52:55], v[170:173], v[178:181], v[52:55]
	s_barrier
; #define PG8_STAGE(bufoff, gbase, voff) do { _Pragma("unroll") for (int _i = 0; _i < 2; ++_i) \
;         __builtin_amdgcn_global_load_lds((const unsigned*)((const char*)(gbase) + (voff)[_i]), (PG8_LAS unsigned*)(lds + (bufoff) + ldsw + _i * 8192), 16, 0, 0); } while (0)
; #define PG8_LDA(dst, b, h) do { _Pragma("unroll") for (int m = 0; m < 4; ++m) _Pragma("unroll") for (int k = 0; k < 2; ++k) dst[m][k] = *(const PG8_LAS bf16x8*)(lds + PG8_SA(b, h) + aoff + m * 2048 + k * 1024); } while (0)
; #define PG8_LDB(dst, b, h) do { _Pragma("unroll") for (int n = 0; n < 2; ++n) _Pragma("unroll") for (int k = 0; k < 2; ++k) dst[n][k] = *(const PG8_LAS bf16x8*)(lds + PG8_SB(b, h) + boff + n * 2048 + k * 1024); } while (0)
; #define PG8_WAIT_V(n) asm volatile("s_waitcnt vmcnt(" #n ")" ::: "memory")
; #define PG8_WAIT_L(n) asm volatile("s_waitcnt lgkmcnt(" #n ")" ::: "memory")
; #define PG8_BAR __builtin_amdgcn_s_barrier()
; #define PG8_SCHED __builtin_amdgcn_sched_barrier(0)
; template <class Epi, class Sched, bool ALIGN_EPI = false, bool SP2 = false, bool I8 = false>
; __device__ __forceinline__ void gemm_phase(PG8_LAS unsigned char* lds, const Gemm g, const Sched& S, const Epi& E) {
;     ...
;             if constexpr (SP2) {
;             PG8_LDB(B0, 0, 0); PG8_LDB(B1, 0, 1); PG8_SCHED; PG8_LDA(At, 0, 0); PG8_STAGE(PG8_SA(1, 1), a1 + hstep, voffA);
;             PG8_WAIT_V(8); PG8_WAIT_L(0); PG8_BAR; PG8_MMA(0, 0, At, B0); PG8_MMA(0, 1, At, B1); PG8_BAR; PG8_SCHED;
;             PG8_LDA(At, 0, 1); PG8_STAGE(PG8_SB(0, 0), b2, voffB); PG8_STAGE(PG8_SB(0, 1), b2 + hstep, voffB); PG8_STAGE(PG8_SA(0, 0), a2, voffA);
;             PG8_WAIT_V(8); PG8_WAIT_L(0); PG8_BAR; PG8_MMA(1, 0, At, B0); PG8_MMA(1, 1, At, B1); PG8_BAR; PG8_SCHED;
;             PG8_LDB(B0, 1, 0); PG8_LDB(B1, 1, 1); PG8_SCHED; PG8_LDA(At, 1, 0); PG8_STAGE(PG8_SA(0, 1), a2 + hstep, voffA);
;             PG8_WAIT_V(8); PG8_WAIT_L(0); PG8_BAR; PG8_MMA(0, 0, At, B0); PG8_MMA(0, 1, At, B1); PG8_BAR; PG8_SCHED;
;             PG8_LDA(At, 1, 1); PG8_STAGE(PG8_SB(1, 0), b3, voffB); PG8_STAGE(PG8_SB(1, 1), b3 + hstep, voffB); PG8_STAGE(PG8_SA(1, 0), a3, voffA);
;             PG8_WAIT_V(8); PG8_WAIT_L(0); PG8_BAR; PG8_MMA(1, 0, At, B0); PG8_MMA(1, 1, At, B1); PG8_BAR; PG8_SCHED;
	s_setprio 0
	s_mov_b32 m0, s47
	s_nop 0
	global_load_lds_dwordx4 v[240:241], off
	s_mov_b32 m0, s50
	s_nop 0
	global_load_lds_dwordx4 v[242:243], off
	s_add_i32 s73, 0, 0x18000
	s_add_i32 s76, 0, 0x1c000
	v_add_u32_e32 v158, s73, v143
	v_add_u32_e32 v174, s76, v143
	ds_read_b128 v[146:149], v158
	ds_read_b128 v[150:153], v158 offset:1024
	ds_read_b128 v[154:157], v158 offset:2048
	ds_read_b128 v[158:161], v158 offset:3072
	ds_read_b128 v[162:165], v174
	ds_read_b128 v[166:169], v174 offset:1024
	ds_read_b128 v[170:173], v174 offset:2048
	ds_read_b128 v[174:177], v174 offset:3072
	s_add_u32 s48, s48, s18
	s_addc_u32 s49, s49, s19
	s_mov_b32 m0, s51
	ds_read_b128 v[178:181], v145 offset:32768
	ds_read_b128 v[182:185], v145 offset:33792
	ds_read_b128 v[186:189], v145 offset:34816
	ds_read_b128 v[204:207], v145 offset:35840
	ds_read_b128 v[208:211], v145 offset:36864
	ds_read_b128 v[212:215], v145 offset:37888
	ds_read_b128 v[216:219], v145 offset:38912
	ds_read_b128 v[220:223], v145 offset:39936
	global_load_lds_dwordx4 v132, s[48:49]
	s_mov_b32 m0, s52
	s_nop 0
	global_load_lds_dwordx4 v134, s[48:49]
	s_waitcnt vmcnt(8)
	s_waitcnt lgkmcnt(0)
	s_setprio 1
	s_barrier
	s_waitcnt lgkmcnt(0)
	v_mfma_f32_16x16x32_bf16 v[124:127], v[146:149], v[178:181], v[124:127]
	v_mfma_f32_16x16x32_bf16 v[124:127], v[150:153], v[182:185], v[124:127]
	v_mfma_f32_16x16x32_bf16 v[112:115], v[150:153], v[204:207], v[112:115]
	v_mfma_f32_16x16x32_bf16 v[112:115], v[146:149], v[186:189], v[112:115]
	v_mfma_f32_16x16x32_bf16 v[96:99], v[146:149], v[208:211], v[96:99]
	v_mfma_f32_16x16x32_bf16 v[96:99], v[150:153], v[212:215], v[96:99]
	v_mfma_f32_16x16x32_bf16 v[80:83], v[150:153], v[220:223], v[80:83]
	v_mfma_f32_16x16x32_bf16 v[80:83], v[146:149], v[216:219], v[80:83]
	v_mfma_f32_16x16x32_bf16 v[76:79], v[154:157], v[216:219], v[76:79]
	v_mfma_f32_16x16x32_bf16 v[76:79], v[158:161], v[220:223], v[76:79]
	v_mfma_f32_16x16x32_bf16 v[92:95], v[158:161], v[212:215], v[92:95]
	v_mfma_f32_16x16x32_bf16 v[92:95], v[154:157], v[208:211], v[92:95]
	v_mfma_f32_16x16x32_bf16 v[108:111], v[154:157], v[186:189], v[108:111]
	v_mfma_f32_16x16x32_bf16 v[108:111], v[158:161], v[204:207], v[108:111]
	v_mfma_f32_16x16x32_bf16 v[128:131], v[158:161], v[182:185], v[128:131]
	v_mfma_f32_16x16x32_bf16 v[128:131], v[154:157], v[178:181], v[128:131]
	v_mfma_f32_16x16x32_bf16 v[120:123], v[162:165], v[178:181], v[120:123]
	v_mfma_f32_16x16x32_bf16 v[120:123], v[166:169], v[182:185], v[120:123]
	v_mfma_f32_16x16x32_bf16 v[104:107], v[166:169], v[204:207], v[104:107]
	v_mfma_f32_16x16x32_bf16 v[104:107], v[162:165], v[186:189], v[104:107]
	v_mfma_f32_16x16x32_bf16 v[88:91], v[162:165], v[208:211], v[88:91]
	v_mfma_f32_16x16x32_bf16 v[88:91], v[166:169], v[212:215], v[88:91]
	v_mfma_f32_16x16x32_bf16 v[72:75], v[166:169], v[220:223], v[72:75]
	v_mfma_f32_16x16x32_bf16 v[72:75], v[162:165], v[216:219], v[72:75]
	v_mfma_f32_16x16x32_bf16 v[68:71], v[170:173], v[216:219], v[68:71]
	v_mfma_f32_16x16x32_bf16 v[68:71], v[174:177], v[220:223], v[68:71]
	v_mfma_f32_16x16x32_bf16 v[84:87], v[174:177], v[212:215], v[84:87]
	v_mfma_f32_16x16x32_bf16 v[84:87], v[170:173], v[208:211], v[84:87]
	v_mfma_f32_16x16x32_bf16 v[100:103], v[170:173], v[186:189], v[100:103]
	v_mfma_f32_16x16x32_bf16 v[100:103], v[174:177], v[204:207], v[100:103]
	v_mfma_f32_16x16x32_bf16 v[116:119], v[174:177], v[182:185], v[116:119]
	v_mfma_f32_16x16x32_bf16 v[116:119], v[170:173], v[178:181], v[116:119]
	s_barrier
	s_setprio 0
	s_add_i32 s48, s73, s28
	v_lshl_add_u64 v[190:191], v[190:191], 0, s[84:85]
	s_mov_b32 m0, s48
	ds_read_b128 v[178:181], v145 offset:49152
	ds_read_b128 v[182:185], v145 offset:50176
	ds_read_b128 v[186:189], v145 offset:51200
	ds_read_b128 v[204:207], v145 offset:52224
	ds_read_b128 v[208:211], v145 offset:53248
	ds_read_b128 v[212:215], v145 offset:54272
	ds_read_b128 v[216:219], v145 offset:55296
	ds_read_b128 v[220:223], v145 offset:56320
	global_load_lds_dwordx4 v[190:191], off
	v_lshl_add_u64 v[190:191], v[224:225], 0, s[84:85]
	s_add_i32 m0, s48, 0x2000
	s_add_i32 s48, s76, s28
	global_load_lds_dwordx4 v[190:191], off
	v_lshl_add_u64 v[190:191], v[226:227], 0, s[84:85]
	s_mov_b32 m0, s48
	s_nop 0
	global_load_lds_dwordx4 v[190:191], off
	v_lshl_add_u64 v[190:191], v[228:229], 0, s[84:85]
	s_add_i32 m0, s48, 0x2000
	s_nop 0
	global_load_lds_dwordx4 v[190:191], off
	v_lshl_add_u64 v[190:191], v[240:241], 0, s[84:85]
	s_mov_b32 m0, s55
	s_nop 0
	global_load_lds_dwordx4 v[190:191], off
	v_lshl_add_u64 v[190:191], v[242:243], 0, s[84:85]
	s_mov_b32 m0, s56
	s_nop 0
	global_load_lds_dwordx4 v[190:191], off
	s_waitcnt vmcnt(8)
	s_waitcnt lgkmcnt(0)
	s_setprio 1
	s_barrier
; #define PG8_STAGE(bufoff, gbase, voff) do { _Pragma("unroll") for (int _i = 0; _i < 2; ++_i) \
;         __builtin_amdgcn_global_load_lds((const unsigned*)((const char*)(gbase) + (voff)[_i]), (PG8_LAS unsigned*)(lds + (bufoff) + ldsw + _i * 8192), 16, 0, 0); } while (0)
; #define PG8_LDA(dst, b, h) do { _Pragma("unroll") for (int m = 0; m < 4; ++m) _Pragma("unroll") for (int k = 0; k < 2; ++k) dst[m][k] = *(const PG8_LAS bf16x8*)(lds + PG8_SA(b, h) + aoff + m * 2048 + k * 1024); } while (0)
; #define PG8_WAIT_V(n) asm volatile("s_waitcnt vmcnt(" #n ")" ::: "memory")
; #define PG8_WAIT_L(n) asm volatile("s_waitcnt lgkmcnt(" #n ")" ::: "memory")
; #define PG8_BAR __builtin_amdgcn_s_barrier()
; template <class Epi, class Sched, bool ALIGN_EPI = false, bool SP2 = false, bool I8 = false>
; __device__ __forceinline__ void gemm_phase(PG8_LAS unsigned char* lds, const Gemm g, const Sched& S, const Epi& E) {
;     ...
;         for (int t = 0; t < nt; t += 2) {
;             const bool last = (t == nt - 2);
;             const char* a1 = cA + (size_t)(t + 1) * kstep;
;             const char* a2 = last ? nA : cA + (size_t)(t + 2) * kstep; const char* b2 = last ? nB : cB + (size_t)(t + 2) * kstep;
;             const char* a3 = a2 + kstep; const char* b3 = b2 + kstep;
;             if (last && has_next) S.a_ready(nxt);
;             if constexpr (SP2) {
;             PG8_LDB(B0, 0, 0); PG8_LDB(B1, 0, 1); PG8_SCHED; PG8_LDA(At, 0, 0); PG8_STAGE(PG8_SA(1, 1), a1 + hstep, voffA);
;             PG8_WAIT_V(8); PG8_WAIT_L(0); PG8_BAR; PG8_MMA(0, 0, At, B0); PG8_MMA(0, 1, At, B1); PG8_BAR; PG8_SCHED;
;             PG8_LDA(At, 0, 1); PG8_STAGE(PG8_SB(0, 0), b2, voffB); PG8_STAGE(PG8_SB(0, 1), b2 + hstep, voffB); PG8_STAGE(PG8_SA(0, 0), a2, voffA);
;             PG8_WAIT_V(8); PG8_WAIT_L(0); PG8_BAR; PG8_MMA(1, 0, At, B0); PG8_MMA(1, 1, At, B1); PG8_BAR; PG8_SCHED;
;             PG8_LDB(B0, 1, 0); PG8_LDB(B1, 1, 1); PG8_SCHED; PG8_LDA(At, 1, 0); PG8_STAGE(PG8_SA(0, 1), a2 + hstep, voffA);
;             PG8_WAIT_V(8); PG8_WAIT_L(0); PG8_BAR; PG8_MMA(0, 0, At, B0); PG8_MMA(0, 1, At, B1); PG8_BAR; PG8_SCHED;
;             PG8_LDA(At, 1, 1); PG8_STAGE(PG8_SB(1, 0), b3, voffB); PG8_STAGE(PG8_SB(1, 1), b3 + hstep, voffB); PG8_STAGE(PG8_SA(1, 0), a3, voffA);
;             PG8_WAIT_V(8); PG8_WAIT_L(0); PG8_BAR; PG8_MMA(1, 0, At, B0); PG8_MMA(1, 1, At, B1); PG8_BAR; PG8_SCHED;
	s_waitcnt lgkmcnt(0)
	v_mfma_f32_16x16x32_bf16 v[64:67], v[146:149], v[178:181], v[64:67]
	v_mfma_f32_16x16x32_bf16 v[64:67], v[150:153], v[182:185], v[64:67]
	v_mfma_f32_16x16x32_bf16 v[48:51], v[150:153], v[204:207], v[48:51]
	v_mfma_f32_16x16x32_bf16 v[48:51], v[146:149], v[186:189], v[48:51]
	v_mfma_f32_16x16x32_bf16 v[32:35], v[146:149], v[208:211], v[32:35]
	v_mfma_f32_16x16x32_bf16 v[32:35], v[150:153], v[212:215], v[32:35]
	v_mfma_f32_16x16x32_bf16 v[16:19], v[150:153], v[220:223], v[16:19]
	v_mfma_f32_16x16x32_bf16 v[16:19], v[146:149], v[216:219], v[16:19]
	v_mfma_f32_16x16x32_bf16 v[12:15], v[154:157], v[216:219], v[12:15]
	v_mfma_f32_16x16x32_bf16 v[12:15], v[158:161], v[220:223], v[12:15]
	v_mfma_f32_16x16x32_bf16 v[28:31], v[158:161], v[212:215], v[28:31]
	v_mfma_f32_16x16x32_bf16 v[28:31], v[154:157], v[208:211], v[28:31]
	v_mfma_f32_16x16x32_bf16 v[44:47], v[154:157], v[186:189], v[44:47]
	v_mfma_f32_16x16x32_bf16 v[44:47], v[158:161], v[204:207], v[44:47]
	v_mfma_f32_16x16x32_bf16 v[60:63], v[158:161], v[182:185], v[60:63]
	v_mfma_f32_16x16x32_bf16 v[60:63], v[154:157], v[178:181], v[60:63]
	v_mfma_f32_16x16x32_bf16 v[56:59], v[162:165], v[178:181], v[56:59]
	v_mfma_f32_16x16x32_bf16 v[56:59], v[166:169], v[182:185], v[56:59]
	v_mfma_f32_16x16x32_bf16 v[40:43], v[166:169], v[204:207], v[40:43]
	v_mfma_f32_16x16x32_bf16 v[40:43], v[162:165], v[186:189], v[40:43]
	v_mfma_f32_16x16x32_bf16 v[24:27], v[162:165], v[208:211], v[24:27]
	v_mfma_f32_16x16x32_bf16 v[24:27], v[166:169], v[212:215], v[24:27]
	v_mfma_f32_16x16x32_bf16 v[8:11], v[166:169], v[220:223], v[8:11]
	v_mfma_f32_16x16x32_bf16 v[8:11], v[162:165], v[216:219], v[8:11]
	v_mfma_f32_16x16x32_bf16 v[4:7], v[170:173], v[216:219], v[4:7]
	v_mfma_f32_16x16x32_bf16 v[4:7], v[174:177], v[220:223], v[4:7]
	v_mfma_f32_16x16x32_bf16 v[20:23], v[174:177], v[212:215], v[20:23]
	v_mfma_f32_16x16x32_bf16 v[20:23], v[170:173], v[208:211], v[20:23]
	v_mfma_f32_16x16x32_bf16 v[36:39], v[170:173], v[186:189], v[36:39]
	v_mfma_f32_16x16x32_bf16 v[36:39], v[174:177], v[204:207], v[36:39]
	v_mfma_f32_16x16x32_bf16 v[52:55], v[174:177], v[182:185], v[52:55]
	v_mfma_f32_16x16x32_bf16 v[52:55], v[170:173], v[178:181], v[52:55]
	s_barrier
	s_setprio 0
	s_add_u32 s44, s44, 0x100
	s_addc_u32 s45, s45, 0
	s_add_u32 s65, s65, 0x100
	s_addc_u32 s67, s67, 0
	s_cmp_ge_i32 s72, s53
	s_mov_b32 s48, s72
	s_cbranch_scc1 .Lkloop_exit_4
.LBB0_1623:
	s_add_i32 s72, s48, 2
	s_add_u32 s73, s44, 0x80
	s_addc_u32 s49, s45, 0
	s_add_i32 s86, 0, 0x10000
	s_cmp_eq_u32 s57, s48
	s_cselect_b32 s49, s13, s49
	s_cselect_b32 s48, s12, s73
	s_cselect_b32 s77, s41, s67
	s_cselect_b32 s76, s40, s65
	s_add_i32 s73, 0, 0x14000
	v_add_u32_e32 v158, s86, v143
	v_add_u32_e32 v174, s73, v143
	ds_read_b128 v[146:149], v158
	ds_read_b128 v[150:153], v158 offset:1024
	ds_read_b128 v[154:157], v158 offset:2048
	ds_read_b128 v[158:161], v158 offset:3072
	ds_read_b128 v[162:165], v174
	ds_read_b128 v[166:169], v174 offset:1024
	ds_read_b128 v[170:173], v174 offset:2048
	ds_read_b128 v[174:177], v174 offset:3072
	v_lshl_add_u64 v[190:191], s[44:45], 0, v[138:139]
	s_add_i32 m0, s47, 0xc000
	ds_read_b128 v[178:181], v145
	ds_read_b128 v[182:185], v145 offset:1024
	ds_read_b128 v[186:189], v145 offset:2048
	ds_read_b128 v[204:207], v145 offset:3072
	ds_read_b128 v[208:211], v145 offset:4096
	ds_read_b128 v[212:215], v145 offset:5120
	ds_read_b128 v[216:219], v145 offset:6144
	ds_read_b128 v[220:223], v145 offset:7168
	global_load_lds_dwordx4 v[190:191], off
	v_lshl_add_u64 v[190:191], s[44:45], 0, v[140:141]
	s_add_i32 m0, s47, 0xe000
	s_nop 0
	global_load_lds_dwordx4 v[190:191], off
	s_waitcnt vmcnt(8)
	s_waitcnt lgkmcnt(0)
	s_setprio 1
	s_barrier
	s_waitcnt lgkmcnt(0)
	v_mfma_f32_16x16x32_bf16 v[124:127], v[146:149], v[178:181], v[124:127]
	v_mfma_f32_16x16x32_bf16 v[124:127], v[150:153], v[182:185], v[124:127]
	v_mfma_f32_16x16x32_bf16 v[112:115], v[150:153], v[204:207], v[112:115]
	v_mfma_f32_16x16x32_bf16 v[112:115], v[146:149], v[186:189], v[112:115]
	v_mfma_f32_16x16x32_bf16 v[96:99], v[146:149], v[208:211], v[96:99]
	v_mfma_f32_16x16x32_bf16 v[96:99], v[150:153], v[212:215], v[96:99]
	v_mfma_f32_16x16x32_bf16 v[80:83], v[150:153], v[220:223], v[80:83]
	v_mfma_f32_16x16x32_bf16 v[80:83], v[146:149], v[216:219], v[80:83]
	v_mfma_f32_16x16x32_bf16 v[76:79], v[154:157], v[216:219], v[76:79]
	v_mfma_f32_16x16x32_bf16 v[76:79], v[158:161], v[220:223], v[76:79]
	v_mfma_f32_16x16x32_bf16 v[92:95], v[158:161], v[212:215], v[92:95]
	v_mfma_f32_16x16x32_bf16 v[92:95], v[154:157], v[208:211], v[92:95]
	v_mfma_f32_16x16x32_bf16 v[108:111], v[154:157], v[186:189], v[108:111]
	v_mfma_f32_16x16x32_bf16 v[108:111], v[158:161], v[204:207], v[108:111]
	v_mfma_f32_16x16x32_bf16 v[128:131], v[158:161], v[182:185], v[128:131]
	v_mfma_f32_16x16x32_bf16 v[128:131], v[154:157], v[178:181], v[128:131]
	v_mfma_f32_16x16x32_bf16 v[120:123], v[162:165], v[178:181], v[120:123]
	v_mfma_f32_16x16x32_bf16 v[120:123], v[166:169], v[182:185], v[120:123]
	v_mfma_f32_16x16x32_bf16 v[104:107], v[166:169], v[204:207], v[104:107]
	v_mfma_f32_16x16x32_bf16 v[104:107], v[162:165], v[186:189], v[104:107]
	v_mfma_f32_16x16x32_bf16 v[88:91], v[162:165], v[208:211], v[88:91]
	v_mfma_f32_16x16x32_bf16 v[88:91], v[166:169], v[212:215], v[88:91]
	v_mfma_f32_16x16x32_bf16 v[72:75], v[166:169], v[220:223], v[72:75]
	v_mfma_f32_16x16x32_bf16 v[72:75], v[162:165], v[216:219], v[72:75]
	v_mfma_f32_16x16x32_bf16 v[68:71], v[170:173], v[216:219], v[68:71]
	v_mfma_f32_16x16x32_bf16 v[68:71], v[174:177], v[220:223], v[68:71]
	v_mfma_f32_16x16x32_bf16 v[84:87], v[174:177], v[212:215], v[84:87]
	v_mfma_f32_16x16x32_bf16 v[84:87], v[170:173], v[208:211], v[84:87]
	v_mfma_f32_16x16x32_bf16 v[100:103], v[170:173], v[186:189], v[100:103]
	v_mfma_f32_16x16x32_bf16 v[100:103], v[174:177], v[204:207], v[100:103]
	v_mfma_f32_16x16x32_bf16 v[116:119], v[174:177], v[182:185], v[116:119]
	v_mfma_f32_16x16x32_bf16 v[116:119], v[170:173], v[178:181], v[116:119]
	s_barrier
; #define PG8_STAGE(bufoff, gbase, voff) do { _Pragma("unroll") for (int _i = 0; _i < 2; ++_i) \
;         __builtin_amdgcn_global_load_lds((const unsigned*)((const char*)(gbase) + (voff)[_i]), (PG8_LAS unsigned*)(lds + (bufoff) + ldsw + _i * 8192), 16, 0, 0); } while (0)
; #define PG8_LDA(dst, b, h) do { _Pragma("unroll") for (int m = 0; m < 4; ++m) _Pragma("unroll") for (int k = 0; k < 2; ++k) dst[m][k] = *(const PG8_LAS bf16x8*)(lds + PG8_SA(b, h) + aoff + m * 2048 + k * 1024); } while (0)
; #define PG8_LDB(dst, b, h) do { _Pragma("unroll") for (int n = 0; n < 2; ++n) _Pragma("unroll") for (int k = 0; k < 2; ++k) dst[n][k] = *(const PG8_LAS bf16x8*)(lds + PG8_SB(b, h) + boff + n * 2048 + k * 1024); } while (0)
; #define PG8_WAIT_V(n) asm volatile("s_waitcnt vmcnt(" #n ")" ::: "memory")
; #define PG8_WAIT_L(n) asm volatile("s_waitcnt lgkmcnt(" #n ")" ::: "memory")
; #define PG8_BAR __builtin_amdgcn_s_barrier()
; #define PG8_SCHED __builtin_amdgcn_sched_barrier(0)
; template <class Epi, class Sched, bool ALIGN_EPI = false, bool SP2 = false, bool I8 = false>
; __device__ __forceinline__ void gemm_phase(PG8_LAS unsigned char* lds, const Gemm g, const Sched& S, const Epi& E) {
;     ...
;             if constexpr (SP2) {
;             PG8_LDB(B0, 0, 0); PG8_LDB(B1, 0, 1); PG8_SCHED; PG8_LDA(At, 0, 0); PG8_STAGE(PG8_SA(1, 1), a1 + hstep, voffA);
;             PG8_WAIT_V(8); PG8_WAIT_L(0); PG8_BAR; PG8_MMA(0, 0, At, B0); PG8_MMA(0, 1, At, B1); PG8_BAR; PG8_SCHED;
;             PG8_LDA(At, 0, 1); PG8_STAGE(PG8_SB(0, 0), b2, voffB); PG8_STAGE(PG8_SB(0, 1), b2 + hstep, voffB); PG8_STAGE(PG8_SA(0, 0), a2, voffA);
;             PG8_WAIT_V(8); PG8_WAIT_L(0); PG8_BAR; PG8_MMA(1, 0, At, B0); PG8_MMA(1, 1, At, B1); PG8_BAR; PG8_SCHED;
;             PG8_LDB(B0, 1, 0); PG8_LDB(B1, 1, 1); PG8_SCHED; PG8_LDA(At, 1, 0); PG8_STAGE(PG8_SA(0, 1), a2 + hstep, voffA);
;             PG8_WAIT_V(8); PG8_WAIT_L(0); PG8_BAR; PG8_MMA(0, 0, At, B0); PG8_MMA(0, 1, At, B1); PG8_BAR; PG8_SCHED;
;             PG8_LDA(At, 1, 1); PG8_STAGE(PG8_SB(1, 0), b3, voffB); PG8_STAGE(PG8_SB(1, 1), b3 + hstep, voffB); PG8_STAGE(PG8_SA(1, 0), a3, voffA);
;             PG8_WAIT_V(8); PG8_WAIT_L(0); PG8_BAR; PG8_MMA(1, 0, At, B0); PG8_MMA(1, 1, At, B1); PG8_BAR; PG8_SCHED;
	s_setprio 0
	s_add_i32 s86, s86, s28
	v_lshl_add_u64 v[190:191], s[76:77], 0, v[2:3]
	s_mov_b32 m0, s86
	ds_read_b128 v[178:181], v145 offset:16384
	ds_read_b128 v[182:185], v145 offset:17408
	ds_read_b128 v[186:189], v145 offset:18432
	ds_read_b128 v[204:207], v145 offset:19456
	ds_read_b128 v[208:211], v145 offset:20480
	ds_read_b128 v[212:215], v145 offset:21504
	ds_read_b128 v[216:219], v145 offset:22528
	ds_read_b128 v[220:223], v145 offset:23552
	global_load_lds_dwordx4 v[190:191], off
	s_add_i32 m0, s86, 0x2000
	v_lshl_add_u64 v[224:225], s[76:77], 0, v[136:137]
	s_add_u32 s76, s76, s18
	s_addc_u32 s77, s77, s19
	s_add_i32 s73, s73, s28
	global_load_lds_dwordx4 v[224:225], off
	v_lshl_add_u64 v[226:227], s[76:77], 0, v[2:3]
	s_mov_b32 m0, s73
	v_lshl_add_u64 v[228:229], s[76:77], 0, v[136:137]
	global_load_lds_dwordx4 v[226:227], off
	s_add_i32 m0, s73, 0x2000
	v_lshl_add_u64 v[240:241], s[48:49], 0, v[132:133]
	global_load_lds_dwordx4 v[228:229], off
	v_lshl_add_u64 v[242:243], s[48:49], 0, v[134:135]
	s_waitcnt vmcnt(6)
	s_waitcnt lgkmcnt(0)
	s_setprio 1
	s_barrier
	s_waitcnt lgkmcnt(0)
	v_mfma_f32_16x16x32_bf16 v[64:67], v[146:149], v[178:181], v[64:67]
	v_mfma_f32_16x16x32_bf16 v[64:67], v[150:153], v[182:185], v[64:67]
	v_mfma_f32_16x16x32_bf16 v[48:51], v[150:153], v[204:207], v[48:51]
	v_mfma_f32_16x16x32_bf16 v[48:51], v[146:149], v[186:189], v[48:51]
	v_mfma_f32_16x16x32_bf16 v[32:35], v[146:149], v[208:211], v[32:35]
	v_mfma_f32_16x16x32_bf16 v[32:35], v[150:153], v[212:215], v[32:35]
	v_mfma_f32_16x16x32_bf16 v[16:19], v[150:153], v[220:223], v[16:19]
	v_mfma_f32_16x16x32_bf16 v[16:19], v[146:149], v[216:219], v[16:19]
	v_mfma_f32_16x16x32_bf16 v[12:15], v[154:157], v[216:219], v[12:15]
	v_mfma_f32_16x16x32_bf16 v[12:15], v[158:161], v[220:223], v[12:15]
	v_mfma_f32_16x16x32_bf16 v[28:31], v[158:161], v[212:215], v[28:31]
	v_mfma_f32_16x16x32_bf16 v[28:31], v[154:157], v[208:211], v[28:31]
	v_mfma_f32_16x16x32_bf16 v[44:47], v[154:157], v[186:189], v[44:47]
	v_mfma_f32_16x16x32_bf16 v[44:47], v[158:161], v[204:207], v[44:47]
	v_mfma_f32_16x16x32_bf16 v[60:63], v[158:161], v[182:185], v[60:63]
	v_mfma_f32_16x16x32_bf16 v[60:63], v[154:157], v[178:181], v[60:63]
	v_mfma_f32_16x16x32_bf16 v[56:59], v[162:165], v[178:181], v[56:59]
	v_mfma_f32_16x16x32_bf16 v[56:59], v[166:169], v[182:185], v[56:59]
	v_mfma_f32_16x16x32_bf16 v[40:43], v[166:169], v[204:207], v[40:43]
	v_mfma_f32_16x16x32_bf16 v[40:43], v[162:165], v[186:189], v[40:43]
	v_mfma_f32_16x16x32_bf16 v[24:27], v[162:165], v[208:211], v[24:27]
	v_mfma_f32_16x16x32_bf16 v[24:27], v[166:169], v[212:215], v[24:27]
	v_mfma_f32_16x16x32_bf16 v[8:11], v[166:169], v[220:223], v[8:11]
	v_mfma_f32_16x16x32_bf16 v[8:11], v[162:165], v[216:219], v[8:11]
	v_mfma_f32_16x16x32_bf16 v[4:7], v[170:173], v[216:219], v[4:7]
	v_mfma_f32_16x16x32_bf16 v[4:7], v[174:177], v[220:223], v[4:7]
	v_mfma_f32_16x16x32_bf16 v[20:23], v[174:177], v[212:215], v[20:23]
	v_mfma_f32_16x16x32_bf16 v[20:23], v[170:173], v[208:211], v[20:23]
	v_mfma_f32_16x16x32_bf16 v[36:39], v[170:173], v[186:189], v[36:39]
	v_mfma_f32_16x16x32_bf16 v[36:39], v[174:177], v[204:207], v[36:39]
	v_mfma_f32_16x16x32_bf16 v[52:55], v[174:177], v[182:185], v[52:55]
	v_mfma_f32_16x16x32_bf16 v[52:55], v[170:173], v[178:181], v[52:55]
	s_barrier
	s_setprio 0
	s_mov_b32 m0, s47
	s_nop 0
	global_load_lds_dwordx4 v[240:241], off
	s_mov_b32 m0, s50
	s_nop 0
	global_load_lds_dwordx4 v[242:243], off
	s_add_i32 s73, 0, 0x18000
	s_add_i32 s76, 0, 0x1c000
	v_add_u32_e32 v158, s73, v143
	v_add_u32_e32 v174, s76, v143
	ds_read_b128 v[146:149], v158
	ds_read_b128 v[150:153], v158 offset:1024
	ds_read_b128 v[154:157], v158 offset:2048
	ds_read_b128 v[158:161], v158 offset:3072
	ds_read_b128 v[162:165], v174
	ds_read_b128 v[166:169], v174 offset:1024
	ds_read_b128 v[170:173], v174 offset:2048
	ds_read_b128 v[174:177], v174 offset:3072
	s_add_u32 s48, s48, s18
	s_addc_u32 s49, s49, s19
	s_mov_b32 m0, s51
	ds_read_b128 v[178:181], v145 offset:32768
	ds_read_b128 v[182:185], v145 offset:33792
	ds_read_b128 v[186:189], v145 offset:34816
	ds_read_b128 v[204:207], v145 offset:35840
	ds_read_b128 v[208:211], v145 offset:36864
	ds_read_b128 v[212:215], v145 offset:37888
	ds_read_b128 v[216:219], v145 offset:38912
	ds_read_b128 v[220:223], v145 offset:39936
	global_load_lds_dwordx4 v132, s[48:49]
	s_mov_b32 m0, s52
	s_nop 0
	global_load_lds_dwordx4 v134, s[48:49]
	s_waitcnt vmcnt(8)
	s_waitcnt lgkmcnt(0)
	s_setprio 1
	s_barrier
; #define PG8_STAGE(bufoff, gbase, voff) do { _Pragma("unroll") for (int _i = 0; _i < 2; ++_i) \
;         __builtin_amdgcn_global_load_lds((const unsigned*)((const char*)(gbase) + (voff)[_i]), (PG8_LAS unsigned*)(lds + (bufoff) + ldsw + _i * 8192), 16, 0, 0); } while (0)
; #define PG8_LDA(dst, b, h) do { _Pragma("unroll") for (int m = 0; m < 4; ++m) _Pragma("unroll") for (int k = 0; k < 2; ++k) dst[m][k] = *(const PG8_LAS bf16x8*)(lds + PG8_SA(b, h) + aoff + m * 2048 + k * 1024); } while (0)
; #define PG8_WAIT_V(n) asm volatile("s_waitcnt vmcnt(" #n ")" ::: "memory")
; #define PG8_WAIT_L(n) asm volatile("s_waitcnt lgkmcnt(" #n ")" ::: "memory")
; #define PG8_BAR __builtin_amdgcn_s_barrier()
; template <class Epi, class Sched, bool ALIGN_EPI = false, bool SP2 = false, bool I8 = false>
; __device__ __forceinline__ void gemm_phase(PG8_LAS unsigned char* lds, const Gemm g, const Sched& S, const Epi& E) {
;     ...
;         for (int t = 0; t < nt; t += 2) {
;             const bool last = (t == nt - 2);
;             const char* a1 = cA + (size_t)(t + 1) * kstep;
;             const char* a2 = last ? nA : cA + (size_t)(t + 2) * kstep; const char* b2 = last ? nB : cB + (size_t)(t + 2) * kstep;
;             const char* a3 = a2 + kstep; const char* b3 = b2 + kstep;
;             if (last && has_next) S.a_ready(nxt);
;             if constexpr (SP2) {
;             PG8_LDB(B0, 0, 0); PG8_LDB(B1, 0, 1); PG8_SCHED; PG8_LDA(At, 0, 0); PG8_STAGE(PG8_SA(1, 1), a1 + hstep, voffA);
;             PG8_WAIT_V(8); PG8_WAIT_L(0); PG8_BAR; PG8_MMA(0, 0, At, B0); PG8_MMA(0, 1, At, B1); PG8_BAR; PG8_SCHED;
;             PG8_LDA(At, 0, 1); PG8_STAGE(PG8_SB(0, 0), b2, voffB); PG8_STAGE(PG8_SB(0, 1), b2 + hstep, voffB); PG8_STAGE(PG8_SA(0, 0), a2, voffA);
;             PG8_WAIT_V(8); PG8_WAIT_L(0); PG8_BAR; PG8_MMA(1, 0, At, B0); PG8_MMA(1, 1, At, B1); PG8_BAR; PG8_SCHED;
;             PG8_LDB(B0, 1, 0); PG8_LDB(B1, 1, 1); PG8_SCHED; PG8_LDA(At, 1, 0); PG8_STAGE(PG8_SA(0, 1), a2 + hstep, voffA);
;             PG8_WAIT_V(8); PG8_WAIT_L(0); PG8_BAR; PG8_MMA(0, 0, At, B0); PG8_MMA(0, 1, At, B1); PG8_BAR; PG8_SCHED;
;             PG8_LDA(At, 1, 1); PG8_STAGE(PG8_SB(1, 0), b3, voffB); PG8_STAGE(PG8_SB(1, 1), b3 + hstep, voffB); PG8_STAGE(PG8_SA(1, 0), a3, voffA);
;             PG8_WAIT_V(8); PG8_WAIT_L(0); PG8_BAR; PG8_MMA(1, 0, At, B0); PG8_MMA(1, 1, At, B1); PG8_BAR; PG8_SCHED;
	s_waitcnt lgkmcnt(0)
	v_mfma_f32_16x16x32_bf16 v[124:127], v[146:149], v[178:181], v[124:127]
	v_mfma_f32_16x16x32_bf16 v[124:127], v[150:153], v[182:185], v[124:127]
	v_mfma_f32_16x16x32_bf16 v[112:115], v[150:153], v[204:207], v[112:115]
	v_mfma_f32_16x16x32_bf16 v[112:115], v[146:149], v[186:189], v[112:115]
	v_mfma_f32_16x16x32_bf16 v[96:99], v[146:149], v[208:211], v[96:99]
	v_mfma_f32_16x16x32_bf16 v[96:99], v[150:153], v[212:215], v[96:99]
	v_mfma_f32_16x16x32_bf16 v[80:83], v[150:153], v[220:223], v[80:83]
	v_mfma_f32_16x16x32_bf16 v[80:83], v[146:149], v[216:219], v[80:83]
	v_mfma_f32_16x16x32_bf16 v[76:79], v[154:157], v[216:219], v[76:79]
	v_mfma_f32_16x16x32_bf16 v[76:79], v[158:161], v[220:223], v[76:79]
	v_mfma_f32_16x16x32_bf16 v[92:95], v[158:161], v[212:215], v[92:95]
	v_mfma_f32_16x16x32_bf16 v[92:95], v[154:157], v[208:211], v[92:95]
	v_mfma_f32_16x16x32_bf16 v[108:111], v[154:157], v[186:189], v[108:111]
	v_mfma_f32_16x16x32_bf16 v[108:111], v[158:161], v[204:207], v[108:111]
	v_mfma_f32_16x16x32_bf16 v[128:131], v[158:161], v[182:185], v[128:131]
	v_mfma_f32_16x16x32_bf16 v[128:131], v[154:157], v[178:181], v[128:131]
	v_mfma_f32_16x16x32_bf16 v[120:123], v[162:165], v[178:181], v[120:123]
	v_mfma_f32_16x16x32_bf16 v[120:123], v[166:169], v[182:185], v[120:123]
	v_mfma_f32_16x16x32_bf16 v[104:107], v[166:169], v[204:207], v[104:107]
	v_mfma_f32_16x16x32_bf16 v[104:107], v[162:165], v[186:189], v[104:107]
	v_mfma_f32_16x16x32_bf16 v[88:91], v[162:165], v[208:211], v[88:91]
	v_mfma_f32_16x16x32_bf16 v[88:91], v[166:169], v[212:215], v[88:91]
	v_mfma_f32_16x16x32_bf16 v[72:75], v[166:169], v[220:223], v[72:75]
	v_mfma_f32_16x16x32_bf16 v[72:75], v[162:165], v[216:219], v[72:75]
	v_mfma_f32_16x16x32_bf16 v[68:71], v[170:173], v[216:219], v[68:71]
	v_mfma_f32_16x16x32_bf16 v[68:71], v[174:177], v[220:223], v[68:71]
	v_mfma_f32_16x16x32_bf16 v[84:87], v[174:177], v[212:215], v[84:87]
	v_mfma_f32_16x16x32_bf16 v[84:87], v[170:173], v[208:211], v[84:87]
	v_mfma_f32_16x16x32_bf16 v[100:103], v[170:173], v[186:189], v[100:103]
	v_mfma_f32_16x16x32_bf16 v[100:103], v[174:177], v[204:207], v[100:103]
	v_mfma_f32_16x16x32_bf16 v[116:119], v[174:177], v[182:185], v[116:119]
	v_mfma_f32_16x16x32_bf16 v[116:119], v[170:173], v[178:181], v[116:119]
	s_barrier
	s_setprio 0
	s_add_i32 s48, s73, s28
	v_lshl_add_u64 v[190:191], v[190:191], 0, s[84:85]
	s_mov_b32 m0, s48
	ds_read_b128 v[178:181], v145 offset:49152
	ds_read_b128 v[182:185], v145 offset:50176
	ds_read_b128 v[186:189], v145 offset:51200
	ds_read_b128 v[204:207], v145 offset:52224
	ds_read_b128 v[208:211], v145 offset:53248
	ds_read_b128 v[212:215], v145 offset:54272
	ds_read_b128 v[216:219], v145 offset:55296
	ds_read_b128 v[220:223], v145 offset:56320
	global_load_lds_dwordx4 v[190:191], off
	v_lshl_add_u64 v[190:191], v[224:225], 0, s[84:85]
	s_add_i32 m0, s48, 0x2000
	s_add_i32 s48, s76, s28
	global_load_lds_dwordx4 v[190:191], off
	v_lshl_add_u64 v[190:191], v[226:227], 0, s[84:85]
	s_mov_b32 m0, s48
	s_nop 0
	global_load_lds_dwordx4 v[190:191], off
	v_lshl_add_u64 v[190:191], v[228:229], 0, s[84:85]
	s_add_i32 m0, s48, 0x2000
	s_nop 0
	global_load_lds_dwordx4 v[190:191], off
	v_lshl_add_u64 v[190:191], v[240:241], 0, s[84:85]
	s_mov_b32 m0, s55
	s_nop 0
	global_load_lds_dwordx4 v[190:191], off
	v_lshl_add_u64 v[190:191], v[242:243], 0, s[84:85]
	s_mov_b32 m0, s56
	s_nop 0
	global_load_lds_dwordx4 v[190:191], off
	s_waitcnt vmcnt(8)
	s_waitcnt lgkmcnt(0)
	s_setprio 1
	s_barrier
	s_waitcnt lgkmcnt(0)
	v_mfma_f32_16x16x32_bf16 v[64:67], v[146:149], v[178:181], v[64:67]
	v_mfma_f32_16x16x32_bf16 v[64:67], v[150:153], v[182:185], v[64:67]
	v_mfma_f32_16x16x32_bf16 v[48:51], v[150:153], v[204:207], v[48:51]
	v_mfma_f32_16x16x32_bf16 v[48:51], v[146:149], v[186:189], v[48:51]
	v_mfma_f32_16x16x32_bf16 v[32:35], v[146:149], v[208:211], v[32:35]
	v_mfma_f32_16x16x32_bf16 v[32:35], v[150:153], v[212:215], v[32:35]
	v_mfma_f32_16x16x32_bf16 v[16:19], v[150:153], v[220:223], v[16:19]
	v_mfma_f32_16x16x32_bf16 v[16:19], v[146:149], v[216:219], v[16:19]
	v_mfma_f32_16x16x32_bf16 v[12:15], v[154:157], v[216:219], v[12:15]
	v_mfma_f32_16x16x32_bf16 v[12:15], v[158:161], v[220:223], v[12:15]
	v_mfma_f32_16x16x32_bf16 v[28:31], v[158:161], v[212:215], v[28:31]
	v_mfma_f32_16x16x32_bf16 v[28:31], v[154:157], v[208:211], v[28:31]
	v_mfma_f32_16x16x32_bf16 v[44:47], v[154:157], v[186:189], v[44:47]
	v_mfma_f32_16x16x32_bf16 v[44:47], v[158:161], v[204:207], v[44:47]
	v_mfma_f32_16x16x32_bf16 v[60:63], v[158:161], v[182:185], v[60:63]
	v_mfma_f32_16x16x32_bf16 v[60:63], v[154:157], v[178:181], v[60:63]
	v_mfma_f32_16x16x32_bf16 v[56:59], v[162:165], v[178:181], v[56:59]
	v_mfma_f32_16x16x32_bf16 v[56:59], v[166:169], v[182:185], v[56:59]
	v_mfma_f32_16x16x32_bf16 v[40:43], v[166:169], v[204:207], v[40:43]
	v_mfma_f32_16x16x32_bf16 v[40:43], v[162:165], v[186:189], v[40:43]
	v_mfma_f32_16x16x32_bf16 v[24:27], v[162:165], v[208:211], v[24:27]
	v_mfma_f32_16x16x32_bf16 v[24:27], v[166:169], v[212:215], v[24:27]
	v_mfma_f32_16x16x32_bf16 v[8:11], v[166:169], v[220:223], v[8:11]
	v_mfma_f32_16x16x32_bf16 v[8:11], v[162:165], v[216:219], v[8:11]
	v_mfma_f32_16x16x32_bf16 v[4:7], v[170:173], v[216:219], v[4:7]
	v_mfma_f32_16x16x32_bf16 v[4:7], v[174:177], v[220:223], v[4:7]
	v_mfma_f32_16x16x32_bf16 v[20:23], v[174:177], v[212:215], v[20:23]
	v_mfma_f32_16x16x32_bf16 v[20:23], v[170:173], v[208:211], v[20:23]
	v_mfma_f32_16x16x32_bf16 v[36:39], v[170:173], v[186:189], v[36:39]
	v_mfma_f32_16x16x32_bf16 v[36:39], v[174:177], v[204:207], v[36:39]
	v_mfma_f32_16x16x32_bf16 v[52:55], v[174:177], v[182:185], v[52:55]
	v_mfma_f32_16x16x32_bf16 v[52:55], v[170:173], v[178:181], v[52:55]
	s_barrier
	s_setprio 0
	s_add_u32 s44, s44, 0x100
	s_addc_u32 s45, s45, 0
	s_add_u32 s65, s65, 0x100
	s_addc_u32 s67, s67, 0
	s_cmp_ge_i32 s72, s53
	s_mov_b32 s48, s72
	s_cbranch_scc0 .LBB0_1623

; #define PG8_STAGE(bufoff, gbase, voff) do { _Pragma("unroll") for (int _i = 0; _i < 2; ++_i) \
;         __builtin_amdgcn_global_load_lds((const unsigned*)((const char*)(gbase) + (voff)[_i]), (PG8_LAS unsigned*)(lds + (bufoff) + ldsw + _i * 8192), 16, 0, 0); } while (0)
; #define PG8_LDA(dst, b, h) do { _Pragma("unroll") for (int m = 0; m < 4; ++m) _Pragma("unroll") for (int k = 0; k < 2; ++k) dst[m][k] = *(const PG8_LAS bf16x8*)(lds + PG8_SA(b, h) + aoff + m * 2048 + k * 1024); } while (0)
; #define PG8_BAR __builtin_amdgcn_s_barrier()
; template <class Epi, class Sched, bool ALIGN_EPI = false, bool SP2 = false, bool I8 = false>
; __device__ __forceinline__ void gemm_phase(PG8_LAS unsigned char* lds, const Gemm g, const Sched& S, const Epi& E) {
;     ...
;         const char* nA = has_next ? (const char*)g.A + (size_t)nxt.pm * tstep : cA; const char* nB = has_next ? (const char*)g.Bt + (size_t)nxt.pn * tstep : cB;
;         for (int t = 0; t < nt; t += 2) {
;             const bool last = (t == nt - 2);
;             const char* a1 = cA + (size_t)(t + 1) * kstep;
;             const char* a2 = last ? nA : cA + (size_t)(t + 2) * kstep; const char* b2 = last ? nB : cB + (size_t)(t + 2) * kstep;
;             const char* a3 = a2 + kstep; const char* b3 = b2 + kstep;
;             if (last && has_next) S.a_ready(nxt);
;             if constexpr (SP2) {
;             PG8_LDB(B0, 0, 0); PG8_LDB(B1, 0, 1); PG8_SCHED; PG8_LDA(At, 0, 0); PG8_STAGE(PG8_SA(1, 1), a1 + hstep, voffA);
;             PG8_WAIT_V(8); PG8_WAIT_L(0); PG8_BAR; PG8_MMA(0, 0, At, B0); PG8_MMA(0, 1, At, B1); PG8_BAR; PG8_SCHED;
;             PG8_LDA(At, 0, 1); PG8_STAGE(PG8_SB(0, 0), b2, voffB); PG8_STAGE(PG8_SB(0, 1), b2 + hstep, voffB); PG8_STAGE(PG8_SA(0, 0), a2, voffA);
;             PG8_WAIT_V(8); PG8_WAIT_L(0); PG8_BAR; PG8_MMA(1, 0, At, B0); PG8_MMA(1, 1, At, B1); PG8_BAR; PG8_SCHED;
;             PG8_LDB(B0, 1, 0); PG8_LDB(B1, 1, 1); PG8_SCHED; PG8_LDA(At, 1, 0); PG8_STAGE(PG8_SA(0, 1), a2 + hstep, voffA);
;             PG8_WAIT_V(8); PG8_WAIT_L(0); PG8_BAR; PG8_MMA(0, 0, At, B0); PG8_MMA(0, 1, At, B1); PG8_BAR; PG8_SCHED;
;             PG8_LDA(At, 1, 1); PG8_STAGE(PG8_SB(1, 0), b3, voffB); PG8_STAGE(PG8_SB(1, 1), b3 + hstep, voffB); PG8_STAGE(PG8_SA(1, 0), a3, voffA);
;             PG8_WAIT_V(8); PG8_WAIT_L(0); PG8_BAR; PG8_MMA(1, 0, At, B0); PG8_MMA(1, 1, At, B1); PG8_BAR; PG8_SCHED;
.LBB0_1699:
	s_add_u32 s53, s24, 0x100
	s_addc_u32 s54, s25, 0
	s_mov_b32 s55, -2
	s_add_u32 s24, s22, 0x100
	s_addc_u32 s25, s23, 0
	s_add_i32 s56, 0, 0x10000
	s_cmpk_eq_i32 s55, 0xa8
	s_cselect_b32 s37, s13, s25
	s_cselect_b32 s36, s12, s24
	s_cselect_b32 s27, s21, s54
	s_cselect_b32 s26, s20, s53
	s_add_i32 s57, 0, 0x14000
	v_add_u32_e32 v144, s56, v240
	v_add_u32_e32 v160, s57, v240
	ds_read_b128 v[124:127], v144
	ds_read_b128 v[128:131], v144 offset:1024
	ds_read_b128 v[132:135], v144 offset:2048
	ds_read_b128 v[144:147], v144 offset:3072
	ds_read_b128 v[148:151], v160
	ds_read_b128 v[152:155], v160 offset:1024
	ds_read_b128 v[156:159], v160 offset:2048
	ds_read_b128 v[160:163], v160 offset:3072
	v_lshl_add_u64 v[218:219], s[22:23], 0, v[210:211]
	s_add_i32 m0, s42, 0xc000
	ds_read_b128 v[164:167], v242
	ds_read_b128 v[168:171], v242 offset:1024
	ds_read_b128 v[172:175], v242 offset:2048
	ds_read_b128 v[176:179], v242 offset:3072
	ds_read_b128 v[180:183], v242 offset:4096
	ds_read_b128 v[184:187], v242 offset:5120
	ds_read_b128 v[188:191], v242 offset:6144
	ds_read_b128 v[214:217], v242 offset:7168
	global_load_lds_dwordx4 v[218:219], off
	v_lshl_add_u64 v[218:219], s[22:23], 0, v[212:213]
	s_add_i32 m0, s42, 0xe000
	s_nop 0
	global_load_lds_dwordx4 v[218:219], off
	s_waitcnt vmcnt(8)
	s_waitcnt lgkmcnt(0)
	s_setprio 1
	s_barrier
	s_waitcnt lgkmcnt(0)
	v_mfma_f32_16x16x32_bf16 v[140:143], v[124:127], v[164:167], 0
	v_mfma_f32_16x16x32_bf16 v[140:143], v[128:131], v[168:171], v[140:143]
	v_mfma_f32_16x16x32_bf16 v[112:115], v[128:131], v[176:179], 0
	v_mfma_f32_16x16x32_bf16 v[112:115], v[124:127], v[172:175], v[112:115]
	v_mfma_f32_16x16x32_bf16 v[96:99], v[124:127], v[180:183], 0
	v_mfma_f32_16x16x32_bf16 v[96:99], v[128:131], v[184:187], v[96:99]
	v_mfma_f32_16x16x32_bf16 v[80:83], v[128:131], v[214:217], 0
	v_mfma_f32_16x16x32_bf16 v[80:83], v[124:127], v[188:191], v[80:83]
	v_mfma_f32_16x16x32_bf16 v[76:79], v[132:135], v[188:191], 0
	v_mfma_f32_16x16x32_bf16 v[76:79], v[144:147], v[214:217], v[76:79]
	v_mfma_f32_16x16x32_bf16 v[92:95], v[144:147], v[184:187], 0
	v_mfma_f32_16x16x32_bf16 v[92:95], v[132:135], v[180:183], v[92:95]
	v_mfma_f32_16x16x32_bf16 v[108:111], v[132:135], v[172:175], 0
	v_mfma_f32_16x16x32_bf16 v[108:111], v[144:147], v[176:179], v[108:111]
	v_mfma_f32_16x16x32_bf16 v[136:139], v[144:147], v[168:171], 0
	v_mfma_f32_16x16x32_bf16 v[136:139], v[132:135], v[164:167], v[136:139]
	v_mfma_f32_16x16x32_bf16 v[120:123], v[148:151], v[164:167], 0
	v_mfma_f32_16x16x32_bf16 v[120:123], v[152:155], v[168:171], v[120:123]
	v_mfma_f32_16x16x32_bf16 v[104:107], v[152:155], v[176:179], 0
	v_mfma_f32_16x16x32_bf16 v[104:107], v[148:151], v[172:175], v[104:107]
	v_mfma_f32_16x16x32_bf16 v[88:91], v[148:151], v[180:183], 0
	v_mfma_f32_16x16x32_bf16 v[88:91], v[152:155], v[184:187], v[88:91]
	v_mfma_f32_16x16x32_bf16 v[72:75], v[152:155], v[214:217], 0
	v_mfma_f32_16x16x32_bf16 v[72:75], v[148:151], v[188:191], v[72:75]
	v_mfma_f32_16x16x32_bf16 v[68:71], v[156:159], v[188:191], 0
	v_mfma_f32_16x16x32_bf16 v[68:71], v[160:163], v[214:217], v[68:71]
	v_mfma_f32_16x16x32_bf16 v[84:87], v[160:163], v[184:187], 0
	v_mfma_f32_16x16x32_bf16 v[84:87], v[156:159], v[180:183], v[84:87]
	v_mfma_f32_16x16x32_bf16 v[100:103], v[156:159], v[172:175], 0
	v_mfma_f32_16x16x32_bf16 v[100:103], v[160:163], v[176:179], v[100:103]
	v_mfma_f32_16x16x32_bf16 v[116:119], v[160:163], v[168:171], 0
	v_mfma_f32_16x16x32_bf16 v[116:119], v[156:159], v[164:167], v[116:119]
	s_barrier
	s_setprio 0
	s_add_i32 s22, s56, s41
	v_lshl_add_u64 v[218:219], s[26:27], 0, v[2:3]
	s_mov_b32 m0, s22
	ds_read_b128 v[164:167], v242 offset:16384
	ds_read_b128 v[168:171], v242 offset:17408
	ds_read_b128 v[172:175], v242 offset:18432
	ds_read_b128 v[176:179], v242 offset:19456
	ds_read_b128 v[180:183], v242 offset:20480
	ds_read_b128 v[184:187], v242 offset:21504
	ds_read_b128 v[188:191], v242 offset:22528
	ds_read_b128 v[214:217], v242 offset:23552
	global_load_lds_dwordx4 v[218:219], off
	s_add_i32 m0, s22, 0x2000
	s_add_u32 s22, s26, 0x2b0000
	v_lshl_add_u64 v[220:221], s[26:27], 0, v[204:205]
	s_addc_u32 s23, s27, 0
	s_add_i32 s56, s57, s41
	global_load_lds_dwordx4 v[220:221], off
	s_mov_b32 m0, s56
	v_lshl_add_u64 v[224:225], s[36:37], 0, v[206:207]
	global_load_lds_dwordx4 v2, s[22:23]
	s_add_i32 m0, s56, 0x2000
	s_nop 0
	global_load_lds_dwordx4 v204, s[22:23]
	v_lshl_add_u64 v[222:223], s[36:37], 0, v[208:209]
	s_waitcnt vmcnt(6)
	s_waitcnt lgkmcnt(0)
	s_setprio 1
	s_barrier
	s_waitcnt lgkmcnt(0)
	v_mfma_f32_16x16x32_bf16 v[64:67], v[124:127], v[164:167], 0
	v_mfma_f32_16x16x32_bf16 v[64:67], v[128:131], v[168:171], v[64:67]
	v_mfma_f32_16x16x32_bf16 v[48:51], v[128:131], v[176:179], 0
	v_mfma_f32_16x16x32_bf16 v[48:51], v[124:127], v[172:175], v[48:51]
	v_mfma_f32_16x16x32_bf16 v[32:35], v[124:127], v[180:183], 0
	v_mfma_f32_16x16x32_bf16 v[32:35], v[128:131], v[184:187], v[32:35]
	v_mfma_f32_16x16x32_bf16 v[16:19], v[128:131], v[214:217], 0
	v_mfma_f32_16x16x32_bf16 v[16:19], v[124:127], v[188:191], v[16:19]
	v_mfma_f32_16x16x32_bf16 v[12:15], v[132:135], v[188:191], 0
	v_mfma_f32_16x16x32_bf16 v[12:15], v[144:147], v[214:217], v[12:15]
	v_mfma_f32_16x16x32_bf16 v[28:31], v[144:147], v[184:187], 0
	v_mfma_f32_16x16x32_bf16 v[28:31], v[132:135], v[180:183], v[28:31]
	v_mfma_f32_16x16x32_bf16 v[44:47], v[132:135], v[172:175], 0
	v_mfma_f32_16x16x32_bf16 v[44:47], v[144:147], v[176:179], v[44:47]
	v_mfma_f32_16x16x32_bf16 v[60:63], v[144:147], v[168:171], 0
	v_mfma_f32_16x16x32_bf16 v[60:63], v[132:135], v[164:167], v[60:63]
	v_mfma_f32_16x16x32_bf16 v[56:59], v[148:151], v[164:167], 0
	v_mfma_f32_16x16x32_bf16 v[56:59], v[152:155], v[168:171], v[56:59]
	v_mfma_f32_16x16x32_bf16 v[40:43], v[152:155], v[176:179], 0
	v_mfma_f32_16x16x32_bf16 v[40:43], v[148:151], v[172:175], v[40:43]
	v_mfma_f32_16x16x32_bf16 v[24:27], v[148:151], v[180:183], 0
	v_mfma_f32_16x16x32_bf16 v[24:27], v[152:155], v[184:187], v[24:27]
	v_mfma_f32_16x16x32_bf16 v[8:11], v[152:155], v[214:217], 0
	v_mfma_f32_16x16x32_bf16 v[8:11], v[148:151], v[188:191], v[8:11]
	v_mfma_f32_16x16x32_bf16 v[4:7], v[156:159], v[188:191], 0
	v_mfma_f32_16x16x32_bf16 v[4:7], v[160:163], v[214:217], v[4:7]
	v_mfma_f32_16x16x32_bf16 v[20:23], v[160:163], v[184:187], 0
	v_mfma_f32_16x16x32_bf16 v[20:23], v[156:159], v[180:183], v[20:23]
	v_mfma_f32_16x16x32_bf16 v[36:39], v[156:159], v[172:175], 0
	v_mfma_f32_16x16x32_bf16 v[36:39], v[160:163], v[176:179], v[36:39]
	v_mfma_f32_16x16x32_bf16 v[52:55], v[160:163], v[168:171], 0
	v_mfma_f32_16x16x32_bf16 v[52:55], v[156:159], v[164:167], v[52:55]
	s_barrier
; #define PG8_STAGE(bufoff, gbase, voff) do { _Pragma("unroll") for (int _i = 0; _i < 2; ++_i) \
;         __builtin_amdgcn_global_load_lds((const unsigned*)((const char*)(gbase) + (voff)[_i]), (PG8_LAS unsigned*)(lds + (bufoff) + ldsw + _i * 8192), 16, 0, 0); } while (0)
; #define PG8_LDA(dst, b, h) do { _Pragma("unroll") for (int m = 0; m < 4; ++m) _Pragma("unroll") for (int k = 0; k < 2; ++k) dst[m][k] = *(const PG8_LAS bf16x8*)(lds + PG8_SA(b, h) + aoff + m * 2048 + k * 1024); } while (0)
; #define PG8_LDB(dst, b, h) do { _Pragma("unroll") for (int n = 0; n < 2; ++n) _Pragma("unroll") for (int k = 0; k < 2; ++k) dst[n][k] = *(const PG8_LAS bf16x8*)(lds + PG8_SB(b, h) + boff + n * 2048 + k * 1024); } while (0)
; #define PG8_WAIT_V(n) asm volatile("s_waitcnt vmcnt(" #n ")" ::: "memory")
; #define PG8_WAIT_L(n) asm volatile("s_waitcnt lgkmcnt(" #n ")" ::: "memory")
; #define PG8_BAR __builtin_amdgcn_s_barrier()
; #define PG8_SCHED __builtin_amdgcn_sched_barrier(0)
; template <class Epi, class Sched, bool ALIGN_EPI = false, bool SP2 = false, bool I8 = false>
; __device__ __forceinline__ void gemm_phase(PG8_LAS unsigned char* lds, const Gemm g, const Sched& S, const Epi& E) {
;     ...
;             if constexpr (SP2) {
;             PG8_LDB(B0, 0, 0); PG8_LDB(B1, 0, 1); PG8_SCHED; PG8_LDA(At, 0, 0); PG8_STAGE(PG8_SA(1, 1), a1 + hstep, voffA);
;             PG8_WAIT_V(8); PG8_WAIT_L(0); PG8_BAR; PG8_MMA(0, 0, At, B0); PG8_MMA(0, 1, At, B1); PG8_BAR; PG8_SCHED;
;             PG8_LDA(At, 0, 1); PG8_STAGE(PG8_SB(0, 0), b2, voffB); PG8_STAGE(PG8_SB(0, 1), b2 + hstep, voffB); PG8_STAGE(PG8_SA(0, 0), a2, voffA);
;             PG8_WAIT_V(8); PG8_WAIT_L(0); PG8_BAR; PG8_MMA(1, 0, At, B0); PG8_MMA(1, 1, At, B1); PG8_BAR; PG8_SCHED;
;             PG8_LDB(B0, 1, 0); PG8_LDB(B1, 1, 1); PG8_SCHED; PG8_LDA(At, 1, 0); PG8_STAGE(PG8_SA(0, 1), a2 + hstep, voffA);
;             PG8_WAIT_V(8); PG8_WAIT_L(0); PG8_BAR; PG8_MMA(0, 0, At, B0); PG8_MMA(0, 1, At, B1); PG8_BAR; PG8_SCHED;
;             PG8_LDA(At, 1, 1); PG8_STAGE(PG8_SB(1, 0), b3, voffB); PG8_STAGE(PG8_SB(1, 1), b3 + hstep, voffB); PG8_STAGE(PG8_SA(1, 0), a3, voffA);
;             PG8_WAIT_V(8); PG8_WAIT_L(0); PG8_BAR; PG8_MMA(1, 0, At, B0); PG8_MMA(1, 1, At, B1); PG8_BAR; PG8_SCHED;
	s_setprio 0
	s_mov_b32 m0, s42
	s_nop 0
	global_load_lds_dwordx4 v[222:223], off
	s_mov_b32 m0, s43
	s_nop 0
	global_load_lds_dwordx4 v[224:225], off
	s_add_i32 s56, 0, 0x18000
	s_add_i32 s57, 0, 0x1c000
	v_add_u32_e32 v144, s56, v240
	v_add_u32_e32 v160, s57, v240
	ds_read_b128 v[124:127], v144
	ds_read_b128 v[128:131], v144 offset:1024
	ds_read_b128 v[132:135], v144 offset:2048
	ds_read_b128 v[144:147], v144 offset:3072
	ds_read_b128 v[148:151], v160
	ds_read_b128 v[152:155], v160 offset:1024
	ds_read_b128 v[156:159], v160 offset:2048
	ds_read_b128 v[160:163], v160 offset:3072
	s_add_u32 s22, s36, 0x2b0000
	s_addc_u32 s23, s37, 0
	s_mov_b32 m0, s44
	ds_read_b128 v[164:167], v242 offset:32768
	ds_read_b128 v[168:171], v242 offset:33792
	ds_read_b128 v[172:175], v242 offset:34816
	ds_read_b128 v[176:179], v242 offset:35840
	ds_read_b128 v[180:183], v242 offset:36864
	ds_read_b128 v[184:187], v242 offset:37888
	ds_read_b128 v[188:191], v242 offset:38912
	ds_read_b128 v[214:217], v242 offset:39936
	global_load_lds_dwordx4 v208, s[22:23]
	s_mov_b32 m0, s45
	s_nop 0
	global_load_lds_dwordx4 v206, s[22:23]
	s_waitcnt vmcnt(8)
	s_waitcnt lgkmcnt(0)
	s_setprio 1
	s_barrier
	s_waitcnt lgkmcnt(0)
	v_mfma_f32_16x16x32_bf16 v[140:143], v[124:127], v[164:167], v[140:143]
	v_mfma_f32_16x16x32_bf16 v[140:143], v[128:131], v[168:171], v[140:143]
	v_mfma_f32_16x16x32_bf16 v[112:115], v[128:131], v[176:179], v[112:115]
	v_mfma_f32_16x16x32_bf16 v[112:115], v[124:127], v[172:175], v[112:115]
	v_mfma_f32_16x16x32_bf16 v[96:99], v[124:127], v[180:183], v[96:99]
	v_mfma_f32_16x16x32_bf16 v[96:99], v[128:131], v[184:187], v[96:99]
	v_mfma_f32_16x16x32_bf16 v[80:83], v[128:131], v[214:217], v[80:83]
	v_mfma_f32_16x16x32_bf16 v[80:83], v[124:127], v[188:191], v[80:83]
	v_mfma_f32_16x16x32_bf16 v[76:79], v[132:135], v[188:191], v[76:79]
	v_mfma_f32_16x16x32_bf16 v[76:79], v[144:147], v[214:217], v[76:79]
	v_mfma_f32_16x16x32_bf16 v[92:95], v[144:147], v[184:187], v[92:95]
	v_mfma_f32_16x16x32_bf16 v[92:95], v[132:135], v[180:183], v[92:95]
	v_mfma_f32_16x16x32_bf16 v[108:111], v[132:135], v[172:175], v[108:111]
	v_mfma_f32_16x16x32_bf16 v[108:111], v[144:147], v[176:179], v[108:111]
	v_mfma_f32_16x16x32_bf16 v[136:139], v[144:147], v[168:171], v[136:139]
	v_mfma_f32_16x16x32_bf16 v[136:139], v[132:135], v[164:167], v[136:139]
	v_mfma_f32_16x16x32_bf16 v[120:123], v[148:151], v[164:167], v[120:123]
	v_mfma_f32_16x16x32_bf16 v[120:123], v[152:155], v[168:171], v[120:123]
	v_mfma_f32_16x16x32_bf16 v[104:107], v[152:155], v[176:179], v[104:107]
	v_mfma_f32_16x16x32_bf16 v[104:107], v[148:151], v[172:175], v[104:107]
	v_mfma_f32_16x16x32_bf16 v[88:91], v[148:151], v[180:183], v[88:91]
	v_mfma_f32_16x16x32_bf16 v[88:91], v[152:155], v[184:187], v[88:91]
	v_mfma_f32_16x16x32_bf16 v[72:75], v[152:155], v[214:217], v[72:75]
	v_mfma_f32_16x16x32_bf16 v[72:75], v[148:151], v[188:191], v[72:75]
	v_mfma_f32_16x16x32_bf16 v[68:71], v[156:159], v[188:191], v[68:71]
	v_mfma_f32_16x16x32_bf16 v[68:71], v[160:163], v[214:217], v[68:71]
	v_mfma_f32_16x16x32_bf16 v[84:87], v[160:163], v[184:187], v[84:87]
	v_mfma_f32_16x16x32_bf16 v[84:87], v[156:159], v[180:183], v[84:87]
	v_mfma_f32_16x16x32_bf16 v[100:103], v[156:159], v[172:175], v[100:103]
	v_mfma_f32_16x16x32_bf16 v[100:103], v[160:163], v[176:179], v[100:103]
	v_mfma_f32_16x16x32_bf16 v[116:119], v[160:163], v[168:171], v[116:119]
	v_mfma_f32_16x16x32_bf16 v[116:119], v[156:159], v[164:167], v[116:119]
	s_barrier
	s_setprio 0
	s_add_i32 s22, s56, s41
	v_lshl_add_u64 v[218:219], v[218:219], 0, s[84:85]
	s_mov_b32 m0, s22
	ds_read_b128 v[164:167], v242 offset:49152
	ds_read_b128 v[168:171], v242 offset:50176
	ds_read_b128 v[172:175], v242 offset:51200
	ds_read_b128 v[176:179], v242 offset:52224
	ds_read_b128 v[180:183], v242 offset:53248
	ds_read_b128 v[184:187], v242 offset:54272
	ds_read_b128 v[188:191], v242 offset:55296
	ds_read_b128 v[214:217], v242 offset:56320
	global_load_lds_dwordx4 v[218:219], off
	s_add_i32 m0, s22, 0x2000
	s_add_u32 s22, s26, 0x2b0080
	v_lshl_add_u64 v[218:219], v[220:221], 0, s[84:85]
	s_addc_u32 s23, s27, 0
	s_add_i32 s26, s57, s41
	global_load_lds_dwordx4 v[218:219], off
	s_mov_b32 m0, s26
	s_nop 0
	global_load_lds_dwordx4 v2, s[22:23]
	s_add_i32 m0, s26, 0x2000
	s_nop 0
	global_load_lds_dwordx4 v204, s[22:23]
	s_cmpk_eq_i32 s55, 0xa8
	s_cbranch_scc0 .Ldefer_1700_peel
	v_lshl_add_u64 v[218:219], v[222:223], 0, s[84:85]
	s_mov_b32 m0, s46
	s_nop 0
	global_load_lds_dwordx4 v[218:219], off
	v_lshl_add_u64 v[218:219], v[224:225], 0, s[84:85]
	s_mov_b32 m0, s47
	s_nop 0
	global_load_lds_dwordx4 v[218:219], off
; #define PG8_STAGE(bufoff, gbase, voff) do { _Pragma("unroll") for (int _i = 0; _i < 2; ++_i) \
;         __builtin_amdgcn_global_load_lds((const unsigned*)((const char*)(gbase) + (voff)[_i]), (PG8_LAS unsigned*)(lds + (bufoff) + ldsw + _i * 8192), 16, 0, 0); } while (0)
; #define PG8_LDA(dst, b, h) do { _Pragma("unroll") for (int m = 0; m < 4; ++m) _Pragma("unroll") for (int k = 0; k < 2; ++k) dst[m][k] = *(const PG8_LAS bf16x8*)(lds + PG8_SA(b, h) + aoff + m * 2048 + k * 1024); } while (0)
; #define PG8_WAIT_V(n) asm volatile("s_waitcnt vmcnt(" #n ")" ::: "memory")
; #define PG8_WAIT_L(n) asm volatile("s_waitcnt lgkmcnt(" #n ")" ::: "memory")
; #define PG8_BAR __builtin_amdgcn_s_barrier()
; template <class Epi, class Sched, bool ALIGN_EPI = false, bool SP2 = false, bool I8 = false>
; __device__ __forceinline__ void gemm_phase(PG8_LAS unsigned char* lds, const Gemm g, const Sched& S, const Epi& E) {
;     ...
;         for (int t = 0; t < nt; t += 2) {
;             const bool last = (t == nt - 2);
;             const char* a1 = cA + (size_t)(t + 1) * kstep;
;             const char* a2 = last ? nA : cA + (size_t)(t + 2) * kstep; const char* b2 = last ? nB : cB + (size_t)(t + 2) * kstep;
;             const char* a3 = a2 + kstep; const char* b3 = b2 + kstep;
;             if (last && has_next) S.a_ready(nxt);
;             if constexpr (SP2) {
;             PG8_LDB(B0, 0, 0); PG8_LDB(B1, 0, 1); PG8_SCHED; PG8_LDA(At, 0, 0); PG8_STAGE(PG8_SA(1, 1), a1 + hstep, voffA);
;             PG8_WAIT_V(8); PG8_WAIT_L(0); PG8_BAR; PG8_MMA(0, 0, At, B0); PG8_MMA(0, 1, At, B1); PG8_BAR; PG8_SCHED;
;             PG8_LDA(At, 0, 1); PG8_STAGE(PG8_SB(0, 0), b2, voffB); PG8_STAGE(PG8_SB(0, 1), b2 + hstep, voffB); PG8_STAGE(PG8_SA(0, 0), a2, voffA);
;             PG8_WAIT_V(8); PG8_WAIT_L(0); PG8_BAR; PG8_MMA(1, 0, At, B0); PG8_MMA(1, 1, At, B1); PG8_BAR; PG8_SCHED;
;             PG8_LDB(B0, 1, 0); PG8_LDB(B1, 1, 1); PG8_SCHED; PG8_LDA(At, 1, 0); PG8_STAGE(PG8_SA(0, 1), a2 + hstep, voffA);
;             PG8_WAIT_V(8); PG8_WAIT_L(0); PG8_BAR; PG8_MMA(0, 0, At, B0); PG8_MMA(0, 1, At, B1); PG8_BAR; PG8_SCHED;
;             PG8_LDA(At, 1, 1); PG8_STAGE(PG8_SB(1, 0), b3, voffB); PG8_STAGE(PG8_SB(1, 1), b3 + hstep, voffB); PG8_STAGE(PG8_SA(1, 0), a3, voffA);
;             PG8_WAIT_V(8); PG8_WAIT_L(0); PG8_BAR; PG8_MMA(1, 0, At, B0); PG8_MMA(1, 1, At, B1); PG8_BAR; PG8_SCHED;
.Ldefer_1700_peel:
	s_waitcnt vmcnt(6)
	s_waitcnt lgkmcnt(0)
	s_setprio 1
	s_barrier
	s_waitcnt lgkmcnt(0)
	v_mfma_f32_16x16x32_bf16 v[64:67], v[124:127], v[164:167], v[64:67]
	v_mfma_f32_16x16x32_bf16 v[64:67], v[128:131], v[168:171], v[64:67]
	v_mfma_f32_16x16x32_bf16 v[48:51], v[128:131], v[176:179], v[48:51]
	v_mfma_f32_16x16x32_bf16 v[48:51], v[124:127], v[172:175], v[48:51]
	v_mfma_f32_16x16x32_bf16 v[32:35], v[124:127], v[180:183], v[32:35]
	v_mfma_f32_16x16x32_bf16 v[32:35], v[128:131], v[184:187], v[32:35]
	v_mfma_f32_16x16x32_bf16 v[16:19], v[128:131], v[214:217], v[16:19]
	v_mfma_f32_16x16x32_bf16 v[16:19], v[124:127], v[188:191], v[16:19]
	v_mfma_f32_16x16x32_bf16 v[12:15], v[132:135], v[188:191], v[12:15]
	v_mfma_f32_16x16x32_bf16 v[12:15], v[144:147], v[214:217], v[12:15]
	v_mfma_f32_16x16x32_bf16 v[28:31], v[144:147], v[184:187], v[28:31]
	v_mfma_f32_16x16x32_bf16 v[28:31], v[132:135], v[180:183], v[28:31]
	v_mfma_f32_16x16x32_bf16 v[44:47], v[132:135], v[172:175], v[44:47]
	v_mfma_f32_16x16x32_bf16 v[44:47], v[144:147], v[176:179], v[44:47]
	v_mfma_f32_16x16x32_bf16 v[60:63], v[144:147], v[168:171], v[60:63]
	v_mfma_f32_16x16x32_bf16 v[60:63], v[132:135], v[164:167], v[60:63]
	v_mfma_f32_16x16x32_bf16 v[56:59], v[148:151], v[164:167], v[56:59]
	v_mfma_f32_16x16x32_bf16 v[56:59], v[152:155], v[168:171], v[56:59]
	v_mfma_f32_16x16x32_bf16 v[40:43], v[152:155], v[176:179], v[40:43]
	v_mfma_f32_16x16x32_bf16 v[40:43], v[148:151], v[172:175], v[40:43]
	v_mfma_f32_16x16x32_bf16 v[24:27], v[148:151], v[180:183], v[24:27]
	v_mfma_f32_16x16x32_bf16 v[24:27], v[152:155], v[184:187], v[24:27]
	v_mfma_f32_16x16x32_bf16 v[8:11], v[152:155], v[214:217], v[8:11]
	v_mfma_f32_16x16x32_bf16 v[8:11], v[148:151], v[188:191], v[8:11]
	v_mfma_f32_16x16x32_bf16 v[4:7], v[156:159], v[188:191], v[4:7]
	v_mfma_f32_16x16x32_bf16 v[4:7], v[160:163], v[214:217], v[4:7]
	v_mfma_f32_16x16x32_bf16 v[20:23], v[160:163], v[184:187], v[20:23]
	v_mfma_f32_16x16x32_bf16 v[20:23], v[156:159], v[180:183], v[20:23]
	v_mfma_f32_16x16x32_bf16 v[36:39], v[156:159], v[172:175], v[36:39]
	v_mfma_f32_16x16x32_bf16 v[36:39], v[160:163], v[176:179], v[36:39]
	v_mfma_f32_16x16x32_bf16 v[52:55], v[160:163], v[168:171], v[52:55]
	v_mfma_f32_16x16x32_bf16 v[52:55], v[156:159], v[164:167], v[52:55]
	s_barrier
	s_setprio 0
	s_add_i32 s55, s55, 2
	s_add_u32 s53, s53, 0x100
	s_addc_u32 s54, s54, 0
	s_cmpk_gt_u32 s55, 0xa9
	s_mov_b64 s[22:23], s[24:25]
	s_cbranch_scc1 .Lkloop_exit_5
.LBB0_1700:
	s_add_u32 s24, s22, 0x100
	s_addc_u32 s25, s23, 0
	s_add_i32 s56, 0, 0x10000
	s_cmpk_eq_i32 s55, 0xa8
	s_cselect_b32 s37, s13, s25
	s_cselect_b32 s36, s12, s24
	s_cselect_b32 s27, s21, s54
	s_cselect_b32 s26, s20, s53
	s_add_i32 s57, 0, 0x14000
	v_add_u32_e32 v144, s56, v240
	v_add_u32_e32 v160, s57, v240
	ds_read_b128 v[124:127], v144
	ds_read_b128 v[128:131], v144 offset:1024
	ds_read_b128 v[132:135], v144 offset:2048
	ds_read_b128 v[144:147], v144 offset:3072
	ds_read_b128 v[148:151], v160
	ds_read_b128 v[152:155], v160 offset:1024
	ds_read_b128 v[156:159], v160 offset:2048
	ds_read_b128 v[160:163], v160 offset:3072
	v_lshl_add_u64 v[218:219], v[222:223], 0, s[84:85]
	s_mov_b32 m0, s46
	s_nop 0
	global_load_lds_dwordx4 v[218:219], off
	v_lshl_add_u64 v[218:219], v[224:225], 0, s[84:85]
	s_mov_b32 m0, s47
	s_nop 0
	global_load_lds_dwordx4 v[218:219], off
	v_lshl_add_u64 v[218:219], s[22:23], 0, v[210:211]
	s_add_i32 m0, s42, 0xc000
	ds_read_b128 v[164:167], v242
	ds_read_b128 v[168:171], v242 offset:1024
	ds_read_b128 v[172:175], v242 offset:2048
	ds_read_b128 v[176:179], v242 offset:3072
	ds_read_b128 v[180:183], v242 offset:4096
	ds_read_b128 v[184:187], v242 offset:5120
	ds_read_b128 v[188:191], v242 offset:6144
	ds_read_b128 v[214:217], v242 offset:7168
	global_load_lds_dwordx4 v[218:219], off
	v_lshl_add_u64 v[218:219], s[22:23], 0, v[212:213]
	s_add_i32 m0, s42, 0xe000
	s_nop 0
	global_load_lds_dwordx4 v[218:219], off
	s_waitcnt vmcnt(8)
	s_waitcnt lgkmcnt(0)
	s_setprio 1
	s_barrier
	s_waitcnt lgkmcnt(0)
	v_mfma_f32_16x16x32_bf16 v[140:143], v[124:127], v[164:167], v[140:143]
	v_mfma_f32_16x16x32_bf16 v[140:143], v[128:131], v[168:171], v[140:143]
	v_mfma_f32_16x16x32_bf16 v[112:115], v[128:131], v[176:179], v[112:115]
	v_mfma_f32_16x16x32_bf16 v[112:115], v[124:127], v[172:175], v[112:115]
	v_mfma_f32_16x16x32_bf16 v[96:99], v[124:127], v[180:183], v[96:99]
	v_mfma_f32_16x16x32_bf16 v[96:99], v[128:131], v[184:187], v[96:99]
	v_mfma_f32_16x16x32_bf16 v[80:83], v[128:131], v[214:217], v[80:83]
	v_mfma_f32_16x16x32_bf16 v[80:83], v[124:127], v[188:191], v[80:83]
	v_mfma_f32_16x16x32_bf16 v[76:79], v[132:135], v[188:191], v[76:79]
	v_mfma_f32_16x16x32_bf16 v[76:79], v[144:147], v[214:217], v[76:79]
	v_mfma_f32_16x16x32_bf16 v[92:95], v[144:147], v[184:187], v[92:95]
	v_mfma_f32_16x16x32_bf16 v[92:95], v[132:135], v[180:183], v[92:95]
	v_mfma_f32_16x16x32_bf16 v[108:111], v[132:135], v[172:175], v[108:111]
	v_mfma_f32_16x16x32_bf16 v[108:111], v[144:147], v[176:179], v[108:111]
	v_mfma_f32_16x16x32_bf16 v[136:139], v[144:147], v[168:171], v[136:139]
	v_mfma_f32_16x16x32_bf16 v[136:139], v[132:135], v[164:167], v[136:139]
	v_mfma_f32_16x16x32_bf16 v[120:123], v[148:151], v[164:167], v[120:123]
	v_mfma_f32_16x16x32_bf16 v[120:123], v[152:155], v[168:171], v[120:123]
	v_mfma_f32_16x16x32_bf16 v[104:107], v[152:155], v[176:179], v[104:107]
	v_mfma_f32_16x16x32_bf16 v[104:107], v[148:151], v[172:175], v[104:107]
	v_mfma_f32_16x16x32_bf16 v[88:91], v[148:151], v[180:183], v[88:91]
	v_mfma_f32_16x16x32_bf16 v[88:91], v[152:155], v[184:187], v[88:91]
	v_mfma_f32_16x16x32_bf16 v[72:75], v[152:155], v[214:217], v[72:75]
	v_mfma_f32_16x16x32_bf16 v[72:75], v[148:151], v[188:191], v[72:75]
	v_mfma_f32_16x16x32_bf16 v[68:71], v[156:159], v[188:191], v[68:71]
	v_mfma_f32_16x16x32_bf16 v[68:71], v[160:163], v[214:217], v[68:71]
	v_mfma_f32_16x16x32_bf16 v[84:87], v[160:163], v[184:187], v[84:87]
	v_mfma_f32_16x16x32_bf16 v[84:87], v[156:159], v[180:183], v[84:87]
	v_mfma_f32_16x16x32_bf16 v[100:103], v[156:159], v[172:175], v[100:103]
	v_mfma_f32_16x16x32_bf16 v[100:103], v[160:163], v[176:179], v[100:103]
	v_mfma_f32_16x16x32_bf16 v[116:119], v[160:163], v[168:171], v[116:119]
	v_mfma_f32_16x16x32_bf16 v[116:119], v[156:159], v[164:167], v[116:119]
	s_barrier
; #define PG8_STAGE(bufoff, gbase, voff) do { _Pragma("unroll") for (int _i = 0; _i < 2; ++_i) \
;         __builtin_amdgcn_global_load_lds((const unsigned*)((const char*)(gbase) + (voff)[_i]), (PG8_LAS unsigned*)(lds + (bufoff) + ldsw + _i * 8192), 16, 0, 0); } while (0)
; #define PG8_LDA(dst, b, h) do { _Pragma("unroll") for (int m = 0; m < 4; ++m) _Pragma("unroll") for (int k = 0; k < 2; ++k) dst[m][k] = *(const PG8_LAS bf16x8*)(lds + PG8_SA(b, h) + aoff + m * 2048 + k * 1024); } while (0)
; #define PG8_LDB(dst, b, h) do { _Pragma("unroll") for (int n = 0; n < 2; ++n) _Pragma("unroll") for (int k = 0; k < 2; ++k) dst[n][k] = *(const PG8_LAS bf16x8*)(lds + PG8_SB(b, h) + boff + n * 2048 + k * 1024); } while (0)
; #define PG8_WAIT_V(n) asm volatile("s_waitcnt vmcnt(" #n ")" ::: "memory")
; #define PG8_WAIT_L(n) asm volatile("s_waitcnt lgkmcnt(" #n ")" ::: "memory")
; #define PG8_BAR __builtin_amdgcn_s_barrier()
; #define PG8_SCHED __builtin_amdgcn_sched_barrier(0)
; template <class Epi, class Sched, bool ALIGN_EPI = false, bool SP2 = false, bool I8 = false>
; __device__ __forceinline__ void gemm_phase(PG8_LAS unsigned char* lds, const Gemm g, const Sched& S, const Epi& E) {
;     ...
;             if constexpr (SP2) {
;             PG8_LDB(B0, 0, 0); PG8_LDB(B1, 0, 1); PG8_SCHED; PG8_LDA(At, 0, 0); PG8_STAGE(PG8_SA(1, 1), a1 + hstep, voffA);
;             PG8_WAIT_V(8); PG8_WAIT_L(0); PG8_BAR; PG8_MMA(0, 0, At, B0); PG8_MMA(0, 1, At, B1); PG8_BAR; PG8_SCHED;
;             PG8_LDA(At, 0, 1); PG8_STAGE(PG8_SB(0, 0), b2, voffB); PG8_STAGE(PG8_SB(0, 1), b2 + hstep, voffB); PG8_STAGE(PG8_SA(0, 0), a2, voffA);
;             PG8_WAIT_V(8); PG8_WAIT_L(0); PG8_BAR; PG8_MMA(1, 0, At, B0); PG8_MMA(1, 1, At, B1); PG8_BAR; PG8_SCHED;
;             PG8_LDB(B0, 1, 0); PG8_LDB(B1, 1, 1); PG8_SCHED; PG8_LDA(At, 1, 0); PG8_STAGE(PG8_SA(0, 1), a2 + hstep, voffA);
;             PG8_WAIT_V(8); PG8_WAIT_L(0); PG8_BAR; PG8_MMA(0, 0, At, B0); PG8_MMA(0, 1, At, B1); PG8_BAR; PG8_SCHED;
;             PG8_LDA(At, 1, 1); PG8_STAGE(PG8_SB(1, 0), b3, voffB); PG8_STAGE(PG8_SB(1, 1), b3 + hstep, voffB); PG8_STAGE(PG8_SA(1, 0), a3, voffA);
;             PG8_WAIT_V(8); PG8_WAIT_L(0); PG8_BAR; PG8_MMA(1, 0, At, B0); PG8_MMA(1, 1, At, B1); PG8_BAR; PG8_SCHED;
	s_setprio 0
	s_add_i32 s22, s56, s41
	v_lshl_add_u64 v[218:219], s[26:27], 0, v[2:3]
	s_mov_b32 m0, s22
	ds_read_b128 v[164:167], v242 offset:16384
	ds_read_b128 v[168:171], v242 offset:17408
	ds_read_b128 v[172:175], v242 offset:18432
	ds_read_b128 v[176:179], v242 offset:19456
	ds_read_b128 v[180:183], v242 offset:20480
	ds_read_b128 v[184:187], v242 offset:21504
	ds_read_b128 v[188:191], v242 offset:22528
	ds_read_b128 v[214:217], v242 offset:23552
	global_load_lds_dwordx4 v[218:219], off
	s_add_i32 m0, s22, 0x2000
	s_add_u32 s22, s26, 0x2b0000
	v_lshl_add_u64 v[220:221], s[26:27], 0, v[204:205]
	s_addc_u32 s23, s27, 0
	s_add_i32 s56, s57, s41
	global_load_lds_dwordx4 v[220:221], off
	s_mov_b32 m0, s56
	v_lshl_add_u64 v[224:225], s[36:37], 0, v[206:207]
	global_load_lds_dwordx4 v2, s[22:23]
	s_add_i32 m0, s56, 0x2000
	s_nop 0
	global_load_lds_dwordx4 v204, s[22:23]
	v_lshl_add_u64 v[222:223], s[36:37], 0, v[208:209]
	s_waitcnt vmcnt(6)
	s_waitcnt lgkmcnt(0)
	s_setprio 1
	s_barrier
	s_waitcnt lgkmcnt(0)
	v_mfma_f32_16x16x32_bf16 v[64:67], v[124:127], v[164:167], v[64:67]
	v_mfma_f32_16x16x32_bf16 v[64:67], v[128:131], v[168:171], v[64:67]
	v_mfma_f32_16x16x32_bf16 v[48:51], v[128:131], v[176:179], v[48:51]
	v_mfma_f32_16x16x32_bf16 v[48:51], v[124:127], v[172:175], v[48:51]
	v_mfma_f32_16x16x32_bf16 v[32:35], v[124:127], v[180:183], v[32:35]
	v_mfma_f32_16x16x32_bf16 v[32:35], v[128:131], v[184:187], v[32:35]
	v_mfma_f32_16x16x32_bf16 v[16:19], v[128:131], v[214:217], v[16:19]
	v_mfma_f32_16x16x32_bf16 v[16:19], v[124:127], v[188:191], v[16:19]
	v_mfma_f32_16x16x32_bf16 v[12:15], v[132:135], v[188:191], v[12:15]
	v_mfma_f32_16x16x32_bf16 v[12:15], v[144:147], v[214:217], v[12:15]
	v_mfma_f32_16x16x32_bf16 v[28:31], v[144:147], v[184:187], v[28:31]
	v_mfma_f32_16x16x32_bf16 v[28:31], v[132:135], v[180:183], v[28:31]
	v_mfma_f32_16x16x32_bf16 v[44:47], v[132:135], v[172:175], v[44:47]
	v_mfma_f32_16x16x32_bf16 v[44:47], v[144:147], v[176:179], v[44:47]
	v_mfma_f32_16x16x32_bf16 v[60:63], v[144:147], v[168:171], v[60:63]
	v_mfma_f32_16x16x32_bf16 v[60:63], v[132:135], v[164:167], v[60:63]
	v_mfma_f32_16x16x32_bf16 v[56:59], v[148:151], v[164:167], v[56:59]
	v_mfma_f32_16x16x32_bf16 v[56:59], v[152:155], v[168:171], v[56:59]
	v_mfma_f32_16x16x32_bf16 v[40:43], v[152:155], v[176:179], v[40:43]
	v_mfma_f32_16x16x32_bf16 v[40:43], v[148:151], v[172:175], v[40:43]
	v_mfma_f32_16x16x32_bf16 v[24:27], v[148:151], v[180:183], v[24:27]
	v_mfma_f32_16x16x32_bf16 v[24:27], v[152:155], v[184:187], v[24:27]
	v_mfma_f32_16x16x32_bf16 v[8:11], v[152:155], v[214:217], v[8:11]
	v_mfma_f32_16x16x32_bf16 v[8:11], v[148:151], v[188:191], v[8:11]
	v_mfma_f32_16x16x32_bf16 v[4:7], v[156:159], v[188:191], v[4:7]
	v_mfma_f32_16x16x32_bf16 v[4:7], v[160:163], v[214:217], v[4:7]
	v_mfma_f32_16x16x32_bf16 v[20:23], v[160:163], v[184:187], v[20:23]
	v_mfma_f32_16x16x32_bf16 v[20:23], v[156:159], v[180:183], v[20:23]
	v_mfma_f32_16x16x32_bf16 v[36:39], v[156:159], v[172:175], v[36:39]
	v_mfma_f32_16x16x32_bf16 v[36:39], v[160:163], v[176:179], v[36:39]
	v_mfma_f32_16x16x32_bf16 v[52:55], v[160:163], v[168:171], v[52:55]
	v_mfma_f32_16x16x32_bf16 v[52:55], v[156:159], v[164:167], v[52:55]
	s_barrier
	s_setprio 0
	s_mov_b32 m0, s42
	s_nop 0
	global_load_lds_dwordx4 v[222:223], off
	s_mov_b32 m0, s43
	s_nop 0
	global_load_lds_dwordx4 v[224:225], off
	s_add_i32 s56, 0, 0x18000
	s_add_i32 s57, 0, 0x1c000
	v_add_u32_e32 v144, s56, v240
	v_add_u32_e32 v160, s57, v240
	ds_read_b128 v[124:127], v144
	ds_read_b128 v[128:131], v144 offset:1024
	ds_read_b128 v[132:135], v144 offset:2048
	ds_read_b128 v[144:147], v144 offset:3072
	ds_read_b128 v[148:151], v160
	ds_read_b128 v[152:155], v160 offset:1024
	ds_read_b128 v[156:159], v160 offset:2048
	ds_read_b128 v[160:163], v160 offset:3072
	s_add_u32 s22, s36, 0x2b0000
	s_addc_u32 s23, s37, 0
	s_mov_b32 m0, s44
	ds_read_b128 v[164:167], v242 offset:32768
	ds_read_b128 v[168:171], v242 offset:33792
	ds_read_b128 v[172:175], v242 offset:34816
	ds_read_b128 v[176:179], v242 offset:35840
	ds_read_b128 v[180:183], v242 offset:36864
	ds_read_b128 v[184:187], v242 offset:37888
	ds_read_b128 v[188:191], v242 offset:38912
	ds_read_b128 v[214:217], v242 offset:39936
	global_load_lds_dwordx4 v208, s[22:23]
	s_mov_b32 m0, s45
	s_nop 0
	global_load_lds_dwordx4 v206, s[22:23]
	s_waitcnt vmcnt(8)
	s_waitcnt lgkmcnt(0)
	s_setprio 1
	s_barrier
; #define PG8_STAGE(bufoff, gbase, voff) do { _Pragma("unroll") for (int _i = 0; _i < 2; ++_i) \
;         __builtin_amdgcn_global_load_lds((const unsigned*)((const char*)(gbase) + (voff)[_i]), (PG8_LAS unsigned*)(lds + (bufoff) + ldsw + _i * 8192), 16, 0, 0); } while (0)
; #define PG8_LDA(dst, b, h) do { _Pragma("unroll") for (int m = 0; m < 4; ++m) _Pragma("unroll") for (int k = 0; k < 2; ++k) dst[m][k] = *(const PG8_LAS bf16x8*)(lds + PG8_SA(b, h) + aoff + m * 2048 + k * 1024); } while (0)
; #define PG8_WAIT_V(n) asm volatile("s_waitcnt vmcnt(" #n ")" ::: "memory")
; #define PG8_WAIT_L(n) asm volatile("s_waitcnt lgkmcnt(" #n ")" ::: "memory")
; #define PG8_BAR __builtin_amdgcn_s_barrier()
; template <class Epi, class Sched, bool ALIGN_EPI = false, bool SP2 = false, bool I8 = false>
; __device__ __forceinline__ void gemm_phase(PG8_LAS unsigned char* lds, const Gemm g, const Sched& S, const Epi& E) {
;     ...
;         for (int t = 0; t < nt; t += 2) {
;             const bool last = (t == nt - 2);
;             const char* a1 = cA + (size_t)(t + 1) * kstep;
;             const char* a2 = last ? nA : cA + (size_t)(t + 2) * kstep; const char* b2 = last ? nB : cB + (size_t)(t + 2) * kstep;
;             const char* a3 = a2 + kstep; const char* b3 = b2 + kstep;
;             if (last && has_next) S.a_ready(nxt);
;             if constexpr (SP2) {
;             PG8_LDB(B0, 0, 0); PG8_LDB(B1, 0, 1); PG8_SCHED; PG8_LDA(At, 0, 0); PG8_STAGE(PG8_SA(1, 1), a1 + hstep, voffA);
;             PG8_WAIT_V(8); PG8_WAIT_L(0); PG8_BAR; PG8_MMA(0, 0, At, B0); PG8_MMA(0, 1, At, B1); PG8_BAR; PG8_SCHED;
;             PG8_LDA(At, 0, 1); PG8_STAGE(PG8_SB(0, 0), b2, voffB); PG8_STAGE(PG8_SB(0, 1), b2 + hstep, voffB); PG8_STAGE(PG8_SA(0, 0), a2, voffA);
;             PG8_WAIT_V(8); PG8_WAIT_L(0); PG8_BAR; PG8_MMA(1, 0, At, B0); PG8_MMA(1, 1, At, B1); PG8_BAR; PG8_SCHED;
;             PG8_LDB(B0, 1, 0); PG8_LDB(B1, 1, 1); PG8_SCHED; PG8_LDA(At, 1, 0); PG8_STAGE(PG8_SA(0, 1), a2 + hstep, voffA);
;             PG8_WAIT_V(8); PG8_WAIT_L(0); PG8_BAR; PG8_MMA(0, 0, At, B0); PG8_MMA(0, 1, At, B1); PG8_BAR; PG8_SCHED;
;             PG8_LDA(At, 1, 1); PG8_STAGE(PG8_SB(1, 0), b3, voffB); PG8_STAGE(PG8_SB(1, 1), b3 + hstep, voffB); PG8_STAGE(PG8_SA(1, 0), a3, voffA);
;             PG8_WAIT_V(8); PG8_WAIT_L(0); PG8_BAR; PG8_MMA(1, 0, At, B0); PG8_MMA(1, 1, At, B1); PG8_BAR; PG8_SCHED;
	s_waitcnt lgkmcnt(0)
	v_mfma_f32_16x16x32_bf16 v[140:143], v[124:127], v[164:167], v[140:143]
	v_mfma_f32_16x16x32_bf16 v[140:143], v[128:131], v[168:171], v[140:143]
	v_mfma_f32_16x16x32_bf16 v[112:115], v[128:131], v[176:179], v[112:115]
	v_mfma_f32_16x16x32_bf16 v[112:115], v[124:127], v[172:175], v[112:115]
	v_mfma_f32_16x16x32_bf16 v[96:99], v[124:127], v[180:183], v[96:99]
	v_mfma_f32_16x16x32_bf16 v[96:99], v[128:131], v[184:187], v[96:99]
	v_mfma_f32_16x16x32_bf16 v[80:83], v[128:131], v[214:217], v[80:83]
	v_mfma_f32_16x16x32_bf16 v[80:83], v[124:127], v[188:191], v[80:83]
	v_mfma_f32_16x16x32_bf16 v[76:79], v[132:135], v[188:191], v[76:79]
	v_mfma_f32_16x16x32_bf16 v[76:79], v[144:147], v[214:217], v[76:79]
	v_mfma_f32_16x16x32_bf16 v[92:95], v[144:147], v[184:187], v[92:95]
	v_mfma_f32_16x16x32_bf16 v[92:95], v[132:135], v[180:183], v[92:95]
	v_mfma_f32_16x16x32_bf16 v[108:111], v[132:135], v[172:175], v[108:111]
	v_mfma_f32_16x16x32_bf16 v[108:111], v[144:147], v[176:179], v[108:111]
	v_mfma_f32_16x16x32_bf16 v[136:139], v[144:147], v[168:171], v[136:139]
	v_mfma_f32_16x16x32_bf16 v[136:139], v[132:135], v[164:167], v[136:139]
	v_mfma_f32_16x16x32_bf16 v[120:123], v[148:151], v[164:167], v[120:123]
	v_mfma_f32_16x16x32_bf16 v[120:123], v[152:155], v[168:171], v[120:123]
	v_mfma_f32_16x16x32_bf16 v[104:107], v[152:155], v[176:179], v[104:107]
	v_mfma_f32_16x16x32_bf16 v[104:107], v[148:151], v[172:175], v[104:107]
	v_mfma_f32_16x16x32_bf16 v[88:91], v[148:151], v[180:183], v[88:91]
	v_mfma_f32_16x16x32_bf16 v[88:91], v[152:155], v[184:187], v[88:91]
	v_mfma_f32_16x16x32_bf16 v[72:75], v[152:155], v[214:217], v[72:75]
	v_mfma_f32_16x16x32_bf16 v[72:75], v[148:151], v[188:191], v[72:75]
	v_mfma_f32_16x16x32_bf16 v[68:71], v[156:159], v[188:191], v[68:71]
	v_mfma_f32_16x16x32_bf16 v[68:71], v[160:163], v[214:217], v[68:71]
	v_mfma_f32_16x16x32_bf16 v[84:87], v[160:163], v[184:187], v[84:87]
	v_mfma_f32_16x16x32_bf16 v[84:87], v[156:159], v[180:183], v[84:87]
	v_mfma_f32_16x16x32_bf16 v[100:103], v[156:159], v[172:175], v[100:103]
	v_mfma_f32_16x16x32_bf16 v[100:103], v[160:163], v[176:179], v[100:103]
	v_mfma_f32_16x16x32_bf16 v[116:119], v[160:163], v[168:171], v[116:119]
	v_mfma_f32_16x16x32_bf16 v[116:119], v[156:159], v[164:167], v[116:119]
	s_barrier
	s_setprio 0
	s_add_i32 s22, s56, s41
	v_lshl_add_u64 v[218:219], v[218:219], 0, s[84:85]
	s_mov_b32 m0, s22
	ds_read_b128 v[164:167], v242 offset:49152
	ds_read_b128 v[168:171], v242 offset:50176
	ds_read_b128 v[172:175], v242 offset:51200
	ds_read_b128 v[176:179], v242 offset:52224
	ds_read_b128 v[180:183], v242 offset:53248
	ds_read_b128 v[184:187], v242 offset:54272
	ds_read_b128 v[188:191], v242 offset:55296
	ds_read_b128 v[214:217], v242 offset:56320
	global_load_lds_dwordx4 v[218:219], off
	s_add_i32 m0, s22, 0x2000
	s_add_u32 s22, s26, 0x2b0080
	v_lshl_add_u64 v[218:219], v[220:221], 0, s[84:85]
	s_addc_u32 s23, s27, 0
	s_add_i32 s26, s57, s41
	global_load_lds_dwordx4 v[218:219], off
	s_mov_b32 m0, s26
	s_nop 0
	global_load_lds_dwordx4 v2, s[22:23]
	s_add_i32 m0, s26, 0x2000
	s_nop 0
	global_load_lds_dwordx4 v204, s[22:23]
	s_cmpk_eq_i32 s55, 0xa8
	s_cbranch_scc0 .Ldefer_1700_body
	v_lshl_add_u64 v[218:219], v[222:223], 0, s[84:85]
	s_mov_b32 m0, s46
	s_nop 0
	global_load_lds_dwordx4 v[218:219], off
	v_lshl_add_u64 v[218:219], v[224:225], 0, s[84:85]
	s_mov_b32 m0, s47
	s_nop 0
	global_load_lds_dwordx4 v[218:219], off
.Ldefer_1700_body:
	s_waitcnt vmcnt(6)
	s_waitcnt lgkmcnt(0)
	s_setprio 1
	s_barrier
	s_waitcnt lgkmcnt(0)
	v_mfma_f32_16x16x32_bf16 v[64:67], v[124:127], v[164:167], v[64:67]
	v_mfma_f32_16x16x32_bf16 v[64:67], v[128:131], v[168:171], v[64:67]
	v_mfma_f32_16x16x32_bf16 v[48:51], v[128:131], v[176:179], v[48:51]
	v_mfma_f32_16x16x32_bf16 v[48:51], v[124:127], v[172:175], v[48:51]
	v_mfma_f32_16x16x32_bf16 v[32:35], v[124:127], v[180:183], v[32:35]
	v_mfma_f32_16x16x32_bf16 v[32:35], v[128:131], v[184:187], v[32:35]
	v_mfma_f32_16x16x32_bf16 v[16:19], v[128:131], v[214:217], v[16:19]
	v_mfma_f32_16x16x32_bf16 v[16:19], v[124:127], v[188:191], v[16:19]
	v_mfma_f32_16x16x32_bf16 v[12:15], v[132:135], v[188:191], v[12:15]
	v_mfma_f32_16x16x32_bf16 v[12:15], v[144:147], v[214:217], v[12:15]
	v_mfma_f32_16x16x32_bf16 v[28:31], v[144:147], v[184:187], v[28:31]
	v_mfma_f32_16x16x32_bf16 v[28:31], v[132:135], v[180:183], v[28:31]
	v_mfma_f32_16x16x32_bf16 v[44:47], v[132:135], v[172:175], v[44:47]
	v_mfma_f32_16x16x32_bf16 v[44:47], v[144:147], v[176:179], v[44:47]
	v_mfma_f32_16x16x32_bf16 v[60:63], v[144:147], v[168:171], v[60:63]
	v_mfma_f32_16x16x32_bf16 v[60:63], v[132:135], v[164:167], v[60:63]
	v_mfma_f32_16x16x32_bf16 v[56:59], v[148:151], v[164:167], v[56:59]
	v_mfma_f32_16x16x32_bf16 v[56:59], v[152:155], v[168:171], v[56:59]
	v_mfma_f32_16x16x32_bf16 v[40:43], v[152:155], v[176:179], v[40:43]
	v_mfma_f32_16x16x32_bf16 v[40:43], v[148:151], v[172:175], v[40:43]
	v_mfma_f32_16x16x32_bf16 v[24:27], v[148:151], v[180:183], v[24:27]
	v_mfma_f32_16x16x32_bf16 v[24:27], v[152:155], v[184:187], v[24:27]
	v_mfma_f32_16x16x32_bf16 v[8:11], v[152:155], v[214:217], v[8:11]
	v_mfma_f32_16x16x32_bf16 v[8:11], v[148:151], v[188:191], v[8:11]
	v_mfma_f32_16x16x32_bf16 v[4:7], v[156:159], v[188:191], v[4:7]
	v_mfma_f32_16x16x32_bf16 v[4:7], v[160:163], v[214:217], v[4:7]
	v_mfma_f32_16x16x32_bf16 v[20:23], v[160:163], v[184:187], v[20:23]
	v_mfma_f32_16x16x32_bf16 v[20:23], v[156:159], v[180:183], v[20:23]
	v_mfma_f32_16x16x32_bf16 v[36:39], v[156:159], v[172:175], v[36:39]
	v_mfma_f32_16x16x32_bf16 v[36:39], v[160:163], v[176:179], v[36:39]
	v_mfma_f32_16x16x32_bf16 v[52:55], v[160:163], v[168:171], v[52:55]
	v_mfma_f32_16x16x32_bf16 v[52:55], v[156:159], v[164:167], v[52:55]
	s_barrier
	s_setprio 0
	s_add_i32 s55, s55, 2
	s_add_u32 s53, s53, 0x100
	s_addc_u32 s54, s54, 0
	s_cmpk_gt_u32 s55, 0xa9
	s_mov_b64 s[22:23], s[24:25]
	s_cbranch_scc0 .LBB0_1700

; #define PG8_STAGE(bufoff, gbase, voff) do { _Pragma("unroll") for (int _i = 0; _i < 2; ++_i) \
;         __builtin_amdgcn_global_load_lds((const unsigned*)((const char*)(gbase) + (voff)[_i]), (PG8_LAS unsigned*)(lds + (bufoff) + ldsw + _i * 8192), 16, 0, 0); } while (0)
; #define PG8_LDA(dst, b, h) do { _Pragma("unroll") for (int m = 0; m < 4; ++m) _Pragma("unroll") for (int k = 0; k < 2; ++k) dst[m][k] = *(const PG8_LAS bf16x8*)(lds + PG8_SA(b, h) + aoff + m * 2048 + k * 1024); } while (0)
; #define PG8_LDB(dst, b, h) do { _Pragma("unroll") for (int n = 0; n < 2; ++n) _Pragma("unroll") for (int k = 0; k < 2; ++k) dst[n][k] = *(const PG8_LAS bf16x8*)(lds + PG8_SB(b, h) + boff + n * 2048 + k * 1024); } while (0)
; #define PG8_WAIT_V(n) asm volatile("s_waitcnt vmcnt(" #n ")" ::: "memory")
; #define PG8_WAIT_L(n) asm volatile("s_waitcnt lgkmcnt(" #n ")" ::: "memory")
; #define PG8_BAR __builtin_amdgcn_s_barrier()
; #define PG8_SCHED __builtin_amdgcn_sched_barrier(0)
; template <class Epi, class Sched, bool ALIGN_EPI = false, bool SP2 = false, bool I8 = false>
; __device__ __forceinline__ void gemm_phase(PG8_LAS unsigned char* lds, const Gemm g, const Sched& S, const Epi& E) {
;     ...
;         const bool has_next = S.next(ui + 1, nxt);
;         const char* nA = has_next ? (const char*)g.A + (size_t)nxt.pm * tstep : cA; const char* nB = has_next ? (const char*)g.Bt + (size_t)nxt.pn * tstep : cB;
;         for (int t = 0; t < nt; t += 2) {
;             const bool last = (t == nt - 2);
;             const char* a1 = cA + (size_t)(t + 1) * kstep;
;             const char* a2 = last ? nA : cA + (size_t)(t + 2) * kstep; const char* b2 = last ? nB : cB + (size_t)(t + 2) * kstep;
;             const char* a3 = a2 + kstep; const char* b3 = b2 + kstep;
;             if (last && has_next) S.a_ready(nxt);
;             if constexpr (SP2) {
;             PG8_LDB(B0, 0, 0); PG8_LDB(B1, 0, 1); PG8_SCHED; PG8_LDA(At, 0, 0); PG8_STAGE(PG8_SA(1, 1), a1 + hstep, voffA);
;             PG8_WAIT_V(8); PG8_WAIT_L(0); PG8_BAR; PG8_MMA(0, 0, At, B0); PG8_MMA(0, 1, At, B1); PG8_BAR; PG8_SCHED;
;             PG8_LDA(At, 0, 1); PG8_STAGE(PG8_SB(0, 0), b2, voffB); PG8_STAGE(PG8_SB(0, 1), b2 + hstep, voffB); PG8_STAGE(PG8_SA(0, 0), a2, voffA);
.LBB0_1842:
	s_ashr_i32 s45, s44, 31
	s_lshl_b64 s[34:35], s[44:45], 20
	s_add_u32 s50, s47, s34
	s_addc_u32 s51, s52, s35
	s_and_b64 s[34:35], s[8:9], exec
	s_cselect_b32 s11, s51, s55
	s_cselect_b32 s13, s50, s54
	s_ashr_i32 s49, s48, 31
	s_lshl_b64 s[34:35], s[48:49], 20
	s_add_u32 s56, s53, s34
	s_addc_u32 s57, s64, s35
	s_and_b64 s[34:35], s[8:9], exec
	s_cselect_b32 s34, s57, s59
	s_cselect_b32 s35, s56, s58
	s_add_u32 s54, s54, 0x80080
	s_addc_u32 s55, s55, 0
	s_add_u32 s45, s58, 0x100
	s_addc_u32 s49, s59, 0
	s_mov_b32 s86, -2
	s_waitcnt lgkmcnt(0)
	s_add_u32 s58, s54, 0xfff80080
	s_addc_u32 s59, s55, -1
	s_add_i32 s87, 0, 0x10000
	s_cmp_eq_u32 s86, 28
	s_cselect_b32 s61, s11, s59
	s_cselect_b32 s60, s13, s58
	s_cselect_b32 s59, s34, s49
	s_cselect_b32 s58, s35, s45
	s_add_i32 vcc_lo, 0, 0x14000
	v_add_u32_e32 v40, s87, v217
	v_add_u32_e32 v160, vcc_lo, v217
	ds_read_b128 v[28:31], v40
	ds_read_b128 v[32:35], v40 offset:1024
	ds_read_b128 v[36:39], v40 offset:2048
	ds_read_b128 v[40:43], v40 offset:3072
	ds_read_b128 v[140:143], v160
	ds_read_b128 v[144:147], v160 offset:1024
	ds_read_b128 v[156:159], v160 offset:2048
	ds_read_b128 v[160:163], v160 offset:3072
	s_add_i32 m0, s65, 0xc000
	ds_read_b128 v[164:167], v219
	ds_read_b128 v[168:171], v219 offset:1024
	ds_read_b128 v[172:175], v219 offset:2048
	ds_read_b128 v[176:179], v219 offset:3072
	ds_read_b128 v[204:207], v219 offset:4096
	ds_read_b128 v[208:211], v219 offset:5120
	ds_read_b128 v[212:215], v219 offset:6144
	ds_read_b128 v[220:223], v219 offset:7168
	global_load_lds_dwordx4 v186, s[54:55]
	s_add_i32 m0, s65, 0xe000
	s_nop 0
	global_load_lds_dwordx4 v188, s[54:55]
	s_waitcnt vmcnt(8)
	s_waitcnt lgkmcnt(0)
	s_setprio 1
	s_barrier
	s_waitcnt lgkmcnt(0)
	v_mfma_i32_16x16x64_i8 v[152:155], v[28:31], v[164:167], 0
	v_mfma_i32_16x16x64_i8 v[152:155], v[32:35], v[168:171], v[152:155]
	v_mfma_i32_16x16x64_i8 v[128:131], v[32:35], v[176:179], 0
	v_mfma_i32_16x16x64_i8 v[128:131], v[28:31], v[172:175], v[128:131]
	v_mfma_i32_16x16x64_i8 v[112:115], v[28:31], v[204:207], 0
	v_mfma_i32_16x16x64_i8 v[112:115], v[32:35], v[208:211], v[112:115]
	v_mfma_i32_16x16x64_i8 v[96:99], v[32:35], v[220:223], 0
	v_mfma_i32_16x16x64_i8 v[96:99], v[28:31], v[212:215], v[96:99]
	v_mfma_i32_16x16x64_i8 v[92:95], v[36:39], v[212:215], 0
	v_mfma_i32_16x16x64_i8 v[92:95], v[40:43], v[220:223], v[92:95]
	v_mfma_i32_16x16x64_i8 v[108:111], v[40:43], v[208:211], 0
	v_mfma_i32_16x16x64_i8 v[108:111], v[36:39], v[204:207], v[108:111]
	v_mfma_i32_16x16x64_i8 v[124:127], v[36:39], v[172:175], 0
	v_mfma_i32_16x16x64_i8 v[124:127], v[40:43], v[176:179], v[124:127]
	v_mfma_i32_16x16x64_i8 v[148:151], v[40:43], v[168:171], 0
	v_mfma_i32_16x16x64_i8 v[148:151], v[36:39], v[164:167], v[148:151]
	v_mfma_i32_16x16x64_i8 v[136:139], v[140:143], v[164:167], 0
	v_mfma_i32_16x16x64_i8 v[136:139], v[144:147], v[168:171], v[136:139]
	v_mfma_i32_16x16x64_i8 v[120:123], v[144:147], v[176:179], 0
	v_mfma_i32_16x16x64_i8 v[120:123], v[140:143], v[172:175], v[120:123]
	v_mfma_i32_16x16x64_i8 v[104:107], v[140:143], v[204:207], 0
	v_mfma_i32_16x16x64_i8 v[104:107], v[144:147], v[208:211], v[104:107]
	v_mfma_i32_16x16x64_i8 v[88:91], v[144:147], v[220:223], 0
	v_mfma_i32_16x16x64_i8 v[88:91], v[140:143], v[212:215], v[88:91]
	v_mfma_i32_16x16x64_i8 v[84:87], v[156:159], v[212:215], 0
	v_mfma_i32_16x16x64_i8 v[84:87], v[160:163], v[220:223], v[84:87]
	v_mfma_i32_16x16x64_i8 v[100:103], v[160:163], v[208:211], 0
	v_mfma_i32_16x16x64_i8 v[100:103], v[156:159], v[204:207], v[100:103]
	v_mfma_i32_16x16x64_i8 v[116:119], v[156:159], v[172:175], 0
	v_mfma_i32_16x16x64_i8 v[116:119], v[160:163], v[176:179], v[116:119]
	v_mfma_i32_16x16x64_i8 v[132:135], v[160:163], v[168:171], 0
	v_mfma_i32_16x16x64_i8 v[132:135], v[156:159], v[164:167], v[132:135]
	s_barrier
	s_setprio 0
	s_add_i32 s87, s87, s46
	v_lshl_add_u64 v[190:191], s[58:59], 0, v[2:3]
	s_mov_b32 m0, s87
	ds_read_b128 v[164:167], v219 offset:16384
	ds_read_b128 v[168:171], v219 offset:17408
	ds_read_b128 v[172:175], v219 offset:18432
	ds_read_b128 v[176:179], v219 offset:19456
	ds_read_b128 v[204:207], v219 offset:20480
	ds_read_b128 v[208:211], v219 offset:21504
	ds_read_b128 v[212:215], v219 offset:22528
	ds_read_b128 v[220:223], v219 offset:23552
	global_load_lds_dwordx4 v[190:191], off
	s_add_i32 m0, s87, 0x2000
	s_add_u32 s96, s58, 0x80000
	v_lshl_add_u64 v[224:225], s[58:59], 0, v[184:185]
	s_addc_u32 s97, s59, 0
	s_add_i32 s87, vcc_lo, s46
	global_load_lds_dwordx4 v[224:225], off
	s_mov_b32 m0, s87
	v_lshl_add_u64 v[228:229], s[60:61], 0, v[182:183]
	global_load_lds_dwordx4 v2, s[96:97]
	s_add_i32 m0, s87, 0x2000
	s_nop 0
	global_load_lds_dwordx4 v184, s[96:97]
	v_lshl_add_u64 v[226:227], s[60:61], 0, v[180:181]
	s_waitcnt vmcnt(6)
	s_waitcnt lgkmcnt(0)
	s_setprio 1
	s_barrier
; #define PG8_STAGE(bufoff, gbase, voff) do { _Pragma("unroll") for (int _i = 0; _i < 2; ++_i) \
;         __builtin_amdgcn_global_load_lds((const unsigned*)((const char*)(gbase) + (voff)[_i]), (PG8_LAS unsigned*)(lds + (bufoff) + ldsw + _i * 8192), 16, 0, 0); } while (0)
; #define PG8_LDA(dst, b, h) do { _Pragma("unroll") for (int m = 0; m < 4; ++m) _Pragma("unroll") for (int k = 0; k < 2; ++k) dst[m][k] = *(const PG8_LAS bf16x8*)(lds + PG8_SA(b, h) + aoff + m * 2048 + k * 1024); } while (0)
; #define PG8_LDB(dst, b, h) do { _Pragma("unroll") for (int n = 0; n < 2; ++n) _Pragma("unroll") for (int k = 0; k < 2; ++k) dst[n][k] = *(const PG8_LAS bf16x8*)(lds + PG8_SB(b, h) + boff + n * 2048 + k * 1024); } while (0)
; #define PG8_WAIT_V(n) asm volatile("s_waitcnt vmcnt(" #n ")" ::: "memory")
; #define PG8_WAIT_L(n) asm volatile("s_waitcnt lgkmcnt(" #n ")" ::: "memory")
; #define PG8_BAR __builtin_amdgcn_s_barrier()
; #define PG8_SCHED __builtin_amdgcn_sched_barrier(0)
; template <class Epi, class Sched, bool ALIGN_EPI = false, bool SP2 = false, bool I8 = false>
; __device__ __forceinline__ void gemm_phase(PG8_LAS unsigned char* lds, const Gemm g, const Sched& S, const Epi& E) {
;     ...
;             if constexpr (SP2) {
;             PG8_LDB(B0, 0, 0); PG8_LDB(B1, 0, 1); PG8_SCHED; PG8_LDA(At, 0, 0); PG8_STAGE(PG8_SA(1, 1), a1 + hstep, voffA);
;             PG8_WAIT_V(8); PG8_WAIT_L(0); PG8_BAR; PG8_MMA(0, 0, At, B0); PG8_MMA(0, 1, At, B1); PG8_BAR; PG8_SCHED;
;             PG8_LDA(At, 0, 1); PG8_STAGE(PG8_SB(0, 0), b2, voffB); PG8_STAGE(PG8_SB(0, 1), b2 + hstep, voffB); PG8_STAGE(PG8_SA(0, 0), a2, voffA);
;             PG8_WAIT_V(8); PG8_WAIT_L(0); PG8_BAR; PG8_MMA(1, 0, At, B0); PG8_MMA(1, 1, At, B1); PG8_BAR; PG8_SCHED;
;             PG8_LDB(B0, 1, 0); PG8_LDB(B1, 1, 1); PG8_SCHED; PG8_LDA(At, 1, 0); PG8_STAGE(PG8_SA(0, 1), a2 + hstep, voffA);
;             PG8_WAIT_V(8); PG8_WAIT_L(0); PG8_BAR; PG8_MMA(0, 0, At, B0); PG8_MMA(0, 1, At, B1); PG8_BAR; PG8_SCHED;
;             PG8_LDA(At, 1, 1); PG8_STAGE(PG8_SB(1, 0), b3, voffB); PG8_STAGE(PG8_SB(1, 1), b3 + hstep, voffB); PG8_STAGE(PG8_SA(1, 0), a3, voffA);
;             PG8_WAIT_V(8); PG8_WAIT_L(0); PG8_BAR; PG8_MMA(1, 0, At, B0); PG8_MMA(1, 1, At, B1); PG8_BAR; PG8_SCHED;
	s_waitcnt lgkmcnt(0)
	v_mfma_i32_16x16x64_i8 v[80:83], v[28:31], v[164:167], 0
	v_mfma_i32_16x16x64_i8 v[80:83], v[32:35], v[168:171], v[80:83]
	v_mfma_i32_16x16x64_i8 v[64:67], v[32:35], v[176:179], 0
	v_mfma_i32_16x16x64_i8 v[64:67], v[28:31], v[172:175], v[64:67]
	v_mfma_i32_16x16x64_i8 v[48:51], v[28:31], v[204:207], 0
	v_mfma_i32_16x16x64_i8 v[48:51], v[32:35], v[208:211], v[48:51]
	v_mfma_i32_16x16x64_i8 v[16:19], v[32:35], v[220:223], 0
	v_mfma_i32_16x16x64_i8 v[16:19], v[28:31], v[212:215], v[16:19]
	v_mfma_i32_16x16x64_i8 v[12:15], v[36:39], v[212:215], 0
	v_mfma_i32_16x16x64_i8 v[12:15], v[40:43], v[220:223], v[12:15]
	v_mfma_i32_16x16x64_i8 v[44:47], v[40:43], v[208:211], 0
	v_mfma_i32_16x16x64_i8 v[44:47], v[36:39], v[204:207], v[44:47]
	v_mfma_i32_16x16x64_i8 v[60:63], v[36:39], v[172:175], 0
	v_mfma_i32_16x16x64_i8 v[60:63], v[40:43], v[176:179], v[60:63]
	v_mfma_i32_16x16x64_i8 v[76:79], v[40:43], v[168:171], 0
	v_mfma_i32_16x16x64_i8 v[76:79], v[36:39], v[164:167], v[76:79]
	v_mfma_i32_16x16x64_i8 v[28:31], v[140:143], v[164:167], 0
	v_mfma_i32_16x16x64_i8 v[28:31], v[144:147], v[168:171], v[28:31]
	v_mfma_i32_16x16x64_i8 v[36:39], v[144:147], v[176:179], 0
	v_mfma_i32_16x16x64_i8 v[36:39], v[140:143], v[172:175], v[36:39]
	v_mfma_i32_16x16x64_i8 v[24:27], v[140:143], v[204:207], 0
	v_mfma_i32_16x16x64_i8 v[24:27], v[144:147], v[208:211], v[24:27]
	v_mfma_i32_16x16x64_i8 v[8:11], v[144:147], v[220:223], 0
	v_mfma_i32_16x16x64_i8 v[8:11], v[140:143], v[212:215], v[8:11]
	v_mfma_i32_16x16x64_i8 v[4:7], v[156:159], v[212:215], 0
	v_mfma_i32_16x16x64_i8 v[4:7], v[160:163], v[220:223], v[4:7]
	v_mfma_i32_16x16x64_i8 v[20:23], v[160:163], v[208:211], 0
	v_mfma_i32_16x16x64_i8 v[20:23], v[156:159], v[204:207], v[20:23]
	v_mfma_i32_16x16x64_i8 v[40:43], v[156:159], v[172:175], 0
	v_mfma_i32_16x16x64_i8 v[40:43], v[160:163], v[176:179], v[40:43]
	v_mfma_i32_16x16x64_i8 v[32:35], v[160:163], v[168:171], 0
	v_mfma_i32_16x16x64_i8 v[32:35], v[156:159], v[164:167], v[32:35]
	s_barrier
	s_setprio 0
	s_mov_b32 m0, s65
	s_nop 0
	global_load_lds_dwordx4 v[226:227], off
	s_mov_b32 m0, s67
	s_nop 0
	global_load_lds_dwordx4 v[228:229], off
	s_add_i32 s87, 0, 0x18000
	s_add_i32 s96, 0, 0x1c000
	v_add_u32_e32 v72, s87, v217
	v_add_u32_e32 v160, s96, v217
	ds_read_b128 v[52:55], v72
	ds_read_b128 v[56:59], v72 offset:1024
	ds_read_b128 v[68:71], v72 offset:2048
	ds_read_b128 v[72:75], v72 offset:3072
	ds_read_b128 v[140:143], v160
	ds_read_b128 v[144:147], v160 offset:1024
	ds_read_b128 v[156:159], v160 offset:2048
	ds_read_b128 v[160:163], v160 offset:3072
	s_add_u32 s60, s60, 0x80000
	s_addc_u32 s61, s61, 0
	s_mov_b32 m0, s72
	ds_read_b128 v[164:167], v219 offset:32768
	ds_read_b128 v[168:171], v219 offset:33792
	ds_read_b128 v[172:175], v219 offset:34816
	ds_read_b128 v[176:179], v219 offset:35840
	ds_read_b128 v[204:207], v219 offset:36864
	ds_read_b128 v[208:211], v219 offset:37888
	ds_read_b128 v[212:215], v219 offset:38912
	ds_read_b128 v[220:223], v219 offset:39936
	global_load_lds_dwordx4 v180, s[60:61]
	s_mov_b32 m0, s73
	s_nop 0
	global_load_lds_dwordx4 v182, s[60:61]
	s_waitcnt vmcnt(8)
	s_waitcnt lgkmcnt(0)
	s_setprio 1
	s_barrier
	s_waitcnt lgkmcnt(0)
	v_mfma_i32_16x16x64_i8 v[152:155], v[52:55], v[164:167], v[152:155]
	v_mfma_i32_16x16x64_i8 v[152:155], v[56:59], v[168:171], v[152:155]
	v_mfma_i32_16x16x64_i8 v[128:131], v[56:59], v[176:179], v[128:131]
	v_mfma_i32_16x16x64_i8 v[128:131], v[52:55], v[172:175], v[128:131]
	v_mfma_i32_16x16x64_i8 v[112:115], v[52:55], v[204:207], v[112:115]
	v_mfma_i32_16x16x64_i8 v[112:115], v[56:59], v[208:211], v[112:115]
	v_mfma_i32_16x16x64_i8 v[96:99], v[56:59], v[220:223], v[96:99]
	v_mfma_i32_16x16x64_i8 v[96:99], v[52:55], v[212:215], v[96:99]
	v_mfma_i32_16x16x64_i8 v[92:95], v[68:71], v[212:215], v[92:95]
	v_mfma_i32_16x16x64_i8 v[92:95], v[72:75], v[220:223], v[92:95]
	v_mfma_i32_16x16x64_i8 v[108:111], v[72:75], v[208:211], v[108:111]
	v_mfma_i32_16x16x64_i8 v[108:111], v[68:71], v[204:207], v[108:111]
	v_mfma_i32_16x16x64_i8 v[124:127], v[68:71], v[172:175], v[124:127]
	v_mfma_i32_16x16x64_i8 v[124:127], v[72:75], v[176:179], v[124:127]
	v_mfma_i32_16x16x64_i8 v[148:151], v[72:75], v[168:171], v[148:151]
	v_mfma_i32_16x16x64_i8 v[148:151], v[68:71], v[164:167], v[148:151]
	v_mfma_i32_16x16x64_i8 v[136:139], v[140:143], v[164:167], v[136:139]
	v_mfma_i32_16x16x64_i8 v[136:139], v[144:147], v[168:171], v[136:139]
	v_mfma_i32_16x16x64_i8 v[120:123], v[144:147], v[176:179], v[120:123]
	v_mfma_i32_16x16x64_i8 v[120:123], v[140:143], v[172:175], v[120:123]
	v_mfma_i32_16x16x64_i8 v[104:107], v[140:143], v[204:207], v[104:107]
	v_mfma_i32_16x16x64_i8 v[104:107], v[144:147], v[208:211], v[104:107]
	v_mfma_i32_16x16x64_i8 v[88:91], v[144:147], v[220:223], v[88:91]
	v_mfma_i32_16x16x64_i8 v[88:91], v[140:143], v[212:215], v[88:91]
	v_mfma_i32_16x16x64_i8 v[84:87], v[156:159], v[212:215], v[84:87]
	v_mfma_i32_16x16x64_i8 v[84:87], v[160:163], v[220:223], v[84:87]
	v_mfma_i32_16x16x64_i8 v[100:103], v[160:163], v[208:211], v[100:103]
	v_mfma_i32_16x16x64_i8 v[100:103], v[156:159], v[204:207], v[100:103]
	v_mfma_i32_16x16x64_i8 v[116:119], v[156:159], v[172:175], v[116:119]
	v_mfma_i32_16x16x64_i8 v[116:119], v[160:163], v[176:179], v[116:119]
	v_mfma_i32_16x16x64_i8 v[132:135], v[160:163], v[168:171], v[132:135]
	v_mfma_i32_16x16x64_i8 v[132:135], v[156:159], v[164:167], v[132:135]
	s_barrier
	s_setprio 0
	s_add_i32 s60, s87, s46
	v_lshl_add_u64 v[190:191], v[190:191], 0, s[84:85]
	s_mov_b32 m0, s60
	ds_read_b128 v[164:167], v219 offset:49152
	ds_read_b128 v[168:171], v219 offset:50176
	ds_read_b128 v[172:175], v219 offset:51200
	ds_read_b128 v[176:179], v219 offset:52224
	ds_read_b128 v[204:207], v219 offset:53248
	ds_read_b128 v[208:211], v219 offset:54272
	ds_read_b128 v[212:215], v219 offset:55296
	ds_read_b128 v[220:223], v219 offset:56320
	global_load_lds_dwordx4 v[190:191], off
	s_add_i32 m0, s60, 0x2000
	s_add_u32 s58, s58, 0x80080
	v_lshl_add_u64 v[190:191], v[224:225], 0, s[84:85]
	s_addc_u32 s59, s59, 0
	s_add_i32 s60, s96, s46
	global_load_lds_dwordx4 v[190:191], off
	s_mov_b32 m0, s60
	s_nop 0
	global_load_lds_dwordx4 v2, s[58:59]
	s_add_i32 m0, s60, 0x2000
	s_nop 0
	global_load_lds_dwordx4 v184, s[58:59]
	s_cmp_eq_u32 s86, 28
	s_cbranch_scc0 .Ldefer_1843_peel
	v_lshl_add_u64 v[190:191], v[226:227], 0, s[84:85]
	s_mov_b32 m0, s28
	s_nop 0
	global_load_lds_dwordx4 v[190:191], off
	v_lshl_add_u64 v[190:191], v[228:229], 0, s[84:85]
	s_mov_b32 m0, s77
	s_nop 0
	global_load_lds_dwordx4 v[190:191], off
; #define PG8_STAGE(bufoff, gbase, voff) do { _Pragma("unroll") for (int _i = 0; _i < 2; ++_i) \
;         __builtin_amdgcn_global_load_lds((const unsigned*)((const char*)(gbase) + (voff)[_i]), (PG8_LAS unsigned*)(lds + (bufoff) + ldsw + _i * 8192), 16, 0, 0); } while (0)
; #define PG8_LDA(dst, b, h) do { _Pragma("unroll") for (int m = 0; m < 4; ++m) _Pragma("unroll") for (int k = 0; k < 2; ++k) dst[m][k] = *(const PG8_LAS bf16x8*)(lds + PG8_SA(b, h) + aoff + m * 2048 + k * 1024); } while (0)
; #define PG8_WAIT_V(n) asm volatile("s_waitcnt vmcnt(" #n ")" ::: "memory")
; #define PG8_WAIT_L(n) asm volatile("s_waitcnt lgkmcnt(" #n ")" ::: "memory")
; #define PG8_BAR __builtin_amdgcn_s_barrier()
; template <class Epi, class Sched, bool ALIGN_EPI = false, bool SP2 = false, bool I8 = false>
; __device__ __forceinline__ void gemm_phase(PG8_LAS unsigned char* lds, const Gemm g, const Sched& S, const Epi& E) {
;     ...
;         for (int t = 0; t < nt; t += 2) {
;             const bool last = (t == nt - 2);
;             const char* a1 = cA + (size_t)(t + 1) * kstep;
;             const char* a2 = last ? nA : cA + (size_t)(t + 2) * kstep; const char* b2 = last ? nB : cB + (size_t)(t + 2) * kstep;
;             const char* a3 = a2 + kstep; const char* b3 = b2 + kstep;
;             if (last && has_next) S.a_ready(nxt);
;             if constexpr (SP2) {
;             PG8_LDB(B0, 0, 0); PG8_LDB(B1, 0, 1); PG8_SCHED; PG8_LDA(At, 0, 0); PG8_STAGE(PG8_SA(1, 1), a1 + hstep, voffA);
;             PG8_WAIT_V(8); PG8_WAIT_L(0); PG8_BAR; PG8_MMA(0, 0, At, B0); PG8_MMA(0, 1, At, B1); PG8_BAR; PG8_SCHED;
;             PG8_LDA(At, 0, 1); PG8_STAGE(PG8_SB(0, 0), b2, voffB); PG8_STAGE(PG8_SB(0, 1), b2 + hstep, voffB); PG8_STAGE(PG8_SA(0, 0), a2, voffA);
;             PG8_WAIT_V(8); PG8_WAIT_L(0); PG8_BAR; PG8_MMA(1, 0, At, B0); PG8_MMA(1, 1, At, B1); PG8_BAR; PG8_SCHED;
;             PG8_LDB(B0, 1, 0); PG8_LDB(B1, 1, 1); PG8_SCHED; PG8_LDA(At, 1, 0); PG8_STAGE(PG8_SA(0, 1), a2 + hstep, voffA);
;             PG8_WAIT_V(8); PG8_WAIT_L(0); PG8_BAR; PG8_MMA(0, 0, At, B0); PG8_MMA(0, 1, At, B1); PG8_BAR; PG8_SCHED;
;             PG8_LDA(At, 1, 1); PG8_STAGE(PG8_SB(1, 0), b3, voffB); PG8_STAGE(PG8_SB(1, 1), b3 + hstep, voffB); PG8_STAGE(PG8_SA(1, 0), a3, voffA);
;             PG8_WAIT_V(8); PG8_WAIT_L(0); PG8_BAR; PG8_MMA(1, 0, At, B0); PG8_MMA(1, 1, At, B1); PG8_BAR; PG8_SCHED;
.Ldefer_1843_peel:
	s_waitcnt vmcnt(6)
	s_waitcnt lgkmcnt(0)
	s_setprio 1
	s_barrier
	s_waitcnt lgkmcnt(0)
	v_mfma_i32_16x16x64_i8 v[80:83], v[52:55], v[164:167], v[80:83]
	v_mfma_i32_16x16x64_i8 v[80:83], v[56:59], v[168:171], v[80:83]
	v_mfma_i32_16x16x64_i8 v[64:67], v[56:59], v[176:179], v[64:67]
	v_mfma_i32_16x16x64_i8 v[64:67], v[52:55], v[172:175], v[64:67]
	v_mfma_i32_16x16x64_i8 v[48:51], v[52:55], v[204:207], v[48:51]
	v_mfma_i32_16x16x64_i8 v[48:51], v[56:59], v[208:211], v[48:51]
	v_mfma_i32_16x16x64_i8 v[16:19], v[56:59], v[220:223], v[16:19]
	v_mfma_i32_16x16x64_i8 v[16:19], v[52:55], v[212:215], v[16:19]
	v_mfma_i32_16x16x64_i8 v[12:15], v[68:71], v[212:215], v[12:15]
	v_mfma_i32_16x16x64_i8 v[12:15], v[72:75], v[220:223], v[12:15]
	v_mfma_i32_16x16x64_i8 v[44:47], v[72:75], v[208:211], v[44:47]
	v_mfma_i32_16x16x64_i8 v[44:47], v[68:71], v[204:207], v[44:47]
	v_mfma_i32_16x16x64_i8 v[60:63], v[68:71], v[172:175], v[60:63]
	v_mfma_i32_16x16x64_i8 v[60:63], v[72:75], v[176:179], v[60:63]
	v_mfma_i32_16x16x64_i8 v[76:79], v[72:75], v[168:171], v[76:79]
	v_mfma_i32_16x16x64_i8 v[76:79], v[68:71], v[164:167], v[76:79]
	v_mfma_i32_16x16x64_i8 v[28:31], v[140:143], v[164:167], v[28:31]
	v_mfma_i32_16x16x64_i8 v[72:75], v[144:147], v[168:171], v[28:31]
	v_mfma_i32_16x16x64_i8 v[28:31], v[144:147], v[176:179], v[36:39]
	v_mfma_i32_16x16x64_i8 v[56:59], v[140:143], v[172:175], v[28:31]
	v_mfma_i32_16x16x64_i8 v[24:27], v[140:143], v[204:207], v[24:27]
	v_mfma_i32_16x16x64_i8 v[24:27], v[144:147], v[208:211], v[24:27]
	v_mfma_i32_16x16x64_i8 v[8:11], v[144:147], v[220:223], v[8:11]
	v_mfma_i32_16x16x64_i8 v[8:11], v[140:143], v[212:215], v[8:11]
	v_mfma_i32_16x16x64_i8 v[4:7], v[156:159], v[212:215], v[4:7]
	v_mfma_i32_16x16x64_i8 v[4:7], v[160:163], v[220:223], v[4:7]
	v_mfma_i32_16x16x64_i8 v[20:23], v[160:163], v[208:211], v[20:23]
	v_mfma_i32_16x16x64_i8 v[20:23], v[156:159], v[204:207], v[20:23]
	v_mfma_i32_16x16x64_i8 v[28:31], v[156:159], v[172:175], v[40:43]
	v_mfma_i32_16x16x64_i8 v[52:55], v[160:163], v[176:179], v[28:31]
	v_mfma_i32_16x16x64_i8 v[28:31], v[160:163], v[168:171], v[32:35]
	v_mfma_i32_16x16x64_i8 v[68:71], v[156:159], v[164:167], v[28:31]
	s_barrier
	s_setprio 0
	s_add_i32 s86, s86, 2
	s_add_u32 s54, s54, 0x100
	s_addc_u32 s55, s55, 0
	s_add_u32 s45, s45, 0x100
	s_addc_u32 s49, s49, 0
	s_cmp_gt_u32 s86, 29
	s_cbranch_scc1 .Lkloop_exit_6
.LBB0_1843:
	s_add_u32 s58, s54, 0xfff80080
	s_addc_u32 s59, s55, -1
	s_add_i32 s87, 0, 0x10000
	s_cmp_eq_u32 s86, 28
	s_cselect_b32 s61, s11, s59
	s_cselect_b32 s60, s13, s58
	s_cselect_b32 s59, s34, s49
	s_cselect_b32 s58, s35, s45
	s_add_i32 vcc_lo, 0, 0x14000
	v_add_u32_e32 v40, s87, v217
	v_add_u32_e32 v160, vcc_lo, v217
	ds_read_b128 v[28:31], v40
	ds_read_b128 v[32:35], v40 offset:1024
	ds_read_b128 v[36:39], v40 offset:2048
	ds_read_b128 v[40:43], v40 offset:3072
	ds_read_b128 v[140:143], v160
	ds_read_b128 v[144:147], v160 offset:1024
	ds_read_b128 v[156:159], v160 offset:2048
	ds_read_b128 v[160:163], v160 offset:3072
	v_lshl_add_u64 v[190:191], v[226:227], 0, s[84:85]
	s_mov_b32 m0, s28
	s_nop 0
	global_load_lds_dwordx4 v[190:191], off
	v_lshl_add_u64 v[190:191], v[228:229], 0, s[84:85]
	s_mov_b32 m0, s77
	s_nop 0
	global_load_lds_dwordx4 v[190:191], off
	s_add_i32 m0, s65, 0xc000
	ds_read_b128 v[164:167], v219
	ds_read_b128 v[168:171], v219 offset:1024
	ds_read_b128 v[172:175], v219 offset:2048
	ds_read_b128 v[176:179], v219 offset:3072
	ds_read_b128 v[204:207], v219 offset:4096
	ds_read_b128 v[208:211], v219 offset:5120
	ds_read_b128 v[212:215], v219 offset:6144
	ds_read_b128 v[220:223], v219 offset:7168
	global_load_lds_dwordx4 v186, s[54:55]
	s_add_i32 m0, s65, 0xe000
	s_nop 0
	global_load_lds_dwordx4 v188, s[54:55]
	s_waitcnt vmcnt(8)
	s_waitcnt lgkmcnt(0)
	s_setprio 1
	s_barrier
	s_waitcnt lgkmcnt(0)
	v_mfma_i32_16x16x64_i8 v[152:155], v[28:31], v[164:167], v[152:155]
	v_mfma_i32_16x16x64_i8 v[152:155], v[32:35], v[168:171], v[152:155]
	v_mfma_i32_16x16x64_i8 v[128:131], v[32:35], v[176:179], v[128:131]
	v_mfma_i32_16x16x64_i8 v[128:131], v[28:31], v[172:175], v[128:131]
	v_mfma_i32_16x16x64_i8 v[112:115], v[28:31], v[204:207], v[112:115]
	v_mfma_i32_16x16x64_i8 v[112:115], v[32:35], v[208:211], v[112:115]
	v_mfma_i32_16x16x64_i8 v[96:99], v[32:35], v[220:223], v[96:99]
	v_mfma_i32_16x16x64_i8 v[96:99], v[28:31], v[212:215], v[96:99]
	v_mfma_i32_16x16x64_i8 v[92:95], v[36:39], v[212:215], v[92:95]
	v_mfma_i32_16x16x64_i8 v[92:95], v[40:43], v[220:223], v[92:95]
	v_mfma_i32_16x16x64_i8 v[108:111], v[40:43], v[208:211], v[108:111]
	v_mfma_i32_16x16x64_i8 v[108:111], v[36:39], v[204:207], v[108:111]
	v_mfma_i32_16x16x64_i8 v[124:127], v[36:39], v[172:175], v[124:127]
	v_mfma_i32_16x16x64_i8 v[124:127], v[40:43], v[176:179], v[124:127]
	v_mfma_i32_16x16x64_i8 v[148:151], v[40:43], v[168:171], v[148:151]
	v_mfma_i32_16x16x64_i8 v[148:151], v[36:39], v[164:167], v[148:151]
	v_mfma_i32_16x16x64_i8 v[136:139], v[140:143], v[164:167], v[136:139]
	v_mfma_i32_16x16x64_i8 v[136:139], v[144:147], v[168:171], v[136:139]
	v_mfma_i32_16x16x64_i8 v[120:123], v[144:147], v[176:179], v[120:123]
	v_mfma_i32_16x16x64_i8 v[120:123], v[140:143], v[172:175], v[120:123]
	v_mfma_i32_16x16x64_i8 v[104:107], v[140:143], v[204:207], v[104:107]
	v_mfma_i32_16x16x64_i8 v[104:107], v[144:147], v[208:211], v[104:107]
	v_mfma_i32_16x16x64_i8 v[88:91], v[144:147], v[220:223], v[88:91]
	v_mfma_i32_16x16x64_i8 v[88:91], v[140:143], v[212:215], v[88:91]
	v_mfma_i32_16x16x64_i8 v[84:87], v[156:159], v[212:215], v[84:87]
	v_mfma_i32_16x16x64_i8 v[84:87], v[160:163], v[220:223], v[84:87]
	v_mfma_i32_16x16x64_i8 v[100:103], v[160:163], v[208:211], v[100:103]
	v_mfma_i32_16x16x64_i8 v[100:103], v[156:159], v[204:207], v[100:103]
	v_mfma_i32_16x16x64_i8 v[116:119], v[156:159], v[172:175], v[116:119]
	v_mfma_i32_16x16x64_i8 v[116:119], v[160:163], v[176:179], v[116:119]
	v_mfma_i32_16x16x64_i8 v[132:135], v[160:163], v[168:171], v[132:135]
	v_mfma_i32_16x16x64_i8 v[132:135], v[156:159], v[164:167], v[132:135]
	s_barrier
; #define PG8_STAGE(bufoff, gbase, voff) do { _Pragma("unroll") for (int _i = 0; _i < 2; ++_i) \
;         __builtin_amdgcn_global_load_lds((const unsigned*)((const char*)(gbase) + (voff)[_i]), (PG8_LAS unsigned*)(lds + (bufoff) + ldsw + _i * 8192), 16, 0, 0); } while (0)
; #define PG8_LDA(dst, b, h) do { _Pragma("unroll") for (int m = 0; m < 4; ++m) _Pragma("unroll") for (int k = 0; k < 2; ++k) dst[m][k] = *(const PG8_LAS bf16x8*)(lds + PG8_SA(b, h) + aoff + m * 2048 + k * 1024); } while (0)
; #define PG8_LDB(dst, b, h) do { _Pragma("unroll") for (int n = 0; n < 2; ++n) _Pragma("unroll") for (int k = 0; k < 2; ++k) dst[n][k] = *(const PG8_LAS bf16x8*)(lds + PG8_SB(b, h) + boff + n * 2048 + k * 1024); } while (0)
; #define PG8_WAIT_V(n) asm volatile("s_waitcnt vmcnt(" #n ")" ::: "memory")
; #define PG8_WAIT_L(n) asm volatile("s_waitcnt lgkmcnt(" #n ")" ::: "memory")
; #define PG8_BAR __builtin_amdgcn_s_barrier()
; #define PG8_SCHED __builtin_amdgcn_sched_barrier(0)
; template <class Epi, class Sched, bool ALIGN_EPI = false, bool SP2 = false, bool I8 = false>
; __device__ __forceinline__ void gemm_phase(PG8_LAS unsigned char* lds, const Gemm g, const Sched& S, const Epi& E) {
;     ...
;             PG8_LDB(B0, 0, 0); PG8_LDB(B1, 0, 1); PG8_SCHED; PG8_LDA(At, 0, 0); PG8_STAGE(PG8_SA(1, 1), a1 + hstep, voffA);
;             PG8_WAIT_V(8); PG8_WAIT_L(0); PG8_BAR; PG8_MMA(0, 0, At, B0); PG8_MMA(0, 1, At, B1); PG8_BAR; PG8_SCHED;
;             PG8_LDA(At, 0, 1); PG8_STAGE(PG8_SB(0, 0), b2, voffB); PG8_STAGE(PG8_SB(0, 1), b2 + hstep, voffB); PG8_STAGE(PG8_SA(0, 0), a2, voffA);
;             PG8_WAIT_V(8); PG8_WAIT_L(0); PG8_BAR; PG8_MMA(1, 0, At, B0); PG8_MMA(1, 1, At, B1); PG8_BAR; PG8_SCHED;
;             PG8_LDB(B0, 1, 0); PG8_LDB(B1, 1, 1); PG8_SCHED; PG8_LDA(At, 1, 0); PG8_STAGE(PG8_SA(0, 1), a2 + hstep, voffA);
;             PG8_WAIT_V(8); PG8_WAIT_L(0); PG8_BAR; PG8_MMA(0, 0, At, B0); PG8_MMA(0, 1, At, B1); PG8_BAR; PG8_SCHED;
;             PG8_LDA(At, 1, 1); PG8_STAGE(PG8_SB(1, 0), b3, voffB); PG8_STAGE(PG8_SB(1, 1), b3 + hstep, voffB); PG8_STAGE(PG8_SA(1, 0), a3, voffA);
;             PG8_WAIT_V(8); PG8_WAIT_L(0); PG8_BAR; PG8_MMA(1, 0, At, B0); PG8_MMA(1, 1, At, B1); PG8_BAR; PG8_SCHED;
	s_setprio 0
	s_add_i32 s87, s87, s46
	v_lshl_add_u64 v[190:191], s[58:59], 0, v[2:3]
	s_mov_b32 m0, s87
	ds_read_b128 v[164:167], v219 offset:16384
	ds_read_b128 v[168:171], v219 offset:17408
	ds_read_b128 v[172:175], v219 offset:18432
	ds_read_b128 v[176:179], v219 offset:19456
	ds_read_b128 v[204:207], v219 offset:20480
	ds_read_b128 v[208:211], v219 offset:21504
	ds_read_b128 v[212:215], v219 offset:22528
	ds_read_b128 v[220:223], v219 offset:23552
	global_load_lds_dwordx4 v[190:191], off
	s_add_i32 m0, s87, 0x2000
	s_add_u32 s96, s58, 0x80000
	v_lshl_add_u64 v[224:225], s[58:59], 0, v[184:185]
	s_addc_u32 s97, s59, 0
	s_add_i32 s87, vcc_lo, s46
	global_load_lds_dwordx4 v[224:225], off
	s_mov_b32 m0, s87
	v_lshl_add_u64 v[228:229], s[60:61], 0, v[182:183]
	global_load_lds_dwordx4 v2, s[96:97]
	s_add_i32 m0, s87, 0x2000
	s_nop 0
	global_load_lds_dwordx4 v184, s[96:97]
	v_lshl_add_u64 v[226:227], s[60:61], 0, v[180:181]
	s_waitcnt vmcnt(6)
	s_waitcnt lgkmcnt(0)
	s_setprio 1
	s_barrier
	s_waitcnt lgkmcnt(0)
	v_mfma_i32_16x16x64_i8 v[80:83], v[28:31], v[164:167], v[80:83]
	v_mfma_i32_16x16x64_i8 v[80:83], v[32:35], v[168:171], v[80:83]
	v_mfma_i32_16x16x64_i8 v[64:67], v[32:35], v[176:179], v[64:67]
	v_mfma_i32_16x16x64_i8 v[64:67], v[28:31], v[172:175], v[64:67]
	v_mfma_i32_16x16x64_i8 v[48:51], v[28:31], v[204:207], v[48:51]
	v_mfma_i32_16x16x64_i8 v[48:51], v[32:35], v[208:211], v[48:51]
	v_mfma_i32_16x16x64_i8 v[16:19], v[32:35], v[220:223], v[16:19]
	v_mfma_i32_16x16x64_i8 v[16:19], v[28:31], v[212:215], v[16:19]
	v_mfma_i32_16x16x64_i8 v[12:15], v[36:39], v[212:215], v[12:15]
	v_mfma_i32_16x16x64_i8 v[12:15], v[40:43], v[220:223], v[12:15]
	v_mfma_i32_16x16x64_i8 v[44:47], v[40:43], v[208:211], v[44:47]
	v_mfma_i32_16x16x64_i8 v[44:47], v[36:39], v[204:207], v[44:47]
	v_mfma_i32_16x16x64_i8 v[60:63], v[36:39], v[172:175], v[60:63]
	v_mfma_i32_16x16x64_i8 v[60:63], v[40:43], v[176:179], v[60:63]
	v_mfma_i32_16x16x64_i8 v[76:79], v[40:43], v[168:171], v[76:79]
	v_mfma_i32_16x16x64_i8 v[76:79], v[36:39], v[164:167], v[76:79]
	v_mfma_i32_16x16x64_i8 v[28:31], v[140:143], v[164:167], v[72:75]
	v_mfma_i32_16x16x64_i8 v[28:31], v[144:147], v[168:171], v[28:31]
	v_mfma_i32_16x16x64_i8 v[36:39], v[144:147], v[176:179], v[56:59]
	v_mfma_i32_16x16x64_i8 v[36:39], v[140:143], v[172:175], v[36:39]
	v_mfma_i32_16x16x64_i8 v[24:27], v[140:143], v[204:207], v[24:27]
	v_mfma_i32_16x16x64_i8 v[24:27], v[144:147], v[208:211], v[24:27]
	v_mfma_i32_16x16x64_i8 v[8:11], v[144:147], v[220:223], v[8:11]
	v_mfma_i32_16x16x64_i8 v[8:11], v[140:143], v[212:215], v[8:11]
	v_mfma_i32_16x16x64_i8 v[4:7], v[156:159], v[212:215], v[4:7]
	v_mfma_i32_16x16x64_i8 v[4:7], v[160:163], v[220:223], v[4:7]
	v_mfma_i32_16x16x64_i8 v[20:23], v[160:163], v[208:211], v[20:23]
	v_mfma_i32_16x16x64_i8 v[20:23], v[156:159], v[204:207], v[20:23]
	v_mfma_i32_16x16x64_i8 v[40:43], v[156:159], v[172:175], v[52:55]
	v_mfma_i32_16x16x64_i8 v[40:43], v[160:163], v[176:179], v[40:43]
	v_mfma_i32_16x16x64_i8 v[32:35], v[160:163], v[168:171], v[68:71]
	v_mfma_i32_16x16x64_i8 v[32:35], v[156:159], v[164:167], v[32:35]
	s_barrier
	s_setprio 0
	s_mov_b32 m0, s65
	s_nop 0
	global_load_lds_dwordx4 v[226:227], off
	s_mov_b32 m0, s67
	s_nop 0
	global_load_lds_dwordx4 v[228:229], off
	s_add_i32 s87, 0, 0x18000
	s_add_i32 s96, 0, 0x1c000
	v_add_u32_e32 v72, s87, v217
	v_add_u32_e32 v160, s96, v217
	ds_read_b128 v[52:55], v72
	ds_read_b128 v[56:59], v72 offset:1024
	ds_read_b128 v[68:71], v72 offset:2048
	ds_read_b128 v[72:75], v72 offset:3072
	ds_read_b128 v[140:143], v160
	ds_read_b128 v[144:147], v160 offset:1024
	ds_read_b128 v[156:159], v160 offset:2048
	ds_read_b128 v[160:163], v160 offset:3072
	s_add_u32 s60, s60, 0x80000
	s_addc_u32 s61, s61, 0
	s_mov_b32 m0, s72
	ds_read_b128 v[164:167], v219 offset:32768
	ds_read_b128 v[168:171], v219 offset:33792
	ds_read_b128 v[172:175], v219 offset:34816
	ds_read_b128 v[176:179], v219 offset:35840
	ds_read_b128 v[204:207], v219 offset:36864
	ds_read_b128 v[208:211], v219 offset:37888
	ds_read_b128 v[212:215], v219 offset:38912
	ds_read_b128 v[220:223], v219 offset:39936
	global_load_lds_dwordx4 v180, s[60:61]
	s_mov_b32 m0, s73
	s_nop 0
	global_load_lds_dwordx4 v182, s[60:61]
	s_waitcnt vmcnt(8)
	s_waitcnt lgkmcnt(0)
	s_setprio 1
	s_barrier
; #define PG8_STAGE(bufoff, gbase, voff) do { _Pragma("unroll") for (int _i = 0; _i < 2; ++_i) \
;         __builtin_amdgcn_global_load_lds((const unsigned*)((const char*)(gbase) + (voff)[_i]), (PG8_LAS unsigned*)(lds + (bufoff) + ldsw + _i * 8192), 16, 0, 0); } while (0)
; #define PG8_LDA(dst, b, h) do { _Pragma("unroll") for (int m = 0; m < 4; ++m) _Pragma("unroll") for (int k = 0; k < 2; ++k) dst[m][k] = *(const PG8_LAS bf16x8*)(lds + PG8_SA(b, h) + aoff + m * 2048 + k * 1024); } while (0)
; #define PG8_LDB(dst, b, h) do { _Pragma("unroll") for (int n = 0; n < 2; ++n) _Pragma("unroll") for (int k = 0; k < 2; ++k) dst[n][k] = *(const PG8_LAS bf16x8*)(lds + PG8_SB(b, h) + boff + n * 2048 + k * 1024); } while (0)
; #define PG8_WAIT_V(n) asm volatile("s_waitcnt vmcnt(" #n ")" ::: "memory")
; #define PG8_WAIT_L(n) asm volatile("s_waitcnt lgkmcnt(" #n ")" ::: "memory")
; #define PG8_BAR __builtin_amdgcn_s_barrier()
; #define PG8_SCHED __builtin_amdgcn_sched_barrier(0)
; template <class Epi, class Sched, bool ALIGN_EPI = false, bool SP2 = false, bool I8 = false>
; __device__ __forceinline__ void gemm_phase(PG8_LAS unsigned char* lds, const Gemm g, const Sched& S, const Epi& E) {
;     ...
;             PG8_LDB(B0, 0, 0); PG8_LDB(B1, 0, 1); PG8_SCHED; PG8_LDA(At, 0, 0); PG8_STAGE(PG8_SA(1, 1), a1 + hstep, voffA);
;             PG8_WAIT_V(8); PG8_WAIT_L(0); PG8_BAR; PG8_MMA(0, 0, At, B0); PG8_MMA(0, 1, At, B1); PG8_BAR; PG8_SCHED;
;             PG8_LDA(At, 0, 1); PG8_STAGE(PG8_SB(0, 0), b2, voffB); PG8_STAGE(PG8_SB(0, 1), b2 + hstep, voffB); PG8_STAGE(PG8_SA(0, 0), a2, voffA);
;             PG8_WAIT_V(8); PG8_WAIT_L(0); PG8_BAR; PG8_MMA(1, 0, At, B0); PG8_MMA(1, 1, At, B1); PG8_BAR; PG8_SCHED;
;             PG8_LDB(B0, 1, 0); PG8_LDB(B1, 1, 1); PG8_SCHED; PG8_LDA(At, 1, 0); PG8_STAGE(PG8_SA(0, 1), a2 + hstep, voffA);
;             PG8_WAIT_V(8); PG8_WAIT_L(0); PG8_BAR; PG8_MMA(0, 0, At, B0); PG8_MMA(0, 1, At, B1); PG8_BAR; PG8_SCHED;
;             PG8_LDA(At, 1, 1); PG8_STAGE(PG8_SB(1, 0), b3, voffB); PG8_STAGE(PG8_SB(1, 1), b3 + hstep, voffB); PG8_STAGE(PG8_SA(1, 0), a3, voffA);
;             PG8_WAIT_V(8); PG8_WAIT_L(0); PG8_BAR; PG8_MMA(1, 0, At, B0); PG8_MMA(1, 1, At, B1); PG8_BAR; PG8_SCHED;
	s_waitcnt lgkmcnt(0)
	v_mfma_i32_16x16x64_i8 v[152:155], v[52:55], v[164:167], v[152:155]
	v_mfma_i32_16x16x64_i8 v[152:155], v[56:59], v[168:171], v[152:155]
	v_mfma_i32_16x16x64_i8 v[128:131], v[56:59], v[176:179], v[128:131]
	v_mfma_i32_16x16x64_i8 v[128:131], v[52:55], v[172:175], v[128:131]
	v_mfma_i32_16x16x64_i8 v[112:115], v[52:55], v[204:207], v[112:115]
	v_mfma_i32_16x16x64_i8 v[112:115], v[56:59], v[208:211], v[112:115]
	v_mfma_i32_16x16x64_i8 v[96:99], v[56:59], v[220:223], v[96:99]
	v_mfma_i32_16x16x64_i8 v[96:99], v[52:55], v[212:215], v[96:99]
	v_mfma_i32_16x16x64_i8 v[92:95], v[68:71], v[212:215], v[92:95]
	v_mfma_i32_16x16x64_i8 v[92:95], v[72:75], v[220:223], v[92:95]
	v_mfma_i32_16x16x64_i8 v[108:111], v[72:75], v[208:211], v[108:111]
	v_mfma_i32_16x16x64_i8 v[108:111], v[68:71], v[204:207], v[108:111]
	v_mfma_i32_16x16x64_i8 v[124:127], v[68:71], v[172:175], v[124:127]
	v_mfma_i32_16x16x64_i8 v[124:127], v[72:75], v[176:179], v[124:127]
	v_mfma_i32_16x16x64_i8 v[148:151], v[72:75], v[168:171], v[148:151]
	v_mfma_i32_16x16x64_i8 v[148:151], v[68:71], v[164:167], v[148:151]
	v_mfma_i32_16x16x64_i8 v[136:139], v[140:143], v[164:167], v[136:139]
	v_mfma_i32_16x16x64_i8 v[136:139], v[144:147], v[168:171], v[136:139]
	v_mfma_i32_16x16x64_i8 v[120:123], v[144:147], v[176:179], v[120:123]
	v_mfma_i32_16x16x64_i8 v[120:123], v[140:143], v[172:175], v[120:123]
	v_mfma_i32_16x16x64_i8 v[104:107], v[140:143], v[204:207], v[104:107]
	v_mfma_i32_16x16x64_i8 v[104:107], v[144:147], v[208:211], v[104:107]
	v_mfma_i32_16x16x64_i8 v[88:91], v[144:147], v[220:223], v[88:91]
	v_mfma_i32_16x16x64_i8 v[88:91], v[140:143], v[212:215], v[88:91]
	v_mfma_i32_16x16x64_i8 v[84:87], v[156:159], v[212:215], v[84:87]
	v_mfma_i32_16x16x64_i8 v[84:87], v[160:163], v[220:223], v[84:87]
	v_mfma_i32_16x16x64_i8 v[100:103], v[160:163], v[208:211], v[100:103]
	v_mfma_i32_16x16x64_i8 v[100:103], v[156:159], v[204:207], v[100:103]
	v_mfma_i32_16x16x64_i8 v[116:119], v[156:159], v[172:175], v[116:119]
	v_mfma_i32_16x16x64_i8 v[116:119], v[160:163], v[176:179], v[116:119]
	v_mfma_i32_16x16x64_i8 v[132:135], v[160:163], v[168:171], v[132:135]
	v_mfma_i32_16x16x64_i8 v[132:135], v[156:159], v[164:167], v[132:135]
	s_barrier
	s_setprio 0
	s_add_i32 s60, s87, s46
	v_lshl_add_u64 v[190:191], v[190:191], 0, s[84:85]
	s_mov_b32 m0, s60
	ds_read_b128 v[164:167], v219 offset:49152
	ds_read_b128 v[168:171], v219 offset:50176
	ds_read_b128 v[172:175], v219 offset:51200
	ds_read_b128 v[176:179], v219 offset:52224
	ds_read_b128 v[204:207], v219 offset:53248
	ds_read_b128 v[208:211], v219 offset:54272
	ds_read_b128 v[212:215], v219 offset:55296
	ds_read_b128 v[220:223], v219 offset:56320
	global_load_lds_dwordx4 v[190:191], off
	s_add_i32 m0, s60, 0x2000
	s_add_u32 s58, s58, 0x80080
	v_lshl_add_u64 v[190:191], v[224:225], 0, s[84:85]
	s_addc_u32 s59, s59, 0
	s_add_i32 s60, s96, s46
	global_load_lds_dwordx4 v[190:191], off
	s_mov_b32 m0, s60
	s_nop 0
	global_load_lds_dwordx4 v2, s[58:59]
	s_add_i32 m0, s60, 0x2000
	s_nop 0
	global_load_lds_dwordx4 v184, s[58:59]
	s_cmp_eq_u32 s86, 28
	s_cbranch_scc0 .Ldefer_1843_body
	v_lshl_add_u64 v[190:191], v[226:227], 0, s[84:85]
	s_mov_b32 m0, s28
	s_nop 0
	global_load_lds_dwordx4 v[190:191], off
	v_lshl_add_u64 v[190:191], v[228:229], 0, s[84:85]
	s_mov_b32 m0, s77
	s_nop 0
	global_load_lds_dwordx4 v[190:191], off
.Ldefer_1843_body:
	s_waitcnt vmcnt(6)
	s_waitcnt lgkmcnt(0)
	s_setprio 1
	s_barrier
	s_waitcnt lgkmcnt(0)
	v_mfma_i32_16x16x64_i8 v[80:83], v[52:55], v[164:167], v[80:83]
	v_mfma_i32_16x16x64_i8 v[80:83], v[56:59], v[168:171], v[80:83]
	v_mfma_i32_16x16x64_i8 v[64:67], v[56:59], v[176:179], v[64:67]
	v_mfma_i32_16x16x64_i8 v[64:67], v[52:55], v[172:175], v[64:67]
	v_mfma_i32_16x16x64_i8 v[48:51], v[52:55], v[204:207], v[48:51]
	v_mfma_i32_16x16x64_i8 v[48:51], v[56:59], v[208:211], v[48:51]
	v_mfma_i32_16x16x64_i8 v[16:19], v[56:59], v[220:223], v[16:19]
	v_mfma_i32_16x16x64_i8 v[16:19], v[52:55], v[212:215], v[16:19]
	v_mfma_i32_16x16x64_i8 v[12:15], v[68:71], v[212:215], v[12:15]
	v_mfma_i32_16x16x64_i8 v[12:15], v[72:75], v[220:223], v[12:15]
	v_mfma_i32_16x16x64_i8 v[44:47], v[72:75], v[208:211], v[44:47]
	v_mfma_i32_16x16x64_i8 v[44:47], v[68:71], v[204:207], v[44:47]
	v_mfma_i32_16x16x64_i8 v[60:63], v[68:71], v[172:175], v[60:63]
	v_mfma_i32_16x16x64_i8 v[60:63], v[72:75], v[176:179], v[60:63]
	v_mfma_i32_16x16x64_i8 v[76:79], v[72:75], v[168:171], v[76:79]
	v_mfma_i32_16x16x64_i8 v[76:79], v[68:71], v[164:167], v[76:79]
	v_mfma_i32_16x16x64_i8 v[28:31], v[140:143], v[164:167], v[28:31]
	v_mfma_i32_16x16x64_i8 v[72:75], v[144:147], v[168:171], v[28:31]
	v_mfma_i32_16x16x64_i8 v[28:31], v[144:147], v[176:179], v[36:39]
	v_mfma_i32_16x16x64_i8 v[56:59], v[140:143], v[172:175], v[28:31]
	v_mfma_i32_16x16x64_i8 v[24:27], v[140:143], v[204:207], v[24:27]
	v_mfma_i32_16x16x64_i8 v[24:27], v[144:147], v[208:211], v[24:27]
	v_mfma_i32_16x16x64_i8 v[8:11], v[144:147], v[220:223], v[8:11]
	v_mfma_i32_16x16x64_i8 v[8:11], v[140:143], v[212:215], v[8:11]
	v_mfma_i32_16x16x64_i8 v[4:7], v[156:159], v[212:215], v[4:7]
	v_mfma_i32_16x16x64_i8 v[4:7], v[160:163], v[220:223], v[4:7]
	v_mfma_i32_16x16x64_i8 v[20:23], v[160:163], v[208:211], v[20:23]
	v_mfma_i32_16x16x64_i8 v[20:23], v[156:159], v[204:207], v[20:23]
	v_mfma_i32_16x16x64_i8 v[28:31], v[156:159], v[172:175], v[40:43]
	v_mfma_i32_16x16x64_i8 v[52:55], v[160:163], v[176:179], v[28:31]
	v_mfma_i32_16x16x64_i8 v[28:31], v[160:163], v[168:171], v[32:35]
	v_mfma_i32_16x16x64_i8 v[68:71], v[156:159], v[164:167], v[28:31]
	s_barrier
	s_setprio 0
	s_add_i32 s86, s86, 2
	s_add_u32 s54, s54, 0x100
	s_addc_u32 s55, s55, 0
	s_add_u32 s45, s45, 0x100
	s_addc_u32 s49, s49, 0
	s_cmp_gt_u32 s86, 29
	s_cbranch_scc0 .LBB0_1843
